# norm epilogues (P1, FF1): consumers read prefetch pool registers directly instead of v_mov copies; refill loads moved to row end
# baseline (speedup 1.0000x reference)
; #define PG8_STAGE(bufoff, gbase, voff) do { _Pragma("unroll") for (int _i = 0; _i < 2; ++_i) \
;         __builtin_amdgcn_global_load_lds((const unsigned*)((const char*)(gbase) + (voff)[_i]), (LAS unsigned*)(lds + (bufoff) + ldsw + _i * 8192), 16, 0, 0); } while (0)
; #define PG8_LDA(dst, b, h) do { _Pragma("unroll") for (int m = 0; m < 4; ++m) _Pragma("unroll") for (int k = 0; k < 2; ++k) dst[m][k] = *(const LAS bf16x8*)(lds + PG8_SA(b, h) + aoff + m * 2048 + k * 1024); } while (0)
; #define PG8_LDB(dst, b, h) do { _Pragma("unroll") for (int n = 0; n < 2; ++n) _Pragma("unroll") for (int k = 0; k < 2; ++k) dst[n][k] = *(const LAS bf16x8*)(lds + PG8_SB(b, h) + boff + n * 2048 + k * 1024); } while (0)
; #define PG8_MMA(ai, bj, At, Bt) do { __builtin_amdgcn_s_setprio(1); _Pragma("unroll") for (int m = 0; m < 4; ++m) _Pragma("unroll") for (int n = 0; n < 2; ++n) _Pragma("unroll") for (int k = 0; k < 2; ++k) \
;         acc[ai][bj][m][n] = __builtin_amdgcn_mfma_f32_16x16x32_bf16(Bt[n][k], At[m][k], acc[ai][bj][m][n], 0, 0, 0); __builtin_amdgcn_s_setprio(0); } while (0)
; #define PG8_WAIT_L(n) asm volatile("s_waitcnt lgkmcnt(" #n ")" ::: "memory")
; #define PG8_BAR __builtin_amdgcn_s_barrier()
; #define PG8_SCHED __builtin_amdgcn_sched_barrier(0)
;     ...
;         for (int t = 0; t < nt; t += 2) {
;             const bool last = (t == nt - 2);
;             const char* a1 = cA + (size_t)(t + 1) * kstep;
;             const char* a2 = last ? nA : cA + (size_t)(t + 2) * kstep; const char* b2 = last ? nB : cB + (size_t)(t + 2) * kstep;
;             const char* a3 = a2 + kstep; const char* b3 = b2 + kstep;
;             if (last && has_next) PG8_A_READY(nxt);
;             PG8_LDB(B0, 0, 0); PG8_SCHED; PG8_LDA(At, 0, 0); PG8_STAGE(PG8_SA(1, 1), a1 + hA, voffA);
;             PG8_WAIT_L(8); PG8_BAR; PG8_WAIT_L(0); PG8_MMA(0, 0, At, B0); PG8_BAR; PG8_SCHED;
;             PG8_LDB(B1, 0, 1); PG8_STAGE(PG8_SB(0, 0), b2, voffB);
;             PG8_BAR; PG8_WAIT_L(0); PG8_MMA(0, 1, At, B1); PG8_BAR;
;             PG8_LDA(At, 0, 1); PG8_STAGE(PG8_SA(0, 0), a2, voffA);
;             PG8_BAR; PG8_WAIT_L(0); PG8_MMA(1, 0, At, B0); PG8_BAR; PG8_SCHED;
.LBB0_125:
	ds_read_b128 v[146:149], v155
	ds_read_b128 v[160:163], v155 offset:1024
	ds_read_b128 v[170:173], v155 offset:2048
	ds_read_b128 v[174:177], v155 offset:3072
	s_add_u32 s34, s30, 0xfffc0080
	s_addc_u32 s35, s31, -1
	s_cmp_eq_u32 s44, 12
	s_cselect_b32 s37, s7, s35
	s_cselect_b32 s36, s23, s34
	s_cselect_b32 s35, s21, s43
	s_cselect_b32 s34, s33, s42
	v_lshl_add_u64 v[150:151], s[30:31], 0, v[138:139]
	s_add_i32 m0, s29, 0xc000
	ds_read_b128 v[178:181], v156
	ds_read_b128 v[182:185], v156 offset:1024
	ds_read_b128 v[186:189], v156 offset:2048
	ds_read_b128 v[190:193], v156 offset:3072
	ds_read_b128 v[194:197], v156 offset:4096
	ds_read_b128 v[198:201], v156 offset:5120
	ds_read_b128 v[202:205], v156 offset:6144
	ds_read_b128 v[206:209], v156 offset:7168
	global_load_lds_dwordx4 v[150:151], off
	v_lshl_add_u64 v[150:151], s[30:31], 0, v[136:137]
	s_add_i32 m0, s29, 0xe000
	s_nop 0
	global_load_lds_dwordx4 v[150:151], off
	s_waitcnt lgkmcnt(8)
	s_barrier
	s_waitcnt lgkmcnt(0)
	s_setprio 1
	s_waitcnt lgkmcnt(0)
	v_mfma_f32_16x16x32_bf16 v[124:127], v[146:149], v[178:181], v[124:127]
	v_mfma_f32_16x16x32_bf16 v[120:123], v[170:173], v[178:181], v[120:123]
	v_mfma_f32_16x16x32_bf16 v[108:111], v[146:149], v[186:189], v[108:111]
	v_mfma_f32_16x16x32_bf16 v[104:107], v[170:173], v[186:189], v[104:107]
	v_mfma_f32_16x16x32_bf16 v[92:95], v[146:149], v[194:197], v[92:95]
	v_mfma_f32_16x16x32_bf16 v[88:91], v[170:173], v[194:197], v[88:91]
	v_mfma_f32_16x16x32_bf16 v[76:79], v[146:149], v[202:205], v[76:79]
	v_mfma_f32_16x16x32_bf16 v[72:75], v[170:173], v[202:205], v[72:75]
	v_mfma_f32_16x16x32_bf16 v[124:127], v[160:163], v[182:185], v[124:127]
	v_mfma_f32_16x16x32_bf16 v[120:123], v[174:177], v[182:185], v[120:123]
	v_mfma_f32_16x16x32_bf16 v[108:111], v[160:163], v[190:193], v[108:111]
	v_mfma_f32_16x16x32_bf16 v[104:107], v[174:177], v[190:193], v[104:107]
	v_mfma_f32_16x16x32_bf16 v[92:95], v[160:163], v[198:201], v[92:95]
	v_mfma_f32_16x16x32_bf16 v[88:91], v[174:177], v[198:201], v[88:91]
	v_mfma_f32_16x16x32_bf16 v[76:79], v[160:163], v[206:209], v[76:79]
	v_mfma_f32_16x16x32_bf16 v[72:75], v[174:177], v[206:209], v[72:75]
	s_setprio 0
	s_barrier
	s_add_i32 s45, s59, s51
	v_lshl_add_u64 v[150:151], s[34:35], 0, v[130:131]
	s_mov_b32 m0, s45
	ds_read_b128 v[210:213], v157
	ds_read_b128 v[214:217], v157 offset:1024
	ds_read_b128 v[218:221], v157 offset:2048
	ds_read_b128 v[222:225], v157 offset:3072
	global_load_lds_dwordx4 v[150:151], off
	v_lshl_add_u64 v[164:165], s[34:35], 0, v[134:135]
	s_add_i32 m0, s45, 0x2000
	s_nop 0
	global_load_lds_dwordx4 v[164:165], off
	s_barrier
	s_waitcnt lgkmcnt(0)
	s_setprio 1
	s_waitcnt lgkmcnt(0)
	v_mfma_f32_16x16x32_bf16 v[116:119], v[210:213], v[178:181], v[116:119]
	v_mfma_f32_16x16x32_bf16 v[112:115], v[218:221], v[178:181], v[112:115]
	v_mfma_f32_16x16x32_bf16 v[100:103], v[210:213], v[186:189], v[100:103]
	v_mfma_f32_16x16x32_bf16 v[96:99], v[218:221], v[186:189], v[96:99]
	v_mfma_f32_16x16x32_bf16 v[84:87], v[210:213], v[194:197], v[84:87]
	v_mfma_f32_16x16x32_bf16 v[80:83], v[218:221], v[194:197], v[80:83]
	v_mfma_f32_16x16x32_bf16 v[68:71], v[210:213], v[202:205], v[68:71]
	v_mfma_f32_16x16x32_bf16 v[64:67], v[218:221], v[202:205], v[64:67]
	v_mfma_f32_16x16x32_bf16 v[116:119], v[214:217], v[182:185], v[116:119]
	v_mfma_f32_16x16x32_bf16 v[112:115], v[222:225], v[182:185], v[112:115]
	v_mfma_f32_16x16x32_bf16 v[100:103], v[214:217], v[190:193], v[100:103]
	v_mfma_f32_16x16x32_bf16 v[96:99], v[222:225], v[190:193], v[96:99]
	v_mfma_f32_16x16x32_bf16 v[84:87], v[214:217], v[198:201], v[84:87]
	v_mfma_f32_16x16x32_bf16 v[80:83], v[222:225], v[198:201], v[80:83]
	v_mfma_f32_16x16x32_bf16 v[68:71], v[214:217], v[206:209], v[68:71]
	v_mfma_f32_16x16x32_bf16 v[64:67], v[222:225], v[206:209], v[64:67]
	s_setprio 0
	s_mov_b32 m0, s29
	v_lshl_add_u64 v[226:227], s[36:37], 0, v[128:129]
	s_barrier
	ds_read_b128 v[178:181], v156 offset:16384
	ds_read_b128 v[182:185], v156 offset:17408
	ds_read_b128 v[186:189], v156 offset:18432
	ds_read_b128 v[190:193], v156 offset:19456
	ds_read_b128 v[194:197], v156 offset:20480
	ds_read_b128 v[198:201], v156 offset:21504
	ds_read_b128 v[202:205], v156 offset:22528
	ds_read_b128 v[206:209], v156 offset:23552
	global_load_lds_dwordx4 v[226:227], off
	v_lshl_add_u64 v[228:229], s[36:37], 0, v[132:133]
	s_mov_b32 m0, s52
	s_nop 0
	global_load_lds_dwordx4 v[228:229], off
	s_barrier
	s_waitcnt lgkmcnt(0)
	s_setprio 1
	s_waitcnt lgkmcnt(0)
	v_mfma_f32_16x16x32_bf16 v[60:63], v[146:149], v[178:181], v[60:63]
	v_mfma_f32_16x16x32_bf16 v[56:59], v[170:173], v[178:181], v[56:59]
	v_mfma_f32_16x16x32_bf16 v[44:47], v[146:149], v[186:189], v[44:47]
	v_mfma_f32_16x16x32_bf16 v[40:43], v[170:173], v[186:189], v[40:43]
	v_mfma_f32_16x16x32_bf16 v[28:31], v[146:149], v[194:197], v[28:31]
	v_mfma_f32_16x16x32_bf16 v[24:27], v[170:173], v[194:197], v[24:27]
	v_mfma_f32_16x16x32_bf16 v[12:15], v[146:149], v[202:205], v[12:15]
	v_mfma_f32_16x16x32_bf16 v[8:11], v[170:173], v[202:205], v[8:11]
	v_mfma_f32_16x16x32_bf16 v[60:63], v[160:163], v[182:185], v[60:63]
	v_mfma_f32_16x16x32_bf16 v[56:59], v[174:177], v[182:185], v[56:59]
	v_mfma_f32_16x16x32_bf16 v[44:47], v[160:163], v[190:193], v[44:47]
	v_mfma_f32_16x16x32_bf16 v[40:43], v[174:177], v[190:193], v[40:43]
	v_mfma_f32_16x16x32_bf16 v[28:31], v[160:163], v[198:201], v[28:31]
	v_mfma_f32_16x16x32_bf16 v[24:27], v[174:177], v[198:201], v[24:27]
	v_mfma_f32_16x16x32_bf16 v[12:15], v[160:163], v[206:209], v[12:15]
	v_mfma_f32_16x16x32_bf16 v[8:11], v[174:177], v[206:209], v[8:11]
	s_setprio 0
	s_barrier
; #define PG8_STAGE(bufoff, gbase, voff) do { _Pragma("unroll") for (int _i = 0; _i < 2; ++_i) \
;         __builtin_amdgcn_global_load_lds((const unsigned*)((const char*)(gbase) + (voff)[_i]), (LAS unsigned*)(lds + (bufoff) + ldsw + _i * 8192), 16, 0, 0); } while (0)
; #define PG8_LDA(dst, b, h) do { _Pragma("unroll") for (int m = 0; m < 4; ++m) _Pragma("unroll") for (int k = 0; k < 2; ++k) dst[m][k] = *(const LAS bf16x8*)(lds + PG8_SA(b, h) + aoff + m * 2048 + k * 1024); } while (0)
; #define PG8_LDB(dst, b, h) do { _Pragma("unroll") for (int n = 0; n < 2; ++n) _Pragma("unroll") for (int k = 0; k < 2; ++k) dst[n][k] = *(const LAS bf16x8*)(lds + PG8_SB(b, h) + boff + n * 2048 + k * 1024); } while (0)
; #define PG8_MMA(ai, bj, At, Bt) do { __builtin_amdgcn_s_setprio(1); _Pragma("unroll") for (int m = 0; m < 4; ++m) _Pragma("unroll") for (int n = 0; n < 2; ++n) _Pragma("unroll") for (int k = 0; k < 2; ++k) \
;         acc[ai][bj][m][n] = __builtin_amdgcn_mfma_f32_16x16x32_bf16(Bt[n][k], At[m][k], acc[ai][bj][m][n], 0, 0, 0); __builtin_amdgcn_s_setprio(0); } while (0)
; #define PG8_WAIT_V(n) asm volatile("s_waitcnt vmcnt(" #n ")" ::: "memory")
; #define PG8_WAIT_L(n) asm volatile("s_waitcnt lgkmcnt(" #n ")" ::: "memory")
; #define PG8_BAR __builtin_amdgcn_s_barrier()
; #define PG8_SCHED __builtin_amdgcn_sched_barrier(0)
;     ...
;             PG8_BAR; PG8_WAIT_L(0); PG8_MMA(1, 0, At, B0); PG8_BAR; PG8_SCHED;
;             PG8_STAGE(PG8_SB(0, 1), b2 + hB, voffB);
;             PG8_WAIT_V(6); PG8_BAR; PG8_MMA(1, 1, At, B1); PG8_BAR;
;             PG8_LDB(B0, 1, 0); PG8_SCHED; PG8_LDA(At, 1, 0); PG8_STAGE(PG8_SA(0, 1), a2 + hA, voffA);
;             PG8_WAIT_L(8); PG8_BAR; PG8_WAIT_L(0); PG8_MMA(0, 0, At, B0); PG8_BAR; PG8_SCHED;
;             PG8_LDB(B1, 1, 1); PG8_STAGE(PG8_SB(1, 0), b3, voffB);
;             PG8_BAR; PG8_WAIT_L(0); PG8_MMA(0, 1, At, B1); PG8_BAR;
;             PG8_LDA(At, 1, 1); PG8_STAGE(PG8_SA(1, 0), a3, voffA);
;             PG8_BAR; PG8_WAIT_L(0); PG8_MMA(1, 0, At, B0); PG8_BAR; PG8_SCHED;
	s_add_u32 s64, s34, 0x40000
	s_addc_u32 s65, s35, 0
	s_add_i32 s45, s60, s51
	v_lshl_add_u64 v[146:147], s[64:65], 0, v[130:131]
	s_mov_b32 m0, s45
	s_nop 0
	global_load_lds_dwordx4 v[146:147], off
	v_lshl_add_u64 v[146:147], s[64:65], 0, v[134:135]
	s_add_i32 m0, s45, 0x2000
	s_nop 0
	global_load_lds_dwordx4 v[146:147], off
	s_waitcnt vmcnt(6)
	s_barrier
	s_setprio 1
	v_mfma_f32_16x16x32_bf16 v[52:55], v[210:213], v[178:181], v[52:55]
	v_mfma_f32_16x16x32_bf16 v[48:51], v[218:221], v[178:181], v[48:51]
	v_mfma_f32_16x16x32_bf16 v[36:39], v[210:213], v[186:189], v[36:39]
	v_mfma_f32_16x16x32_bf16 v[32:35], v[218:221], v[186:189], v[32:35]
	v_mfma_f32_16x16x32_bf16 v[20:23], v[210:213], v[194:197], v[20:23]
	v_mfma_f32_16x16x32_bf16 v[16:19], v[218:221], v[194:197], v[16:19]
	v_mfma_f32_16x16x32_bf16 v[4:7], v[210:213], v[202:205], v[4:7]
	v_mfma_f32_16x16x32_bf16 v[0:3], v[218:221], v[202:205], v[0:3]
	v_mfma_f32_16x16x32_bf16 v[52:55], v[214:217], v[182:185], v[52:55]
	v_mfma_f32_16x16x32_bf16 v[48:51], v[222:225], v[182:185], v[48:51]
	v_mfma_f32_16x16x32_bf16 v[36:39], v[214:217], v[190:193], v[36:39]
	v_mfma_f32_16x16x32_bf16 v[32:35], v[222:225], v[190:193], v[32:35]
	v_mfma_f32_16x16x32_bf16 v[20:23], v[214:217], v[198:201], v[20:23]
	v_mfma_f32_16x16x32_bf16 v[16:19], v[222:225], v[198:201], v[16:19]
	v_mfma_f32_16x16x32_bf16 v[4:7], v[214:217], v[206:209], v[4:7]
	v_mfma_f32_16x16x32_bf16 v[0:3], v[222:225], v[206:209], v[0:3]
	s_setprio 0
	s_add_i32 s45, 0, 0x18000
	v_add_u32_e32 v159, s45, v153
	s_barrier
	ds_read_b128 v[146:149], v159
	ds_read_b128 v[160:163], v159 offset:1024
	ds_read_b128 v[170:173], v159 offset:2048
	ds_read_b128 v[174:177], v159 offset:3072
	s_add_u32 s36, s36, 0x40000
	s_addc_u32 s37, s37, 0
	s_mov_b32 m0, s53
	v_lshl_add_u64 v[210:211], s[36:37], 0, v[128:129]
	ds_read_b128 v[178:181], v156 offset:32768
	ds_read_b128 v[182:185], v156 offset:33792
	ds_read_b128 v[186:189], v156 offset:34816
	ds_read_b128 v[190:193], v156 offset:35840
	ds_read_b128 v[194:197], v156 offset:36864
	ds_read_b128 v[198:201], v156 offset:37888
	ds_read_b128 v[202:205], v156 offset:38912
	ds_read_b128 v[206:209], v156 offset:39936
	global_load_lds_dwordx4 v[210:211], off
	v_lshl_add_u64 v[210:211], s[36:37], 0, v[132:133]
	s_mov_b32 m0, s54
	s_nop 0
	global_load_lds_dwordx4 v[210:211], off
	s_waitcnt lgkmcnt(8)
	s_barrier
	s_waitcnt lgkmcnt(0)
	s_setprio 1
	s_waitcnt lgkmcnt(0)
	v_mfma_f32_16x16x32_bf16 v[124:127], v[146:149], v[178:181], v[124:127]
	v_mfma_f32_16x16x32_bf16 v[120:123], v[170:173], v[178:181], v[120:123]
	v_mfma_f32_16x16x32_bf16 v[108:111], v[146:149], v[186:189], v[108:111]
	v_mfma_f32_16x16x32_bf16 v[104:107], v[170:173], v[186:189], v[104:107]
	v_mfma_f32_16x16x32_bf16 v[92:95], v[146:149], v[194:197], v[92:95]
	v_mfma_f32_16x16x32_bf16 v[88:91], v[170:173], v[194:197], v[88:91]
	v_mfma_f32_16x16x32_bf16 v[76:79], v[146:149], v[202:205], v[76:79]
	v_mfma_f32_16x16x32_bf16 v[72:75], v[170:173], v[202:205], v[72:75]
	v_mfma_f32_16x16x32_bf16 v[124:127], v[160:163], v[182:185], v[124:127]
	v_mfma_f32_16x16x32_bf16 v[120:123], v[174:177], v[182:185], v[120:123]
	v_mfma_f32_16x16x32_bf16 v[108:111], v[160:163], v[190:193], v[108:111]
	v_mfma_f32_16x16x32_bf16 v[104:107], v[174:177], v[190:193], v[104:107]
	v_mfma_f32_16x16x32_bf16 v[92:95], v[160:163], v[198:201], v[92:95]
	v_mfma_f32_16x16x32_bf16 v[88:91], v[174:177], v[198:201], v[88:91]
	v_mfma_f32_16x16x32_bf16 v[76:79], v[160:163], v[206:209], v[76:79]
	v_mfma_f32_16x16x32_bf16 v[72:75], v[174:177], v[206:209], v[72:75]
	s_setprio 0
	s_barrier
	s_add_i32 s36, 0, 0x1c000
	s_add_i32 s37, s45, s51
	v_add_u32_e32 v159, s36, v153
	v_lshl_add_u64 v[150:151], v[150:151], 0, s[18:19]
	s_mov_b32 m0, s37
	ds_read_b128 v[210:213], v159
	ds_read_b128 v[214:217], v159 offset:1024
	ds_read_b128 v[218:221], v159 offset:2048
	ds_read_b128 v[222:225], v159 offset:3072
	global_load_lds_dwordx4 v[150:151], off
	v_lshl_add_u64 v[150:151], v[164:165], 0, s[18:19]
	s_add_i32 m0, s37, 0x2000
	s_nop 0
	global_load_lds_dwordx4 v[150:151], off
	s_barrier
	s_waitcnt lgkmcnt(0)
	s_setprio 1
	s_waitcnt lgkmcnt(0)
	v_mfma_f32_16x16x32_bf16 v[116:119], v[210:213], v[178:181], v[116:119]
	v_mfma_f32_16x16x32_bf16 v[112:115], v[218:221], v[178:181], v[112:115]
	v_mfma_f32_16x16x32_bf16 v[100:103], v[210:213], v[186:189], v[100:103]
	v_mfma_f32_16x16x32_bf16 v[96:99], v[218:221], v[186:189], v[96:99]
	v_mfma_f32_16x16x32_bf16 v[84:87], v[210:213], v[194:197], v[84:87]
	v_mfma_f32_16x16x32_bf16 v[80:83], v[218:221], v[194:197], v[80:83]
	v_mfma_f32_16x16x32_bf16 v[68:71], v[210:213], v[202:205], v[68:71]
	v_mfma_f32_16x16x32_bf16 v[64:67], v[218:221], v[202:205], v[64:67]
	v_mfma_f32_16x16x32_bf16 v[116:119], v[214:217], v[182:185], v[116:119]
	v_mfma_f32_16x16x32_bf16 v[112:115], v[222:225], v[182:185], v[112:115]
	v_mfma_f32_16x16x32_bf16 v[100:103], v[214:217], v[190:193], v[100:103]
	v_mfma_f32_16x16x32_bf16 v[96:99], v[222:225], v[190:193], v[96:99]
	v_mfma_f32_16x16x32_bf16 v[84:87], v[214:217], v[198:201], v[84:87]
	v_mfma_f32_16x16x32_bf16 v[80:83], v[222:225], v[198:201], v[80:83]
	v_mfma_f32_16x16x32_bf16 v[68:71], v[214:217], v[206:209], v[68:71]
	v_mfma_f32_16x16x32_bf16 v[64:67], v[222:225], v[206:209], v[64:67]
	s_setprio 0
	s_mov_b32 m0, s56
	v_lshl_add_u64 v[150:151], v[226:227], 0, s[18:19]
	s_barrier
	ds_read_b128 v[178:181], v156 offset:49152
	ds_read_b128 v[182:185], v156 offset:50176
	ds_read_b128 v[186:189], v156 offset:51200
	ds_read_b128 v[190:193], v156 offset:52224
	ds_read_b128 v[194:197], v156 offset:53248
	ds_read_b128 v[198:201], v156 offset:54272
	ds_read_b128 v[202:205], v156 offset:55296
	ds_read_b128 v[206:209], v156 offset:56320
	global_load_lds_dwordx4 v[150:151], off
	v_lshl_add_u64 v[150:151], v[228:229], 0, s[18:19]
	s_mov_b32 m0, s57
	s_nop 0
	global_load_lds_dwordx4 v[150:151], off
	s_barrier
; #define PG8_STAGE(bufoff, gbase, voff) do { _Pragma("unroll") for (int _i = 0; _i < 2; ++_i) \
;         __builtin_amdgcn_global_load_lds((const unsigned*)((const char*)(gbase) + (voff)[_i]), (LAS unsigned*)(lds + (bufoff) + ldsw + _i * 8192), 16, 0, 0); } while (0)
; #define PG8_MMA(ai, bj, At, Bt) do { __builtin_amdgcn_s_setprio(1); _Pragma("unroll") for (int m = 0; m < 4; ++m) _Pragma("unroll") for (int n = 0; n < 2; ++n) _Pragma("unroll") for (int k = 0; k < 2; ++k) \
;         acc[ai][bj][m][n] = __builtin_amdgcn_mfma_f32_16x16x32_bf16(Bt[n][k], At[m][k], acc[ai][bj][m][n], 0, 0, 0); __builtin_amdgcn_s_setprio(0); } while (0)
; #define PG8_WAIT_V(n) asm volatile("s_waitcnt vmcnt(" #n ")" ::: "memory")
; #define PG8_WAIT_L(n) asm volatile("s_waitcnt lgkmcnt(" #n ")" ::: "memory")
; #define PG8_BAR __builtin_amdgcn_s_barrier()
; #define PG8_SCHED __builtin_amdgcn_sched_barrier(0)
;     ...
;             PG8_BAR; PG8_WAIT_L(0); PG8_MMA(1, 0, At, B0); PG8_BAR; PG8_SCHED;
;             PG8_STAGE(PG8_SB(1, 1), b3 + hB, voffB);
;             PG8_WAIT_V(6); PG8_BAR; PG8_MMA(1, 1, At, B1); PG8_BAR;
; __device__ __forceinline__ float row_rstd(const float* ssq, int row) {
;     const f32x4* p = (const f32x4*)(ssq + (size_t)row * 16);
;     const f32x4 a = p[0], b = p[1], c = p[2], d = p[3];
	s_waitcnt lgkmcnt(0)
	s_setprio 1
	s_waitcnt lgkmcnt(0)
	v_mfma_f32_16x16x32_bf16 v[60:63], v[146:149], v[178:181], v[60:63]
	v_mfma_f32_16x16x32_bf16 v[56:59], v[170:173], v[178:181], v[56:59]
	v_mfma_f32_16x16x32_bf16 v[44:47], v[146:149], v[186:189], v[44:47]
	v_mfma_f32_16x16x32_bf16 v[40:43], v[170:173], v[186:189], v[40:43]
	v_mfma_f32_16x16x32_bf16 v[28:31], v[146:149], v[194:197], v[28:31]
	v_mfma_f32_16x16x32_bf16 v[24:27], v[170:173], v[194:197], v[24:27]
	v_mfma_f32_16x16x32_bf16 v[12:15], v[146:149], v[202:205], v[12:15]
	v_mfma_f32_16x16x32_bf16 v[8:11], v[170:173], v[202:205], v[8:11]
	v_mfma_f32_16x16x32_bf16 v[60:63], v[160:163], v[182:185], v[60:63]
	v_mfma_f32_16x16x32_bf16 v[56:59], v[174:177], v[182:185], v[56:59]
	v_mfma_f32_16x16x32_bf16 v[44:47], v[160:163], v[190:193], v[44:47]
	v_mfma_f32_16x16x32_bf16 v[40:43], v[174:177], v[190:193], v[40:43]
	v_mfma_f32_16x16x32_bf16 v[28:31], v[160:163], v[198:201], v[28:31]
	v_mfma_f32_16x16x32_bf16 v[24:27], v[174:177], v[198:201], v[24:27]
	v_mfma_f32_16x16x32_bf16 v[12:15], v[160:163], v[206:209], v[12:15]
	v_mfma_f32_16x16x32_bf16 v[8:11], v[174:177], v[206:209], v[8:11]
	s_setprio 0
	s_barrier
	s_add_u32 s34, s34, 0x40080
	s_addc_u32 s35, s35, 0
	s_add_i32 s36, s36, s51
	v_lshl_add_u64 v[146:147], s[34:35], 0, v[130:131]
	s_mov_b32 m0, s36
	s_nop 0
	global_load_lds_dwordx4 v[146:147], off
	v_lshl_add_u64 v[146:147], s[34:35], 0, v[134:135]
	s_add_i32 m0, s36, 0x2000
	s_nop 0
	global_load_lds_dwordx4 v[146:147], off
	s_waitcnt vmcnt(6)
	s_barrier
	s_setprio 1
	v_mfma_f32_16x16x32_bf16 v[52:55], v[210:213], v[178:181], v[52:55]
	v_mfma_f32_16x16x32_bf16 v[48:51], v[218:221], v[178:181], v[48:51]
	v_mfma_f32_16x16x32_bf16 v[36:39], v[210:213], v[186:189], v[36:39]
	v_mfma_f32_16x16x32_bf16 v[32:35], v[218:221], v[186:189], v[32:35]
	v_mfma_f32_16x16x32_bf16 v[20:23], v[210:213], v[194:197], v[20:23]
	v_mfma_f32_16x16x32_bf16 v[16:19], v[218:221], v[194:197], v[16:19]
	v_mfma_f32_16x16x32_bf16 v[4:7], v[210:213], v[202:205], v[4:7]
	v_mfma_f32_16x16x32_bf16 v[0:3], v[218:221], v[202:205], v[0:3]
	v_mfma_f32_16x16x32_bf16 v[52:55], v[214:217], v[182:185], v[52:55]
	v_mfma_f32_16x16x32_bf16 v[48:51], v[222:225], v[182:185], v[48:51]
	v_mfma_f32_16x16x32_bf16 v[36:39], v[214:217], v[190:193], v[36:39]
	v_mfma_f32_16x16x32_bf16 v[32:35], v[222:225], v[190:193], v[32:35]
	v_mfma_f32_16x16x32_bf16 v[20:23], v[214:217], v[198:201], v[20:23]
	v_mfma_f32_16x16x32_bf16 v[16:19], v[222:225], v[198:201], v[16:19]
	v_mfma_f32_16x16x32_bf16 v[4:7], v[214:217], v[206:209], v[4:7]
	v_mfma_f32_16x16x32_bf16 v[0:3], v[222:225], v[206:209], v[0:3]
	s_setprio 0
	s_add_i32 s44, s44, 2
	s_add_u32 s42, s42, 0x100
	s_addc_u32 s43, s43, 0
	s_add_u32 s30, s30, 0x100
	s_addc_u32 s31, s31, 0
	s_cmp_gt_u32 s44, 13
	s_barrier
	s_cbranch_scc0 .LBB0_125
	v_lshl_add_u32 v150, s28, 8, v152
	v_ashrrev_i32_e32 v151, 31, v150
	v_lshlrev_b64 v[146:147], 6, v[150:151]
	v_lshl_add_u64 v[146:147], s[16:17], 0, v[146:147]
	v_subrev_u32_e32 v186, s16, v146
	v_add_u32_e32 v187, 0x0, v186
	global_load_dwordx4 v[188:191], v187, s[16:17]
	v_add_u32_e32 v187, 0x20, v186
	global_load_dwordx4 v[192:195], v187, s[16:17]
	v_add_u32_e32 v187, 0x10, v186
	global_load_dwordx4 v[196:199], v187, s[16:17]
	v_add_u32_e32 v187, 0x30, v186
	global_load_dwordx4 v[200:203], v187, s[16:17]
	v_add_u32_e32 v187, 0x400, v186
	global_load_dwordx4 v[204:207], v187, s[16:17]
	v_add_u32_e32 v187, 0x410, v186
	global_load_dwordx4 v[208:211], v187, s[16:17]
	v_add_u32_e32 v187, 0x420, v186
	global_load_dwordx4 v[212:215], v187, s[16:17]
	v_add_u32_e32 v187, 0x430, v186
	global_load_dwordx4 v[216:219], v187, s[16:17]
	v_add_u32_e32 v187, 0x800, v186
	global_load_dwordx4 v[220:223], v187, s[16:17]
	v_add_u32_e32 v187, 0x810, v186
	global_load_dwordx4 v[232:235], v187, s[16:17]
	v_add_u32_e32 v187, 0x820, v186
	global_load_dwordx4 v[236:239], v187, s[16:17]
	v_add_u32_e32 v187, 0x830, v186
	global_load_dwordx4 v[240:243], v187, s[16:17]
	v_lshl_or_b32 v148, s6, 8, v154
	v_mov_b64_e32 v[146:147], s[14:15]
	v_ashrrev_i32_e32 v149, 31, v148
	v_mad_i64_i32 v[164:165], s[6:7], v150, s62, v[146:147]
	v_or_b32_e32 v182, 16, v150
	v_lshlrev_b64 v[148:149], 1, v[148:149]
	v_ashrrev_i32_e32 v183, 31, v182
	s_mov_b64 s[34:35], s[24:25]
	s_mov_b32 s28, s22
	s_mov_b64 s[30:31], s[26:27]
	s_waitcnt vmcnt(8)
; __device__ __forceinline__ u32x4 pack8(const f32x4 v0, const f32x4 v1) { u32x4 w; w.x = pk2(v0[0], v0[1]); w.y = pk2(v0[2], v0[3]); w.z = pk2(v1[0], v1[1]); w.w = pk2(v1[2], v1[3]); return w; }
; __device__ __forceinline__ float row_rstd(const float* ssq, int row) {
;     const f32x4* p = (const f32x4*)(ssq + (size_t)row * 16);
;     const f32x4 a = p[0], b = p[1], c = p[2], d = p[3];
;     const float s = ((a[0] + a[1]) + (a[2] + a[3])) + ((b[0] + b[1]) + (b[2] + b[3])) + ((c[0] + c[1]) + (c[2] + c[3])) + ((d[0] + d[1]) + (d[2] + d[3]));
;     return rsqrtf(s * (1.0f / 1024.0f) + 1e-6f);
;     __device__ __forceinline__ void operator()(const f32x4 (&acc)[2][2][4][2], const Unit& u, int wr, int wc, int fr, int fq) const {
;         const int row0 = u.pm * 256 + wr * 64 + fr, col0 = u.pn * 256 + wc * 32 + 8 * fq;
; #pragma unroll
;         for (int ai = 0; ai < 2; ++ai)
; #pragma unroll
;             for (int m = 0; m < 4; ++m) {
;                 const int row = row0 + ai * 128 + m * 16; const float rs = row_rstd(ssq, row);
;                 bf16_t* rowp = O + (size_t)row * ldc + col0;
; #pragma unroll
;                 for (int bj = 0; bj < 2; ++bj) { f32x4 v0 = acc[ai][bj][m][0] * rs, v1 = acc[ai][bj][m][1] * rs;
;                     if (ACT == 1) {
; #pragma unroll
;                         for (int j = 0; j < 4; ++j) { const float a = fmaxf(v0[j], 0.f), b = fmaxf(v1[j], 0.f); v0[j] = a * a; v1[j] = b * b; } }
;                     *(u32x4*)(rowp + bj * 128) = pack8(v0, v1); }
	v_mov_b32_e32 v184, v189
	v_mov_b32_e32 v185, v190
	v_mov_b32_e32 v161, v191
	v_add_f32_e32 v162, v192, v193
	v_add_f32_e32 v170, v194, v195
	v_mov_b32_e32 v172, v197
	v_mov_b32_e32 v173, v198
	v_mov_b32_e32 v175, v199
	v_mov_b32_e32 v163, v202
	v_mov_b32_e32 v171, v203
	v_mov_b32_e32 v160, v188
	v_pk_add_f32 v[160:161], v[184:185], v[160:161]
	v_mov_b32_e32 v174, v196
	v_pk_add_f32 v[172:173], v[172:173], v[174:175]
	v_pk_add_f32 v[162:163], v[162:163], v[170:171]
	v_pk_add_f32 v[160:161], v[160:161], v[160:161] op_sel:[0,1] op_sel_hi:[1,0]
	v_pk_add_f32 v[170:171], v[172:173], v[172:173] op_sel:[0,1] op_sel_hi:[1,0]
	v_mov_b32_e32 v161, v200
	v_mov_b32_e32 v171, v201
	v_pk_add_f32 v[160:161], v[160:161], v[170:171]
	s_nop 0
	v_pk_add_f32 v[160:161], v[160:161], v[162:163]
	v_lshlrev_b64 v[162:163], 6, v[182:183]
	v_add_f32_e32 v151, v160, v161
	v_fmamk_f32 v151, v151, 0x3a800000, v158
	v_mul_f32_e32 v159, 0x4b800000, v151
	v_cmp_gt_f32_e32 vcc, s61, v151
	v_lshl_add_u64 v[160:161], v[164:165], 0, v[148:149]
	v_lshl_add_u64 v[162:163], s[16:17], 0, v[162:163]
	v_cndmask_b32_e32 v151, v151, v159, vcc
	v_rsq_f32_e32 v151, v151
	s_nop 0
	v_mul_f32_e32 v159, 0x45800000, v151
	v_cndmask_b32_e32 v164, v151, v159, vcc
	v_pk_mul_f32 v[126:127], v[126:127], v[164:165] op_sel_hi:[1,0]
	v_pk_mul_f32 v[124:125], v[124:125], v[164:165] op_sel_hi:[1,0]
	v_pk_mul_f32 v[122:123], v[122:123], v[164:165] op_sel_hi:[1,0]
	v_pk_mul_f32 v[120:121], v[120:121], v[164:165] op_sel_hi:[1,0]
	v_pk_mul_f32 v[118:119], v[118:119], v[164:165] op_sel_hi:[1,0]
	v_pk_mul_f32 v[116:117], v[116:117], v[164:165] op_sel_hi:[1,0]
	v_pk_mul_f32 v[170:171], v[114:115], v[164:165] op_sel_hi:[1,0]
	v_pk_mul_f32 v[164:165], v[112:113], v[164:165] op_sel_hi:[1,0]
	v_cvt_pk_bf16_f32 v112, v124, v125
	v_cvt_pk_bf16_f32 v113, v126, v127
	v_cvt_pk_bf16_f32 v114, v120, v121
	v_cvt_pk_bf16_f32 v115, v122, v123
	global_store_dwordx4 v[160:161], v[112:115], off
	s_nop 1
	v_cvt_pk_bf16_f32 v112, v116, v117
	v_cvt_pk_bf16_f32 v113, v118, v119
	v_cvt_pk_bf16_f32 v114, v164, v165
	v_cvt_pk_bf16_f32 v115, v170, v171
	global_store_dwordx4 v[160:161], v[112:115], off offset:256
	s_nop 0
	v_or_b32_e32 v160, 32, v150
	v_mad_i64_i32 v[162:163], s[6:7], v182, s62, v[146:147]
	v_ashrrev_i32_e32 v161, 31, v160
	v_add_u32_e32 v187, 0xc00, v186
	global_load_dwordx4 v[188:191], v187, s[16:17]
	v_add_u32_e32 v187, 0xc10, v186
	global_load_dwordx4 v[192:195], v187, s[16:17]
	v_add_u32_e32 v187, 0xc20, v186
	global_load_dwordx4 v[196:199], v187, s[16:17]
	v_add_u32_e32 v187, 0xc30, v186
	global_load_dwordx4 v[200:203], v187, s[16:17]
	s_waitcnt vmcnt(10)
	v_mov_b32_e32 v164, v205
	v_mov_b32_e32 v165, v206
	v_mov_b32_e32 v113, v207
	v_mov_b32_e32 v114, v209
	v_mov_b32_e32 v115, v210
	v_mov_b32_e32 v117, v211
	v_mov_b32_e32 v112, v204
	v_pk_add_f32 v[112:113], v[164:165], v[112:113]
	v_mov_b32_e32 v116, v208
	v_pk_add_f32 v[114:115], v[114:115], v[116:117]
	v_pk_add_f32 v[112:113], v[112:113], v[112:113] op_sel:[0,1] op_sel_hi:[1,0]
	v_pk_add_f32 v[114:115], v[114:115], v[114:115] op_sel:[0,1] op_sel_hi:[1,0]
	v_add_f32_e32 v118, v212, v213
	v_add_f32_e32 v120, v214, v215
	v_mov_b32_e32 v119, v218
	v_mov_b32_e32 v121, v219
	v_mov_b32_e32 v113, v216
	v_mov_b32_e32 v115, v217
	v_pk_add_f32 v[116:117], v[118:119], v[120:121]
	v_pk_add_f32 v[112:113], v[112:113], v[114:115]
	v_lshlrev_b64 v[114:115], 6, v[160:161]
	v_pk_add_f32 v[112:113], v[112:113], v[116:117]
	v_lshl_add_u64 v[114:115], s[16:17], 0, v[114:115]
	v_add_f32_e32 v112, v112, v113
	v_fmamk_f32 v112, v112, 0x3a800000, v158
	v_mul_f32_e32 v113, 0x4b800000, v112
	v_cmp_gt_f32_e32 vcc, s61, v112
	s_nop 1
	v_cndmask_b32_e32 v112, v112, v113, vcc
	v_rsq_f32_e32 v116, v112
	v_lshl_add_u64 v[112:113], v[162:163], 0, v[148:149]
	v_mul_f32_e32 v117, 0x45800000, v116
	v_cndmask_b32_e32 v116, v116, v117, vcc
	v_pk_mul_f32 v[110:111], v[110:111], v[116:117] op_sel_hi:[1,0]
	v_pk_mul_f32 v[108:109], v[108:109], v[116:117] op_sel_hi:[1,0]
	v_pk_mul_f32 v[106:107], v[106:107], v[116:117] op_sel_hi:[1,0]
	v_pk_mul_f32 v[104:105], v[104:105], v[116:117] op_sel_hi:[1,0]
	v_pk_mul_f32 v[102:103], v[102:103], v[116:117] op_sel_hi:[1,0]
	v_pk_mul_f32 v[100:101], v[100:101], v[116:117] op_sel_hi:[1,0]
	v_pk_mul_f32 v[118:119], v[98:99], v[116:117] op_sel_hi:[1,0]
	v_pk_mul_f32 v[116:117], v[96:97], v[116:117] op_sel_hi:[1,0]
	v_cvt_pk_bf16_f32 v96, v108, v109
	v_cvt_pk_bf16_f32 v97, v110, v111
	v_cvt_pk_bf16_f32 v98, v104, v105
	v_cvt_pk_bf16_f32 v99, v106, v107
	global_store_dwordx4 v[112:113], v[96:99], off
	s_nop 1
	v_cvt_pk_bf16_f32 v96, v100, v101
	v_cvt_pk_bf16_f32 v97, v102, v103
	v_cvt_pk_bf16_f32 v98, v116, v117
	v_cvt_pk_bf16_f32 v99, v118, v119
	global_store_dwordx4 v[112:113], v[96:99], off offset:256
	s_nop 0
	v_or_b32_e32 v112, 48, v150
	v_mad_i64_i32 v[114:115], s[6:7], v160, s62, v[146:147]
	v_ashrrev_i32_e32 v113, 31, v112
	v_add_u32_e32 v187, 0x2000, v186
	global_load_dwordx4 v[204:207], v187, s[16:17]
	v_add_u32_e32 v187, 0x2010, v186
	global_load_dwordx4 v[208:211], v187, s[16:17]
	v_add_u32_e32 v187, 0x2020, v186
	global_load_dwordx4 v[212:215], v187, s[16:17]
	v_add_u32_e32 v187, 0x2030, v186
	global_load_dwordx4 v[216:219], v187, s[16:17]
	s_waitcnt vmcnt(12)
; __device__ __forceinline__ u32x4 pack8(const f32x4 v0, const f32x4 v1) { u32x4 w; w.x = pk2(v0[0], v0[1]); w.y = pk2(v0[2], v0[3]); w.z = pk2(v1[0], v1[1]); w.w = pk2(v1[2], v1[3]); return w; }
; __device__ __forceinline__ float row_rstd(const float* ssq, int row) {
;     const f32x4* p = (const f32x4*)(ssq + (size_t)row * 16);
;     const f32x4 a = p[0], b = p[1], c = p[2], d = p[3];
;     const float s = ((a[0] + a[1]) + (a[2] + a[3])) + ((b[0] + b[1]) + (b[2] + b[3])) + ((c[0] + c[1]) + (c[2] + c[3])) + ((d[0] + d[1]) + (d[2] + d[3]));
;     return rsqrtf(s * (1.0f / 1024.0f) + 1e-6f);
;     __device__ __forceinline__ void operator()(const f32x4 (&acc)[2][2][4][2], const Unit& u, int wr, int wc, int fr, int fq) const {
;         const int row0 = u.pm * 256 + wr * 64 + fr, col0 = u.pn * 256 + wc * 32 + 8 * fq;
; #pragma unroll
;         for (int ai = 0; ai < 2; ++ai)
; #pragma unroll
;             for (int m = 0; m < 4; ++m) {
;                 const int row = row0 + ai * 128 + m * 16; const float rs = row_rstd(ssq, row);
;                 bf16_t* rowp = O + (size_t)row * ldc + col0;
; #pragma unroll
;                 for (int bj = 0; bj < 2; ++bj) { f32x4 v0 = acc[ai][bj][m][0] * rs, v1 = acc[ai][bj][m][1] * rs;
;                     if (ACT == 1) {
; #pragma unroll
;                         for (int j = 0; j < 4; ++j) { const float a = fmaxf(v0[j], 0.f), b = fmaxf(v1[j], 0.f); v0[j] = a * a; v1[j] = b * b; } }
;                     *(u32x4*)(rowp + bj * 128) = pack8(v0, v1); }
	v_mov_b32_e32 v116, v221
	v_mov_b32_e32 v117, v222
	v_mov_b32_e32 v97, v223
	v_mov_b32_e32 v98, v233
	v_mov_b32_e32 v99, v234
	v_mov_b32_e32 v101, v235
	v_mov_b32_e32 v96, v220
	v_pk_add_f32 v[96:97], v[116:117], v[96:97]
	v_mov_b32_e32 v100, v232
	v_pk_add_f32 v[98:99], v[98:99], v[100:101]
	v_pk_add_f32 v[96:97], v[96:97], v[96:97] op_sel:[0,1] op_sel_hi:[1,0]
	v_pk_add_f32 v[98:99], v[98:99], v[98:99] op_sel:[0,1] op_sel_hi:[1,0]
	v_add_f32_e32 v102, v236, v237
	v_add_f32_e32 v104, v238, v239
	v_mov_b32_e32 v103, v242
	v_mov_b32_e32 v105, v243
	v_mov_b32_e32 v97, v240
	v_mov_b32_e32 v99, v241
	v_pk_add_f32 v[100:101], v[102:103], v[104:105]
	v_pk_add_f32 v[96:97], v[96:97], v[98:99]
	v_lshlrev_b64 v[98:99], 6, v[112:113]
	v_pk_add_f32 v[96:97], v[96:97], v[100:101]
	v_lshl_add_u64 v[98:99], s[16:17], 0, v[98:99]
	v_add_f32_e32 v96, v96, v97
	v_fmamk_f32 v96, v96, 0x3a800000, v158
	v_mul_f32_e32 v97, 0x4b800000, v96
	v_cmp_gt_f32_e32 vcc, s61, v96
	s_nop 1
	v_cndmask_b32_e32 v96, v96, v97, vcc
	v_rsq_f32_e32 v100, v96
	v_lshl_add_u64 v[96:97], v[114:115], 0, v[148:149]
	v_mul_f32_e32 v101, 0x45800000, v100
	v_cndmask_b32_e32 v100, v100, v101, vcc
	v_pk_mul_f32 v[94:95], v[94:95], v[100:101] op_sel_hi:[1,0]
	v_pk_mul_f32 v[92:93], v[92:93], v[100:101] op_sel_hi:[1,0]
	v_pk_mul_f32 v[90:91], v[90:91], v[100:101] op_sel_hi:[1,0]
	v_pk_mul_f32 v[88:89], v[88:89], v[100:101] op_sel_hi:[1,0]
	v_pk_mul_f32 v[86:87], v[86:87], v[100:101] op_sel_hi:[1,0]
	v_pk_mul_f32 v[84:85], v[84:85], v[100:101] op_sel_hi:[1,0]
	v_pk_mul_f32 v[102:103], v[82:83], v[100:101] op_sel_hi:[1,0]
	v_pk_mul_f32 v[100:101], v[80:81], v[100:101] op_sel_hi:[1,0]
	v_cvt_pk_bf16_f32 v80, v92, v93
	v_cvt_pk_bf16_f32 v81, v94, v95
	v_cvt_pk_bf16_f32 v82, v88, v89
	v_cvt_pk_bf16_f32 v83, v90, v91
	global_store_dwordx4 v[96:97], v[80:83], off
	s_nop 1
	v_cvt_pk_bf16_f32 v80, v84, v85
	v_cvt_pk_bf16_f32 v81, v86, v87
	v_cvt_pk_bf16_f32 v82, v100, v101
	v_cvt_pk_bf16_f32 v83, v102, v103
	global_store_dwordx4 v[96:97], v[80:83], off offset:256
	s_nop 0
	v_add_u32_e32 v96, 0x80, v150
	v_mad_i64_i32 v[98:99], s[6:7], v112, s62, v[146:147]
	v_ashrrev_i32_e32 v97, 31, v96
	v_add_u32_e32 v187, 0x2400, v186
	global_load_dwordx4 v[220:223], v187, s[16:17]
	v_add_u32_e32 v187, 0x2410, v186
	global_load_dwordx4 v[232:235], v187, s[16:17]
	v_add_u32_e32 v187, 0x2420, v186
	global_load_dwordx4 v[236:239], v187, s[16:17]
	v_add_u32_e32 v187, 0x2430, v186
	global_load_dwordx4 v[240:243], v187, s[16:17]
	s_waitcnt vmcnt(12)
	v_mov_b32_e32 v100, v189
	v_mov_b32_e32 v101, v190
	v_mov_b32_e32 v81, v191
	v_mov_b32_e32 v82, v193
	v_mov_b32_e32 v83, v194
	v_mov_b32_e32 v85, v195
	v_mov_b32_e32 v80, v188
	v_pk_add_f32 v[80:81], v[100:101], v[80:81]
	v_mov_b32_e32 v84, v192
	v_pk_add_f32 v[82:83], v[82:83], v[84:85]
	v_pk_add_f32 v[80:81], v[80:81], v[80:81] op_sel:[0,1] op_sel_hi:[1,0]
	v_pk_add_f32 v[82:83], v[82:83], v[82:83] op_sel:[0,1] op_sel_hi:[1,0]
	v_add_f32_e32 v86, v196, v197
	v_add_f32_e32 v88, v198, v199
	v_mov_b32_e32 v87, v202
	v_mov_b32_e32 v89, v203
	v_mov_b32_e32 v81, v200
	v_mov_b32_e32 v83, v201
	v_pk_add_f32 v[84:85], v[86:87], v[88:89]
	v_pk_add_f32 v[80:81], v[80:81], v[82:83]
	v_lshlrev_b64 v[82:83], 6, v[96:97]
	v_pk_add_f32 v[80:81], v[80:81], v[84:85]
	v_lshl_add_u64 v[82:83], s[16:17], 0, v[82:83]
	v_add_f32_e32 v80, v80, v81
	v_fmamk_f32 v80, v80, 0x3a800000, v158
	v_mul_f32_e32 v81, 0x4b800000, v80
	v_cmp_gt_f32_e32 vcc, s61, v80
	s_nop 1
	v_cndmask_b32_e32 v80, v80, v81, vcc
	v_rsq_f32_e32 v84, v80
	v_lshl_add_u64 v[80:81], v[98:99], 0, v[148:149]
	v_mul_f32_e32 v85, 0x45800000, v84
	v_cndmask_b32_e32 v84, v84, v85, vcc
	v_pk_mul_f32 v[78:79], v[78:79], v[84:85] op_sel_hi:[1,0]
	v_pk_mul_f32 v[76:77], v[76:77], v[84:85] op_sel_hi:[1,0]
	v_pk_mul_f32 v[74:75], v[74:75], v[84:85] op_sel_hi:[1,0]
	v_pk_mul_f32 v[72:73], v[72:73], v[84:85] op_sel_hi:[1,0]
	v_pk_mul_f32 v[70:71], v[70:71], v[84:85] op_sel_hi:[1,0]
	v_pk_mul_f32 v[68:69], v[68:69], v[84:85] op_sel_hi:[1,0]
	v_pk_mul_f32 v[86:87], v[66:67], v[84:85] op_sel_hi:[1,0]
	v_pk_mul_f32 v[84:85], v[64:65], v[84:85] op_sel_hi:[1,0]
	v_cvt_pk_bf16_f32 v64, v76, v77
	v_cvt_pk_bf16_f32 v65, v78, v79
	v_cvt_pk_bf16_f32 v66, v72, v73
	v_cvt_pk_bf16_f32 v67, v74, v75
	global_store_dwordx4 v[80:81], v[64:67], off
	s_nop 1
	v_cvt_pk_bf16_f32 v64, v68, v69
	v_cvt_pk_bf16_f32 v65, v70, v71
	v_cvt_pk_bf16_f32 v66, v84, v85
	v_cvt_pk_bf16_f32 v67, v86, v87
	global_store_dwordx4 v[80:81], v[64:67], off offset:256
	s_nop 0
	v_add_u32_e32 v80, 0x90, v150
	v_mad_i64_i32 v[82:83], s[6:7], v96, s62, v[146:147]
	v_ashrrev_i32_e32 v81, 31, v80
	v_add_u32_e32 v187, 0x2800, v186
	global_load_dwordx4 v[188:191], v187, s[16:17]
	v_add_u32_e32 v187, 0x2810, v186
	global_load_dwordx4 v[192:195], v187, s[16:17]
	v_add_u32_e32 v187, 0x2820, v186
	global_load_dwordx4 v[196:199], v187, s[16:17]
	v_add_u32_e32 v187, 0x2830, v186
	global_load_dwordx4 v[200:203], v187, s[16:17]
	s_waitcnt vmcnt(12)
; __device__ __forceinline__ u32x4 pack8(const f32x4 v0, const f32x4 v1) { u32x4 w; w.x = pk2(v0[0], v0[1]); w.y = pk2(v0[2], v0[3]); w.z = pk2(v1[0], v1[1]); w.w = pk2(v1[2], v1[3]); return w; }
; __device__ __forceinline__ float row_rstd(const float* ssq, int row) {
;     const f32x4* p = (const f32x4*)(ssq + (size_t)row * 16);
;     const f32x4 a = p[0], b = p[1], c = p[2], d = p[3];
;     const float s = ((a[0] + a[1]) + (a[2] + a[3])) + ((b[0] + b[1]) + (b[2] + b[3])) + ((c[0] + c[1]) + (c[2] + c[3])) + ((d[0] + d[1]) + (d[2] + d[3]));
;     return rsqrtf(s * (1.0f / 1024.0f) + 1e-6f);
;     __device__ __forceinline__ void operator()(const f32x4 (&acc)[2][2][4][2], const Unit& u, int wr, int wc, int fr, int fq) const {
;         const int row0 = u.pm * 256 + wr * 64 + fr, col0 = u.pn * 256 + wc * 32 + 8 * fq;
; #pragma unroll
;         for (int ai = 0; ai < 2; ++ai)
; #pragma unroll
;             for (int m = 0; m < 4; ++m) {
;                 const int row = row0 + ai * 128 + m * 16; const float rs = row_rstd(ssq, row);
;                 bf16_t* rowp = O + (size_t)row * ldc + col0;
; #pragma unroll
;                 for (int bj = 0; bj < 2; ++bj) { f32x4 v0 = acc[ai][bj][m][0] * rs, v1 = acc[ai][bj][m][1] * rs;
;                     if (ACT == 1) {
; #pragma unroll
;                         for (int j = 0; j < 4; ++j) { const float a = fmaxf(v0[j], 0.f), b = fmaxf(v1[j], 0.f); v0[j] = a * a; v1[j] = b * b; } }
;                     *(u32x4*)(rowp + bj * 128) = pack8(v0, v1); }
	v_mov_b32_e32 v84, v205
	v_mov_b32_e32 v85, v206
	v_mov_b32_e32 v65, v207
	v_mov_b32_e32 v66, v209
	v_mov_b32_e32 v67, v210
	v_mov_b32_e32 v69, v211
	v_mov_b32_e32 v64, v204
	v_pk_add_f32 v[64:65], v[84:85], v[64:65]
	v_mov_b32_e32 v68, v208
	v_pk_add_f32 v[66:67], v[66:67], v[68:69]
	v_pk_add_f32 v[64:65], v[64:65], v[64:65] op_sel:[0,1] op_sel_hi:[1,0]
	v_pk_add_f32 v[66:67], v[66:67], v[66:67] op_sel:[0,1] op_sel_hi:[1,0]
	v_add_f32_e32 v70, v212, v213
	v_add_f32_e32 v72, v214, v215
	v_mov_b32_e32 v71, v218
	v_mov_b32_e32 v73, v219
	v_mov_b32_e32 v65, v216
	v_mov_b32_e32 v67, v217
	v_pk_add_f32 v[68:69], v[70:71], v[72:73]
	v_pk_add_f32 v[64:65], v[64:65], v[66:67]
	v_lshlrev_b64 v[66:67], 6, v[80:81]
	v_pk_add_f32 v[64:65], v[64:65], v[68:69]
	v_lshl_add_u64 v[66:67], s[16:17], 0, v[66:67]
	v_add_f32_e32 v64, v64, v65
	v_fmamk_f32 v64, v64, 0x3a800000, v158
	v_mul_f32_e32 v65, 0x4b800000, v64
	v_cmp_gt_f32_e32 vcc, s61, v64
	s_nop 1
	v_cndmask_b32_e32 v64, v64, v65, vcc
	v_rsq_f32_e32 v68, v64
	v_lshl_add_u64 v[64:65], v[82:83], 0, v[148:149]
	v_mul_f32_e32 v69, 0x45800000, v68
	v_cndmask_b32_e32 v68, v68, v69, vcc
	v_pk_mul_f32 v[62:63], v[62:63], v[68:69] op_sel_hi:[1,0]
	v_pk_mul_f32 v[60:61], v[60:61], v[68:69] op_sel_hi:[1,0]
	v_pk_mul_f32 v[58:59], v[58:59], v[68:69] op_sel_hi:[1,0]
	v_pk_mul_f32 v[56:57], v[56:57], v[68:69] op_sel_hi:[1,0]
	v_pk_mul_f32 v[54:55], v[54:55], v[68:69] op_sel_hi:[1,0]
	v_pk_mul_f32 v[52:53], v[52:53], v[68:69] op_sel_hi:[1,0]
	v_pk_mul_f32 v[70:71], v[50:51], v[68:69] op_sel_hi:[1,0]
	v_pk_mul_f32 v[68:69], v[48:49], v[68:69] op_sel_hi:[1,0]
	v_cvt_pk_bf16_f32 v48, v60, v61
	v_cvt_pk_bf16_f32 v49, v62, v63
	v_cvt_pk_bf16_f32 v50, v56, v57
	v_cvt_pk_bf16_f32 v51, v58, v59
	global_store_dwordx4 v[64:65], v[48:51], off
	s_nop 1
	v_cvt_pk_bf16_f32 v48, v52, v53
	v_cvt_pk_bf16_f32 v49, v54, v55
	v_cvt_pk_bf16_f32 v50, v68, v69
	v_cvt_pk_bf16_f32 v51, v70, v71
	global_store_dwordx4 v[64:65], v[48:51], off offset:256
	s_nop 0
	v_add_u32_e32 v64, 0xa0, v150
	v_mad_i64_i32 v[66:67], s[6:7], v80, s62, v[146:147]
	v_ashrrev_i32_e32 v65, 31, v64
	v_add_u32_e32 v187, 0x2c00, v186
	global_load_dwordx4 v[204:207], v187, s[16:17]
	v_add_u32_e32 v187, 0x2c10, v186
	global_load_dwordx4 v[208:211], v187, s[16:17]
	v_add_u32_e32 v187, 0x2c20, v186
	global_load_dwordx4 v[212:215], v187, s[16:17]
	v_add_u32_e32 v187, 0x2c30, v186
	global_load_dwordx4 v[216:219], v187, s[16:17]
	s_waitcnt vmcnt(12)
	v_mov_b32_e32 v68, v221
	v_mov_b32_e32 v69, v222
	v_mov_b32_e32 v49, v223
	v_mov_b32_e32 v50, v233
	v_mov_b32_e32 v51, v234
	v_mov_b32_e32 v53, v235
	v_mov_b32_e32 v48, v220
	v_pk_add_f32 v[48:49], v[68:69], v[48:49]
	v_mov_b32_e32 v52, v232
	v_pk_add_f32 v[50:51], v[50:51], v[52:53]
	v_pk_add_f32 v[48:49], v[48:49], v[48:49] op_sel:[0,1] op_sel_hi:[1,0]
	v_pk_add_f32 v[50:51], v[50:51], v[50:51] op_sel:[0,1] op_sel_hi:[1,0]
	v_add_f32_e32 v54, v236, v237
	v_add_f32_e32 v56, v238, v239
	v_mov_b32_e32 v55, v242
	v_mov_b32_e32 v57, v243
	v_mov_b32_e32 v49, v240
	v_mov_b32_e32 v51, v241
	v_pk_add_f32 v[52:53], v[54:55], v[56:57]
	v_pk_add_f32 v[48:49], v[48:49], v[50:51]
	v_lshlrev_b64 v[50:51], 6, v[64:65]
	v_pk_add_f32 v[48:49], v[48:49], v[52:53]
	v_lshl_add_u64 v[50:51], s[16:17], 0, v[50:51]
	v_add_f32_e32 v48, v48, v49
	v_fmamk_f32 v48, v48, 0x3a800000, v158
	v_mul_f32_e32 v49, 0x4b800000, v48
	v_cmp_gt_f32_e32 vcc, s61, v48
	s_nop 1
	v_cndmask_b32_e32 v48, v48, v49, vcc
	v_rsq_f32_e32 v52, v48
	v_lshl_add_u64 v[48:49], v[66:67], 0, v[148:149]
	v_mul_f32_e32 v53, 0x45800000, v52
	v_cndmask_b32_e32 v52, v52, v53, vcc
	v_pk_mul_f32 v[46:47], v[46:47], v[52:53] op_sel_hi:[1,0]
	v_pk_mul_f32 v[44:45], v[44:45], v[52:53] op_sel_hi:[1,0]
	v_pk_mul_f32 v[42:43], v[42:43], v[52:53] op_sel_hi:[1,0]
	v_pk_mul_f32 v[40:41], v[40:41], v[52:53] op_sel_hi:[1,0]
	v_pk_mul_f32 v[38:39], v[38:39], v[52:53] op_sel_hi:[1,0]
	v_pk_mul_f32 v[36:37], v[36:37], v[52:53] op_sel_hi:[1,0]
	v_pk_mul_f32 v[54:55], v[34:35], v[52:53] op_sel_hi:[1,0]
	v_pk_mul_f32 v[52:53], v[32:33], v[52:53] op_sel_hi:[1,0]
	v_cvt_pk_bf16_f32 v32, v44, v45
	v_cvt_pk_bf16_f32 v33, v46, v47
	v_cvt_pk_bf16_f32 v34, v40, v41
	v_cvt_pk_bf16_f32 v35, v42, v43
	global_store_dwordx4 v[48:49], v[32:35], off
	s_nop 1
	v_cvt_pk_bf16_f32 v32, v36, v37
	v_cvt_pk_bf16_f32 v33, v38, v39
	v_cvt_pk_bf16_f32 v34, v52, v53
	v_cvt_pk_bf16_f32 v35, v54, v55
	global_store_dwordx4 v[48:49], v[32:35], off offset:256
	s_nop 0
	v_add_u32_e32 v48, 0xb0, v150
	v_mad_i64_i32 v[50:51], s[6:7], v64, s62, v[146:147]
	v_ashrrev_i32_e32 v49, 31, v48
	s_mov_b32 s6, s20
	s_waitcnt vmcnt(8)
; __device__ __forceinline__ u32x4 pack8(const f32x4 v0, const f32x4 v1) { u32x4 w; w.x = pk2(v0[0], v0[1]); w.y = pk2(v0[2], v0[3]); w.z = pk2(v1[0], v1[1]); w.w = pk2(v1[2], v1[3]); return w; }
; __device__ __forceinline__ float row_rstd(const float* ssq, int row) {
;     const f32x4* p = (const f32x4*)(ssq + (size_t)row * 16);
;     const f32x4 a = p[0], b = p[1], c = p[2], d = p[3];
;     const float s = ((a[0] + a[1]) + (a[2] + a[3])) + ((b[0] + b[1]) + (b[2] + b[3])) + ((c[0] + c[1]) + (c[2] + c[3])) + ((d[0] + d[1]) + (d[2] + d[3]));
;     return rsqrtf(s * (1.0f / 1024.0f) + 1e-6f);
;     __device__ __forceinline__ void operator()(const f32x4 (&acc)[2][2][4][2], const Unit& u, int wr, int wc, int fr, int fq) const {
;         const int row0 = u.pm * 256 + wr * 64 + fr, col0 = u.pn * 256 + wc * 32 + 8 * fq;
; #pragma unroll
;         for (int ai = 0; ai < 2; ++ai)
; #pragma unroll
;             for (int m = 0; m < 4; ++m) {
;                 const int row = row0 + ai * 128 + m * 16; const float rs = row_rstd(ssq, row);
;                 bf16_t* rowp = O + (size_t)row * ldc + col0;
; #pragma unroll
;                 for (int bj = 0; bj < 2; ++bj) { f32x4 v0 = acc[ai][bj][m][0] * rs, v1 = acc[ai][bj][m][1] * rs;
;                     if (ACT == 1) {
; #pragma unroll
;                         for (int j = 0; j < 4; ++j) { const float a = fmaxf(v0[j], 0.f), b = fmaxf(v1[j], 0.f); v0[j] = a * a; v1[j] = b * b; } }
;                     *(u32x4*)(rowp + bj * 128) = pack8(v0, v1); }
	v_mov_b32_e32 v52, v189
	v_mov_b32_e32 v53, v190
	v_mov_b32_e32 v33, v191
	v_mov_b32_e32 v34, v193
	v_mov_b32_e32 v35, v194
	v_mov_b32_e32 v37, v195
	v_mov_b32_e32 v32, v188
	v_pk_add_f32 v[32:33], v[52:53], v[32:33]
	v_mov_b32_e32 v36, v192
	v_pk_add_f32 v[34:35], v[34:35], v[36:37]
	v_pk_add_f32 v[32:33], v[32:33], v[32:33] op_sel:[0,1] op_sel_hi:[1,0]
	v_pk_add_f32 v[34:35], v[34:35], v[34:35] op_sel:[0,1] op_sel_hi:[1,0]
	v_add_f32_e32 v38, v196, v197
	v_add_f32_e32 v40, v198, v199
	v_mov_b32_e32 v39, v202
	v_mov_b32_e32 v41, v203
	v_mov_b32_e32 v33, v200
	v_mov_b32_e32 v35, v201
	v_pk_add_f32 v[36:37], v[38:39], v[40:41]
	v_pk_add_f32 v[32:33], v[32:33], v[34:35]
	v_lshlrev_b64 v[34:35], 6, v[48:49]
	v_pk_add_f32 v[32:33], v[32:33], v[36:37]
	v_lshl_add_u64 v[34:35], s[16:17], 0, v[34:35]
	v_add_f32_e32 v32, v32, v33
	v_fmamk_f32 v32, v32, 0x3a800000, v158
	v_mul_f32_e32 v33, 0x4b800000, v32
	v_cmp_gt_f32_e32 vcc, s61, v32
	s_nop 1
	v_cndmask_b32_e32 v32, v32, v33, vcc
	v_rsq_f32_e32 v36, v32
	v_lshl_add_u64 v[32:33], v[50:51], 0, v[148:149]
	v_mul_f32_e32 v37, 0x45800000, v36
	v_cndmask_b32_e32 v36, v36, v37, vcc
	v_pk_mul_f32 v[30:31], v[30:31], v[36:37] op_sel_hi:[1,0]
	v_pk_mul_f32 v[28:29], v[28:29], v[36:37] op_sel_hi:[1,0]
	v_pk_mul_f32 v[26:27], v[26:27], v[36:37] op_sel_hi:[1,0]
	v_pk_mul_f32 v[24:25], v[24:25], v[36:37] op_sel_hi:[1,0]
	v_pk_mul_f32 v[22:23], v[22:23], v[36:37] op_sel_hi:[1,0]
	v_pk_mul_f32 v[20:21], v[20:21], v[36:37] op_sel_hi:[1,0]
	v_pk_mul_f32 v[38:39], v[18:19], v[36:37] op_sel_hi:[1,0]
	v_pk_mul_f32 v[36:37], v[16:17], v[36:37] op_sel_hi:[1,0]
	v_cvt_pk_bf16_f32 v16, v28, v29
	v_cvt_pk_bf16_f32 v17, v30, v31
	v_cvt_pk_bf16_f32 v18, v24, v25
	v_cvt_pk_bf16_f32 v19, v26, v27
	global_store_dwordx4 v[32:33], v[16:19], off
	s_and_b64 vcc, exec, s[8:9]
	s_nop 0
	v_cvt_pk_bf16_f32 v16, v20, v21
	v_cvt_pk_bf16_f32 v17, v22, v23
	v_cvt_pk_bf16_f32 v18, v36, v37
	v_cvt_pk_bf16_f32 v19, v38, v39
	global_store_dwordx4 v[32:33], v[16:19], off offset:256
	s_nop 0
	s_waitcnt vmcnt(4)
	v_mov_b32_e32 v32, v205
	v_mov_b32_e32 v33, v206
	v_mov_b32_e32 v17, v207
	v_mov_b32_e32 v18, v209
	v_mov_b32_e32 v19, v210
	v_mov_b32_e32 v21, v211
	v_mov_b32_e32 v16, v204
	v_pk_add_f32 v[16:17], v[32:33], v[16:17]
	v_mov_b32_e32 v20, v208
	v_pk_add_f32 v[18:19], v[18:19], v[20:21]
	v_pk_add_f32 v[16:17], v[16:17], v[16:17] op_sel:[0,1] op_sel_hi:[1,0]
	v_pk_add_f32 v[18:19], v[18:19], v[18:19] op_sel:[0,1] op_sel_hi:[1,0]
	v_add_f32_e32 v22, v212, v213
	v_add_f32_e32 v24, v214, v215
	v_mov_b32_e32 v23, v218
	v_mov_b32_e32 v25, v219
	v_mov_b32_e32 v17, v216
	v_mov_b32_e32 v19, v217
	v_pk_add_f32 v[20:21], v[22:23], v[24:25]
	v_pk_add_f32 v[16:17], v[16:17], v[18:19]
	s_nop 0
	v_pk_add_f32 v[16:17], v[16:17], v[20:21]
	s_nop 0
	v_add_f32_e32 v16, v16, v17
	v_fmamk_f32 v16, v16, 0x3a800000, v158
	v_mul_f32_e32 v17, 0x4b800000, v16
	v_cmp_gt_f32_e64 s[8:9], s61, v16
	s_nop 1
	v_cndmask_b32_e64 v16, v16, v17, s[8:9]
	v_rsq_f32_e32 v18, v16
	v_mad_i64_i32 v[16:17], s[24:25], v48, s62, v[146:147]
	v_lshl_add_u64 v[16:17], v[16:17], 0, v[148:149]
	v_mul_f32_e32 v19, 0x45800000, v18
	v_cndmask_b32_e64 v18, v18, v19, s[8:9]
	v_pk_mul_f32 v[14:15], v[14:15], v[18:19] op_sel_hi:[1,0]
	v_pk_mul_f32 v[12:13], v[12:13], v[18:19] op_sel_hi:[1,0]
	v_pk_mul_f32 v[10:11], v[10:11], v[18:19] op_sel_hi:[1,0]
	v_pk_mul_f32 v[8:9], v[8:9], v[18:19] op_sel_hi:[1,0]
	v_pk_mul_f32 v[6:7], v[6:7], v[18:19] op_sel_hi:[1,0]
	v_pk_mul_f32 v[4:5], v[4:5], v[18:19] op_sel_hi:[1,0]
	v_pk_mul_f32 v[20:21], v[2:3], v[18:19] op_sel_hi:[1,0]
	v_pk_mul_f32 v[18:19], v[0:1], v[18:19] op_sel_hi:[1,0]
	v_cvt_pk_bf16_f32 v0, v12, v13
	v_cvt_pk_bf16_f32 v1, v14, v15
	v_cvt_pk_bf16_f32 v2, v8, v9
	v_cvt_pk_bf16_f32 v3, v10, v11
	global_store_dwordx4 v[16:17], v[0:3], off
	s_nop 1
	v_cvt_pk_bf16_f32 v0, v4, v5
	v_cvt_pk_bf16_f32 v1, v6, v7
	v_cvt_pk_bf16_f32 v2, v18, v19
	v_cvt_pk_bf16_f32 v3, v20, v21
	global_store_dwordx4 v[16:17], v[0:3], off offset:256
	s_cbranch_vccz .LBB0_118
	s_waitcnt vmcnt(0)
	s_cmpk_gt_u32 s40, 0xff
	s_cbranch_scc1 .LBB0_129
	s_barrier

; #define PG8_STAGE(bufoff, gbase, voff) do { _Pragma("unroll") for (int _i = 0; _i < 2; ++_i) \
;         __builtin_amdgcn_global_load_lds((const unsigned*)((const char*)(gbase) + (voff)[_i]), (LAS unsigned*)(lds + (bufoff) + ldsw + _i * 8192), 16, 0, 0); } while (0)
; #define PG8_LDA(dst, b, h) do { _Pragma("unroll") for (int m = 0; m < 4; ++m) _Pragma("unroll") for (int k = 0; k < 2; ++k) dst[m][k] = *(const LAS bf16x8*)(lds + PG8_SA(b, h) + aoff + m * 2048 + k * 1024); } while (0)
; #define PG8_LDB(dst, b, h) do { _Pragma("unroll") for (int n = 0; n < 2; ++n) _Pragma("unroll") for (int k = 0; k < 2; ++k) dst[n][k] = *(const LAS bf16x8*)(lds + PG8_SB(b, h) + boff + n * 2048 + k * 1024); } while (0)
; #define PG8_MMA(ai, bj, At, Bt) do { __builtin_amdgcn_s_setprio(1); _Pragma("unroll") for (int m = 0; m < 4; ++m) _Pragma("unroll") for (int n = 0; n < 2; ++n) _Pragma("unroll") for (int k = 0; k < 2; ++k) \
;         acc[ai][bj][m][n] = __builtin_amdgcn_mfma_f32_16x16x32_bf16(Bt[n][k], At[m][k], acc[ai][bj][m][n], 0, 0, 0); __builtin_amdgcn_s_setprio(0); } while (0)
; #define PG8_WAIT_L(n) asm volatile("s_waitcnt lgkmcnt(" #n ")" ::: "memory")
; #define PG8_BAR __builtin_amdgcn_s_barrier()
; #define PG8_SCHED __builtin_amdgcn_sched_barrier(0)
;     ...
;         for (int t = 0; t < nt; t += 2) {
;             const bool last = (t == nt - 2);
;             const char* a1 = cA + (size_t)(t + 1) * kstep;
;             const char* a2 = last ? nA : cA + (size_t)(t + 2) * kstep; const char* b2 = last ? nB : cB + (size_t)(t + 2) * kstep;
;             const char* a3 = a2 + kstep; const char* b3 = b2 + kstep;
;             if (last && has_next) PG8_A_READY(nxt);
;             PG8_LDB(B0, 0, 0); PG8_SCHED; PG8_LDA(At, 0, 0); PG8_STAGE(PG8_SA(1, 1), a1 + hA, voffA);
;             PG8_WAIT_L(8); PG8_BAR; PG8_WAIT_L(0); PG8_MMA(0, 0, At, B0); PG8_BAR; PG8_SCHED;
;             PG8_LDB(B1, 0, 1); PG8_STAGE(PG8_SB(0, 0), b2, voffB);
;             PG8_BAR; PG8_WAIT_L(0); PG8_MMA(0, 1, At, B1); PG8_BAR;
;             PG8_LDA(At, 0, 1); PG8_STAGE(PG8_SA(0, 0), a2, voffA);
;             PG8_BAR; PG8_WAIT_L(0); PG8_MMA(1, 0, At, B0); PG8_BAR; PG8_SCHED;
.LBB0_958:
	ds_read_b128 v[156:159], v151
	ds_read_b128 v[160:163], v151 offset:1024
	ds_read_b128 v[170:173], v151 offset:2048
	ds_read_b128 v[174:177], v151 offset:3072
	s_add_u32 s43, s40, 0xfffc0080
	s_addc_u32 s44, s41, -1
	s_cmp_eq_u32 s42, 12
	s_cselect_b32 s57, s7, s44
	s_cselect_b32 s56, s8, s43
	s_cselect_b32 s55, s9, s39
	s_cselect_b32 s54, s29, s33
	v_lshl_add_u64 v[146:147], s[40:41], 0, v[138:139]
	s_add_i32 m0, s61, 0xc000
	ds_read_b128 v[178:181], v152
	ds_read_b128 v[182:185], v152 offset:1024
	ds_read_b128 v[186:189], v152 offset:2048
	ds_read_b128 v[190:193], v152 offset:3072
	ds_read_b128 v[194:197], v152 offset:4096
	ds_read_b128 v[198:201], v152 offset:5120
	ds_read_b128 v[202:205], v152 offset:6144
	ds_read_b128 v[206:209], v152 offset:7168
	global_load_lds_dwordx4 v[146:147], off
	v_lshl_add_u64 v[146:147], s[40:41], 0, v[136:137]
	s_add_i32 m0, s61, 0xe000
	s_nop 0
	global_load_lds_dwordx4 v[146:147], off
	s_waitcnt lgkmcnt(8)
	s_barrier
	s_waitcnt lgkmcnt(0)
	s_setprio 1
	s_waitcnt lgkmcnt(0)
	v_mfma_f32_16x16x32_bf16 v[124:127], v[156:159], v[178:181], v[124:127]
	v_mfma_f32_16x16x32_bf16 v[120:123], v[170:173], v[178:181], v[120:123]
	v_mfma_f32_16x16x32_bf16 v[108:111], v[156:159], v[186:189], v[108:111]
	v_mfma_f32_16x16x32_bf16 v[104:107], v[170:173], v[186:189], v[104:107]
	v_mfma_f32_16x16x32_bf16 v[92:95], v[156:159], v[194:197], v[92:95]
	v_mfma_f32_16x16x32_bf16 v[88:91], v[170:173], v[194:197], v[88:91]
	v_mfma_f32_16x16x32_bf16 v[76:79], v[156:159], v[202:205], v[76:79]
	v_mfma_f32_16x16x32_bf16 v[72:75], v[170:173], v[202:205], v[72:75]
	v_mfma_f32_16x16x32_bf16 v[124:127], v[160:163], v[182:185], v[124:127]
	v_mfma_f32_16x16x32_bf16 v[120:123], v[174:177], v[182:185], v[120:123]
	v_mfma_f32_16x16x32_bf16 v[108:111], v[160:163], v[190:193], v[108:111]
	v_mfma_f32_16x16x32_bf16 v[104:107], v[174:177], v[190:193], v[104:107]
	v_mfma_f32_16x16x32_bf16 v[92:95], v[160:163], v[198:201], v[92:95]
	v_mfma_f32_16x16x32_bf16 v[88:91], v[174:177], v[198:201], v[88:91]
	v_mfma_f32_16x16x32_bf16 v[76:79], v[160:163], v[206:209], v[76:79]
	v_mfma_f32_16x16x32_bf16 v[72:75], v[174:177], v[206:209], v[72:75]
	s_setprio 0
	s_barrier
	s_add_i32 s43, s69, s60
	v_lshl_add_u64 v[146:147], s[54:55], 0, v[130:131]
	s_mov_b32 m0, s43
	ds_read_b128 v[210:213], v153
	ds_read_b128 v[214:217], v153 offset:1024
	ds_read_b128 v[218:221], v153 offset:2048
	ds_read_b128 v[222:225], v153 offset:3072
	global_load_lds_dwordx4 v[146:147], off
	v_lshl_add_u64 v[164:165], s[54:55], 0, v[134:135]
	s_add_i32 m0, s43, 0x2000
	s_nop 0
	global_load_lds_dwordx4 v[164:165], off
	s_barrier
	s_waitcnt lgkmcnt(0)
	s_setprio 1
	s_waitcnt lgkmcnt(0)
	v_mfma_f32_16x16x32_bf16 v[116:119], v[210:213], v[178:181], v[116:119]
	v_mfma_f32_16x16x32_bf16 v[112:115], v[218:221], v[178:181], v[112:115]
	v_mfma_f32_16x16x32_bf16 v[100:103], v[210:213], v[186:189], v[100:103]
	v_mfma_f32_16x16x32_bf16 v[96:99], v[218:221], v[186:189], v[96:99]
	v_mfma_f32_16x16x32_bf16 v[84:87], v[210:213], v[194:197], v[84:87]
	v_mfma_f32_16x16x32_bf16 v[80:83], v[218:221], v[194:197], v[80:83]
	v_mfma_f32_16x16x32_bf16 v[68:71], v[210:213], v[202:205], v[68:71]
	v_mfma_f32_16x16x32_bf16 v[64:67], v[218:221], v[202:205], v[64:67]
	v_mfma_f32_16x16x32_bf16 v[116:119], v[214:217], v[182:185], v[116:119]
	v_mfma_f32_16x16x32_bf16 v[112:115], v[222:225], v[182:185], v[112:115]
	v_mfma_f32_16x16x32_bf16 v[100:103], v[214:217], v[190:193], v[100:103]
	v_mfma_f32_16x16x32_bf16 v[96:99], v[222:225], v[190:193], v[96:99]
	v_mfma_f32_16x16x32_bf16 v[84:87], v[214:217], v[198:201], v[84:87]
	v_mfma_f32_16x16x32_bf16 v[80:83], v[222:225], v[198:201], v[80:83]
	v_mfma_f32_16x16x32_bf16 v[68:71], v[214:217], v[206:209], v[68:71]
	v_mfma_f32_16x16x32_bf16 v[64:67], v[222:225], v[206:209], v[64:67]
	s_setprio 0
	s_mov_b32 m0, s61
	v_lshl_add_u64 v[226:227], s[56:57], 0, v[128:129]
	s_barrier
	ds_read_b128 v[178:181], v152 offset:16384
	ds_read_b128 v[182:185], v152 offset:17408
	ds_read_b128 v[186:189], v152 offset:18432
	ds_read_b128 v[190:193], v152 offset:19456
	ds_read_b128 v[194:197], v152 offset:20480
	ds_read_b128 v[198:201], v152 offset:21504
	ds_read_b128 v[202:205], v152 offset:22528
	ds_read_b128 v[206:209], v152 offset:23552
	global_load_lds_dwordx4 v[226:227], off
	v_lshl_add_u64 v[228:229], s[56:57], 0, v[132:133]
	s_mov_b32 m0, s62
	s_nop 0
	global_load_lds_dwordx4 v[228:229], off
	s_barrier
	s_waitcnt lgkmcnt(0)
	s_setprio 1
	s_waitcnt lgkmcnt(0)
	v_mfma_f32_16x16x32_bf16 v[60:63], v[156:159], v[178:181], v[60:63]
	v_mfma_f32_16x16x32_bf16 v[56:59], v[170:173], v[178:181], v[56:59]
	v_mfma_f32_16x16x32_bf16 v[44:47], v[156:159], v[186:189], v[44:47]
	v_mfma_f32_16x16x32_bf16 v[40:43], v[170:173], v[186:189], v[40:43]
	v_mfma_f32_16x16x32_bf16 v[28:31], v[156:159], v[194:197], v[28:31]
	v_mfma_f32_16x16x32_bf16 v[24:27], v[170:173], v[194:197], v[24:27]
	v_mfma_f32_16x16x32_bf16 v[12:15], v[156:159], v[202:205], v[12:15]
	v_mfma_f32_16x16x32_bf16 v[8:11], v[170:173], v[202:205], v[8:11]
	v_mfma_f32_16x16x32_bf16 v[60:63], v[160:163], v[182:185], v[60:63]
	v_mfma_f32_16x16x32_bf16 v[56:59], v[174:177], v[182:185], v[56:59]
	v_mfma_f32_16x16x32_bf16 v[44:47], v[160:163], v[190:193], v[44:47]
	v_mfma_f32_16x16x32_bf16 v[40:43], v[174:177], v[190:193], v[40:43]
	v_mfma_f32_16x16x32_bf16 v[28:31], v[160:163], v[198:201], v[28:31]
	v_mfma_f32_16x16x32_bf16 v[24:27], v[174:177], v[198:201], v[24:27]
	v_mfma_f32_16x16x32_bf16 v[12:15], v[160:163], v[206:209], v[12:15]
	v_mfma_f32_16x16x32_bf16 v[8:11], v[174:177], v[206:209], v[8:11]
	s_setprio 0
	s_barrier
; #define PG8_STAGE(bufoff, gbase, voff) do { _Pragma("unroll") for (int _i = 0; _i < 2; ++_i) \
;         __builtin_amdgcn_global_load_lds((const unsigned*)((const char*)(gbase) + (voff)[_i]), (LAS unsigned*)(lds + (bufoff) + ldsw + _i * 8192), 16, 0, 0); } while (0)
; #define PG8_LDA(dst, b, h) do { _Pragma("unroll") for (int m = 0; m < 4; ++m) _Pragma("unroll") for (int k = 0; k < 2; ++k) dst[m][k] = *(const LAS bf16x8*)(lds + PG8_SA(b, h) + aoff + m * 2048 + k * 1024); } while (0)
; #define PG8_LDB(dst, b, h) do { _Pragma("unroll") for (int n = 0; n < 2; ++n) _Pragma("unroll") for (int k = 0; k < 2; ++k) dst[n][k] = *(const LAS bf16x8*)(lds + PG8_SB(b, h) + boff + n * 2048 + k * 1024); } while (0)
; #define PG8_MMA(ai, bj, At, Bt) do { __builtin_amdgcn_s_setprio(1); _Pragma("unroll") for (int m = 0; m < 4; ++m) _Pragma("unroll") for (int n = 0; n < 2; ++n) _Pragma("unroll") for (int k = 0; k < 2; ++k) \
;         acc[ai][bj][m][n] = __builtin_amdgcn_mfma_f32_16x16x32_bf16(Bt[n][k], At[m][k], acc[ai][bj][m][n], 0, 0, 0); __builtin_amdgcn_s_setprio(0); } while (0)
; #define PG8_WAIT_V(n) asm volatile("s_waitcnt vmcnt(" #n ")" ::: "memory")
; #define PG8_WAIT_L(n) asm volatile("s_waitcnt lgkmcnt(" #n ")" ::: "memory")
; #define PG8_BAR __builtin_amdgcn_s_barrier()
; #define PG8_SCHED __builtin_amdgcn_sched_barrier(0)
;     ...
;             PG8_BAR; PG8_WAIT_L(0); PG8_MMA(1, 0, At, B0); PG8_BAR; PG8_SCHED;
;             PG8_STAGE(PG8_SB(0, 1), b2 + hB, voffB);
;             PG8_WAIT_V(6); PG8_BAR; PG8_MMA(1, 1, At, B1); PG8_BAR;
;             PG8_LDB(B0, 1, 0); PG8_SCHED; PG8_LDA(At, 1, 0); PG8_STAGE(PG8_SA(0, 1), a2 + hA, voffA);
;             PG8_WAIT_L(8); PG8_BAR; PG8_WAIT_L(0); PG8_MMA(0, 0, At, B0); PG8_BAR; PG8_SCHED;
;             PG8_LDB(B1, 1, 1); PG8_STAGE(PG8_SB(1, 0), b3, voffB);
;             PG8_BAR; PG8_WAIT_L(0); PG8_MMA(0, 1, At, B1); PG8_BAR;
;             PG8_LDA(At, 1, 1); PG8_STAGE(PG8_SA(1, 0), a3, voffA);
;             PG8_BAR; PG8_WAIT_L(0); PG8_MMA(1, 0, At, B0); PG8_BAR; PG8_SCHED;
	s_add_u32 s44, s54, 0x40000
	s_addc_u32 s45, s55, 0
	s_add_i32 s43, s70, s60
	v_lshl_add_u64 v[156:157], s[44:45], 0, v[130:131]
	s_mov_b32 m0, s43
	s_nop 0
	global_load_lds_dwordx4 v[156:157], off
	v_lshl_add_u64 v[156:157], s[44:45], 0, v[134:135]
	s_add_i32 m0, s43, 0x2000
	s_nop 0
	global_load_lds_dwordx4 v[156:157], off
	s_waitcnt vmcnt(6)
	s_barrier
	s_setprio 1
	v_mfma_f32_16x16x32_bf16 v[52:55], v[210:213], v[178:181], v[52:55]
	v_mfma_f32_16x16x32_bf16 v[48:51], v[218:221], v[178:181], v[48:51]
	v_mfma_f32_16x16x32_bf16 v[36:39], v[210:213], v[186:189], v[36:39]
	v_mfma_f32_16x16x32_bf16 v[32:35], v[218:221], v[186:189], v[32:35]
	v_mfma_f32_16x16x32_bf16 v[20:23], v[210:213], v[194:197], v[20:23]
	v_mfma_f32_16x16x32_bf16 v[16:19], v[218:221], v[194:197], v[16:19]
	v_mfma_f32_16x16x32_bf16 v[4:7], v[210:213], v[202:205], v[4:7]
	v_mfma_f32_16x16x32_bf16 v[0:3], v[218:221], v[202:205], v[0:3]
	v_mfma_f32_16x16x32_bf16 v[52:55], v[214:217], v[182:185], v[52:55]
	v_mfma_f32_16x16x32_bf16 v[48:51], v[222:225], v[182:185], v[48:51]
	v_mfma_f32_16x16x32_bf16 v[36:39], v[214:217], v[190:193], v[36:39]
	v_mfma_f32_16x16x32_bf16 v[32:35], v[222:225], v[190:193], v[32:35]
	v_mfma_f32_16x16x32_bf16 v[20:23], v[214:217], v[198:201], v[20:23]
	v_mfma_f32_16x16x32_bf16 v[16:19], v[222:225], v[198:201], v[16:19]
	v_mfma_f32_16x16x32_bf16 v[4:7], v[214:217], v[206:209], v[4:7]
	v_mfma_f32_16x16x32_bf16 v[0:3], v[222:225], v[206:209], v[0:3]
	s_setprio 0
	s_add_i32 s43, 0, 0x18000
	v_add_u32_e32 v155, s43, v149
	s_barrier
	ds_read_b128 v[156:159], v155
	ds_read_b128 v[160:163], v155 offset:1024
	ds_read_b128 v[170:173], v155 offset:2048
	ds_read_b128 v[174:177], v155 offset:3072
	s_add_u32 s44, s56, 0x40000
	s_addc_u32 s45, s57, 0
	s_mov_b32 m0, s63
	v_lshl_add_u64 v[210:211], s[44:45], 0, v[128:129]
	ds_read_b128 v[178:181], v152 offset:32768
	ds_read_b128 v[182:185], v152 offset:33792
	ds_read_b128 v[186:189], v152 offset:34816
	ds_read_b128 v[190:193], v152 offset:35840
	ds_read_b128 v[194:197], v152 offset:36864
	ds_read_b128 v[198:201], v152 offset:37888
	ds_read_b128 v[202:205], v152 offset:38912
	ds_read_b128 v[206:209], v152 offset:39936
	global_load_lds_dwordx4 v[210:211], off
	v_lshl_add_u64 v[210:211], s[44:45], 0, v[132:133]
	s_mov_b32 m0, s64
	s_nop 0
	global_load_lds_dwordx4 v[210:211], off
	s_waitcnt lgkmcnt(8)
	s_barrier
	s_waitcnt lgkmcnt(0)
	s_setprio 1
	s_waitcnt lgkmcnt(0)
	v_mfma_f32_16x16x32_bf16 v[124:127], v[156:159], v[178:181], v[124:127]
	v_mfma_f32_16x16x32_bf16 v[120:123], v[170:173], v[178:181], v[120:123]
	v_mfma_f32_16x16x32_bf16 v[108:111], v[156:159], v[186:189], v[108:111]
	v_mfma_f32_16x16x32_bf16 v[104:107], v[170:173], v[186:189], v[104:107]
	v_mfma_f32_16x16x32_bf16 v[92:95], v[156:159], v[194:197], v[92:95]
	v_mfma_f32_16x16x32_bf16 v[88:91], v[170:173], v[194:197], v[88:91]
	v_mfma_f32_16x16x32_bf16 v[76:79], v[156:159], v[202:205], v[76:79]
	v_mfma_f32_16x16x32_bf16 v[72:75], v[170:173], v[202:205], v[72:75]
	v_mfma_f32_16x16x32_bf16 v[124:127], v[160:163], v[182:185], v[124:127]
	v_mfma_f32_16x16x32_bf16 v[120:123], v[174:177], v[182:185], v[120:123]
	v_mfma_f32_16x16x32_bf16 v[108:111], v[160:163], v[190:193], v[108:111]
	v_mfma_f32_16x16x32_bf16 v[104:107], v[174:177], v[190:193], v[104:107]
	v_mfma_f32_16x16x32_bf16 v[92:95], v[160:163], v[198:201], v[92:95]
	v_mfma_f32_16x16x32_bf16 v[88:91], v[174:177], v[198:201], v[88:91]
	v_mfma_f32_16x16x32_bf16 v[76:79], v[160:163], v[206:209], v[76:79]
	v_mfma_f32_16x16x32_bf16 v[72:75], v[174:177], v[206:209], v[72:75]
	s_setprio 0
	s_barrier
	s_add_i32 s56, 0, 0x1c000
	s_add_i32 s43, s43, s60
	v_add_u32_e32 v155, s56, v149
	v_lshl_add_u64 v[146:147], v[146:147], 0, s[30:31]
	s_mov_b32 m0, s43
	ds_read_b128 v[210:213], v155
	ds_read_b128 v[214:217], v155 offset:1024
	ds_read_b128 v[218:221], v155 offset:2048
	ds_read_b128 v[222:225], v155 offset:3072
	global_load_lds_dwordx4 v[146:147], off
	v_lshl_add_u64 v[146:147], v[164:165], 0, s[30:31]
	s_add_i32 m0, s43, 0x2000
	s_nop 0
	global_load_lds_dwordx4 v[146:147], off
	s_barrier
	s_waitcnt lgkmcnt(0)
	s_setprio 1
	s_waitcnt lgkmcnt(0)
	v_mfma_f32_16x16x32_bf16 v[116:119], v[210:213], v[178:181], v[116:119]
	v_mfma_f32_16x16x32_bf16 v[112:115], v[218:221], v[178:181], v[112:115]
	v_mfma_f32_16x16x32_bf16 v[100:103], v[210:213], v[186:189], v[100:103]
	v_mfma_f32_16x16x32_bf16 v[96:99], v[218:221], v[186:189], v[96:99]
	v_mfma_f32_16x16x32_bf16 v[84:87], v[210:213], v[194:197], v[84:87]
	v_mfma_f32_16x16x32_bf16 v[80:83], v[218:221], v[194:197], v[80:83]
	v_mfma_f32_16x16x32_bf16 v[68:71], v[210:213], v[202:205], v[68:71]
	v_mfma_f32_16x16x32_bf16 v[64:67], v[218:221], v[202:205], v[64:67]
	v_mfma_f32_16x16x32_bf16 v[116:119], v[214:217], v[182:185], v[116:119]
	v_mfma_f32_16x16x32_bf16 v[112:115], v[222:225], v[182:185], v[112:115]
	v_mfma_f32_16x16x32_bf16 v[100:103], v[214:217], v[190:193], v[100:103]
	v_mfma_f32_16x16x32_bf16 v[96:99], v[222:225], v[190:193], v[96:99]
	v_mfma_f32_16x16x32_bf16 v[84:87], v[214:217], v[198:201], v[84:87]
	v_mfma_f32_16x16x32_bf16 v[80:83], v[222:225], v[198:201], v[80:83]
	v_mfma_f32_16x16x32_bf16 v[68:71], v[214:217], v[206:209], v[68:71]
	v_mfma_f32_16x16x32_bf16 v[64:67], v[222:225], v[206:209], v[64:67]
	s_setprio 0
	s_mov_b32 m0, s66
	v_lshl_add_u64 v[146:147], v[226:227], 0, s[30:31]
	s_barrier
	ds_read_b128 v[178:181], v152 offset:49152
	ds_read_b128 v[182:185], v152 offset:50176
	ds_read_b128 v[186:189], v152 offset:51200
	ds_read_b128 v[190:193], v152 offset:52224
	ds_read_b128 v[194:197], v152 offset:53248
	ds_read_b128 v[198:201], v152 offset:54272
	ds_read_b128 v[202:205], v152 offset:55296
	ds_read_b128 v[206:209], v152 offset:56320
	global_load_lds_dwordx4 v[146:147], off
	v_lshl_add_u64 v[146:147], v[228:229], 0, s[30:31]
	s_mov_b32 m0, s67
	s_nop 0
	global_load_lds_dwordx4 v[146:147], off
	s_barrier
; #define PG8_STAGE(bufoff, gbase, voff) do { _Pragma("unroll") for (int _i = 0; _i < 2; ++_i) \
;         __builtin_amdgcn_global_load_lds((const unsigned*)((const char*)(gbase) + (voff)[_i]), (LAS unsigned*)(lds + (bufoff) + ldsw + _i * 8192), 16, 0, 0); } while (0)
; #define PG8_MMA(ai, bj, At, Bt) do { __builtin_amdgcn_s_setprio(1); _Pragma("unroll") for (int m = 0; m < 4; ++m) _Pragma("unroll") for (int n = 0; n < 2; ++n) _Pragma("unroll") for (int k = 0; k < 2; ++k) \
;         acc[ai][bj][m][n] = __builtin_amdgcn_mfma_f32_16x16x32_bf16(Bt[n][k], At[m][k], acc[ai][bj][m][n], 0, 0, 0); __builtin_amdgcn_s_setprio(0); } while (0)
; #define PG8_WAIT_V(n) asm volatile("s_waitcnt vmcnt(" #n ")" ::: "memory")
; #define PG8_WAIT_L(n) asm volatile("s_waitcnt lgkmcnt(" #n ")" ::: "memory")
; #define PG8_BAR __builtin_amdgcn_s_barrier()
; #define PG8_SCHED __builtin_amdgcn_sched_barrier(0)
;     ...
;             PG8_BAR; PG8_WAIT_L(0); PG8_MMA(1, 0, At, B0); PG8_BAR; PG8_SCHED;
;             PG8_STAGE(PG8_SB(1, 1), b3 + hB, voffB);
;             PG8_WAIT_V(6); PG8_BAR; PG8_MMA(1, 1, At, B1); PG8_BAR;
; __device__ __forceinline__ float row_rstd(const float* ssq, int row) {
;     const f32x4* p = (const f32x4*)(ssq + (size_t)row * 16);
;     const f32x4 a = p[0], b = p[1], c = p[2], d = p[3];
	s_waitcnt lgkmcnt(0)
	s_setprio 1
	s_waitcnt lgkmcnt(0)
	v_mfma_f32_16x16x32_bf16 v[60:63], v[156:159], v[178:181], v[60:63]
	v_mfma_f32_16x16x32_bf16 v[56:59], v[170:173], v[178:181], v[56:59]
	v_mfma_f32_16x16x32_bf16 v[44:47], v[156:159], v[186:189], v[44:47]
	v_mfma_f32_16x16x32_bf16 v[40:43], v[170:173], v[186:189], v[40:43]
	v_mfma_f32_16x16x32_bf16 v[28:31], v[156:159], v[194:197], v[28:31]
	v_mfma_f32_16x16x32_bf16 v[24:27], v[170:173], v[194:197], v[24:27]
	v_mfma_f32_16x16x32_bf16 v[12:15], v[156:159], v[202:205], v[12:15]
	v_mfma_f32_16x16x32_bf16 v[8:11], v[170:173], v[202:205], v[8:11]
	v_mfma_f32_16x16x32_bf16 v[60:63], v[160:163], v[182:185], v[60:63]
	v_mfma_f32_16x16x32_bf16 v[56:59], v[174:177], v[182:185], v[56:59]
	v_mfma_f32_16x16x32_bf16 v[44:47], v[160:163], v[190:193], v[44:47]
	v_mfma_f32_16x16x32_bf16 v[40:43], v[174:177], v[190:193], v[40:43]
	v_mfma_f32_16x16x32_bf16 v[28:31], v[160:163], v[198:201], v[28:31]
	v_mfma_f32_16x16x32_bf16 v[24:27], v[174:177], v[198:201], v[24:27]
	v_mfma_f32_16x16x32_bf16 v[12:15], v[160:163], v[206:209], v[12:15]
	v_mfma_f32_16x16x32_bf16 v[8:11], v[174:177], v[206:209], v[8:11]
	s_setprio 0
	s_barrier
	s_add_u32 s44, s54, 0x40080
	s_addc_u32 s45, s55, 0
	s_add_i32 s43, s56, s60
	v_lshl_add_u64 v[146:147], s[44:45], 0, v[130:131]
	s_mov_b32 m0, s43
	s_nop 0
	global_load_lds_dwordx4 v[146:147], off
	v_lshl_add_u64 v[146:147], s[44:45], 0, v[134:135]
	s_add_i32 m0, s43, 0x2000
	s_nop 0
	global_load_lds_dwordx4 v[146:147], off
	s_waitcnt vmcnt(6)
	s_barrier
	s_setprio 1
	v_mfma_f32_16x16x32_bf16 v[52:55], v[210:213], v[178:181], v[52:55]
	v_mfma_f32_16x16x32_bf16 v[48:51], v[218:221], v[178:181], v[48:51]
	v_mfma_f32_16x16x32_bf16 v[36:39], v[210:213], v[186:189], v[36:39]
	v_mfma_f32_16x16x32_bf16 v[32:35], v[218:221], v[186:189], v[32:35]
	v_mfma_f32_16x16x32_bf16 v[20:23], v[210:213], v[194:197], v[20:23]
	v_mfma_f32_16x16x32_bf16 v[16:19], v[218:221], v[194:197], v[16:19]
	v_mfma_f32_16x16x32_bf16 v[4:7], v[210:213], v[202:205], v[4:7]
	v_mfma_f32_16x16x32_bf16 v[0:3], v[218:221], v[202:205], v[0:3]
	v_mfma_f32_16x16x32_bf16 v[52:55], v[214:217], v[182:185], v[52:55]
	v_mfma_f32_16x16x32_bf16 v[48:51], v[222:225], v[182:185], v[48:51]
	v_mfma_f32_16x16x32_bf16 v[36:39], v[214:217], v[190:193], v[36:39]
	v_mfma_f32_16x16x32_bf16 v[32:35], v[222:225], v[190:193], v[32:35]
	v_mfma_f32_16x16x32_bf16 v[20:23], v[214:217], v[198:201], v[20:23]
	v_mfma_f32_16x16x32_bf16 v[16:19], v[222:225], v[198:201], v[16:19]
	v_mfma_f32_16x16x32_bf16 v[4:7], v[214:217], v[206:209], v[4:7]
	v_mfma_f32_16x16x32_bf16 v[0:3], v[222:225], v[206:209], v[0:3]
	s_setprio 0
	s_add_i32 s42, s42, 2
	s_add_u32 s33, s33, 0x100
	s_addc_u32 s39, s39, 0
	s_add_u32 s40, s40, 0x100
	s_addc_u32 s41, s41, 0
	s_cmp_gt_u32 s42, 13
	s_barrier
	s_cbranch_scc0 .LBB0_958
	v_lshl_add_u32 v146, s75, 8, v148
	v_ashrrev_i32_e32 v147, 31, v146
	v_lshlrev_b64 v[156:157], 6, v[146:147]
	v_lshl_add_u64 v[164:165], s[26:27], 0, v[156:157]
	v_subrev_u32_e32 v180, s26, v164
	v_add_u32_e32 v181, 0x0, v180
	global_load_dwordx4 v[182:185], v181, s[26:27]
	v_add_u32_e32 v181, 0x10, v180
	global_load_dwordx4 v[186:189], v181, s[26:27]
	v_add_u32_e32 v181, 0x20, v180
	global_load_dwordx4 v[190:193], v181, s[26:27]
	v_add_u32_e32 v181, 0x30, v180
	global_load_dwordx4 v[194:197], v181, s[26:27]
	v_add_u32_e32 v181, 0x400, v180
	global_load_dwordx4 v[198:201], v181, s[26:27]
	v_add_u32_e32 v181, 0x410, v180
	global_load_dwordx4 v[202:205], v181, s[26:27]
	v_add_u32_e32 v181, 0x420, v180
	global_load_dwordx4 v[206:209], v181, s[26:27]
	v_add_u32_e32 v181, 0x430, v180
	global_load_dwordx4 v[210:213], v181, s[26:27]
	v_add_u32_e32 v181, 0x800, v180
	global_load_dwordx4 v[214:217], v181, s[26:27]
	v_add_u32_e32 v181, 0x810, v180
	global_load_dwordx4 v[218:221], v181, s[26:27]
	v_add_u32_e32 v181, 0x820, v180
	global_load_dwordx4 v[222:225], v181, s[26:27]
	v_add_u32_e32 v181, 0x830, v180
	global_load_dwordx4 v[232:235], v181, s[26:27]
	v_add_u32_e32 v181, 0xc00, v180
	global_load_dwordx4 v[236:239], v181, s[26:27]
	v_add_u32_e32 v181, 0xc10, v180
	global_load_dwordx4 v[240:243], v181, s[26:27]
	v_add_u32_e32 v181, 0xc20, v180
	global_load_dwordx4 v[244:247], v181, s[26:27]
	v_add_u32_e32 v181, 0xc30, v180
	global_load_dwordx4 v[248:251], v181, s[26:27]
	v_or_b32_e32 v164, 16, v146
	v_lshl_or_b32 v147, s6, 9, v150
	v_ashrrev_i32_e32 v165, 31, v164
	v_lshl_add_u32 v155, v146, 13, v147
	s_waitcnt vmcnt(12)
; __device__ __forceinline__ u32x4 pack8(const f32x4 v0, const f32x4 v1) { u32x4 w; w.x = pk2(v0[0], v0[1]); w.y = pk2(v0[2], v0[3]); w.z = pk2(v1[0], v1[1]); w.w = pk2(v1[2], v1[3]); return w; }
; __device__ __forceinline__ float row_rstd(const float* ssq, int row) {
;     const f32x4* p = (const f32x4*)(ssq + (size_t)row * 16);
;     const f32x4 a = p[0], b = p[1], c = p[2], d = p[3];
;     const float s = ((a[0] + a[1]) + (a[2] + a[3])) + ((b[0] + b[1]) + (b[2] + b[3])) + ((c[0] + c[1]) + (c[2] + c[3])) + ((d[0] + d[1]) + (d[2] + d[3]));
;     return rsqrtf(s * (1.0f / 1024.0f) + 1e-6f);
;     __device__ __forceinline__ void operator()(const f32x4 (&acc)[2][2][4][2], const Unit& u, int wr, int wc, int fr, int fq) const {
;     ...
;                 const int row = row0 + ai * 128 + m * 16; const float rs = row_rstd(ssq, row);
; #pragma unroll
;                 for (int bj = 0; bj < 2; ++bj) { f32x4 v0 = acc[ai][bj][m][0] * rs, v1 = acc[ai][bj][m][1] * rs;
; #pragma unroll
;                     for (int j = 0; j < 4; ++j) { const float a = fmaxf(v0[j], 0.f), b = fmaxf(v1[j], 0.f); v0[j] = a * a; v1[j] = b * b; }
;                     __builtin_amdgcn_raw_buffer_store_b128(pack8(v0, v1), rsrc, (unsigned)(((size_t)row * DFF + col0 + bj * 128) * 2), 0, 16  ); }
	v_mov_b32_e32 v178, v183
	v_mov_b32_e32 v179, v184
	v_mov_b32_e32 v157, v185
	v_mov_b32_e32 v158, v187
	v_mov_b32_e32 v159, v188
	v_mov_b32_e32 v161, v189
	v_mov_b32_e32 v156, v182
	v_pk_add_f32 v[156:157], v[178:179], v[156:157]
	v_mov_b32_e32 v160, v186
	v_pk_add_f32 v[158:159], v[158:159], v[160:161]
	v_pk_add_f32 v[156:157], v[156:157], v[156:157] op_sel:[0,1] op_sel_hi:[1,0]
	v_pk_add_f32 v[158:159], v[158:159], v[158:159] op_sel:[0,1] op_sel_hi:[1,0]
	v_add_f32_e32 v162, v190, v191
	v_add_f32_e32 v170, v192, v193
	v_mov_b32_e32 v163, v196
	v_mov_b32_e32 v171, v197
	v_mov_b32_e32 v157, v194
	v_mov_b32_e32 v159, v195
	v_pk_add_f32 v[160:161], v[162:163], v[170:171]
	v_pk_add_f32 v[156:157], v[156:157], v[158:159]
	s_nop 0
	v_pk_add_f32 v[156:157], v[156:157], v[160:161]
	s_nop 0
	v_add_f32_e32 v156, v156, v157
	v_fmamk_f32 v156, v156, 0x3a800000, v154
	v_mul_f32_e32 v157, 0x4b800000, v156
	v_cmp_gt_f32_e32 vcc, s71, v156
	s_nop 1
	v_cndmask_b32_e32 v156, v156, v157, vcc
	v_rsq_f32_e32 v158, v156
	v_lshlrev_b64 v[156:157], 6, v[164:165]
	v_lshl_add_u64 v[156:157], s[26:27], 0, v[156:157]
	v_mul_f32_e32 v159, 0x45800000, v158
	v_cndmask_b32_e32 v158, v158, v159, vcc
	v_pk_mul_f32 v[126:127], v[126:127], v[158:159] op_sel_hi:[1,0]
	v_pk_mul_f32 v[124:125], v[124:125], v[158:159] op_sel_hi:[1,0]
	v_pk_mul_f32 v[122:123], v[122:123], v[158:159] op_sel_hi:[1,0]
	v_pk_mul_f32 v[120:121], v[120:121], v[158:159] op_sel_hi:[1,0]
	v_pk_mul_f32 v[114:115], v[114:115], v[158:159] op_sel_hi:[1,0]
	v_pk_mul_f32 v[112:113], v[112:113], v[158:159] op_sel_hi:[1,0]
	v_pk_mul_f32 v[118:119], v[118:119], v[158:159] op_sel_hi:[1,0]
	v_pk_mul_f32 v[116:117], v[116:117], v[158:159] op_sel_hi:[1,0]
	v_max_f32_e32 v124, 0, v124
	v_max_f32_e32 v120, 0, v120
	v_max_f32_e32 v125, 0, v125
	v_max_f32_e32 v121, 0, v121
	v_max_f32_e32 v126, 0, v126
	v_max_f32_e32 v122, 0, v122
	v_max_f32_e32 v127, 0, v127
	v_max_f32_e32 v123, 0, v123
	v_max_f32_e32 v112, 0, v112
	v_max_f32_e32 v113, 0, v113
	v_max_f32_e32 v114, 0, v114
	v_max_f32_e32 v115, 0, v115
	v_max_f32_e32 v116, 0, v116
	v_max_f32_e32 v117, 0, v117
	v_max_f32_e32 v118, 0, v118
	v_max_f32_e32 v119, 0, v119
	v_mul_f32_e32 v124, v124, v124
	v_mul_f32_e32 v120, v120, v120
	v_mul_f32_e32 v125, v125, v125
	v_mul_f32_e32 v121, v121, v121
	v_mul_f32_e32 v126, v126, v126
	v_mul_f32_e32 v122, v122, v122
	v_mul_f32_e32 v127, v127, v127
	v_mul_f32_e32 v123, v123, v123
	v_mul_f32_e32 v158, v112, v112
	v_mul_f32_e32 v159, v113, v113
	v_mul_f32_e32 v160, v114, v114
	v_mul_f32_e32 v161, v115, v115
	v_cvt_pk_bf16_f32 v112, v124, v125
	v_cvt_pk_bf16_f32 v113, v126, v127
	v_cvt_pk_bf16_f32 v114, v120, v121
	v_cvt_pk_bf16_f32 v115, v122, v123
	v_mul_f32_e32 v116, v116, v116
	v_mul_f32_e32 v117, v117, v117
	v_mul_f32_e32 v118, v118, v118
	v_mul_f32_e32 v119, v119, v119
	buffer_store_dwordx4 v[112:115], v155, s[16:19], 0 offen sc1
	s_nop 1
	v_cvt_pk_bf16_f32 v112, v116, v117
	v_cvt_pk_bf16_f32 v113, v118, v119
	v_cvt_pk_bf16_f32 v114, v158, v159
	v_cvt_pk_bf16_f32 v115, v160, v161
	buffer_store_dwordx4 v[112:115], v155, s[16:19], 0 offen offset:256 sc1
	s_nop 0
	v_or_b32_e32 v156, 32, v146
	v_ashrrev_i32_e32 v157, 31, v156
	v_lshl_add_u32 v155, v164, 13, v147
	v_add_u32_e32 v181, 0x2000, v180
	global_load_dwordx4 v[182:185], v181, s[26:27]
	v_add_u32_e32 v181, 0x2010, v180
	global_load_dwordx4 v[186:189], v181, s[26:27]
	v_add_u32_e32 v181, 0x2020, v180
	global_load_dwordx4 v[190:193], v181, s[26:27]
	v_add_u32_e32 v181, 0x2030, v180
	global_load_dwordx4 v[194:197], v181, s[26:27]
	s_waitcnt vmcnt(14)
	v_mov_b32_e32 v158, v199
	v_mov_b32_e32 v159, v200
	v_mov_b32_e32 v113, v201
	v_mov_b32_e32 v114, v203
	v_mov_b32_e32 v115, v204
	v_mov_b32_e32 v117, v205
	v_mov_b32_e32 v112, v198
	v_pk_add_f32 v[112:113], v[158:159], v[112:113]
	v_mov_b32_e32 v116, v202
	v_pk_add_f32 v[114:115], v[114:115], v[116:117]
	v_pk_add_f32 v[112:113], v[112:113], v[112:113] op_sel:[0,1] op_sel_hi:[1,0]
	v_pk_add_f32 v[114:115], v[114:115], v[114:115] op_sel:[0,1] op_sel_hi:[1,0]
	v_add_f32_e32 v118, v206, v207
	v_add_f32_e32 v120, v208, v209
	v_mov_b32_e32 v119, v212
	v_mov_b32_e32 v121, v213
	v_mov_b32_e32 v113, v210
	v_mov_b32_e32 v115, v211
	v_pk_add_f32 v[116:117], v[118:119], v[120:121]
	v_pk_add_f32 v[112:113], v[112:113], v[114:115]
	s_nop 0
	v_pk_add_f32 v[112:113], v[112:113], v[116:117]
	s_nop 0
	v_add_f32_e32 v112, v112, v113
	v_fmamk_f32 v112, v112, 0x3a800000, v154
	v_mul_f32_e32 v113, 0x4b800000, v112
	v_cmp_gt_f32_e32 vcc, s71, v112
	s_nop 1
	v_cndmask_b32_e32 v112, v112, v113, vcc
	v_rsq_f32_e32 v114, v112
	v_lshlrev_b64 v[112:113], 6, v[156:157]
	v_lshl_add_u64 v[112:113], s[26:27], 0, v[112:113]
	v_mul_f32_e32 v115, 0x45800000, v114
	v_cndmask_b32_e32 v114, v114, v115, vcc
	v_pk_mul_f32 v[110:111], v[110:111], v[114:115] op_sel_hi:[1,0]
	v_pk_mul_f32 v[108:109], v[108:109], v[114:115] op_sel_hi:[1,0]
	v_pk_mul_f32 v[106:107], v[106:107], v[114:115] op_sel_hi:[1,0]
	v_pk_mul_f32 v[104:105], v[104:105], v[114:115] op_sel_hi:[1,0]
	v_pk_mul_f32 v[98:99], v[98:99], v[114:115] op_sel_hi:[1,0]
	v_pk_mul_f32 v[96:97], v[96:97], v[114:115] op_sel_hi:[1,0]
	v_pk_mul_f32 v[102:103], v[102:103], v[114:115] op_sel_hi:[1,0]
	v_pk_mul_f32 v[100:101], v[100:101], v[114:115] op_sel_hi:[1,0]
	v_max_f32_e32 v108, 0, v108
	v_max_f32_e32 v104, 0, v104
	v_max_f32_e32 v109, 0, v109
	v_max_f32_e32 v105, 0, v105
	v_max_f32_e32 v110, 0, v110
	v_max_f32_e32 v106, 0, v106
	v_max_f32_e32 v111, 0, v111
	v_max_f32_e32 v107, 0, v107
	v_max_f32_e32 v96, 0, v96
	v_max_f32_e32 v97, 0, v97
	v_max_f32_e32 v98, 0, v98
	v_max_f32_e32 v99, 0, v99
	v_max_f32_e32 v100, 0, v100
; __device__ __forceinline__ u32x4 pack8(const f32x4 v0, const f32x4 v1) { u32x4 w; w.x = pk2(v0[0], v0[1]); w.y = pk2(v0[2], v0[3]); w.z = pk2(v1[0], v1[1]); w.w = pk2(v1[2], v1[3]); return w; }
; __device__ __forceinline__ float row_rstd(const float* ssq, int row) {
;     const f32x4* p = (const f32x4*)(ssq + (size_t)row * 16);
;     const f32x4 a = p[0], b = p[1], c = p[2], d = p[3];
;     const float s = ((a[0] + a[1]) + (a[2] + a[3])) + ((b[0] + b[1]) + (b[2] + b[3])) + ((c[0] + c[1]) + (c[2] + c[3])) + ((d[0] + d[1]) + (d[2] + d[3]));
;     return rsqrtf(s * (1.0f / 1024.0f) + 1e-6f);
;     __device__ __forceinline__ void operator()(const f32x4 (&acc)[2][2][4][2], const Unit& u, int wr, int wc, int fr, int fq) const {
;     ...
;                 const int row = row0 + ai * 128 + m * 16; const float rs = row_rstd(ssq, row);
; #pragma unroll
;                 for (int bj = 0; bj < 2; ++bj) { f32x4 v0 = acc[ai][bj][m][0] * rs, v1 = acc[ai][bj][m][1] * rs;
; #pragma unroll
;                     for (int j = 0; j < 4; ++j) { const float a = fmaxf(v0[j], 0.f), b = fmaxf(v1[j], 0.f); v0[j] = a * a; v1[j] = b * b; }
;                     __builtin_amdgcn_raw_buffer_store_b128(pack8(v0, v1), rsrc, (unsigned)(((size_t)row * DFF + col0 + bj * 128) * 2), 0, 16  ); }
	v_max_f32_e32 v101, 0, v101
	v_max_f32_e32 v102, 0, v102
	v_max_f32_e32 v103, 0, v103
	v_mul_f32_e32 v108, v108, v108
	v_mul_f32_e32 v104, v104, v104
	v_mul_f32_e32 v109, v109, v109
	v_mul_f32_e32 v105, v105, v105
	v_mul_f32_e32 v110, v110, v110
	v_mul_f32_e32 v106, v106, v106
	v_mul_f32_e32 v111, v111, v111
	v_mul_f32_e32 v107, v107, v107
	v_mul_f32_e32 v114, v96, v96
	v_mul_f32_e32 v115, v97, v97
	v_mul_f32_e32 v116, v98, v98
	v_mul_f32_e32 v117, v99, v99
	v_cvt_pk_bf16_f32 v96, v108, v109
	v_cvt_pk_bf16_f32 v97, v110, v111
	v_cvt_pk_bf16_f32 v98, v104, v105
	v_cvt_pk_bf16_f32 v99, v106, v107
	v_mul_f32_e32 v100, v100, v100
	v_mul_f32_e32 v101, v101, v101
	v_mul_f32_e32 v102, v102, v102
	v_mul_f32_e32 v103, v103, v103
	buffer_store_dwordx4 v[96:99], v155, s[16:19], 0 offen sc1
	s_nop 1
	v_cvt_pk_bf16_f32 v96, v100, v101
	v_cvt_pk_bf16_f32 v97, v102, v103
	v_cvt_pk_bf16_f32 v98, v114, v115
	v_cvt_pk_bf16_f32 v99, v116, v117
	buffer_store_dwordx4 v[96:99], v155, s[16:19], 0 offen offset:256 sc1
	s_nop 0
	v_or_b32_e32 v112, 48, v146
	v_ashrrev_i32_e32 v113, 31, v112
	v_lshl_add_u32 v116, v156, 13, v147
	v_add_u32_e32 v181, 0x2400, v180
	global_load_dwordx4 v[198:201], v181, s[26:27]
	v_add_u32_e32 v181, 0x2410, v180
	global_load_dwordx4 v[202:205], v181, s[26:27]
	v_add_u32_e32 v181, 0x2420, v180
	global_load_dwordx4 v[206:209], v181, s[26:27]
	v_add_u32_e32 v181, 0x2430, v180
	global_load_dwordx4 v[210:213], v181, s[26:27]
	s_waitcnt vmcnt(16)
	v_mov_b32_e32 v114, v215
	v_mov_b32_e32 v115, v216
	v_mov_b32_e32 v97, v217
	v_mov_b32_e32 v98, v219
	v_mov_b32_e32 v99, v220
	v_mov_b32_e32 v101, v221
	v_mov_b32_e32 v96, v214
	v_pk_add_f32 v[96:97], v[114:115], v[96:97]
	v_mov_b32_e32 v100, v218
	v_pk_add_f32 v[98:99], v[98:99], v[100:101]
	v_pk_add_f32 v[96:97], v[96:97], v[96:97] op_sel:[0,1] op_sel_hi:[1,0]
	v_pk_add_f32 v[98:99], v[98:99], v[98:99] op_sel:[0,1] op_sel_hi:[1,0]
	v_add_f32_e32 v102, v222, v223
	v_add_f32_e32 v104, v224, v225
	v_mov_b32_e32 v103, v234
	v_mov_b32_e32 v105, v235
	v_mov_b32_e32 v97, v232
	v_mov_b32_e32 v99, v233
	v_pk_add_f32 v[100:101], v[102:103], v[104:105]
	v_pk_add_f32 v[96:97], v[96:97], v[98:99]
	s_nop 0
	v_pk_add_f32 v[96:97], v[96:97], v[100:101]
	s_nop 0
	v_add_f32_e32 v96, v96, v97
	v_fmamk_f32 v96, v96, 0x3a800000, v154
	v_mul_f32_e32 v97, 0x4b800000, v96
	v_cmp_gt_f32_e32 vcc, s71, v96
	s_nop 1
	v_cndmask_b32_e32 v96, v96, v97, vcc
	v_rsq_f32_e32 v98, v96
	v_lshlrev_b64 v[96:97], 6, v[112:113]
	v_lshl_add_u64 v[96:97], s[26:27], 0, v[96:97]
	v_mul_f32_e32 v99, 0x45800000, v98
	v_cndmask_b32_e32 v98, v98, v99, vcc
	v_pk_mul_f32 v[94:95], v[94:95], v[98:99] op_sel_hi:[1,0]
	v_pk_mul_f32 v[92:93], v[92:93], v[98:99] op_sel_hi:[1,0]
	v_pk_mul_f32 v[90:91], v[90:91], v[98:99] op_sel_hi:[1,0]
	v_pk_mul_f32 v[88:89], v[88:89], v[98:99] op_sel_hi:[1,0]
	v_pk_mul_f32 v[82:83], v[82:83], v[98:99] op_sel_hi:[1,0]
	v_pk_mul_f32 v[80:81], v[80:81], v[98:99] op_sel_hi:[1,0]
	v_pk_mul_f32 v[86:87], v[86:87], v[98:99] op_sel_hi:[1,0]
	v_pk_mul_f32 v[84:85], v[84:85], v[98:99] op_sel_hi:[1,0]
	v_max_f32_e32 v92, 0, v92
	v_max_f32_e32 v88, 0, v88
	v_max_f32_e32 v93, 0, v93
	v_max_f32_e32 v89, 0, v89
	v_max_f32_e32 v94, 0, v94
	v_max_f32_e32 v90, 0, v90
	v_max_f32_e32 v95, 0, v95
	v_max_f32_e32 v91, 0, v91
	v_max_f32_e32 v80, 0, v80
	v_max_f32_e32 v81, 0, v81
	v_max_f32_e32 v82, 0, v82
	v_max_f32_e32 v83, 0, v83
	v_max_f32_e32 v84, 0, v84
	v_max_f32_e32 v85, 0, v85
	v_max_f32_e32 v86, 0, v86
	v_max_f32_e32 v87, 0, v87
	v_mul_f32_e32 v92, v92, v92
	v_mul_f32_e32 v88, v88, v88
	v_mul_f32_e32 v93, v93, v93
	v_mul_f32_e32 v89, v89, v89
	v_mul_f32_e32 v94, v94, v94
	v_mul_f32_e32 v90, v90, v90
	v_mul_f32_e32 v95, v95, v95
	v_mul_f32_e32 v91, v91, v91
	v_mul_f32_e32 v98, v80, v80
	v_mul_f32_e32 v99, v81, v81
	v_mul_f32_e32 v100, v82, v82
	v_mul_f32_e32 v101, v83, v83
	v_cvt_pk_bf16_f32 v80, v92, v93
	v_cvt_pk_bf16_f32 v81, v94, v95
	v_cvt_pk_bf16_f32 v82, v88, v89
	v_cvt_pk_bf16_f32 v83, v90, v91
	v_mul_f32_e32 v84, v84, v84
	v_mul_f32_e32 v85, v85, v85
	v_mul_f32_e32 v86, v86, v86
	v_mul_f32_e32 v87, v87, v87
	buffer_store_dwordx4 v[80:83], v116, s[16:19], 0 offen sc1
	s_nop 1
	v_cvt_pk_bf16_f32 v80, v84, v85
	v_cvt_pk_bf16_f32 v81, v86, v87
	v_cvt_pk_bf16_f32 v82, v98, v99
	v_cvt_pk_bf16_f32 v83, v100, v101
	buffer_store_dwordx4 v[80:83], v116, s[16:19], 0 offen offset:256 sc1
	s_nop 0
	v_add_u32_e32 v96, 0x80, v146
	v_ashrrev_i32_e32 v97, 31, v96
	v_lshl_add_u32 v100, v112, 13, v147
	v_add_u32_e32 v181, 0x2800, v180
	global_load_dwordx4 v[214:217], v181, s[26:27]
	v_add_u32_e32 v181, 0x2810, v180
	global_load_dwordx4 v[218:221], v181, s[26:27]
	v_add_u32_e32 v181, 0x2820, v180
	global_load_dwordx4 v[222:225], v181, s[26:27]
	v_add_u32_e32 v181, 0x2830, v180
	global_load_dwordx4 v[232:235], v181, s[26:27]
	s_waitcnt vmcnt(18)
; __device__ __forceinline__ u32x4 pack8(const f32x4 v0, const f32x4 v1) { u32x4 w; w.x = pk2(v0[0], v0[1]); w.y = pk2(v0[2], v0[3]); w.z = pk2(v1[0], v1[1]); w.w = pk2(v1[2], v1[3]); return w; }
; __device__ __forceinline__ float row_rstd(const float* ssq, int row) {
;     const f32x4* p = (const f32x4*)(ssq + (size_t)row * 16);
;     const f32x4 a = p[0], b = p[1], c = p[2], d = p[3];
;     const float s = ((a[0] + a[1]) + (a[2] + a[3])) + ((b[0] + b[1]) + (b[2] + b[3])) + ((c[0] + c[1]) + (c[2] + c[3])) + ((d[0] + d[1]) + (d[2] + d[3]));
;     return rsqrtf(s * (1.0f / 1024.0f) + 1e-6f);
;     __device__ __forceinline__ void operator()(const f32x4 (&acc)[2][2][4][2], const Unit& u, int wr, int wc, int fr, int fq) const {
;         const __amdgpu_buffer_rsrc_t rsrc = __builtin_amdgcn_make_buffer_rsrc((void*)O, 0, T_ALL * DFF * 2, 0x00020000);
;         const int row0 = row_off + u.pm * 256 + wr * 64 + fr, col0 = u.pn * 256 + wc * 32 + 8 * fq;
; #pragma unroll
;         for (int ai = 0; ai < 2; ++ai)
; #pragma unroll
;             for (int m = 0; m < 4; ++m) {
;                 const int row = row0 + ai * 128 + m * 16; const float rs = row_rstd(ssq, row);
; #pragma unroll
;                 for (int bj = 0; bj < 2; ++bj) { f32x4 v0 = acc[ai][bj][m][0] * rs, v1 = acc[ai][bj][m][1] * rs;
; #pragma unroll
;                     for (int j = 0; j < 4; ++j) { const float a = fmaxf(v0[j], 0.f), b = fmaxf(v1[j], 0.f); v0[j] = a * a; v1[j] = b * b; }
;                     __builtin_amdgcn_raw_buffer_store_b128(pack8(v0, v1), rsrc, (unsigned)(((size_t)row * DFF + col0 + bj * 128) * 2), 0, 16  ); }
	v_mov_b32_e32 v98, v237
	v_mov_b32_e32 v99, v238
	v_mov_b32_e32 v81, v239
	v_mov_b32_e32 v82, v241
	v_mov_b32_e32 v83, v242
	v_mov_b32_e32 v85, v243
	v_mov_b32_e32 v80, v236
	v_pk_add_f32 v[80:81], v[98:99], v[80:81]
	v_mov_b32_e32 v84, v240
	v_pk_add_f32 v[82:83], v[82:83], v[84:85]
	v_pk_add_f32 v[80:81], v[80:81], v[80:81] op_sel:[0,1] op_sel_hi:[1,0]
	v_pk_add_f32 v[82:83], v[82:83], v[82:83] op_sel:[0,1] op_sel_hi:[1,0]
	v_add_f32_e32 v86, v244, v245
	v_add_f32_e32 v88, v246, v247
	v_mov_b32_e32 v87, v250
	v_mov_b32_e32 v89, v251
	v_mov_b32_e32 v81, v248
	v_mov_b32_e32 v83, v249
	v_pk_add_f32 v[84:85], v[86:87], v[88:89]
	v_pk_add_f32 v[80:81], v[80:81], v[82:83]
	s_nop 0
	v_pk_add_f32 v[80:81], v[80:81], v[84:85]
	s_nop 0
	v_add_f32_e32 v80, v80, v81
	v_fmamk_f32 v80, v80, 0x3a800000, v154
	v_mul_f32_e32 v81, 0x4b800000, v80
	v_cmp_gt_f32_e32 vcc, s71, v80
	s_nop 1
	v_cndmask_b32_e32 v80, v80, v81, vcc
	v_rsq_f32_e32 v82, v80
	v_lshlrev_b64 v[80:81], 6, v[96:97]
	v_lshl_add_u64 v[80:81], s[26:27], 0, v[80:81]
	v_mul_f32_e32 v83, 0x45800000, v82
	v_cndmask_b32_e32 v82, v82, v83, vcc
	v_pk_mul_f32 v[78:79], v[78:79], v[82:83] op_sel_hi:[1,0]
	v_pk_mul_f32 v[76:77], v[76:77], v[82:83] op_sel_hi:[1,0]
	v_pk_mul_f32 v[74:75], v[74:75], v[82:83] op_sel_hi:[1,0]
	v_pk_mul_f32 v[72:73], v[72:73], v[82:83] op_sel_hi:[1,0]
	v_pk_mul_f32 v[66:67], v[66:67], v[82:83] op_sel_hi:[1,0]
	v_pk_mul_f32 v[64:65], v[64:65], v[82:83] op_sel_hi:[1,0]
	v_pk_mul_f32 v[70:71], v[70:71], v[82:83] op_sel_hi:[1,0]
	v_pk_mul_f32 v[68:69], v[68:69], v[82:83] op_sel_hi:[1,0]
	v_max_f32_e32 v76, 0, v76
	v_max_f32_e32 v72, 0, v72
	v_max_f32_e32 v77, 0, v77
	v_max_f32_e32 v73, 0, v73
	v_max_f32_e32 v78, 0, v78
	v_max_f32_e32 v74, 0, v74
	v_max_f32_e32 v79, 0, v79
	v_max_f32_e32 v75, 0, v75
	v_max_f32_e32 v64, 0, v64
	v_max_f32_e32 v65, 0, v65
	v_max_f32_e32 v66, 0, v66
	v_max_f32_e32 v67, 0, v67
	v_max_f32_e32 v68, 0, v68
	v_max_f32_e32 v69, 0, v69
	v_max_f32_e32 v70, 0, v70
	v_max_f32_e32 v71, 0, v71
	v_mul_f32_e32 v76, v76, v76
	v_mul_f32_e32 v72, v72, v72
	v_mul_f32_e32 v77, v77, v77
	v_mul_f32_e32 v73, v73, v73
	v_mul_f32_e32 v78, v78, v78
	v_mul_f32_e32 v74, v74, v74
	v_mul_f32_e32 v79, v79, v79
	v_mul_f32_e32 v75, v75, v75
	v_mul_f32_e32 v82, v64, v64
	v_mul_f32_e32 v83, v65, v65
	v_mul_f32_e32 v84, v66, v66
	v_mul_f32_e32 v85, v67, v67
	v_cvt_pk_bf16_f32 v64, v76, v77
	v_cvt_pk_bf16_f32 v65, v78, v79
	v_cvt_pk_bf16_f32 v66, v72, v73
	v_cvt_pk_bf16_f32 v67, v74, v75
	v_mul_f32_e32 v68, v68, v68
	v_mul_f32_e32 v69, v69, v69
	v_mul_f32_e32 v70, v70, v70
	v_mul_f32_e32 v71, v71, v71
	buffer_store_dwordx4 v[64:67], v100, s[16:19], 0 offen sc1
	s_nop 1
	v_cvt_pk_bf16_f32 v64, v68, v69
	v_cvt_pk_bf16_f32 v65, v70, v71
	v_cvt_pk_bf16_f32 v66, v82, v83
	v_cvt_pk_bf16_f32 v67, v84, v85
	buffer_store_dwordx4 v[64:67], v100, s[16:19], 0 offen offset:256 sc1
	s_nop 0
	v_add_u32_e32 v80, 0x90, v146
	v_ashrrev_i32_e32 v81, 31, v80
	v_lshl_add_u32 v84, v96, 13, v147
	v_add_u32_e32 v181, 0x2c00, v180
	global_load_dwordx4 v[236:239], v181, s[26:27]
	v_add_u32_e32 v181, 0x2c10, v180
	global_load_dwordx4 v[240:243], v181, s[26:27]
	v_add_u32_e32 v181, 0x2c20, v180
	global_load_dwordx4 v[244:247], v181, s[26:27]
	v_add_u32_e32 v181, 0x2c30, v180
	global_load_dwordx4 v[248:251], v181, s[26:27]
	s_waitcnt vmcnt(18)
	v_mov_b32_e32 v82, v183
	v_mov_b32_e32 v83, v184
	v_mov_b32_e32 v65, v185
	v_mov_b32_e32 v66, v187
	v_mov_b32_e32 v67, v188
	v_mov_b32_e32 v69, v189
	v_mov_b32_e32 v64, v182
	v_pk_add_f32 v[64:65], v[82:83], v[64:65]
	v_mov_b32_e32 v68, v186
	v_pk_add_f32 v[66:67], v[66:67], v[68:69]
	v_pk_add_f32 v[64:65], v[64:65], v[64:65] op_sel:[0,1] op_sel_hi:[1,0]
	v_pk_add_f32 v[66:67], v[66:67], v[66:67] op_sel:[0,1] op_sel_hi:[1,0]
	v_add_f32_e32 v70, v190, v191
	v_add_f32_e32 v72, v192, v193
	v_mov_b32_e32 v71, v196
	v_mov_b32_e32 v73, v197
	v_mov_b32_e32 v65, v194
	v_mov_b32_e32 v67, v195
	v_pk_add_f32 v[68:69], v[70:71], v[72:73]
	v_pk_add_f32 v[64:65], v[64:65], v[66:67]
	s_nop 0
	v_pk_add_f32 v[64:65], v[64:65], v[68:69]
	s_nop 0
	v_add_f32_e32 v64, v64, v65
	v_fmamk_f32 v64, v64, 0x3a800000, v154
	v_mul_f32_e32 v65, 0x4b800000, v64
	v_cmp_gt_f32_e32 vcc, s71, v64
	s_nop 1
	v_cndmask_b32_e32 v64, v64, v65, vcc
	v_rsq_f32_e32 v66, v64
	v_lshlrev_b64 v[64:65], 6, v[80:81]
	v_lshl_add_u64 v[64:65], s[26:27], 0, v[64:65]
	v_mul_f32_e32 v67, 0x45800000, v66
	v_cndmask_b32_e32 v66, v66, v67, vcc
	v_pk_mul_f32 v[62:63], v[62:63], v[66:67] op_sel_hi:[1,0]
	v_pk_mul_f32 v[60:61], v[60:61], v[66:67] op_sel_hi:[1,0]
	v_pk_mul_f32 v[58:59], v[58:59], v[66:67] op_sel_hi:[1,0]
	v_pk_mul_f32 v[56:57], v[56:57], v[66:67] op_sel_hi:[1,0]
	v_pk_mul_f32 v[50:51], v[50:51], v[66:67] op_sel_hi:[1,0]
	v_pk_mul_f32 v[48:49], v[48:49], v[66:67] op_sel_hi:[1,0]
	v_pk_mul_f32 v[54:55], v[54:55], v[66:67] op_sel_hi:[1,0]
	v_pk_mul_f32 v[52:53], v[52:53], v[66:67] op_sel_hi:[1,0]
	v_max_f32_e32 v60, 0, v60
	v_max_f32_e32 v56, 0, v56
	v_max_f32_e32 v61, 0, v61
	v_max_f32_e32 v57, 0, v57
	v_max_f32_e32 v62, 0, v62
	v_max_f32_e32 v58, 0, v58
	v_max_f32_e32 v63, 0, v63
	v_max_f32_e32 v59, 0, v59
	v_max_f32_e32 v48, 0, v48
	v_max_f32_e32 v49, 0, v49
	v_max_f32_e32 v50, 0, v50
	v_max_f32_e32 v51, 0, v51
	v_max_f32_e32 v52, 0, v52
	v_max_f32_e32 v53, 0, v53
	v_max_f32_e32 v54, 0, v54
	v_max_f32_e32 v55, 0, v55
	v_mul_f32_e32 v60, v60, v60
	v_mul_f32_e32 v56, v56, v56
	v_mul_f32_e32 v61, v61, v61
	v_mul_f32_e32 v57, v57, v57
	v_mul_f32_e32 v62, v62, v62
	v_mul_f32_e32 v58, v58, v58
	v_mul_f32_e32 v63, v63, v63
	v_mul_f32_e32 v59, v59, v59
	v_mul_f32_e32 v66, v48, v48
	v_mul_f32_e32 v67, v49, v49
	v_mul_f32_e32 v68, v50, v50
	v_mul_f32_e32 v69, v51, v51
	v_cvt_pk_bf16_f32 v48, v60, v61
	v_cvt_pk_bf16_f32 v49, v62, v63
	v_cvt_pk_bf16_f32 v50, v56, v57
	v_cvt_pk_bf16_f32 v51, v58, v59
	v_mul_f32_e32 v52, v52, v52
	v_mul_f32_e32 v53, v53, v53
	v_mul_f32_e32 v54, v54, v54
	v_mul_f32_e32 v55, v55, v55
	buffer_store_dwordx4 v[48:51], v84, s[16:19], 0 offen sc1
	s_nop 1
	v_cvt_pk_bf16_f32 v48, v52, v53
	v_cvt_pk_bf16_f32 v49, v54, v55
	v_cvt_pk_bf16_f32 v50, v66, v67
	v_cvt_pk_bf16_f32 v51, v68, v69
	buffer_store_dwordx4 v[48:51], v84, s[16:19], 0 offen offset:256 sc1
	s_nop 0
	v_add_u32_e32 v64, 0xa0, v146
	v_ashrrev_i32_e32 v65, 31, v64
	v_lshl_add_u32 v68, v80, 13, v147
	s_waitcnt vmcnt(14)
; __device__ __forceinline__ u32x4 pack8(const f32x4 v0, const f32x4 v1) { u32x4 w; w.x = pk2(v0[0], v0[1]); w.y = pk2(v0[2], v0[3]); w.z = pk2(v1[0], v1[1]); w.w = pk2(v1[2], v1[3]); return w; }
; __device__ __forceinline__ float row_rstd(const float* ssq, int row) {
;     const f32x4* p = (const f32x4*)(ssq + (size_t)row * 16);
;     const f32x4 a = p[0], b = p[1], c = p[2], d = p[3];
;     const float s = ((a[0] + a[1]) + (a[2] + a[3])) + ((b[0] + b[1]) + (b[2] + b[3])) + ((c[0] + c[1]) + (c[2] + c[3])) + ((d[0] + d[1]) + (d[2] + d[3]));
;     return rsqrtf(s * (1.0f / 1024.0f) + 1e-6f);
;     __device__ __forceinline__ void operator()(const f32x4 (&acc)[2][2][4][2], const Unit& u, int wr, int wc, int fr, int fq) const {
;     ...
;         for (int ai = 0; ai < 2; ++ai)
; #pragma unroll
;             for (int m = 0; m < 4; ++m) {
;                 const int row = row0 + ai * 128 + m * 16; const float rs = row_rstd(ssq, row);
; #pragma unroll
;                 for (int bj = 0; bj < 2; ++bj) { f32x4 v0 = acc[ai][bj][m][0] * rs, v1 = acc[ai][bj][m][1] * rs;
; #pragma unroll
;                     for (int j = 0; j < 4; ++j) { const float a = fmaxf(v0[j], 0.f), b = fmaxf(v1[j], 0.f); v0[j] = a * a; v1[j] = b * b; }
;                     __builtin_amdgcn_raw_buffer_store_b128(pack8(v0, v1), rsrc, (unsigned)(((size_t)row * DFF + col0 + bj * 128) * 2), 0, 16  ); }
	v_mov_b32_e32 v66, v199
	v_mov_b32_e32 v67, v200
	v_mov_b32_e32 v49, v201
	v_mov_b32_e32 v50, v203
	v_mov_b32_e32 v51, v204
	v_mov_b32_e32 v53, v205
	v_mov_b32_e32 v48, v198
	v_pk_add_f32 v[48:49], v[66:67], v[48:49]
	v_mov_b32_e32 v52, v202
	v_pk_add_f32 v[50:51], v[50:51], v[52:53]
	v_pk_add_f32 v[48:49], v[48:49], v[48:49] op_sel:[0,1] op_sel_hi:[1,0]
	v_pk_add_f32 v[50:51], v[50:51], v[50:51] op_sel:[0,1] op_sel_hi:[1,0]
	v_add_f32_e32 v54, v206, v207
	v_add_f32_e32 v56, v208, v209
	v_mov_b32_e32 v55, v212
	v_mov_b32_e32 v57, v213
	v_mov_b32_e32 v49, v210
	v_mov_b32_e32 v51, v211
	v_pk_add_f32 v[52:53], v[54:55], v[56:57]
	v_pk_add_f32 v[48:49], v[48:49], v[50:51]
	s_nop 0
	v_pk_add_f32 v[48:49], v[48:49], v[52:53]
	s_nop 0
	v_add_f32_e32 v48, v48, v49
	v_fmamk_f32 v48, v48, 0x3a800000, v154
	v_mul_f32_e32 v49, 0x4b800000, v48
	v_cmp_gt_f32_e32 vcc, s71, v48
	s_nop 1
	v_cndmask_b32_e32 v48, v48, v49, vcc
	v_rsq_f32_e32 v50, v48
	v_lshlrev_b64 v[48:49], 6, v[64:65]
	v_lshl_add_u64 v[48:49], s[26:27], 0, v[48:49]
	v_mul_f32_e32 v51, 0x45800000, v50
	v_cndmask_b32_e32 v50, v50, v51, vcc
	v_pk_mul_f32 v[46:47], v[46:47], v[50:51] op_sel_hi:[1,0]
	v_pk_mul_f32 v[44:45], v[44:45], v[50:51] op_sel_hi:[1,0]
	v_pk_mul_f32 v[42:43], v[42:43], v[50:51] op_sel_hi:[1,0]
	v_pk_mul_f32 v[40:41], v[40:41], v[50:51] op_sel_hi:[1,0]
	v_pk_mul_f32 v[34:35], v[34:35], v[50:51] op_sel_hi:[1,0]
	v_pk_mul_f32 v[32:33], v[32:33], v[50:51] op_sel_hi:[1,0]
	v_pk_mul_f32 v[38:39], v[38:39], v[50:51] op_sel_hi:[1,0]
	v_pk_mul_f32 v[36:37], v[36:37], v[50:51] op_sel_hi:[1,0]
	v_max_f32_e32 v44, 0, v44
	v_max_f32_e32 v40, 0, v40
	v_max_f32_e32 v45, 0, v45
	v_max_f32_e32 v41, 0, v41
	v_max_f32_e32 v46, 0, v46
	v_max_f32_e32 v42, 0, v42
	v_max_f32_e32 v47, 0, v47
	v_max_f32_e32 v43, 0, v43
	v_max_f32_e32 v32, 0, v32
	v_max_f32_e32 v33, 0, v33
	v_max_f32_e32 v34, 0, v34
	v_max_f32_e32 v35, 0, v35
	v_max_f32_e32 v36, 0, v36
	v_max_f32_e32 v37, 0, v37
	v_max_f32_e32 v38, 0, v38
	v_max_f32_e32 v39, 0, v39
	v_mul_f32_e32 v44, v44, v44
	v_mul_f32_e32 v40, v40, v40
	v_mul_f32_e32 v45, v45, v45
	v_mul_f32_e32 v41, v41, v41
	v_mul_f32_e32 v46, v46, v46
	v_mul_f32_e32 v42, v42, v42
	v_mul_f32_e32 v47, v47, v47
	v_mul_f32_e32 v43, v43, v43
	v_mul_f32_e32 v50, v32, v32
	v_mul_f32_e32 v51, v33, v33
	v_mul_f32_e32 v52, v34, v34
	v_mul_f32_e32 v53, v35, v35
	v_cvt_pk_bf16_f32 v32, v44, v45
	v_cvt_pk_bf16_f32 v33, v46, v47
	v_cvt_pk_bf16_f32 v34, v40, v41
	v_cvt_pk_bf16_f32 v35, v42, v43
	v_mul_f32_e32 v36, v36, v36
	v_mul_f32_e32 v37, v37, v37
	v_mul_f32_e32 v38, v38, v38
	v_mul_f32_e32 v39, v39, v39
	buffer_store_dwordx4 v[32:35], v68, s[16:19], 0 offen sc1
	s_nop 1
	v_cvt_pk_bf16_f32 v32, v36, v37
	v_cvt_pk_bf16_f32 v33, v38, v39
	v_cvt_pk_bf16_f32 v34, v50, v51
	v_cvt_pk_bf16_f32 v35, v52, v53
	buffer_store_dwordx4 v[32:35], v68, s[16:19], 0 offen offset:256 sc1
	s_nop 0
	v_add_u32_e32 v48, 0xb0, v146
	v_ashrrev_i32_e32 v49, 31, v48
	v_lshl_add_u32 v52, v64, 13, v147
	s_waitcnt vmcnt(10)
	v_mov_b32_e32 v50, v215
	v_mov_b32_e32 v51, v216
	v_mov_b32_e32 v33, v217
	v_mov_b32_e32 v34, v219
	v_mov_b32_e32 v35, v220
	v_mov_b32_e32 v37, v221
	v_mov_b32_e32 v32, v214
	v_pk_add_f32 v[32:33], v[50:51], v[32:33]
	v_mov_b32_e32 v36, v218
	v_pk_add_f32 v[34:35], v[34:35], v[36:37]
	v_pk_add_f32 v[32:33], v[32:33], v[32:33] op_sel:[0,1] op_sel_hi:[1,0]
	v_pk_add_f32 v[34:35], v[34:35], v[34:35] op_sel:[0,1] op_sel_hi:[1,0]
	v_add_f32_e32 v38, v222, v223
	v_add_f32_e32 v40, v224, v225
	v_mov_b32_e32 v39, v234
	v_mov_b32_e32 v41, v235
	v_mov_b32_e32 v33, v232
	v_mov_b32_e32 v35, v233
	v_pk_add_f32 v[36:37], v[38:39], v[40:41]
	v_pk_add_f32 v[32:33], v[32:33], v[34:35]
	s_nop 0
	v_pk_add_f32 v[32:33], v[32:33], v[36:37]
	s_nop 0
	v_add_f32_e32 v32, v32, v33
	v_fmamk_f32 v32, v32, 0x3a800000, v154
	v_mul_f32_e32 v33, 0x4b800000, v32
	v_cmp_gt_f32_e32 vcc, s71, v32
	s_nop 1
	v_cndmask_b32_e32 v32, v32, v33, vcc
	v_rsq_f32_e32 v34, v32
	v_lshlrev_b64 v[32:33], 6, v[48:49]
	v_lshl_add_u64 v[32:33], s[26:27], 0, v[32:33]
	v_mul_f32_e32 v35, 0x45800000, v34
	v_cndmask_b32_e32 v34, v34, v35, vcc
	v_pk_mul_f32 v[30:31], v[30:31], v[34:35] op_sel_hi:[1,0]
	v_pk_mul_f32 v[28:29], v[28:29], v[34:35] op_sel_hi:[1,0]
	v_pk_mul_f32 v[26:27], v[26:27], v[34:35] op_sel_hi:[1,0]
	v_pk_mul_f32 v[24:25], v[24:25], v[34:35] op_sel_hi:[1,0]
	v_pk_mul_f32 v[18:19], v[18:19], v[34:35] op_sel_hi:[1,0]
	v_pk_mul_f32 v[16:17], v[16:17], v[34:35] op_sel_hi:[1,0]
	v_pk_mul_f32 v[22:23], v[22:23], v[34:35] op_sel_hi:[1,0]
	v_pk_mul_f32 v[20:21], v[20:21], v[34:35] op_sel_hi:[1,0]
	v_max_f32_e32 v28, 0, v28
	v_max_f32_e32 v24, 0, v24
	v_max_f32_e32 v29, 0, v29
	v_max_f32_e32 v25, 0, v25
	v_max_f32_e32 v30, 0, v30
	v_max_f32_e32 v26, 0, v26
	v_max_f32_e32 v31, 0, v31
	v_max_f32_e32 v27, 0, v27
	v_max_f32_e32 v16, 0, v16
	v_max_f32_e32 v17, 0, v17
	v_max_f32_e32 v18, 0, v18
	v_max_f32_e32 v19, 0, v19
	v_max_f32_e32 v20, 0, v20
	v_max_f32_e32 v21, 0, v21
	v_max_f32_e32 v22, 0, v22
	v_max_f32_e32 v23, 0, v23
	v_mul_f32_e32 v28, v28, v28
	v_mul_f32_e32 v24, v24, v24
	v_mul_f32_e32 v29, v29, v29
	v_mul_f32_e32 v25, v25, v25
	v_mul_f32_e32 v30, v30, v30
	v_mul_f32_e32 v26, v26, v26
	v_mul_f32_e32 v31, v31, v31
	v_mul_f32_e32 v27, v27, v27
	v_mul_f32_e32 v34, v16, v16
	v_mul_f32_e32 v35, v17, v17
	v_mul_f32_e32 v36, v18, v18
	v_mul_f32_e32 v37, v19, v19
	v_cvt_pk_bf16_f32 v16, v28, v29
	v_cvt_pk_bf16_f32 v17, v30, v31
	v_cvt_pk_bf16_f32 v18, v24, v25
	v_cvt_pk_bf16_f32 v19, v26, v27
	v_mul_f32_e32 v20, v20, v20
	v_mul_f32_e32 v21, v21, v21
	v_mul_f32_e32 v22, v22, v22
	v_mul_f32_e32 v23, v23, v23
	buffer_store_dwordx4 v[16:19], v52, s[16:19], 0 offen sc1
	s_nop 1
	v_cvt_pk_bf16_f32 v16, v20, v21
	v_cvt_pk_bf16_f32 v17, v22, v23
	v_cvt_pk_bf16_f32 v18, v34, v35
	v_cvt_pk_bf16_f32 v19, v36, v37
	buffer_store_dwordx4 v[16:19], v52, s[16:19], 0 offen offset:256 sc1
	s_nop 0
	s_waitcnt vmcnt(6)
; __device__ __forceinline__ u32x4 pack8(const f32x4 v0, const f32x4 v1) { u32x4 w; w.x = pk2(v0[0], v0[1]); w.y = pk2(v0[2], v0[3]); w.z = pk2(v1[0], v1[1]); w.w = pk2(v1[2], v1[3]); return w; }
; __device__ __forceinline__ float row_rstd(const float* ssq, int row) {
;     const f32x4* p = (const f32x4*)(ssq + (size_t)row * 16);
;     const f32x4 a = p[0], b = p[1], c = p[2], d = p[3];
;     const float s = ((a[0] + a[1]) + (a[2] + a[3])) + ((b[0] + b[1]) + (b[2] + b[3])) + ((c[0] + c[1]) + (c[2] + c[3])) + ((d[0] + d[1]) + (d[2] + d[3]));
;     return rsqrtf(s * (1.0f / 1024.0f) + 1e-6f);
;     __device__ __forceinline__ void operator()(const f32x4 (&acc)[2][2][4][2], const Unit& u, int wr, int wc, int fr, int fq) const {
;     ...
;         for (int ai = 0; ai < 2; ++ai)
; #pragma unroll
;             for (int m = 0; m < 4; ++m) {
;                 const int row = row0 + ai * 128 + m * 16; const float rs = row_rstd(ssq, row);
; #pragma unroll
;                 for (int bj = 0; bj < 2; ++bj) { f32x4 v0 = acc[ai][bj][m][0] * rs, v1 = acc[ai][bj][m][1] * rs;
; #pragma unroll
;                     for (int j = 0; j < 4; ++j) { const float a = fmaxf(v0[j], 0.f), b = fmaxf(v1[j], 0.f); v0[j] = a * a; v1[j] = b * b; }
;                     __builtin_amdgcn_raw_buffer_store_b128(pack8(v0, v1), rsrc, (unsigned)(((size_t)row * DFF + col0 + bj * 128) * 2), 0, 16  ); }
;             }
;         asm volatile("s_waitcnt vmcnt(0)" ::: "memory");
;         if (fr == 0 && fq == 0) (void)__hip_atomic_fetch_add(ready + 64 * (pm_off + u.pm), 1u, __ATOMIC_RELAXED, __HIP_MEMORY_SCOPE_AGENT);
	v_mov_b32_e32 v32, v237
	v_mov_b32_e32 v33, v238
	v_mov_b32_e32 v17, v239
	v_mov_b32_e32 v18, v241
	v_mov_b32_e32 v19, v242
	v_mov_b32_e32 v21, v243
	v_mov_b32_e32 v16, v236
	v_pk_add_f32 v[16:17], v[32:33], v[16:17]
	v_mov_b32_e32 v20, v240
	v_pk_add_f32 v[18:19], v[18:19], v[20:21]
	v_pk_add_f32 v[16:17], v[16:17], v[16:17] op_sel:[0,1] op_sel_hi:[1,0]
	v_pk_add_f32 v[18:19], v[18:19], v[18:19] op_sel:[0,1] op_sel_hi:[1,0]
	v_add_f32_e32 v22, v244, v245
	v_add_f32_e32 v24, v246, v247
	v_mov_b32_e32 v23, v250
	v_mov_b32_e32 v25, v251
	v_mov_b32_e32 v17, v248
	v_mov_b32_e32 v19, v249
	v_pk_add_f32 v[20:21], v[22:23], v[24:25]
	v_pk_add_f32 v[16:17], v[16:17], v[18:19]
	s_nop 0
	v_pk_add_f32 v[16:17], v[16:17], v[20:21]
	s_nop 0
	v_add_f32_e32 v16, v16, v17
	v_fmamk_f32 v16, v16, 0x3a800000, v154
	v_mul_f32_e32 v17, 0x4b800000, v16
	v_cmp_gt_f32_e32 vcc, s71, v16
	s_nop 1
	v_cndmask_b32_e32 v16, v16, v17, vcc
	v_rsq_f32_e32 v16, v16
	v_lshl_add_u32 v17, v48, 13, v147
	v_mul_f32_e32 v18, 0x45800000, v16
	v_cndmask_b32_e32 v16, v16, v18, vcc
	v_pk_mul_f32 v[14:15], v[14:15], v[16:17] op_sel_hi:[1,0]
	v_pk_mul_f32 v[12:13], v[12:13], v[16:17] op_sel_hi:[1,0]
	v_pk_mul_f32 v[10:11], v[10:11], v[16:17] op_sel_hi:[1,0]
	v_pk_mul_f32 v[8:9], v[8:9], v[16:17] op_sel_hi:[1,0]
	v_pk_mul_f32 v[2:3], v[2:3], v[16:17] op_sel_hi:[1,0]
	v_pk_mul_f32 v[0:1], v[0:1], v[16:17] op_sel_hi:[1,0]
	v_pk_mul_f32 v[6:7], v[6:7], v[16:17] op_sel_hi:[1,0]
	v_pk_mul_f32 v[4:5], v[4:5], v[16:17] op_sel_hi:[1,0]
	v_max_f32_e32 v12, 0, v12
	v_max_f32_e32 v8, 0, v8
	v_max_f32_e32 v13, 0, v13
	v_max_f32_e32 v9, 0, v9
	v_max_f32_e32 v14, 0, v14
	v_max_f32_e32 v10, 0, v10
	v_max_f32_e32 v15, 0, v15
	v_max_f32_e32 v11, 0, v11
	v_max_f32_e32 v0, 0, v0
	v_max_f32_e32 v1, 0, v1
	v_max_f32_e32 v2, 0, v2
	v_max_f32_e32 v3, 0, v3
	v_max_f32_e32 v4, 0, v4
	v_max_f32_e32 v5, 0, v5
	v_max_f32_e32 v6, 0, v6
	v_max_f32_e32 v7, 0, v7
	v_mul_f32_e32 v12, v12, v12
	v_mul_f32_e32 v8, v8, v8
	v_mul_f32_e32 v13, v13, v13
	v_mul_f32_e32 v9, v9, v9
	v_mul_f32_e32 v14, v14, v14
	v_mul_f32_e32 v10, v10, v10
	v_mul_f32_e32 v15, v15, v15
	v_mul_f32_e32 v11, v11, v11
	v_mul_f32_e32 v16, v0, v0
	v_mul_f32_e32 v18, v1, v1
	v_mul_f32_e32 v19, v2, v2
	v_mul_f32_e32 v20, v3, v3
	v_cvt_pk_bf16_f32 v0, v12, v13
	v_cvt_pk_bf16_f32 v1, v14, v15
	v_cvt_pk_bf16_f32 v2, v8, v9
	v_cvt_pk_bf16_f32 v3, v10, v11
	v_mul_f32_e32 v4, v4, v4
	v_mul_f32_e32 v5, v5, v5
	v_mul_f32_e32 v6, v6, v6
	v_mul_f32_e32 v7, v7, v7
	buffer_store_dwordx4 v[0:3], v17, s[16:19], 0 offen sc1
	s_nop 1
	v_cvt_pk_bf16_f32 v0, v4, v5
	v_cvt_pk_bf16_f32 v1, v6, v7
	v_cvt_pk_bf16_f32 v2, v16, v18
	v_cvt_pk_bf16_f32 v3, v19, v20
	buffer_store_dwordx4 v[0:3], v17, s[16:19], 0 offen offset:256 sc1
	s_waitcnt vmcnt(0)
	s_and_saveexec_b64 s[40:41], s[10:11]
	s_cbranch_execz .LBB0_950
	s_mov_b64 s[54:55], exec
	v_mbcnt_lo_u32_b32 v0, s54, 0
	v_mbcnt_hi_u32_b32 v0, s55, v0
	v_cmp_eq_u32_e32 vcc, 0, v0
	s_and_b64 s[6:7], exec, vcc
	s_mov_b64 exec, s[6:7]
	s_cbranch_execz .LBB0_950
	s_lshl_b32 s6, s75, 6
	s_ashr_i32 s7, s6, 31
	s_lshl_b64 s[6:7], s[6:7], 2
	s_add_u32 s6, s73, s6
	s_addc_u32 s7, s74, s7
	s_bcnt1_i32_b64 s8, s[54:55]
	v_mov_b32_e32 v0, s8
	global_atomic_add v131, v0, s[6:7]
	s_branch .LBB0_950

; #define PG8_STAGE(bufoff, gbase, voff) do { _Pragma("unroll") for (int _i = 0; _i < 2; ++_i) \
;         __builtin_amdgcn_global_load_lds((const unsigned*)((const char*)(gbase) + (voff)[_i]), (LAS unsigned*)(lds + (bufoff) + ldsw + _i * 8192), 16, 0, 0); } while (0)
; #define PG8_LDA(dst, b, h) do { _Pragma("unroll") for (int m = 0; m < 4; ++m) _Pragma("unroll") for (int k = 0; k < 2; ++k) dst[m][k] = *(const LAS bf16x8*)(lds + PG8_SA(b, h) + aoff + m * 2048 + k * 1024); } while (0)
; #define PG8_LDB(dst, b, h) do { _Pragma("unroll") for (int n = 0; n < 2; ++n) _Pragma("unroll") for (int k = 0; k < 2; ++k) dst[n][k] = *(const LAS bf16x8*)(lds + PG8_SB(b, h) + boff + n * 2048 + k * 1024); } while (0)
; #define PG8_MMA(ai, bj, At, Bt) do { __builtin_amdgcn_s_setprio(1); _Pragma("unroll") for (int m = 0; m < 4; ++m) _Pragma("unroll") for (int n = 0; n < 2; ++n) _Pragma("unroll") for (int k = 0; k < 2; ++k) \
;         acc[ai][bj][m][n] = __builtin_amdgcn_mfma_f32_16x16x32_bf16(Bt[n][k], At[m][k], acc[ai][bj][m][n], 0, 0, 0); __builtin_amdgcn_s_setprio(0); } while (0)
; #define PG8_WAIT_V(n) asm volatile("s_waitcnt vmcnt(" #n ")" ::: "memory")
; #define PG8_WAIT_L(n) asm volatile("s_waitcnt lgkmcnt(" #n ")" ::: "memory")
; #define PG8_BAR __builtin_amdgcn_s_barrier()
; #define PG8_SCHED __builtin_amdgcn_sched_barrier(0)
;     ...
;             PG8_LDB(B0, 0, 0); PG8_SCHED; PG8_LDA(At, 0, 0); PG8_STAGE(PG8_SA(1, 1), a1 + hA, voffA);
;             PG8_WAIT_L(8); PG8_BAR; PG8_WAIT_L(0); PG8_MMA(0, 0, At, B0); PG8_BAR; PG8_SCHED;
;             PG8_LDB(B1, 0, 1); PG8_STAGE(PG8_SB(0, 0), b2, voffB);
;             PG8_BAR; PG8_WAIT_L(0); PG8_MMA(0, 1, At, B1); PG8_BAR;
;             PG8_LDA(At, 0, 1); PG8_STAGE(PG8_SA(0, 0), a2, voffA);
;             PG8_BAR; PG8_WAIT_L(0); PG8_MMA(1, 0, At, B0); PG8_BAR; PG8_SCHED;
;             PG8_STAGE(PG8_SB(0, 1), b2 + hB, voffB);
;             PG8_WAIT_V(6); PG8_BAR; PG8_MMA(1, 1, At, B1); PG8_BAR;
.LBB0_981:
	ds_read_b128 v[150:153], v143
	ds_read_b128 v[154:157], v143 offset:1024
	ds_read_b128 v[158:161], v143 offset:2048
	ds_read_b128 v[162:165], v143 offset:3072
	s_add_u32 s40, s38, 0xfffc0080
	s_addc_u32 s41, s39, -1
	s_cmp_eq_u32 s42, 12
	s_cselect_b32 s55, s7, s41
	s_cselect_b32 s54, s8, s40
	s_cselect_b32 s41, s9, s35
	s_cselect_b32 s40, s25, s33
	v_lshl_add_u64 v[202:203], s[38:39], 0, v[138:139]
	s_add_i32 m0, s61, 0xc000
	ds_read_b128 v[170:173], v146
	ds_read_b128 v[174:177], v146 offset:1024
	ds_read_b128 v[178:181], v146 offset:2048
	ds_read_b128 v[182:185], v146 offset:3072
	ds_read_b128 v[186:189], v146 offset:4096
	ds_read_b128 v[190:193], v146 offset:5120
	ds_read_b128 v[194:197], v146 offset:6144
	ds_read_b128 v[198:201], v146 offset:7168
	global_load_lds_dwordx4 v[202:203], off
	v_lshl_add_u64 v[202:203], s[38:39], 0, v[136:137]
	s_add_i32 m0, s61, 0xe000
	s_nop 0
	global_load_lds_dwordx4 v[202:203], off
	s_waitcnt lgkmcnt(8)
	s_barrier
	s_waitcnt lgkmcnt(0)
	s_setprio 1
	s_waitcnt lgkmcnt(0)
	v_mfma_f32_16x16x32_bf16 v[124:127], v[150:153], v[170:173], v[124:127]
	v_mfma_f32_16x16x32_bf16 v[120:123], v[158:161], v[170:173], v[120:123]
	v_mfma_f32_16x16x32_bf16 v[108:111], v[150:153], v[178:181], v[108:111]
	v_mfma_f32_16x16x32_bf16 v[104:107], v[158:161], v[178:181], v[104:107]
	v_mfma_f32_16x16x32_bf16 v[92:95], v[150:153], v[186:189], v[92:95]
	v_mfma_f32_16x16x32_bf16 v[88:91], v[158:161], v[186:189], v[88:91]
	v_mfma_f32_16x16x32_bf16 v[76:79], v[150:153], v[194:197], v[76:79]
	v_mfma_f32_16x16x32_bf16 v[72:75], v[158:161], v[194:197], v[72:75]
	v_mfma_f32_16x16x32_bf16 v[124:127], v[154:157], v[174:177], v[124:127]
	v_mfma_f32_16x16x32_bf16 v[120:123], v[162:165], v[174:177], v[120:123]
	v_mfma_f32_16x16x32_bf16 v[108:111], v[154:157], v[182:185], v[108:111]
	v_mfma_f32_16x16x32_bf16 v[104:107], v[162:165], v[182:185], v[104:107]
	v_mfma_f32_16x16x32_bf16 v[92:95], v[154:157], v[190:193], v[92:95]
	v_mfma_f32_16x16x32_bf16 v[88:91], v[162:165], v[190:193], v[88:91]
	v_mfma_f32_16x16x32_bf16 v[76:79], v[154:157], v[198:201], v[76:79]
	v_mfma_f32_16x16x32_bf16 v[72:75], v[162:165], v[198:201], v[72:75]
	s_setprio 0
	s_barrier
	s_add_i32 s43, s69, s60
	v_lshl_add_u64 v[218:219], s[40:41], 0, v[130:131]
	s_mov_b32 m0, s43
	ds_read_b128 v[202:205], v147
	ds_read_b128 v[206:209], v147 offset:1024
	ds_read_b128 v[210:213], v147 offset:2048
	ds_read_b128 v[214:217], v147 offset:3072
	global_load_lds_dwordx4 v[218:219], off
	v_lshl_add_u64 v[220:221], s[40:41], 0, v[134:135]
	s_add_i32 m0, s43, 0x2000
	s_nop 0
	global_load_lds_dwordx4 v[220:221], off
	s_barrier
	s_waitcnt lgkmcnt(0)
	s_setprio 1
	s_waitcnt lgkmcnt(0)
	v_mfma_f32_16x16x32_bf16 v[116:119], v[202:205], v[170:173], v[116:119]
	v_mfma_f32_16x16x32_bf16 v[112:115], v[210:213], v[170:173], v[112:115]
	v_mfma_f32_16x16x32_bf16 v[100:103], v[202:205], v[178:181], v[100:103]
	v_mfma_f32_16x16x32_bf16 v[96:99], v[210:213], v[178:181], v[96:99]
	v_mfma_f32_16x16x32_bf16 v[84:87], v[202:205], v[186:189], v[84:87]
	v_mfma_f32_16x16x32_bf16 v[80:83], v[210:213], v[186:189], v[80:83]
	v_mfma_f32_16x16x32_bf16 v[68:71], v[202:205], v[194:197], v[68:71]
	v_mfma_f32_16x16x32_bf16 v[64:67], v[210:213], v[194:197], v[64:67]
	v_mfma_f32_16x16x32_bf16 v[116:119], v[206:209], v[174:177], v[116:119]
	v_mfma_f32_16x16x32_bf16 v[112:115], v[214:217], v[174:177], v[112:115]
	v_mfma_f32_16x16x32_bf16 v[100:103], v[206:209], v[182:185], v[100:103]
	v_mfma_f32_16x16x32_bf16 v[96:99], v[214:217], v[182:185], v[96:99]
	v_mfma_f32_16x16x32_bf16 v[84:87], v[206:209], v[190:193], v[84:87]
	v_mfma_f32_16x16x32_bf16 v[80:83], v[214:217], v[190:193], v[80:83]
	v_mfma_f32_16x16x32_bf16 v[68:71], v[206:209], v[198:201], v[68:71]
	v_mfma_f32_16x16x32_bf16 v[64:67], v[214:217], v[198:201], v[64:67]
	s_setprio 0
	s_mov_b32 m0, s61
	v_lshl_add_u64 v[222:223], s[54:55], 0, v[128:129]
	s_barrier
	ds_read_b128 v[170:173], v146 offset:16384
	ds_read_b128 v[174:177], v146 offset:17408
	ds_read_b128 v[178:181], v146 offset:18432
	ds_read_b128 v[182:185], v146 offset:19456
	ds_read_b128 v[186:189], v146 offset:20480
	ds_read_b128 v[190:193], v146 offset:21504
	ds_read_b128 v[194:197], v146 offset:22528
	ds_read_b128 v[198:201], v146 offset:23552
	global_load_lds_dwordx4 v[222:223], off
	v_lshl_add_u64 v[224:225], s[54:55], 0, v[132:133]
	s_mov_b32 m0, s62
	s_nop 0
	global_load_lds_dwordx4 v[224:225], off
	s_barrier
	s_waitcnt lgkmcnt(0)
	s_setprio 1
	s_waitcnt lgkmcnt(0)
	v_mfma_f32_16x16x32_bf16 v[60:63], v[150:153], v[170:173], v[60:63]
	v_mfma_f32_16x16x32_bf16 v[56:59], v[158:161], v[170:173], v[56:59]
	v_mfma_f32_16x16x32_bf16 v[44:47], v[150:153], v[178:181], v[44:47]
	v_mfma_f32_16x16x32_bf16 v[40:43], v[158:161], v[178:181], v[40:43]
	v_mfma_f32_16x16x32_bf16 v[28:31], v[150:153], v[186:189], v[28:31]
	v_mfma_f32_16x16x32_bf16 v[24:27], v[158:161], v[186:189], v[24:27]
	v_mfma_f32_16x16x32_bf16 v[12:15], v[150:153], v[194:197], v[12:15]
	v_mfma_f32_16x16x32_bf16 v[8:11], v[158:161], v[194:197], v[8:11]
	v_mfma_f32_16x16x32_bf16 v[60:63], v[154:157], v[174:177], v[60:63]
	v_mfma_f32_16x16x32_bf16 v[56:59], v[162:165], v[174:177], v[56:59]
	v_mfma_f32_16x16x32_bf16 v[44:47], v[154:157], v[182:185], v[44:47]
	v_mfma_f32_16x16x32_bf16 v[40:43], v[162:165], v[182:185], v[40:43]
	v_mfma_f32_16x16x32_bf16 v[28:31], v[154:157], v[190:193], v[28:31]
	v_mfma_f32_16x16x32_bf16 v[24:27], v[162:165], v[190:193], v[24:27]
	v_mfma_f32_16x16x32_bf16 v[12:15], v[154:157], v[198:201], v[12:15]
	v_mfma_f32_16x16x32_bf16 v[8:11], v[162:165], v[198:201], v[8:11]
	s_setprio 0
	s_barrier
; #define PG8_STAGE(bufoff, gbase, voff) do { _Pragma("unroll") for (int _i = 0; _i < 2; ++_i) \
;         __builtin_amdgcn_global_load_lds((const unsigned*)((const char*)(gbase) + (voff)[_i]), (LAS unsigned*)(lds + (bufoff) + ldsw + _i * 8192), 16, 0, 0); } while (0)
; #define PG8_LDA(dst, b, h) do { _Pragma("unroll") for (int m = 0; m < 4; ++m) _Pragma("unroll") for (int k = 0; k < 2; ++k) dst[m][k] = *(const LAS bf16x8*)(lds + PG8_SA(b, h) + aoff + m * 2048 + k * 1024); } while (0)
; #define PG8_LDB(dst, b, h) do { _Pragma("unroll") for (int n = 0; n < 2; ++n) _Pragma("unroll") for (int k = 0; k < 2; ++k) dst[n][k] = *(const LAS bf16x8*)(lds + PG8_SB(b, h) + boff + n * 2048 + k * 1024); } while (0)
; #define PG8_MMA(ai, bj, At, Bt) do { __builtin_amdgcn_s_setprio(1); _Pragma("unroll") for (int m = 0; m < 4; ++m) _Pragma("unroll") for (int n = 0; n < 2; ++n) _Pragma("unroll") for (int k = 0; k < 2; ++k) \
;         acc[ai][bj][m][n] = __builtin_amdgcn_mfma_f32_16x16x32_bf16(Bt[n][k], At[m][k], acc[ai][bj][m][n], 0, 0, 0); __builtin_amdgcn_s_setprio(0); } while (0)
; #define PG8_WAIT_V(n) asm volatile("s_waitcnt vmcnt(" #n ")" ::: "memory")
; #define PG8_WAIT_L(n) asm volatile("s_waitcnt lgkmcnt(" #n ")" ::: "memory")
; #define PG8_BAR __builtin_amdgcn_s_barrier()
; #define PG8_SCHED __builtin_amdgcn_sched_barrier(0)
;     ...
;             PG8_WAIT_V(6); PG8_BAR; PG8_MMA(1, 1, At, B1); PG8_BAR;
;             PG8_LDB(B0, 1, 0); PG8_SCHED; PG8_LDA(At, 1, 0); PG8_STAGE(PG8_SA(0, 1), a2 + hA, voffA);
;             PG8_WAIT_L(8); PG8_BAR; PG8_WAIT_L(0); PG8_MMA(0, 0, At, B0); PG8_BAR; PG8_SCHED;
;             PG8_LDB(B1, 1, 1); PG8_STAGE(PG8_SB(1, 0), b3, voffB);
;             PG8_BAR; PG8_WAIT_L(0); PG8_MMA(0, 1, At, B1); PG8_BAR;
;             PG8_LDA(At, 1, 1); PG8_STAGE(PG8_SA(1, 0), a3, voffA);
;             PG8_BAR; PG8_WAIT_L(0); PG8_MMA(1, 0, At, B0); PG8_BAR; PG8_SCHED;
	s_add_u32 s44, s40, 0x40000
	s_addc_u32 s45, s41, 0
	s_add_i32 s43, s70, s60
	v_lshl_add_u64 v[150:151], s[44:45], 0, v[130:131]
	s_mov_b32 m0, s43
	s_nop 0
	global_load_lds_dwordx4 v[150:151], off
	v_lshl_add_u64 v[150:151], s[44:45], 0, v[134:135]
	s_add_i32 m0, s43, 0x2000
	s_nop 0
	global_load_lds_dwordx4 v[150:151], off
	s_waitcnt vmcnt(6)
	s_barrier
	s_setprio 1
	v_mfma_f32_16x16x32_bf16 v[52:55], v[202:205], v[170:173], v[52:55]
	v_mfma_f32_16x16x32_bf16 v[48:51], v[210:213], v[170:173], v[48:51]
	v_mfma_f32_16x16x32_bf16 v[36:39], v[202:205], v[178:181], v[36:39]
	v_mfma_f32_16x16x32_bf16 v[32:35], v[210:213], v[178:181], v[32:35]
	v_mfma_f32_16x16x32_bf16 v[20:23], v[202:205], v[186:189], v[20:23]
	v_mfma_f32_16x16x32_bf16 v[16:19], v[210:213], v[186:189], v[16:19]
	v_mfma_f32_16x16x32_bf16 v[4:7], v[202:205], v[194:197], v[4:7]
	v_mfma_f32_16x16x32_bf16 v[0:3], v[210:213], v[194:197], v[0:3]
	v_mfma_f32_16x16x32_bf16 v[52:55], v[206:209], v[174:177], v[52:55]
	v_mfma_f32_16x16x32_bf16 v[48:51], v[214:217], v[174:177], v[48:51]
	v_mfma_f32_16x16x32_bf16 v[36:39], v[206:209], v[182:185], v[36:39]
	v_mfma_f32_16x16x32_bf16 v[32:35], v[214:217], v[182:185], v[32:35]
	v_mfma_f32_16x16x32_bf16 v[20:23], v[206:209], v[190:193], v[20:23]
	v_mfma_f32_16x16x32_bf16 v[16:19], v[214:217], v[190:193], v[16:19]
	v_mfma_f32_16x16x32_bf16 v[4:7], v[206:209], v[198:201], v[4:7]
	v_mfma_f32_16x16x32_bf16 v[0:3], v[214:217], v[198:201], v[0:3]
	s_setprio 0
	s_add_i32 s43, 0, 0x18000
	v_add_u32_e32 v149, s43, v141
	s_barrier
	ds_read_b128 v[150:153], v149
	ds_read_b128 v[154:157], v149 offset:1024
	ds_read_b128 v[158:161], v149 offset:2048
	ds_read_b128 v[162:165], v149 offset:3072
	s_add_u32 s44, s54, 0x40000
	s_addc_u32 s45, s55, 0
	s_mov_b32 m0, s63
	v_lshl_add_u64 v[202:203], s[44:45], 0, v[128:129]
	ds_read_b128 v[170:173], v146 offset:32768
	ds_read_b128 v[174:177], v146 offset:33792
	ds_read_b128 v[178:181], v146 offset:34816
	ds_read_b128 v[182:185], v146 offset:35840
	ds_read_b128 v[186:189], v146 offset:36864
	ds_read_b128 v[190:193], v146 offset:37888
	ds_read_b128 v[194:197], v146 offset:38912
	ds_read_b128 v[198:201], v146 offset:39936
	global_load_lds_dwordx4 v[202:203], off
	v_lshl_add_u64 v[202:203], s[44:45], 0, v[132:133]
	s_mov_b32 m0, s64
	s_nop 0
	global_load_lds_dwordx4 v[202:203], off
	s_waitcnt lgkmcnt(8)
	s_barrier
	s_waitcnt lgkmcnt(0)
	s_setprio 1
	s_waitcnt lgkmcnt(0)
	v_mfma_f32_16x16x32_bf16 v[124:127], v[150:153], v[170:173], v[124:127]
	v_mfma_f32_16x16x32_bf16 v[120:123], v[158:161], v[170:173], v[120:123]
	v_mfma_f32_16x16x32_bf16 v[108:111], v[150:153], v[178:181], v[108:111]
	v_mfma_f32_16x16x32_bf16 v[104:107], v[158:161], v[178:181], v[104:107]
	v_mfma_f32_16x16x32_bf16 v[92:95], v[150:153], v[186:189], v[92:95]
	v_mfma_f32_16x16x32_bf16 v[88:91], v[158:161], v[186:189], v[88:91]
	v_mfma_f32_16x16x32_bf16 v[76:79], v[150:153], v[194:197], v[76:79]
	v_mfma_f32_16x16x32_bf16 v[72:75], v[158:161], v[194:197], v[72:75]
	v_mfma_f32_16x16x32_bf16 v[124:127], v[154:157], v[174:177], v[124:127]
	v_mfma_f32_16x16x32_bf16 v[120:123], v[162:165], v[174:177], v[120:123]
	v_mfma_f32_16x16x32_bf16 v[108:111], v[154:157], v[182:185], v[108:111]
	v_mfma_f32_16x16x32_bf16 v[104:107], v[162:165], v[182:185], v[104:107]
	v_mfma_f32_16x16x32_bf16 v[92:95], v[154:157], v[190:193], v[92:95]
	v_mfma_f32_16x16x32_bf16 v[88:91], v[162:165], v[190:193], v[88:91]
	v_mfma_f32_16x16x32_bf16 v[76:79], v[154:157], v[198:201], v[76:79]
	v_mfma_f32_16x16x32_bf16 v[72:75], v[162:165], v[198:201], v[72:75]
	s_setprio 0
	s_barrier
	s_add_i32 s44, 0, 0x1c000
	s_add_i32 s43, s43, s60
	v_add_u32_e32 v149, s44, v141
	v_lshl_add_u64 v[218:219], v[218:219], 0, s[26:27]
	s_mov_b32 m0, s43
	ds_read_b128 v[202:205], v149
	ds_read_b128 v[206:209], v149 offset:1024
	ds_read_b128 v[210:213], v149 offset:2048
	ds_read_b128 v[214:217], v149 offset:3072
	global_load_lds_dwordx4 v[218:219], off
	v_lshl_add_u64 v[218:219], v[220:221], 0, s[26:27]
	s_add_i32 m0, s43, 0x2000
	s_nop 0
	global_load_lds_dwordx4 v[218:219], off
	s_barrier
	s_waitcnt lgkmcnt(0)
	s_setprio 1
	s_waitcnt lgkmcnt(0)
	v_mfma_f32_16x16x32_bf16 v[116:119], v[202:205], v[170:173], v[116:119]
	v_mfma_f32_16x16x32_bf16 v[112:115], v[210:213], v[170:173], v[112:115]
	v_mfma_f32_16x16x32_bf16 v[100:103], v[202:205], v[178:181], v[100:103]
	v_mfma_f32_16x16x32_bf16 v[96:99], v[210:213], v[178:181], v[96:99]
	v_mfma_f32_16x16x32_bf16 v[84:87], v[202:205], v[186:189], v[84:87]
	v_mfma_f32_16x16x32_bf16 v[80:83], v[210:213], v[186:189], v[80:83]
	v_mfma_f32_16x16x32_bf16 v[68:71], v[202:205], v[194:197], v[68:71]
	v_mfma_f32_16x16x32_bf16 v[64:67], v[210:213], v[194:197], v[64:67]
	v_mfma_f32_16x16x32_bf16 v[116:119], v[206:209], v[174:177], v[116:119]
	v_mfma_f32_16x16x32_bf16 v[112:115], v[214:217], v[174:177], v[112:115]
	v_mfma_f32_16x16x32_bf16 v[100:103], v[206:209], v[182:185], v[100:103]
	v_mfma_f32_16x16x32_bf16 v[96:99], v[214:217], v[182:185], v[96:99]
	v_mfma_f32_16x16x32_bf16 v[84:87], v[206:209], v[190:193], v[84:87]
	v_mfma_f32_16x16x32_bf16 v[80:83], v[214:217], v[190:193], v[80:83]
	v_mfma_f32_16x16x32_bf16 v[68:71], v[206:209], v[198:201], v[68:71]
	v_mfma_f32_16x16x32_bf16 v[64:67], v[214:217], v[198:201], v[64:67]
	s_setprio 0
	s_mov_b32 m0, s66
	v_lshl_add_u64 v[218:219], v[222:223], 0, s[26:27]
	s_barrier
	ds_read_b128 v[170:173], v146 offset:49152
	ds_read_b128 v[174:177], v146 offset:50176
	ds_read_b128 v[178:181], v146 offset:51200
	ds_read_b128 v[182:185], v146 offset:52224
	ds_read_b128 v[186:189], v146 offset:53248
	ds_read_b128 v[190:193], v146 offset:54272
	ds_read_b128 v[194:197], v146 offset:55296
	ds_read_b128 v[198:201], v146 offset:56320
	global_load_lds_dwordx4 v[218:219], off
	v_lshl_add_u64 v[218:219], v[224:225], 0, s[26:27]
	s_mov_b32 m0, s67
	s_nop 0
	global_load_lds_dwordx4 v[218:219], off
	s_barrier
; #define PG8_STAGE(bufoff, gbase, voff) do { _Pragma("unroll") for (int _i = 0; _i < 2; ++_i) \
;         __builtin_amdgcn_global_load_lds((const unsigned*)((const char*)(gbase) + (voff)[_i]), (LAS unsigned*)(lds + (bufoff) + ldsw + _i * 8192), 16, 0, 0); } while (0)
; #define PG8_LDA(dst, b, h) do { _Pragma("unroll") for (int m = 0; m < 4; ++m) _Pragma("unroll") for (int k = 0; k < 2; ++k) dst[m][k] = *(const LAS bf16x8*)(lds + PG8_SA(b, h) + aoff + m * 2048 + k * 1024); } while (0)
; #define PG8_LDB(dst, b, h) do { _Pragma("unroll") for (int n = 0; n < 2; ++n) _Pragma("unroll") for (int k = 0; k < 2; ++k) dst[n][k] = *(const LAS bf16x8*)(lds + PG8_SB(b, h) + boff + n * 2048 + k * 1024); } while (0)
; #define PG8_MMA(ai, bj, At, Bt) do { __builtin_amdgcn_s_setprio(1); _Pragma("unroll") for (int m = 0; m < 4; ++m) _Pragma("unroll") for (int n = 0; n < 2; ++n) _Pragma("unroll") for (int k = 0; k < 2; ++k) \
;         acc[ai][bj][m][n] = __builtin_amdgcn_mfma_f32_16x16x32_bf16(Bt[n][k], At[m][k], acc[ai][bj][m][n], 0, 0, 0); __builtin_amdgcn_s_setprio(0); } while (0)
; #define PG8_WAIT_V(n) asm volatile("s_waitcnt vmcnt(" #n ")" ::: "memory")
; #define PG8_WAIT_L(n) asm volatile("s_waitcnt lgkmcnt(" #n ")" ::: "memory")
; #define PG8_BAR __builtin_amdgcn_s_barrier()
; #define PG8_SCHED __builtin_amdgcn_sched_barrier(0)
;     ...
;             PG8_WAIT_L(8); PG8_BAR; PG8_WAIT_L(0); PG8_MMA(0, 0, At, B0); PG8_BAR; PG8_SCHED;
;             PG8_LDB(B1, 1, 1); PG8_STAGE(PG8_SB(1, 0), b3, voffB);
;             PG8_BAR; PG8_WAIT_L(0); PG8_MMA(0, 1, At, B1); PG8_BAR;
;             PG8_LDA(At, 1, 1); PG8_STAGE(PG8_SA(1, 0), a3, voffA);
;             PG8_BAR; PG8_WAIT_L(0); PG8_MMA(1, 0, At, B0); PG8_BAR; PG8_SCHED;
;             PG8_STAGE(PG8_SB(1, 1), b3 + hB, voffB);
;             PG8_WAIT_V(6); PG8_BAR; PG8_MMA(1, 1, At, B1); PG8_BAR;
; __device__ __forceinline__ float row_rstd(const float* ssq, int row) {
;     const f32x4* p = (const f32x4*)(ssq + (size_t)row * 16);
;     const f32x4 a = p[0], b = p[1], c = p[2], d = p[3];
;     const float s = ((a[0] + a[1]) + (a[2] + a[3])) + ((b[0] + b[1]) + (b[2] + b[3])) + ((c[0] + c[1]) + (c[2] + c[3])) + ((d[0] + d[1]) + (d[2] + d[3]));
;     return rsqrtf(s * (1.0f / 1024.0f) + 1e-6f);
	s_waitcnt lgkmcnt(0)
	s_setprio 1
	s_waitcnt lgkmcnt(0)
	v_mfma_f32_16x16x32_bf16 v[60:63], v[150:153], v[170:173], v[60:63]
	v_mfma_f32_16x16x32_bf16 v[56:59], v[158:161], v[170:173], v[56:59]
	v_mfma_f32_16x16x32_bf16 v[44:47], v[150:153], v[178:181], v[44:47]
	v_mfma_f32_16x16x32_bf16 v[40:43], v[158:161], v[178:181], v[40:43]
	v_mfma_f32_16x16x32_bf16 v[28:31], v[150:153], v[186:189], v[28:31]
	v_mfma_f32_16x16x32_bf16 v[24:27], v[158:161], v[186:189], v[24:27]
	v_mfma_f32_16x16x32_bf16 v[12:15], v[150:153], v[194:197], v[12:15]
	v_mfma_f32_16x16x32_bf16 v[8:11], v[158:161], v[194:197], v[8:11]
	v_mfma_f32_16x16x32_bf16 v[60:63], v[154:157], v[174:177], v[60:63]
	v_mfma_f32_16x16x32_bf16 v[56:59], v[162:165], v[174:177], v[56:59]
	v_mfma_f32_16x16x32_bf16 v[44:47], v[154:157], v[182:185], v[44:47]
	v_mfma_f32_16x16x32_bf16 v[40:43], v[162:165], v[182:185], v[40:43]
	v_mfma_f32_16x16x32_bf16 v[28:31], v[154:157], v[190:193], v[28:31]
	v_mfma_f32_16x16x32_bf16 v[24:27], v[162:165], v[190:193], v[24:27]
	v_mfma_f32_16x16x32_bf16 v[12:15], v[154:157], v[198:201], v[12:15]
	v_mfma_f32_16x16x32_bf16 v[8:11], v[162:165], v[198:201], v[8:11]
	s_setprio 0
	s_barrier
	s_add_u32 s40, s40, 0x40080
	s_addc_u32 s41, s41, 0
	s_add_i32 s43, s44, s60
	v_lshl_add_u64 v[150:151], s[40:41], 0, v[130:131]
	s_mov_b32 m0, s43
	s_nop 0
	global_load_lds_dwordx4 v[150:151], off
	v_lshl_add_u64 v[150:151], s[40:41], 0, v[134:135]
	s_add_i32 m0, s43, 0x2000
	s_nop 0
	global_load_lds_dwordx4 v[150:151], off
	s_waitcnt vmcnt(6)
	s_barrier
	s_setprio 1
	v_mfma_f32_16x16x32_bf16 v[52:55], v[202:205], v[170:173], v[52:55]
	v_mfma_f32_16x16x32_bf16 v[48:51], v[210:213], v[170:173], v[48:51]
	v_mfma_f32_16x16x32_bf16 v[36:39], v[202:205], v[178:181], v[36:39]
	v_mfma_f32_16x16x32_bf16 v[32:35], v[210:213], v[178:181], v[32:35]
	v_mfma_f32_16x16x32_bf16 v[20:23], v[202:205], v[186:189], v[20:23]
	v_mfma_f32_16x16x32_bf16 v[16:19], v[210:213], v[186:189], v[16:19]
	v_mfma_f32_16x16x32_bf16 v[4:7], v[202:205], v[194:197], v[4:7]
	v_mfma_f32_16x16x32_bf16 v[0:3], v[210:213], v[194:197], v[0:3]
	v_mfma_f32_16x16x32_bf16 v[52:55], v[206:209], v[174:177], v[52:55]
	v_mfma_f32_16x16x32_bf16 v[48:51], v[214:217], v[174:177], v[48:51]
	v_mfma_f32_16x16x32_bf16 v[36:39], v[206:209], v[182:185], v[36:39]
	v_mfma_f32_16x16x32_bf16 v[32:35], v[214:217], v[182:185], v[32:35]
	v_mfma_f32_16x16x32_bf16 v[20:23], v[206:209], v[190:193], v[20:23]
	v_mfma_f32_16x16x32_bf16 v[16:19], v[214:217], v[190:193], v[16:19]
	v_mfma_f32_16x16x32_bf16 v[4:7], v[206:209], v[198:201], v[4:7]
	v_mfma_f32_16x16x32_bf16 v[0:3], v[214:217], v[198:201], v[0:3]
	s_setprio 0
	s_add_i32 s42, s42, 2
	s_add_u32 s33, s33, 0x100
	s_addc_u32 s35, s35, 0
	s_add_u32 s38, s38, 0x100
	s_addc_u32 s39, s39, 0
	s_cmp_gt_u32 s42, 13
	s_barrier
	s_cbranch_scc0 .LBB0_981
	v_lshl_add_u32 v150, s75, 8, v140
	v_add_u32_e32 v164, 0x4000, v150
	v_ashrrev_i32_e32 v165, 31, v164
	v_lshlrev_b64 v[152:153], 6, v[164:165]
	v_lshl_add_u64 v[170:171], s[18:19], 0, v[152:153]
	v_subrev_u32_e32 v176, s18, v170
	v_add_u32_e32 v177, 0x0, v176
	global_load_dwordx4 v[178:181], v177, s[18:19]
	v_add_u32_e32 v177, 0x10, v176
	global_load_dwordx4 v[182:185], v177, s[18:19]
	v_add_u32_e32 v177, 0x20, v176
	global_load_dwordx4 v[186:189], v177, s[18:19]
	v_add_u32_e32 v177, 0x30, v176
	global_load_dwordx4 v[190:193], v177, s[18:19]
	v_add_u32_e32 v177, 0x400, v176
	global_load_dwordx4 v[194:197], v177, s[18:19]
	v_add_u32_e32 v177, 0x410, v176
	global_load_dwordx4 v[198:201], v177, s[18:19]
	v_add_u32_e32 v177, 0x420, v176
	global_load_dwordx4 v[202:205], v177, s[18:19]
	v_add_u32_e32 v177, 0x430, v176
	global_load_dwordx4 v[206:209], v177, s[18:19]
	v_add_u32_e32 v177, 0x800, v176
	global_load_dwordx4 v[210:213], v177, s[18:19]
	v_add_u32_e32 v177, 0x810, v176
	global_load_dwordx4 v[214:217], v177, s[18:19]
	v_add_u32_e32 v177, 0x820, v176
	global_load_dwordx4 v[232:235], v177, s[18:19]
	v_add_u32_e32 v177, 0x830, v176
	global_load_dwordx4 v[236:239], v177, s[18:19]
	v_add_u32_e32 v177, 0xc00, v176
	global_load_dwordx4 v[240:243], v177, s[18:19]
	v_add_u32_e32 v177, 0xc10, v176
	global_load_dwordx4 v[244:247], v177, s[18:19]
	v_add_u32_e32 v177, 0xc20, v176
	global_load_dwordx4 v[248:251], v177, s[18:19]
	v_add_u32_e32 v177, 0xc30, v176
	global_load_dwordx4 v[252:255], v177, s[18:19]
	s_nop 0
	v_lshl_or_b32 v149, s6, 9, v142
	v_lshl_add_u32 v151, v164, 13, v149
	v_add_u32_e32 v174, 0x4010, v150
	v_ashrrev_i32_e32 v175, 31, v174
	s_waitcnt vmcnt(12)
; __device__ __forceinline__ u32x4 pack8(const f32x4 v0, const f32x4 v1) { u32x4 w; w.x = pk2(v0[0], v0[1]); w.y = pk2(v0[2], v0[3]); w.z = pk2(v1[0], v1[1]); w.w = pk2(v1[2], v1[3]); return w; }
; __device__ __forceinline__ float row_rstd(const float* ssq, int row) {
;     const f32x4* p = (const f32x4*)(ssq + (size_t)row * 16);
;     const f32x4 a = p[0], b = p[1], c = p[2], d = p[3];
;     const float s = ((a[0] + a[1]) + (a[2] + a[3])) + ((b[0] + b[1]) + (b[2] + b[3])) + ((c[0] + c[1]) + (c[2] + c[3])) + ((d[0] + d[1]) + (d[2] + d[3]));
;     return rsqrtf(s * (1.0f / 1024.0f) + 1e-6f);
;     __device__ __forceinline__ void operator()(const f32x4 (&acc)[2][2][4][2], const Unit& u, int wr, int wc, int fr, int fq) const {
;     ...
;         for (int ai = 0; ai < 2; ++ai)
; #pragma unroll
;             for (int m = 0; m < 4; ++m) {
;                 const int row = row0 + ai * 128 + m * 16; const float rs = row_rstd(ssq, row);
; #pragma unroll
;                 for (int bj = 0; bj < 2; ++bj) { f32x4 v0 = acc[ai][bj][m][0] * rs, v1 = acc[ai][bj][m][1] * rs;
; #pragma unroll
;                     for (int j = 0; j < 4; ++j) { const float a = fmaxf(v0[j], 0.f), b = fmaxf(v1[j], 0.f); v0[j] = a * a; v1[j] = b * b; }
;                     __builtin_amdgcn_raw_buffer_store_b128(pack8(v0, v1), rsrc, (unsigned)(((size_t)row * DFF + col0 + bj * 128) * 2), 0, 16  ); }
	v_mov_b32_e32 v164, v179
	v_mov_b32_e32 v165, v180
	v_mov_b32_e32 v153, v181
	v_mov_b32_e32 v154, v183
	v_mov_b32_e32 v155, v184
	v_mov_b32_e32 v157, v185
	v_mov_b32_e32 v152, v178
	v_pk_add_f32 v[152:153], v[164:165], v[152:153]
	v_mov_b32_e32 v156, v182
	v_pk_add_f32 v[154:155], v[154:155], v[156:157]
	v_pk_add_f32 v[152:153], v[152:153], v[152:153] op_sel:[0,1] op_sel_hi:[1,0]
	v_pk_add_f32 v[154:155], v[154:155], v[154:155] op_sel:[0,1] op_sel_hi:[1,0]
	v_add_f32_e32 v158, v186, v187
	v_add_f32_e32 v160, v188, v189
	v_mov_b32_e32 v159, v192
	v_mov_b32_e32 v161, v193
	v_mov_b32_e32 v153, v190
	v_mov_b32_e32 v155, v191
	v_pk_add_f32 v[156:157], v[158:159], v[160:161]
	v_pk_add_f32 v[152:153], v[152:153], v[154:155]
	s_nop 0
	v_pk_add_f32 v[152:153], v[152:153], v[156:157]
	s_nop 0
	v_add_f32_e32 v152, v152, v153
	v_fmamk_f32 v152, v152, 0x3a800000, v148
	v_mul_f32_e32 v153, 0x4b800000, v152
	v_cmp_gt_f32_e32 vcc, s71, v152
	s_nop 1
	v_cndmask_b32_e32 v152, v152, v153, vcc
	v_rsq_f32_e32 v154, v152
	v_lshlrev_b64 v[152:153], 6, v[174:175]
	v_lshl_add_u64 v[152:153], s[18:19], 0, v[152:153]
	v_mul_f32_e32 v155, 0x45800000, v154
	v_cndmask_b32_e32 v154, v154, v155, vcc
	v_pk_mul_f32 v[126:127], v[126:127], v[154:155] op_sel_hi:[1,0]
	v_pk_mul_f32 v[124:125], v[124:125], v[154:155] op_sel_hi:[1,0]
	v_pk_mul_f32 v[122:123], v[122:123], v[154:155] op_sel_hi:[1,0]
	v_pk_mul_f32 v[120:121], v[120:121], v[154:155] op_sel_hi:[1,0]
	v_pk_mul_f32 v[114:115], v[114:115], v[154:155] op_sel_hi:[1,0]
	v_pk_mul_f32 v[112:113], v[112:113], v[154:155] op_sel_hi:[1,0]
	v_pk_mul_f32 v[118:119], v[118:119], v[154:155] op_sel_hi:[1,0]
	v_pk_mul_f32 v[116:117], v[116:117], v[154:155] op_sel_hi:[1,0]
	v_max_f32_e32 v124, 0, v124
	v_max_f32_e32 v120, 0, v120
	v_max_f32_e32 v125, 0, v125
	v_max_f32_e32 v121, 0, v121
	v_max_f32_e32 v126, 0, v126
	v_max_f32_e32 v122, 0, v122
	v_max_f32_e32 v127, 0, v127
	v_max_f32_e32 v123, 0, v123
	v_max_f32_e32 v112, 0, v112
	v_max_f32_e32 v113, 0, v113
	v_max_f32_e32 v114, 0, v114
	v_max_f32_e32 v115, 0, v115
	v_max_f32_e32 v116, 0, v116
	v_max_f32_e32 v117, 0, v117
	v_max_f32_e32 v118, 0, v118
	v_max_f32_e32 v119, 0, v119
	v_mul_f32_e32 v124, v124, v124
	v_mul_f32_e32 v120, v120, v120
	v_mul_f32_e32 v125, v125, v125
	v_mul_f32_e32 v121, v121, v121
	v_mul_f32_e32 v126, v126, v126
	v_mul_f32_e32 v122, v122, v122
	v_mul_f32_e32 v127, v127, v127
	v_mul_f32_e32 v123, v123, v123
	v_mul_f32_e32 v154, v112, v112
	v_mul_f32_e32 v155, v113, v113
	v_mul_f32_e32 v156, v114, v114
	v_mul_f32_e32 v157, v115, v115
	v_cvt_pk_bf16_f32 v112, v124, v125
	v_cvt_pk_bf16_f32 v113, v126, v127
	v_cvt_pk_bf16_f32 v114, v120, v121
	v_cvt_pk_bf16_f32 v115, v122, v123
	v_mul_f32_e32 v116, v116, v116
	v_mul_f32_e32 v117, v117, v117
	v_mul_f32_e32 v118, v118, v118
	v_mul_f32_e32 v119, v119, v119
	buffer_store_dwordx4 v[112:115], v151, s[12:15], 0 offen sc1
	s_nop 1
	v_cvt_pk_bf16_f32 v112, v116, v117
	v_cvt_pk_bf16_f32 v113, v118, v119
	v_cvt_pk_bf16_f32 v114, v154, v155
	v_cvt_pk_bf16_f32 v115, v156, v157
	buffer_store_dwordx4 v[112:115], v151, s[12:15], 0 offen offset:256 sc1
	s_nop 0
	v_add_u32_e32 v152, 0x4020, v150
	v_ashrrev_i32_e32 v153, 31, v152
	v_lshl_add_u32 v151, v174, 13, v149
	v_add_u32_e32 v177, 0x2000, v176
	global_load_dwordx4 v[178:181], v177, s[18:19]
	v_add_u32_e32 v177, 0x2010, v176
	global_load_dwordx4 v[182:185], v177, s[18:19]
	v_add_u32_e32 v177, 0x2020, v176
	global_load_dwordx4 v[186:189], v177, s[18:19]
	v_add_u32_e32 v177, 0x2030, v176
	global_load_dwordx4 v[190:193], v177, s[18:19]
	s_waitcnt vmcnt(14)
	v_mov_b32_e32 v154, v195
	v_mov_b32_e32 v155, v196
	v_mov_b32_e32 v113, v197
	v_mov_b32_e32 v114, v199
	v_mov_b32_e32 v115, v200
	v_mov_b32_e32 v117, v201
	v_mov_b32_e32 v112, v194
	v_pk_add_f32 v[112:113], v[154:155], v[112:113]
	v_mov_b32_e32 v116, v198
	v_pk_add_f32 v[114:115], v[114:115], v[116:117]
	v_pk_add_f32 v[112:113], v[112:113], v[112:113] op_sel:[0,1] op_sel_hi:[1,0]
	v_pk_add_f32 v[114:115], v[114:115], v[114:115] op_sel:[0,1] op_sel_hi:[1,0]
	v_add_f32_e32 v118, v202, v203
	v_add_f32_e32 v120, v204, v205
	v_mov_b32_e32 v119, v208
	v_mov_b32_e32 v121, v209
	v_mov_b32_e32 v113, v206
	v_mov_b32_e32 v115, v207
	v_pk_add_f32 v[116:117], v[118:119], v[120:121]
	v_pk_add_f32 v[112:113], v[112:113], v[114:115]
	s_nop 0
	v_pk_add_f32 v[112:113], v[112:113], v[116:117]
	s_nop 0
	v_add_f32_e32 v112, v112, v113
	v_fmamk_f32 v112, v112, 0x3a800000, v148
	v_mul_f32_e32 v113, 0x4b800000, v112
	v_cmp_gt_f32_e32 vcc, s71, v112
	s_nop 1
	v_cndmask_b32_e32 v112, v112, v113, vcc
	v_rsq_f32_e32 v114, v112
	v_lshlrev_b64 v[112:113], 6, v[152:153]
	v_lshl_add_u64 v[112:113], s[18:19], 0, v[112:113]
	v_mul_f32_e32 v115, 0x45800000, v114
	v_cndmask_b32_e32 v114, v114, v115, vcc
	v_pk_mul_f32 v[110:111], v[110:111], v[114:115] op_sel_hi:[1,0]
	v_pk_mul_f32 v[108:109], v[108:109], v[114:115] op_sel_hi:[1,0]
	v_pk_mul_f32 v[106:107], v[106:107], v[114:115] op_sel_hi:[1,0]
	v_pk_mul_f32 v[104:105], v[104:105], v[114:115] op_sel_hi:[1,0]
	v_pk_mul_f32 v[98:99], v[98:99], v[114:115] op_sel_hi:[1,0]
	v_pk_mul_f32 v[96:97], v[96:97], v[114:115] op_sel_hi:[1,0]
	v_pk_mul_f32 v[102:103], v[102:103], v[114:115] op_sel_hi:[1,0]
	v_pk_mul_f32 v[100:101], v[100:101], v[114:115] op_sel_hi:[1,0]
	v_max_f32_e32 v108, 0, v108
	v_max_f32_e32 v104, 0, v104
	v_max_f32_e32 v109, 0, v109
	v_max_f32_e32 v105, 0, v105
	v_max_f32_e32 v110, 0, v110
	v_max_f32_e32 v106, 0, v106
	v_max_f32_e32 v111, 0, v111
	v_max_f32_e32 v107, 0, v107
	v_max_f32_e32 v96, 0, v96
	v_max_f32_e32 v97, 0, v97
	v_max_f32_e32 v98, 0, v98
	v_max_f32_e32 v99, 0, v99
	v_max_f32_e32 v100, 0, v100
; __device__ __forceinline__ u32x4 pack8(const f32x4 v0, const f32x4 v1) { u32x4 w; w.x = pk2(v0[0], v0[1]); w.y = pk2(v0[2], v0[3]); w.z = pk2(v1[0], v1[1]); w.w = pk2(v1[2], v1[3]); return w; }
; __device__ __forceinline__ float row_rstd(const float* ssq, int row) {
;     const f32x4* p = (const f32x4*)(ssq + (size_t)row * 16);
;     const f32x4 a = p[0], b = p[1], c = p[2], d = p[3];
;     const float s = ((a[0] + a[1]) + (a[2] + a[3])) + ((b[0] + b[1]) + (b[2] + b[3])) + ((c[0] + c[1]) + (c[2] + c[3])) + ((d[0] + d[1]) + (d[2] + d[3]));
;     return rsqrtf(s * (1.0f / 1024.0f) + 1e-6f);
;     __device__ __forceinline__ void operator()(const f32x4 (&acc)[2][2][4][2], const Unit& u, int wr, int wc, int fr, int fq) const {
;     ...
;         for (int ai = 0; ai < 2; ++ai)
; #pragma unroll
;             for (int m = 0; m < 4; ++m) {
;                 const int row = row0 + ai * 128 + m * 16; const float rs = row_rstd(ssq, row);
; #pragma unroll
;                 for (int bj = 0; bj < 2; ++bj) { f32x4 v0 = acc[ai][bj][m][0] * rs, v1 = acc[ai][bj][m][1] * rs;
; #pragma unroll
;                     for (int j = 0; j < 4; ++j) { const float a = fmaxf(v0[j], 0.f), b = fmaxf(v1[j], 0.f); v0[j] = a * a; v1[j] = b * b; }
;                     __builtin_amdgcn_raw_buffer_store_b128(pack8(v0, v1), rsrc, (unsigned)(((size_t)row * DFF + col0 + bj * 128) * 2), 0, 16  ); }
	v_max_f32_e32 v101, 0, v101
	v_max_f32_e32 v102, 0, v102
	v_max_f32_e32 v103, 0, v103
	v_mul_f32_e32 v108, v108, v108
	v_mul_f32_e32 v104, v104, v104
	v_mul_f32_e32 v109, v109, v109
	v_mul_f32_e32 v105, v105, v105
	v_mul_f32_e32 v110, v110, v110
	v_mul_f32_e32 v106, v106, v106
	v_mul_f32_e32 v111, v111, v111
	v_mul_f32_e32 v107, v107, v107
	v_mul_f32_e32 v114, v96, v96
	v_mul_f32_e32 v115, v97, v97
	v_mul_f32_e32 v116, v98, v98
	v_mul_f32_e32 v117, v99, v99
	v_cvt_pk_bf16_f32 v96, v108, v109
	v_cvt_pk_bf16_f32 v97, v110, v111
	v_cvt_pk_bf16_f32 v98, v104, v105
	v_cvt_pk_bf16_f32 v99, v106, v107
	v_mul_f32_e32 v100, v100, v100
	v_mul_f32_e32 v101, v101, v101
	v_mul_f32_e32 v102, v102, v102
	v_mul_f32_e32 v103, v103, v103
	buffer_store_dwordx4 v[96:99], v151, s[12:15], 0 offen sc1
	s_nop 1
	v_cvt_pk_bf16_f32 v96, v100, v101
	v_cvt_pk_bf16_f32 v97, v102, v103
	v_cvt_pk_bf16_f32 v98, v114, v115
	v_cvt_pk_bf16_f32 v99, v116, v117
	buffer_store_dwordx4 v[96:99], v151, s[12:15], 0 offen offset:256 sc1
	s_nop 0
	v_add_u32_e32 v112, 0x4030, v150
	v_ashrrev_i32_e32 v113, 31, v112
	v_lshl_add_u32 v116, v152, 13, v149
	v_add_u32_e32 v177, 0x2400, v176
	global_load_dwordx4 v[194:197], v177, s[18:19]
	v_add_u32_e32 v177, 0x2410, v176
	global_load_dwordx4 v[198:201], v177, s[18:19]
	v_add_u32_e32 v177, 0x2420, v176
	global_load_dwordx4 v[202:205], v177, s[18:19]
	v_add_u32_e32 v177, 0x2430, v176
	global_load_dwordx4 v[206:209], v177, s[18:19]
	s_waitcnt vmcnt(16)
	v_mov_b32_e32 v114, v211
	v_mov_b32_e32 v115, v212
	v_mov_b32_e32 v97, v213
	v_mov_b32_e32 v98, v215
	v_mov_b32_e32 v99, v216
	v_mov_b32_e32 v101, v217
	v_mov_b32_e32 v96, v210
	v_pk_add_f32 v[96:97], v[114:115], v[96:97]
	v_mov_b32_e32 v100, v214
	v_pk_add_f32 v[98:99], v[98:99], v[100:101]
	v_pk_add_f32 v[96:97], v[96:97], v[96:97] op_sel:[0,1] op_sel_hi:[1,0]
	v_pk_add_f32 v[98:99], v[98:99], v[98:99] op_sel:[0,1] op_sel_hi:[1,0]
	v_add_f32_e32 v102, v232, v233
	v_add_f32_e32 v104, v234, v235
	v_mov_b32_e32 v103, v238
	v_mov_b32_e32 v105, v239
	v_mov_b32_e32 v97, v236
	v_mov_b32_e32 v99, v237
	v_pk_add_f32 v[100:101], v[102:103], v[104:105]
	v_pk_add_f32 v[96:97], v[96:97], v[98:99]
	s_nop 0
	v_pk_add_f32 v[96:97], v[96:97], v[100:101]
	s_nop 0
	v_add_f32_e32 v96, v96, v97
	v_fmamk_f32 v96, v96, 0x3a800000, v148
	v_mul_f32_e32 v97, 0x4b800000, v96
	v_cmp_gt_f32_e32 vcc, s71, v96
	s_nop 1
	v_cndmask_b32_e32 v96, v96, v97, vcc
	v_rsq_f32_e32 v98, v96
	v_lshlrev_b64 v[96:97], 6, v[112:113]
	v_lshl_add_u64 v[96:97], s[18:19], 0, v[96:97]
	v_mul_f32_e32 v99, 0x45800000, v98
	v_cndmask_b32_e32 v98, v98, v99, vcc
	v_pk_mul_f32 v[94:95], v[94:95], v[98:99] op_sel_hi:[1,0]
	v_pk_mul_f32 v[92:93], v[92:93], v[98:99] op_sel_hi:[1,0]
	v_pk_mul_f32 v[90:91], v[90:91], v[98:99] op_sel_hi:[1,0]
	v_pk_mul_f32 v[88:89], v[88:89], v[98:99] op_sel_hi:[1,0]
	v_pk_mul_f32 v[82:83], v[82:83], v[98:99] op_sel_hi:[1,0]
	v_pk_mul_f32 v[80:81], v[80:81], v[98:99] op_sel_hi:[1,0]
	v_pk_mul_f32 v[86:87], v[86:87], v[98:99] op_sel_hi:[1,0]
	v_pk_mul_f32 v[84:85], v[84:85], v[98:99] op_sel_hi:[1,0]
	v_max_f32_e32 v92, 0, v92
	v_max_f32_e32 v88, 0, v88
	v_max_f32_e32 v93, 0, v93
	v_max_f32_e32 v89, 0, v89
	v_max_f32_e32 v94, 0, v94
	v_max_f32_e32 v90, 0, v90
	v_max_f32_e32 v95, 0, v95
	v_max_f32_e32 v91, 0, v91
	v_max_f32_e32 v80, 0, v80
	v_max_f32_e32 v81, 0, v81
	v_max_f32_e32 v82, 0, v82
	v_max_f32_e32 v83, 0, v83
	v_max_f32_e32 v84, 0, v84
	v_max_f32_e32 v85, 0, v85
	v_max_f32_e32 v86, 0, v86
	v_max_f32_e32 v87, 0, v87
	v_mul_f32_e32 v92, v92, v92
	v_mul_f32_e32 v88, v88, v88
	v_mul_f32_e32 v93, v93, v93
	v_mul_f32_e32 v89, v89, v89
	v_mul_f32_e32 v94, v94, v94
	v_mul_f32_e32 v90, v90, v90
	v_mul_f32_e32 v95, v95, v95
	v_mul_f32_e32 v91, v91, v91
	v_mul_f32_e32 v98, v80, v80
	v_mul_f32_e32 v99, v81, v81
	v_mul_f32_e32 v100, v82, v82
	v_mul_f32_e32 v101, v83, v83
	v_cvt_pk_bf16_f32 v80, v92, v93
	v_cvt_pk_bf16_f32 v81, v94, v95
	v_cvt_pk_bf16_f32 v82, v88, v89
	v_cvt_pk_bf16_f32 v83, v90, v91
	v_mul_f32_e32 v84, v84, v84
	v_mul_f32_e32 v85, v85, v85
	v_mul_f32_e32 v86, v86, v86
	v_mul_f32_e32 v87, v87, v87
	buffer_store_dwordx4 v[80:83], v116, s[12:15], 0 offen sc1
	s_nop 1
	v_cvt_pk_bf16_f32 v80, v84, v85
	v_cvt_pk_bf16_f32 v81, v86, v87
	v_cvt_pk_bf16_f32 v82, v98, v99
	v_cvt_pk_bf16_f32 v83, v100, v101
	buffer_store_dwordx4 v[80:83], v116, s[12:15], 0 offen offset:256 sc1
	s_nop 0
	v_add_u32_e32 v96, 0x4080, v150
	v_ashrrev_i32_e32 v97, 31, v96
	v_lshl_add_u32 v100, v112, 13, v149
	v_add_u32_e32 v177, 0x2800, v176
	global_load_dwordx4 v[210:213], v177, s[18:19]
	v_add_u32_e32 v177, 0x2810, v176
	global_load_dwordx4 v[214:217], v177, s[18:19]
	v_add_u32_e32 v177, 0x2820, v176
	global_load_dwordx4 v[232:235], v177, s[18:19]
	v_add_u32_e32 v177, 0x2830, v176
	global_load_dwordx4 v[236:239], v177, s[18:19]
	s_waitcnt vmcnt(18)
; __device__ __forceinline__ u32x4 pack8(const f32x4 v0, const f32x4 v1) { u32x4 w; w.x = pk2(v0[0], v0[1]); w.y = pk2(v0[2], v0[3]); w.z = pk2(v1[0], v1[1]); w.w = pk2(v1[2], v1[3]); return w; }
; __device__ __forceinline__ float row_rstd(const float* ssq, int row) {
;     const f32x4* p = (const f32x4*)(ssq + (size_t)row * 16);
;     const f32x4 a = p[0], b = p[1], c = p[2], d = p[3];
;     const float s = ((a[0] + a[1]) + (a[2] + a[3])) + ((b[0] + b[1]) + (b[2] + b[3])) + ((c[0] + c[1]) + (c[2] + c[3])) + ((d[0] + d[1]) + (d[2] + d[3]));
;     return rsqrtf(s * (1.0f / 1024.0f) + 1e-6f);
;     __device__ __forceinline__ void operator()(const f32x4 (&acc)[2][2][4][2], const Unit& u, int wr, int wc, int fr, int fq) const {
;     ...
;         for (int ai = 0; ai < 2; ++ai)
; #pragma unroll
;             for (int m = 0; m < 4; ++m) {
;                 const int row = row0 + ai * 128 + m * 16; const float rs = row_rstd(ssq, row);
; #pragma unroll
;                 for (int bj = 0; bj < 2; ++bj) { f32x4 v0 = acc[ai][bj][m][0] * rs, v1 = acc[ai][bj][m][1] * rs;
; #pragma unroll
;                     for (int j = 0; j < 4; ++j) { const float a = fmaxf(v0[j], 0.f), b = fmaxf(v1[j], 0.f); v0[j] = a * a; v1[j] = b * b; }
;                     __builtin_amdgcn_raw_buffer_store_b128(pack8(v0, v1), rsrc, (unsigned)(((size_t)row * DFF + col0 + bj * 128) * 2), 0, 16  ); }
	v_mov_b32_e32 v98, v241
	v_mov_b32_e32 v99, v242
	v_mov_b32_e32 v81, v243
	v_mov_b32_e32 v82, v245
	v_mov_b32_e32 v83, v246
	v_mov_b32_e32 v85, v247
	v_mov_b32_e32 v80, v240
	v_pk_add_f32 v[80:81], v[98:99], v[80:81]
	v_mov_b32_e32 v84, v244
	v_pk_add_f32 v[82:83], v[82:83], v[84:85]
	v_pk_add_f32 v[80:81], v[80:81], v[80:81] op_sel:[0,1] op_sel_hi:[1,0]
	v_pk_add_f32 v[82:83], v[82:83], v[82:83] op_sel:[0,1] op_sel_hi:[1,0]
	v_add_f32_e32 v86, v248, v249
	v_add_f32_e32 v88, v250, v251
	v_mov_b32_e32 v87, v254
	v_mov_b32_e32 v89, v255
	v_mov_b32_e32 v81, v252
	v_mov_b32_e32 v83, v253
	v_pk_add_f32 v[84:85], v[86:87], v[88:89]
	v_pk_add_f32 v[80:81], v[80:81], v[82:83]
	s_nop 0
	v_pk_add_f32 v[80:81], v[80:81], v[84:85]
	s_nop 0
	v_add_f32_e32 v80, v80, v81
	v_fmamk_f32 v80, v80, 0x3a800000, v148
	v_mul_f32_e32 v81, 0x4b800000, v80
	v_cmp_gt_f32_e32 vcc, s71, v80
	s_nop 1
	v_cndmask_b32_e32 v80, v80, v81, vcc
	v_rsq_f32_e32 v82, v80
	v_lshlrev_b64 v[80:81], 6, v[96:97]
	v_lshl_add_u64 v[80:81], s[18:19], 0, v[80:81]
	v_mul_f32_e32 v83, 0x45800000, v82
	v_cndmask_b32_e32 v82, v82, v83, vcc
	v_pk_mul_f32 v[78:79], v[78:79], v[82:83] op_sel_hi:[1,0]
	v_pk_mul_f32 v[76:77], v[76:77], v[82:83] op_sel_hi:[1,0]
	v_pk_mul_f32 v[74:75], v[74:75], v[82:83] op_sel_hi:[1,0]
	v_pk_mul_f32 v[72:73], v[72:73], v[82:83] op_sel_hi:[1,0]
	v_pk_mul_f32 v[66:67], v[66:67], v[82:83] op_sel_hi:[1,0]
	v_pk_mul_f32 v[64:65], v[64:65], v[82:83] op_sel_hi:[1,0]
	v_pk_mul_f32 v[70:71], v[70:71], v[82:83] op_sel_hi:[1,0]
	v_pk_mul_f32 v[68:69], v[68:69], v[82:83] op_sel_hi:[1,0]
	v_max_f32_e32 v76, 0, v76
	v_max_f32_e32 v72, 0, v72
	v_max_f32_e32 v77, 0, v77
	v_max_f32_e32 v73, 0, v73
	v_max_f32_e32 v78, 0, v78
	v_max_f32_e32 v74, 0, v74
	v_max_f32_e32 v79, 0, v79
	v_max_f32_e32 v75, 0, v75
	v_max_f32_e32 v64, 0, v64
	v_max_f32_e32 v65, 0, v65
	v_max_f32_e32 v66, 0, v66
	v_max_f32_e32 v67, 0, v67
	v_max_f32_e32 v68, 0, v68
	v_max_f32_e32 v69, 0, v69
	v_max_f32_e32 v70, 0, v70
	v_max_f32_e32 v71, 0, v71
	v_mul_f32_e32 v76, v76, v76
	v_mul_f32_e32 v72, v72, v72
	v_mul_f32_e32 v77, v77, v77
	v_mul_f32_e32 v73, v73, v73
	v_mul_f32_e32 v78, v78, v78
	v_mul_f32_e32 v74, v74, v74
	v_mul_f32_e32 v79, v79, v79
	v_mul_f32_e32 v75, v75, v75
	v_mul_f32_e32 v82, v64, v64
	v_mul_f32_e32 v83, v65, v65
	v_mul_f32_e32 v84, v66, v66
	v_mul_f32_e32 v85, v67, v67
	v_cvt_pk_bf16_f32 v64, v76, v77
	v_cvt_pk_bf16_f32 v65, v78, v79
	v_cvt_pk_bf16_f32 v66, v72, v73
	v_cvt_pk_bf16_f32 v67, v74, v75
	v_mul_f32_e32 v68, v68, v68
	v_mul_f32_e32 v69, v69, v69
	v_mul_f32_e32 v70, v70, v70
	v_mul_f32_e32 v71, v71, v71
	buffer_store_dwordx4 v[64:67], v100, s[12:15], 0 offen sc1
	s_nop 1
	v_cvt_pk_bf16_f32 v64, v68, v69
	v_cvt_pk_bf16_f32 v65, v70, v71
	v_cvt_pk_bf16_f32 v66, v82, v83
	v_cvt_pk_bf16_f32 v67, v84, v85
	buffer_store_dwordx4 v[64:67], v100, s[12:15], 0 offen offset:256 sc1
	s_nop 0
	v_add_u32_e32 v80, 0x4090, v150
	v_ashrrev_i32_e32 v81, 31, v80
	v_lshl_add_u32 v84, v96, 13, v149
	v_add_u32_e32 v177, 0x2c00, v176
	global_load_dwordx4 v[240:243], v177, s[18:19]
	v_add_u32_e32 v177, 0x2c10, v176
	global_load_dwordx4 v[244:247], v177, s[18:19]
	v_add_u32_e32 v177, 0x2c20, v176
	global_load_dwordx4 v[248:251], v177, s[18:19]
	v_add_u32_e32 v177, 0x2c30, v176
	global_load_dwordx4 v[252:255], v177, s[18:19]
	s_waitcnt vmcnt(18)
	v_mov_b32_e32 v82, v179
	v_mov_b32_e32 v83, v180
	v_mov_b32_e32 v65, v181
	v_mov_b32_e32 v66, v183
	v_mov_b32_e32 v67, v184
	v_mov_b32_e32 v69, v185
	v_mov_b32_e32 v64, v178
	v_pk_add_f32 v[64:65], v[82:83], v[64:65]
	v_mov_b32_e32 v68, v182
	v_pk_add_f32 v[66:67], v[66:67], v[68:69]
	v_pk_add_f32 v[64:65], v[64:65], v[64:65] op_sel:[0,1] op_sel_hi:[1,0]
	v_pk_add_f32 v[66:67], v[66:67], v[66:67] op_sel:[0,1] op_sel_hi:[1,0]
	v_add_f32_e32 v70, v186, v187
	v_add_f32_e32 v72, v188, v189
	v_mov_b32_e32 v71, v192
	v_mov_b32_e32 v73, v193
	v_mov_b32_e32 v65, v190
	v_mov_b32_e32 v67, v191
	v_pk_add_f32 v[68:69], v[70:71], v[72:73]
	v_pk_add_f32 v[64:65], v[64:65], v[66:67]
	s_nop 0
	v_pk_add_f32 v[64:65], v[64:65], v[68:69]
	s_nop 0
	v_add_f32_e32 v64, v64, v65
	v_fmamk_f32 v64, v64, 0x3a800000, v148
	v_mul_f32_e32 v65, 0x4b800000, v64
	v_cmp_gt_f32_e32 vcc, s71, v64
	s_nop 1
	v_cndmask_b32_e32 v64, v64, v65, vcc
	v_rsq_f32_e32 v66, v64
	v_lshlrev_b64 v[64:65], 6, v[80:81]
	v_lshl_add_u64 v[64:65], s[18:19], 0, v[64:65]
	v_mul_f32_e32 v67, 0x45800000, v66
	v_cndmask_b32_e32 v66, v66, v67, vcc
	v_pk_mul_f32 v[62:63], v[62:63], v[66:67] op_sel_hi:[1,0]
	v_pk_mul_f32 v[60:61], v[60:61], v[66:67] op_sel_hi:[1,0]
	v_pk_mul_f32 v[58:59], v[58:59], v[66:67] op_sel_hi:[1,0]
	v_pk_mul_f32 v[56:57], v[56:57], v[66:67] op_sel_hi:[1,0]
	v_pk_mul_f32 v[50:51], v[50:51], v[66:67] op_sel_hi:[1,0]
	v_pk_mul_f32 v[48:49], v[48:49], v[66:67] op_sel_hi:[1,0]
	v_pk_mul_f32 v[54:55], v[54:55], v[66:67] op_sel_hi:[1,0]
	v_pk_mul_f32 v[52:53], v[52:53], v[66:67] op_sel_hi:[1,0]
	v_max_f32_e32 v60, 0, v60
	v_max_f32_e32 v56, 0, v56
	v_max_f32_e32 v61, 0, v61
	v_max_f32_e32 v57, 0, v57
	v_max_f32_e32 v62, 0, v62
	v_max_f32_e32 v58, 0, v58
	v_max_f32_e32 v63, 0, v63
	v_max_f32_e32 v59, 0, v59
	v_max_f32_e32 v48, 0, v48
	v_max_f32_e32 v49, 0, v49
	v_max_f32_e32 v50, 0, v50
	v_max_f32_e32 v51, 0, v51
	v_max_f32_e32 v52, 0, v52
	v_max_f32_e32 v53, 0, v53
	v_max_f32_e32 v54, 0, v54
	v_max_f32_e32 v55, 0, v55
	v_mul_f32_e32 v60, v60, v60
	v_mul_f32_e32 v56, v56, v56
	v_mul_f32_e32 v61, v61, v61
	v_mul_f32_e32 v57, v57, v57
	v_mul_f32_e32 v62, v62, v62
	v_mul_f32_e32 v58, v58, v58
	v_mul_f32_e32 v63, v63, v63
	v_mul_f32_e32 v59, v59, v59
	v_mul_f32_e32 v66, v48, v48
	v_mul_f32_e32 v67, v49, v49
	v_mul_f32_e32 v68, v50, v50
	v_mul_f32_e32 v69, v51, v51
	v_cvt_pk_bf16_f32 v48, v60, v61
	v_cvt_pk_bf16_f32 v49, v62, v63
	v_cvt_pk_bf16_f32 v50, v56, v57
	v_cvt_pk_bf16_f32 v51, v58, v59
	v_mul_f32_e32 v52, v52, v52
	v_mul_f32_e32 v53, v53, v53
	v_mul_f32_e32 v54, v54, v54
	v_mul_f32_e32 v55, v55, v55
	buffer_store_dwordx4 v[48:51], v84, s[12:15], 0 offen sc1
	s_nop 1
	v_cvt_pk_bf16_f32 v48, v52, v53
	v_cvt_pk_bf16_f32 v49, v54, v55
	v_cvt_pk_bf16_f32 v50, v66, v67
	v_cvt_pk_bf16_f32 v51, v68, v69
	buffer_store_dwordx4 v[48:51], v84, s[12:15], 0 offen offset:256 sc1
	s_nop 0
	v_add_u32_e32 v64, 0x40a0, v150
	v_ashrrev_i32_e32 v65, 31, v64
	v_lshl_add_u32 v68, v80, 13, v149
	s_waitcnt vmcnt(14)
; __device__ __forceinline__ u32x4 pack8(const f32x4 v0, const f32x4 v1) { u32x4 w; w.x = pk2(v0[0], v0[1]); w.y = pk2(v0[2], v0[3]); w.z = pk2(v1[0], v1[1]); w.w = pk2(v1[2], v1[3]); return w; }
; __device__ __forceinline__ float row_rstd(const float* ssq, int row) {
;     const f32x4* p = (const f32x4*)(ssq + (size_t)row * 16);
;     const f32x4 a = p[0], b = p[1], c = p[2], d = p[3];
;     const float s = ((a[0] + a[1]) + (a[2] + a[3])) + ((b[0] + b[1]) + (b[2] + b[3])) + ((c[0] + c[1]) + (c[2] + c[3])) + ((d[0] + d[1]) + (d[2] + d[3]));
;     return rsqrtf(s * (1.0f / 1024.0f) + 1e-6f);
;     __device__ __forceinline__ void operator()(const f32x4 (&acc)[2][2][4][2], const Unit& u, int wr, int wc, int fr, int fq) const {
;     ...
;         for (int ai = 0; ai < 2; ++ai)
; #pragma unroll
;             for (int m = 0; m < 4; ++m) {
;                 const int row = row0 + ai * 128 + m * 16; const float rs = row_rstd(ssq, row);
; #pragma unroll
;                 for (int bj = 0; bj < 2; ++bj) { f32x4 v0 = acc[ai][bj][m][0] * rs, v1 = acc[ai][bj][m][1] * rs;
; #pragma unroll
;                     for (int j = 0; j < 4; ++j) { const float a = fmaxf(v0[j], 0.f), b = fmaxf(v1[j], 0.f); v0[j] = a * a; v1[j] = b * b; }
;                     __builtin_amdgcn_raw_buffer_store_b128(pack8(v0, v1), rsrc, (unsigned)(((size_t)row * DFF + col0 + bj * 128) * 2), 0, 16  ); }
	v_mov_b32_e32 v66, v195
	v_mov_b32_e32 v67, v196
	v_mov_b32_e32 v49, v197
	v_mov_b32_e32 v50, v199
	v_mov_b32_e32 v51, v200
	v_mov_b32_e32 v53, v201
	v_mov_b32_e32 v48, v194
	v_pk_add_f32 v[48:49], v[66:67], v[48:49]
	v_mov_b32_e32 v52, v198
	v_pk_add_f32 v[50:51], v[50:51], v[52:53]
	v_pk_add_f32 v[48:49], v[48:49], v[48:49] op_sel:[0,1] op_sel_hi:[1,0]
	v_pk_add_f32 v[50:51], v[50:51], v[50:51] op_sel:[0,1] op_sel_hi:[1,0]
	v_add_f32_e32 v54, v202, v203
	v_add_f32_e32 v56, v204, v205
	v_mov_b32_e32 v55, v208
	v_mov_b32_e32 v57, v209
	v_mov_b32_e32 v49, v206
	v_mov_b32_e32 v51, v207
	v_pk_add_f32 v[52:53], v[54:55], v[56:57]
	v_pk_add_f32 v[48:49], v[48:49], v[50:51]
	s_nop 0
	v_pk_add_f32 v[48:49], v[48:49], v[52:53]
	s_nop 0
	v_add_f32_e32 v48, v48, v49
	v_fmamk_f32 v48, v48, 0x3a800000, v148
	v_mul_f32_e32 v49, 0x4b800000, v48
	v_cmp_gt_f32_e32 vcc, s71, v48
	s_nop 1
	v_cndmask_b32_e32 v48, v48, v49, vcc
	v_rsq_f32_e32 v50, v48
	v_lshlrev_b64 v[48:49], 6, v[64:65]
	v_lshl_add_u64 v[48:49], s[18:19], 0, v[48:49]
	v_mul_f32_e32 v51, 0x45800000, v50
	v_cndmask_b32_e32 v50, v50, v51, vcc
	v_pk_mul_f32 v[46:47], v[46:47], v[50:51] op_sel_hi:[1,0]
	v_pk_mul_f32 v[44:45], v[44:45], v[50:51] op_sel_hi:[1,0]
	v_pk_mul_f32 v[42:43], v[42:43], v[50:51] op_sel_hi:[1,0]
	v_pk_mul_f32 v[40:41], v[40:41], v[50:51] op_sel_hi:[1,0]
	v_pk_mul_f32 v[34:35], v[34:35], v[50:51] op_sel_hi:[1,0]
	v_pk_mul_f32 v[32:33], v[32:33], v[50:51] op_sel_hi:[1,0]
	v_pk_mul_f32 v[38:39], v[38:39], v[50:51] op_sel_hi:[1,0]
	v_pk_mul_f32 v[36:37], v[36:37], v[50:51] op_sel_hi:[1,0]
	v_max_f32_e32 v44, 0, v44
	v_max_f32_e32 v40, 0, v40
	v_max_f32_e32 v45, 0, v45
	v_max_f32_e32 v41, 0, v41
	v_max_f32_e32 v46, 0, v46
	v_max_f32_e32 v42, 0, v42
	v_max_f32_e32 v47, 0, v47
	v_max_f32_e32 v43, 0, v43
	v_max_f32_e32 v32, 0, v32
	v_max_f32_e32 v33, 0, v33
	v_max_f32_e32 v34, 0, v34
	v_max_f32_e32 v35, 0, v35
	v_max_f32_e32 v36, 0, v36
	v_max_f32_e32 v37, 0, v37
	v_max_f32_e32 v38, 0, v38
	v_max_f32_e32 v39, 0, v39
	v_mul_f32_e32 v44, v44, v44
	v_mul_f32_e32 v40, v40, v40
	v_mul_f32_e32 v45, v45, v45
	v_mul_f32_e32 v41, v41, v41
	v_mul_f32_e32 v46, v46, v46
	v_mul_f32_e32 v42, v42, v42
	v_mul_f32_e32 v47, v47, v47
	v_mul_f32_e32 v43, v43, v43
	v_mul_f32_e32 v50, v32, v32
	v_mul_f32_e32 v51, v33, v33
	v_mul_f32_e32 v52, v34, v34
	v_mul_f32_e32 v53, v35, v35
	v_cvt_pk_bf16_f32 v32, v44, v45
	v_cvt_pk_bf16_f32 v33, v46, v47
	v_cvt_pk_bf16_f32 v34, v40, v41
	v_cvt_pk_bf16_f32 v35, v42, v43
	v_mul_f32_e32 v36, v36, v36
	v_mul_f32_e32 v37, v37, v37
	v_mul_f32_e32 v38, v38, v38
	v_mul_f32_e32 v39, v39, v39
	buffer_store_dwordx4 v[32:35], v68, s[12:15], 0 offen sc1
	s_nop 1
	v_cvt_pk_bf16_f32 v32, v36, v37
	v_cvt_pk_bf16_f32 v33, v38, v39
	v_cvt_pk_bf16_f32 v34, v50, v51
	v_cvt_pk_bf16_f32 v35, v52, v53
	buffer_store_dwordx4 v[32:35], v68, s[12:15], 0 offen offset:256 sc1
	s_nop 0
	v_add_u32_e32 v48, 0x40b0, v150
	v_ashrrev_i32_e32 v49, 31, v48
	v_lshl_add_u32 v52, v64, 13, v149
	s_waitcnt vmcnt(10)
	v_mov_b32_e32 v50, v211
	v_mov_b32_e32 v51, v212
	v_mov_b32_e32 v33, v213
	v_mov_b32_e32 v34, v215
	v_mov_b32_e32 v35, v216
	v_mov_b32_e32 v37, v217
	v_mov_b32_e32 v32, v210
	v_pk_add_f32 v[32:33], v[50:51], v[32:33]
	v_mov_b32_e32 v36, v214
	v_pk_add_f32 v[34:35], v[34:35], v[36:37]
	v_pk_add_f32 v[32:33], v[32:33], v[32:33] op_sel:[0,1] op_sel_hi:[1,0]
	v_pk_add_f32 v[34:35], v[34:35], v[34:35] op_sel:[0,1] op_sel_hi:[1,0]
	v_add_f32_e32 v38, v232, v233
	v_add_f32_e32 v40, v234, v235
	v_mov_b32_e32 v39, v238
	v_mov_b32_e32 v41, v239
	v_mov_b32_e32 v33, v236
	v_mov_b32_e32 v35, v237
	v_pk_add_f32 v[36:37], v[38:39], v[40:41]
	v_pk_add_f32 v[32:33], v[32:33], v[34:35]
	s_nop 0
	v_pk_add_f32 v[32:33], v[32:33], v[36:37]
	s_nop 0
	v_add_f32_e32 v32, v32, v33
	v_fmamk_f32 v32, v32, 0x3a800000, v148
	v_mul_f32_e32 v33, 0x4b800000, v32
	v_cmp_gt_f32_e32 vcc, s71, v32
	s_nop 1
	v_cndmask_b32_e32 v32, v32, v33, vcc
	v_rsq_f32_e32 v34, v32
	v_lshlrev_b64 v[32:33], 6, v[48:49]
	v_lshl_add_u64 v[32:33], s[18:19], 0, v[32:33]
	v_mul_f32_e32 v35, 0x45800000, v34
	v_cndmask_b32_e32 v34, v34, v35, vcc
	v_pk_mul_f32 v[30:31], v[30:31], v[34:35] op_sel_hi:[1,0]
	v_pk_mul_f32 v[28:29], v[28:29], v[34:35] op_sel_hi:[1,0]
	v_pk_mul_f32 v[26:27], v[26:27], v[34:35] op_sel_hi:[1,0]
	v_pk_mul_f32 v[24:25], v[24:25], v[34:35] op_sel_hi:[1,0]
	v_pk_mul_f32 v[18:19], v[18:19], v[34:35] op_sel_hi:[1,0]
	v_pk_mul_f32 v[16:17], v[16:17], v[34:35] op_sel_hi:[1,0]
	v_pk_mul_f32 v[22:23], v[22:23], v[34:35] op_sel_hi:[1,0]
	v_pk_mul_f32 v[20:21], v[20:21], v[34:35] op_sel_hi:[1,0]
	v_max_f32_e32 v28, 0, v28
	v_max_f32_e32 v24, 0, v24
	v_max_f32_e32 v29, 0, v29
	v_max_f32_e32 v25, 0, v25
	v_max_f32_e32 v30, 0, v30
	v_max_f32_e32 v26, 0, v26
	v_max_f32_e32 v31, 0, v31
	v_max_f32_e32 v27, 0, v27
	v_max_f32_e32 v16, 0, v16
	v_max_f32_e32 v17, 0, v17
	v_max_f32_e32 v18, 0, v18
	v_max_f32_e32 v19, 0, v19
	v_max_f32_e32 v20, 0, v20
	v_max_f32_e32 v21, 0, v21
	v_max_f32_e32 v22, 0, v22
	v_max_f32_e32 v23, 0, v23
	v_mul_f32_e32 v28, v28, v28
	v_mul_f32_e32 v24, v24, v24
	v_mul_f32_e32 v29, v29, v29
	v_mul_f32_e32 v25, v25, v25
	v_mul_f32_e32 v30, v30, v30
	v_mul_f32_e32 v26, v26, v26
	v_mul_f32_e32 v31, v31, v31
	v_mul_f32_e32 v27, v27, v27
	v_mul_f32_e32 v34, v16, v16
	v_mul_f32_e32 v35, v17, v17
	v_mul_f32_e32 v36, v18, v18
	v_mul_f32_e32 v37, v19, v19
	v_cvt_pk_bf16_f32 v16, v28, v29
	v_cvt_pk_bf16_f32 v17, v30, v31
	v_cvt_pk_bf16_f32 v18, v24, v25
	v_cvt_pk_bf16_f32 v19, v26, v27
	v_mul_f32_e32 v20, v20, v20
	v_mul_f32_e32 v21, v21, v21
	v_mul_f32_e32 v22, v22, v22
	v_mul_f32_e32 v23, v23, v23
	buffer_store_dwordx4 v[16:19], v52, s[12:15], 0 offen sc1
	s_nop 1
	v_cvt_pk_bf16_f32 v16, v20, v21
	v_cvt_pk_bf16_f32 v17, v22, v23
	v_cvt_pk_bf16_f32 v18, v34, v35
	v_cvt_pk_bf16_f32 v19, v36, v37
	buffer_store_dwordx4 v[16:19], v52, s[12:15], 0 offen offset:256 sc1
	s_nop 0
	s_waitcnt vmcnt(6)
; __device__ __forceinline__ u32x4 pack8(const f32x4 v0, const f32x4 v1) { u32x4 w; w.x = pk2(v0[0], v0[1]); w.y = pk2(v0[2], v0[3]); w.z = pk2(v1[0], v1[1]); w.w = pk2(v1[2], v1[3]); return w; }
; __device__ __forceinline__ float row_rstd(const float* ssq, int row) {
;     const f32x4* p = (const f32x4*)(ssq + (size_t)row * 16);
;     const f32x4 a = p[0], b = p[1], c = p[2], d = p[3];
;     const float s = ((a[0] + a[1]) + (a[2] + a[3])) + ((b[0] + b[1]) + (b[2] + b[3])) + ((c[0] + c[1]) + (c[2] + c[3])) + ((d[0] + d[1]) + (d[2] + d[3]));
;     return rsqrtf(s * (1.0f / 1024.0f) + 1e-6f);
;     __device__ __forceinline__ void operator()(const f32x4 (&acc)[2][2][4][2], const Unit& u, int wr, int wc, int fr, int fq) const {
;     ...
;         for (int ai = 0; ai < 2; ++ai)
; #pragma unroll
;             for (int m = 0; m < 4; ++m) {
;                 const int row = row0 + ai * 128 + m * 16; const float rs = row_rstd(ssq, row);
; #pragma unroll
;                 for (int bj = 0; bj < 2; ++bj) { f32x4 v0 = acc[ai][bj][m][0] * rs, v1 = acc[ai][bj][m][1] * rs;
; #pragma unroll
;                     for (int j = 0; j < 4; ++j) { const float a = fmaxf(v0[j], 0.f), b = fmaxf(v1[j], 0.f); v0[j] = a * a; v1[j] = b * b; }
;                     __builtin_amdgcn_raw_buffer_store_b128(pack8(v0, v1), rsrc, (unsigned)(((size_t)row * DFF + col0 + bj * 128) * 2), 0, 16  ); }
;             }
;         asm volatile("s_waitcnt vmcnt(0)" ::: "memory");
;         if (fr == 0 && fq == 0) (void)__hip_atomic_fetch_add(ready + 64 * (pm_off + u.pm), 1u, __ATOMIC_RELAXED, __HIP_MEMORY_SCOPE_AGENT);
	v_mov_b32_e32 v32, v241
	v_mov_b32_e32 v33, v242
	v_mov_b32_e32 v17, v243
	v_mov_b32_e32 v18, v245
	v_mov_b32_e32 v19, v246
	v_mov_b32_e32 v21, v247
	v_mov_b32_e32 v16, v240
	v_pk_add_f32 v[16:17], v[32:33], v[16:17]
	v_mov_b32_e32 v20, v244
	v_pk_add_f32 v[18:19], v[18:19], v[20:21]
	v_pk_add_f32 v[16:17], v[16:17], v[16:17] op_sel:[0,1] op_sel_hi:[1,0]
	v_pk_add_f32 v[18:19], v[18:19], v[18:19] op_sel:[0,1] op_sel_hi:[1,0]
	v_add_f32_e32 v22, v248, v249
	v_add_f32_e32 v24, v250, v251
	v_mov_b32_e32 v23, v254
	v_mov_b32_e32 v25, v255
	v_mov_b32_e32 v17, v252
	v_mov_b32_e32 v19, v253
	v_pk_add_f32 v[20:21], v[22:23], v[24:25]
	v_pk_add_f32 v[16:17], v[16:17], v[18:19]
	s_nop 0
	v_pk_add_f32 v[16:17], v[16:17], v[20:21]
	s_nop 0
	v_add_f32_e32 v16, v16, v17
	v_fmamk_f32 v16, v16, 0x3a800000, v148
	v_mul_f32_e32 v17, 0x4b800000, v16
	v_cmp_gt_f32_e32 vcc, s71, v16
	s_nop 1
	v_cndmask_b32_e32 v16, v16, v17, vcc
	v_rsq_f32_e32 v16, v16
	v_lshl_add_u32 v17, v48, 13, v149
	v_mul_f32_e32 v18, 0x45800000, v16
	v_cndmask_b32_e32 v16, v16, v18, vcc
	v_pk_mul_f32 v[14:15], v[14:15], v[16:17] op_sel_hi:[1,0]
	v_pk_mul_f32 v[12:13], v[12:13], v[16:17] op_sel_hi:[1,0]
	v_pk_mul_f32 v[10:11], v[10:11], v[16:17] op_sel_hi:[1,0]
	v_pk_mul_f32 v[8:9], v[8:9], v[16:17] op_sel_hi:[1,0]
	v_pk_mul_f32 v[2:3], v[2:3], v[16:17] op_sel_hi:[1,0]
	v_pk_mul_f32 v[0:1], v[0:1], v[16:17] op_sel_hi:[1,0]
	v_pk_mul_f32 v[6:7], v[6:7], v[16:17] op_sel_hi:[1,0]
	v_pk_mul_f32 v[4:5], v[4:5], v[16:17] op_sel_hi:[1,0]
	v_max_f32_e32 v12, 0, v12
	v_max_f32_e32 v8, 0, v8
	v_max_f32_e32 v13, 0, v13
	v_max_f32_e32 v9, 0, v9
	v_max_f32_e32 v14, 0, v14
	v_max_f32_e32 v10, 0, v10
	v_max_f32_e32 v15, 0, v15
	v_max_f32_e32 v11, 0, v11
	v_max_f32_e32 v0, 0, v0
	v_max_f32_e32 v1, 0, v1
	v_max_f32_e32 v2, 0, v2
	v_max_f32_e32 v3, 0, v3
	v_max_f32_e32 v4, 0, v4
	v_max_f32_e32 v5, 0, v5
	v_max_f32_e32 v6, 0, v6
	v_max_f32_e32 v7, 0, v7
	v_mul_f32_e32 v12, v12, v12
	v_mul_f32_e32 v8, v8, v8
	v_mul_f32_e32 v13, v13, v13
	v_mul_f32_e32 v9, v9, v9
	v_mul_f32_e32 v14, v14, v14
	v_mul_f32_e32 v10, v10, v10
	v_mul_f32_e32 v15, v15, v15
	v_mul_f32_e32 v11, v11, v11
	v_mul_f32_e32 v16, v0, v0
	v_mul_f32_e32 v18, v1, v1
	v_mul_f32_e32 v19, v2, v2
	v_mul_f32_e32 v20, v3, v3
	v_cvt_pk_bf16_f32 v0, v12, v13
	v_cvt_pk_bf16_f32 v1, v14, v15
	v_cvt_pk_bf16_f32 v2, v8, v9
	v_cvt_pk_bf16_f32 v3, v10, v11
	v_mul_f32_e32 v4, v4, v4
	v_mul_f32_e32 v5, v5, v5
	v_mul_f32_e32 v6, v6, v6
	v_mul_f32_e32 v7, v7, v7
	buffer_store_dwordx4 v[0:3], v17, s[12:15], 0 offen sc1
	s_nop 1
	v_cvt_pk_bf16_f32 v0, v4, v5
	v_cvt_pk_bf16_f32 v1, v6, v7
	v_cvt_pk_bf16_f32 v2, v16, v18
	v_cvt_pk_bf16_f32 v3, v19, v20
	buffer_store_dwordx4 v[0:3], v17, s[12:15], 0 offen offset:256 sc1
	s_waitcnt vmcnt(0)
	s_and_saveexec_b64 s[38:39], s[10:11]
	s_cbranch_execz .LBB0_973
	s_mov_b64 s[40:41], exec
	v_mbcnt_lo_u32_b32 v0, s40, 0
	v_mbcnt_hi_u32_b32 v0, s41, v0
	v_cmp_eq_u32_e32 vcc, 0, v0
	s_and_b64 s[6:7], exec, vcc
	s_mov_b64 exec, s[6:7]
	s_cbranch_execz .LBB0_973
	s_lshl_b32 s6, s75, 6
	s_addk_i32 s6, 0x1000
	s_ashr_i32 s7, s6, 31
	s_lshl_b64 s[6:7], s[6:7], 2
	s_add_u32 s6, s73, s6
	s_addc_u32 s7, s74, s7
	s_bcnt1_i32_b64 s8, s[40:41]
	v_mov_b32_e32 v0, s8
	global_atomic_add v131, v0, s[6:7]
	s_branch .LBB0_973

; #define PG8_STAGE(bufoff, gbase, voff) do { _Pragma("unroll") for (int _i = 0; _i < 2; ++_i) \
;         __builtin_amdgcn_global_load_lds((const unsigned*)((const char*)(gbase) + (voff)[_i]), (LAS unsigned*)(lds + (bufoff) + ldsw + _i * 8192), 16, 0, 0); } while (0)
; #define PG8_LDA(dst, b, h) do { _Pragma("unroll") for (int m = 0; m < 4; ++m) _Pragma("unroll") for (int k = 0; k < 2; ++k) dst[m][k] = *(const LAS bf16x8*)(lds + PG8_SA(b, h) + aoff + m * 2048 + k * 1024); } while (0)
; #define PG8_LDB(dst, b, h) do { _Pragma("unroll") for (int n = 0; n < 2; ++n) _Pragma("unroll") for (int k = 0; k < 2; ++k) dst[n][k] = *(const LAS bf16x8*)(lds + PG8_SB(b, h) + boff + n * 2048 + k * 1024); } while (0)
; #define PG8_MMA(ai, bj, At, Bt) do { __builtin_amdgcn_s_setprio(1); _Pragma("unroll") for (int m = 0; m < 4; ++m) _Pragma("unroll") for (int n = 0; n < 2; ++n) _Pragma("unroll") for (int k = 0; k < 2; ++k) \
;         acc[ai][bj][m][n] = __builtin_amdgcn_mfma_f32_16x16x32_bf16(Bt[n][k], At[m][k], acc[ai][bj][m][n], 0, 0, 0); __builtin_amdgcn_s_setprio(0); } while (0)
; #define PG8_WAIT_V(n) asm volatile("s_waitcnt vmcnt(" #n ")" ::: "memory")
; #define PG8_WAIT_L(n) asm volatile("s_waitcnt lgkmcnt(" #n ")" ::: "memory")
; #define PG8_BAR __builtin_amdgcn_s_barrier()
; #define PG8_SCHED __builtin_amdgcn_sched_barrier(0)
;     ...
;             PG8_LDB(B0, 0, 0); PG8_SCHED; PG8_LDA(At, 0, 0); PG8_STAGE(PG8_SA(1, 1), a1 + hA, voffA);
;             PG8_WAIT_L(8); PG8_BAR; PG8_WAIT_L(0); PG8_MMA(0, 0, At, B0); PG8_BAR; PG8_SCHED;
;             PG8_LDB(B1, 0, 1); PG8_STAGE(PG8_SB(0, 0), b2, voffB);
;             PG8_BAR; PG8_WAIT_L(0); PG8_MMA(0, 1, At, B1); PG8_BAR;
;             PG8_LDA(At, 0, 1); PG8_STAGE(PG8_SA(0, 0), a2, voffA);
;             PG8_BAR; PG8_WAIT_L(0); PG8_MMA(1, 0, At, B0); PG8_BAR; PG8_SCHED;
;             PG8_STAGE(PG8_SB(0, 1), b2 + hB, voffB);
;             PG8_WAIT_V(6); PG8_BAR; PG8_MMA(1, 1, At, B1); PG8_BAR;
.LBB0_1288:
	ds_read_b128 v[146:149], v155
	ds_read_b128 v[160:163], v155 offset:1024
	ds_read_b128 v[170:173], v155 offset:2048
	ds_read_b128 v[174:177], v155 offset:3072
	s_add_u32 s36, s34, 0xfffc0080
	s_addc_u32 s37, s35, -1
	s_cmp_eq_u32 s42, 12
	s_cselect_b32 s39, s7, s37
	s_cselect_b32 s38, s8, s36
	s_cselect_b32 s37, s9, s33
	s_cselect_b32 s36, s23, s25
	v_lshl_add_u64 v[150:151], s[34:35], 0, v[138:139]
	s_add_i32 m0, s31, 0xc000
	ds_read_b128 v[178:181], v156
	ds_read_b128 v[182:185], v156 offset:1024
	ds_read_b128 v[186:189], v156 offset:2048
	ds_read_b128 v[190:193], v156 offset:3072
	ds_read_b128 v[194:197], v156 offset:4096
	ds_read_b128 v[198:201], v156 offset:5120
	ds_read_b128 v[202:205], v156 offset:6144
	ds_read_b128 v[206:209], v156 offset:7168
	global_load_lds_dwordx4 v[150:151], off
	v_lshl_add_u64 v[150:151], s[34:35], 0, v[136:137]
	s_add_i32 m0, s31, 0xe000
	s_nop 0
	global_load_lds_dwordx4 v[150:151], off
	s_waitcnt lgkmcnt(8)
	s_barrier
	s_waitcnt lgkmcnt(0)
	s_setprio 1
	s_waitcnt lgkmcnt(0)
	v_mfma_f32_16x16x32_bf16 v[124:127], v[146:149], v[178:181], v[124:127]
	v_mfma_f32_16x16x32_bf16 v[120:123], v[170:173], v[178:181], v[120:123]
	v_mfma_f32_16x16x32_bf16 v[108:111], v[146:149], v[186:189], v[108:111]
	v_mfma_f32_16x16x32_bf16 v[104:107], v[170:173], v[186:189], v[104:107]
	v_mfma_f32_16x16x32_bf16 v[92:95], v[146:149], v[194:197], v[92:95]
	v_mfma_f32_16x16x32_bf16 v[88:91], v[170:173], v[194:197], v[88:91]
	v_mfma_f32_16x16x32_bf16 v[76:79], v[146:149], v[202:205], v[76:79]
	v_mfma_f32_16x16x32_bf16 v[72:75], v[170:173], v[202:205], v[72:75]
	v_mfma_f32_16x16x32_bf16 v[124:127], v[160:163], v[182:185], v[124:127]
	v_mfma_f32_16x16x32_bf16 v[120:123], v[174:177], v[182:185], v[120:123]
	v_mfma_f32_16x16x32_bf16 v[108:111], v[160:163], v[190:193], v[108:111]
	v_mfma_f32_16x16x32_bf16 v[104:107], v[174:177], v[190:193], v[104:107]
	v_mfma_f32_16x16x32_bf16 v[92:95], v[160:163], v[198:201], v[92:95]
	v_mfma_f32_16x16x32_bf16 v[88:91], v[174:177], v[198:201], v[88:91]
	v_mfma_f32_16x16x32_bf16 v[76:79], v[160:163], v[206:209], v[76:79]
	v_mfma_f32_16x16x32_bf16 v[72:75], v[174:177], v[206:209], v[72:75]
	s_setprio 0
	s_barrier
	s_add_i32 s43, s63, s55
	v_lshl_add_u64 v[150:151], s[36:37], 0, v[130:131]
	s_mov_b32 m0, s43
	ds_read_b128 v[210:213], v157
	ds_read_b128 v[214:217], v157 offset:1024
	ds_read_b128 v[218:221], v157 offset:2048
	ds_read_b128 v[222:225], v157 offset:3072
	global_load_lds_dwordx4 v[150:151], off
	v_lshl_add_u64 v[164:165], s[36:37], 0, v[134:135]
	s_add_i32 m0, s43, 0x2000
	s_nop 0
	global_load_lds_dwordx4 v[164:165], off
	s_barrier
	s_waitcnt lgkmcnt(0)
	s_setprio 1
	s_waitcnt lgkmcnt(0)
	v_mfma_f32_16x16x32_bf16 v[116:119], v[210:213], v[178:181], v[116:119]
	v_mfma_f32_16x16x32_bf16 v[112:115], v[218:221], v[178:181], v[112:115]
	v_mfma_f32_16x16x32_bf16 v[100:103], v[210:213], v[186:189], v[100:103]
	v_mfma_f32_16x16x32_bf16 v[96:99], v[218:221], v[186:189], v[96:99]
	v_mfma_f32_16x16x32_bf16 v[84:87], v[210:213], v[194:197], v[84:87]
	v_mfma_f32_16x16x32_bf16 v[80:83], v[218:221], v[194:197], v[80:83]
	v_mfma_f32_16x16x32_bf16 v[68:71], v[210:213], v[202:205], v[68:71]
	v_mfma_f32_16x16x32_bf16 v[64:67], v[218:221], v[202:205], v[64:67]
	v_mfma_f32_16x16x32_bf16 v[116:119], v[214:217], v[182:185], v[116:119]
	v_mfma_f32_16x16x32_bf16 v[112:115], v[222:225], v[182:185], v[112:115]
	v_mfma_f32_16x16x32_bf16 v[100:103], v[214:217], v[190:193], v[100:103]
	v_mfma_f32_16x16x32_bf16 v[96:99], v[222:225], v[190:193], v[96:99]
	v_mfma_f32_16x16x32_bf16 v[84:87], v[214:217], v[198:201], v[84:87]
	v_mfma_f32_16x16x32_bf16 v[80:83], v[222:225], v[198:201], v[80:83]
	v_mfma_f32_16x16x32_bf16 v[68:71], v[214:217], v[206:209], v[68:71]
	v_mfma_f32_16x16x32_bf16 v[64:67], v[222:225], v[206:209], v[64:67]
	s_setprio 0
	s_mov_b32 m0, s31
	v_lshl_add_u64 v[226:227], s[38:39], 0, v[128:129]
	s_barrier
	ds_read_b128 v[178:181], v156 offset:16384
	ds_read_b128 v[182:185], v156 offset:17408
	ds_read_b128 v[186:189], v156 offset:18432
	ds_read_b128 v[190:193], v156 offset:19456
	ds_read_b128 v[194:197], v156 offset:20480
	ds_read_b128 v[198:201], v156 offset:21504
	ds_read_b128 v[202:205], v156 offset:22528
	ds_read_b128 v[206:209], v156 offset:23552
	global_load_lds_dwordx4 v[226:227], off
	v_lshl_add_u64 v[228:229], s[38:39], 0, v[132:133]
	s_mov_b32 m0, s56
	s_nop 0
	global_load_lds_dwordx4 v[228:229], off
	s_barrier
	s_waitcnt lgkmcnt(0)
	s_setprio 1
	s_waitcnt lgkmcnt(0)
	v_mfma_f32_16x16x32_bf16 v[60:63], v[146:149], v[178:181], v[60:63]
	v_mfma_f32_16x16x32_bf16 v[56:59], v[170:173], v[178:181], v[56:59]
	v_mfma_f32_16x16x32_bf16 v[44:47], v[146:149], v[186:189], v[44:47]
	v_mfma_f32_16x16x32_bf16 v[40:43], v[170:173], v[186:189], v[40:43]
	v_mfma_f32_16x16x32_bf16 v[28:31], v[146:149], v[194:197], v[28:31]
	v_mfma_f32_16x16x32_bf16 v[24:27], v[170:173], v[194:197], v[24:27]
	v_mfma_f32_16x16x32_bf16 v[12:15], v[146:149], v[202:205], v[12:15]
	v_mfma_f32_16x16x32_bf16 v[8:11], v[170:173], v[202:205], v[8:11]
	v_mfma_f32_16x16x32_bf16 v[60:63], v[160:163], v[182:185], v[60:63]
	v_mfma_f32_16x16x32_bf16 v[56:59], v[174:177], v[182:185], v[56:59]
	v_mfma_f32_16x16x32_bf16 v[44:47], v[160:163], v[190:193], v[44:47]
	v_mfma_f32_16x16x32_bf16 v[40:43], v[174:177], v[190:193], v[40:43]
	v_mfma_f32_16x16x32_bf16 v[28:31], v[160:163], v[198:201], v[28:31]
	v_mfma_f32_16x16x32_bf16 v[24:27], v[174:177], v[198:201], v[24:27]
	v_mfma_f32_16x16x32_bf16 v[12:15], v[160:163], v[206:209], v[12:15]
	v_mfma_f32_16x16x32_bf16 v[8:11], v[174:177], v[206:209], v[8:11]
	s_setprio 0
	s_barrier
; #define PG8_STAGE(bufoff, gbase, voff) do { _Pragma("unroll") for (int _i = 0; _i < 2; ++_i) \
;         __builtin_amdgcn_global_load_lds((const unsigned*)((const char*)(gbase) + (voff)[_i]), (LAS unsigned*)(lds + (bufoff) + ldsw + _i * 8192), 16, 0, 0); } while (0)
; #define PG8_LDA(dst, b, h) do { _Pragma("unroll") for (int m = 0; m < 4; ++m) _Pragma("unroll") for (int k = 0; k < 2; ++k) dst[m][k] = *(const LAS bf16x8*)(lds + PG8_SA(b, h) + aoff + m * 2048 + k * 1024); } while (0)
; #define PG8_LDB(dst, b, h) do { _Pragma("unroll") for (int n = 0; n < 2; ++n) _Pragma("unroll") for (int k = 0; k < 2; ++k) dst[n][k] = *(const LAS bf16x8*)(lds + PG8_SB(b, h) + boff + n * 2048 + k * 1024); } while (0)
; #define PG8_MMA(ai, bj, At, Bt) do { __builtin_amdgcn_s_setprio(1); _Pragma("unroll") for (int m = 0; m < 4; ++m) _Pragma("unroll") for (int n = 0; n < 2; ++n) _Pragma("unroll") for (int k = 0; k < 2; ++k) \
;         acc[ai][bj][m][n] = __builtin_amdgcn_mfma_f32_16x16x32_bf16(Bt[n][k], At[m][k], acc[ai][bj][m][n], 0, 0, 0); __builtin_amdgcn_s_setprio(0); } while (0)
; #define PG8_WAIT_V(n) asm volatile("s_waitcnt vmcnt(" #n ")" ::: "memory")
; #define PG8_WAIT_L(n) asm volatile("s_waitcnt lgkmcnt(" #n ")" ::: "memory")
; #define PG8_BAR __builtin_amdgcn_s_barrier()
; #define PG8_SCHED __builtin_amdgcn_sched_barrier(0)
;     ...
;             PG8_WAIT_V(6); PG8_BAR; PG8_MMA(1, 1, At, B1); PG8_BAR;
;             PG8_LDB(B0, 1, 0); PG8_SCHED; PG8_LDA(At, 1, 0); PG8_STAGE(PG8_SA(0, 1), a2 + hA, voffA);
;             PG8_WAIT_L(8); PG8_BAR; PG8_WAIT_L(0); PG8_MMA(0, 0, At, B0); PG8_BAR; PG8_SCHED;
;             PG8_LDB(B1, 1, 1); PG8_STAGE(PG8_SB(1, 0), b3, voffB);
;             PG8_BAR; PG8_WAIT_L(0); PG8_MMA(0, 1, At, B1); PG8_BAR;
;             PG8_LDA(At, 1, 1); PG8_STAGE(PG8_SA(1, 0), a3, voffA);
;             PG8_BAR; PG8_WAIT_L(0); PG8_MMA(1, 0, At, B0); PG8_BAR; PG8_SCHED;
	s_add_u32 s44, s36, 0x40000
	s_addc_u32 s45, s37, 0
	s_add_i32 s43, s64, s55
	v_lshl_add_u64 v[146:147], s[44:45], 0, v[130:131]
	s_mov_b32 m0, s43
	s_nop 0
	global_load_lds_dwordx4 v[146:147], off
	v_lshl_add_u64 v[146:147], s[44:45], 0, v[134:135]
	s_add_i32 m0, s43, 0x2000
	s_nop 0
	global_load_lds_dwordx4 v[146:147], off
	s_waitcnt vmcnt(6)
	s_barrier
	s_setprio 1
	v_mfma_f32_16x16x32_bf16 v[52:55], v[210:213], v[178:181], v[52:55]
	v_mfma_f32_16x16x32_bf16 v[48:51], v[218:221], v[178:181], v[48:51]
	v_mfma_f32_16x16x32_bf16 v[36:39], v[210:213], v[186:189], v[36:39]
	v_mfma_f32_16x16x32_bf16 v[32:35], v[218:221], v[186:189], v[32:35]
	v_mfma_f32_16x16x32_bf16 v[20:23], v[210:213], v[194:197], v[20:23]
	v_mfma_f32_16x16x32_bf16 v[16:19], v[218:221], v[194:197], v[16:19]
	v_mfma_f32_16x16x32_bf16 v[4:7], v[210:213], v[202:205], v[4:7]
	v_mfma_f32_16x16x32_bf16 v[0:3], v[218:221], v[202:205], v[0:3]
	v_mfma_f32_16x16x32_bf16 v[52:55], v[214:217], v[182:185], v[52:55]
	v_mfma_f32_16x16x32_bf16 v[48:51], v[222:225], v[182:185], v[48:51]
	v_mfma_f32_16x16x32_bf16 v[36:39], v[214:217], v[190:193], v[36:39]
	v_mfma_f32_16x16x32_bf16 v[32:35], v[222:225], v[190:193], v[32:35]
	v_mfma_f32_16x16x32_bf16 v[20:23], v[214:217], v[198:201], v[20:23]
	v_mfma_f32_16x16x32_bf16 v[16:19], v[222:225], v[198:201], v[16:19]
	v_mfma_f32_16x16x32_bf16 v[4:7], v[214:217], v[206:209], v[4:7]
	v_mfma_f32_16x16x32_bf16 v[0:3], v[222:225], v[206:209], v[0:3]
	s_setprio 0
	s_add_i32 s43, 0, 0x18000
	v_add_u32_e32 v159, s43, v153
	s_barrier
	ds_read_b128 v[146:149], v159
	ds_read_b128 v[160:163], v159 offset:1024
	ds_read_b128 v[170:173], v159 offset:2048
	ds_read_b128 v[174:177], v159 offset:3072
	s_add_u32 s38, s38, 0x40000
	s_addc_u32 s39, s39, 0
	s_mov_b32 m0, s57
	v_lshl_add_u64 v[210:211], s[38:39], 0, v[128:129]
	ds_read_b128 v[178:181], v156 offset:32768
	ds_read_b128 v[182:185], v156 offset:33792
	ds_read_b128 v[186:189], v156 offset:34816
	ds_read_b128 v[190:193], v156 offset:35840
	ds_read_b128 v[194:197], v156 offset:36864
	ds_read_b128 v[198:201], v156 offset:37888
	ds_read_b128 v[202:205], v156 offset:38912
	ds_read_b128 v[206:209], v156 offset:39936
	global_load_lds_dwordx4 v[210:211], off
	v_lshl_add_u64 v[210:211], s[38:39], 0, v[132:133]
	s_mov_b32 m0, s58
	s_nop 0
	global_load_lds_dwordx4 v[210:211], off
	s_waitcnt lgkmcnt(8)
	s_barrier
	s_waitcnt lgkmcnt(0)
	s_setprio 1
	s_waitcnt lgkmcnt(0)
	v_mfma_f32_16x16x32_bf16 v[124:127], v[146:149], v[178:181], v[124:127]
	v_mfma_f32_16x16x32_bf16 v[120:123], v[170:173], v[178:181], v[120:123]
	v_mfma_f32_16x16x32_bf16 v[108:111], v[146:149], v[186:189], v[108:111]
	v_mfma_f32_16x16x32_bf16 v[104:107], v[170:173], v[186:189], v[104:107]
	v_mfma_f32_16x16x32_bf16 v[92:95], v[146:149], v[194:197], v[92:95]
	v_mfma_f32_16x16x32_bf16 v[88:91], v[170:173], v[194:197], v[88:91]
	v_mfma_f32_16x16x32_bf16 v[76:79], v[146:149], v[202:205], v[76:79]
	v_mfma_f32_16x16x32_bf16 v[72:75], v[170:173], v[202:205], v[72:75]
	v_mfma_f32_16x16x32_bf16 v[124:127], v[160:163], v[182:185], v[124:127]
	v_mfma_f32_16x16x32_bf16 v[120:123], v[174:177], v[182:185], v[120:123]
	v_mfma_f32_16x16x32_bf16 v[108:111], v[160:163], v[190:193], v[108:111]
	v_mfma_f32_16x16x32_bf16 v[104:107], v[174:177], v[190:193], v[104:107]
	v_mfma_f32_16x16x32_bf16 v[92:95], v[160:163], v[198:201], v[92:95]
	v_mfma_f32_16x16x32_bf16 v[88:91], v[174:177], v[198:201], v[88:91]
	v_mfma_f32_16x16x32_bf16 v[76:79], v[160:163], v[206:209], v[76:79]
	v_mfma_f32_16x16x32_bf16 v[72:75], v[174:177], v[206:209], v[72:75]
	s_setprio 0
	s_barrier
	s_add_i32 s38, 0, 0x1c000
	s_add_i32 s39, s43, s55
	v_add_u32_e32 v159, s38, v153
	v_lshl_add_u64 v[150:151], v[150:151], 0, s[20:21]
	s_mov_b32 m0, s39
	ds_read_b128 v[210:213], v159
	ds_read_b128 v[214:217], v159 offset:1024
	ds_read_b128 v[218:221], v159 offset:2048
	ds_read_b128 v[222:225], v159 offset:3072
	global_load_lds_dwordx4 v[150:151], off
	v_lshl_add_u64 v[150:151], v[164:165], 0, s[20:21]
	s_add_i32 m0, s39, 0x2000
	s_nop 0
	global_load_lds_dwordx4 v[150:151], off
	s_barrier
	s_waitcnt lgkmcnt(0)
	s_setprio 1
	s_waitcnt lgkmcnt(0)
	v_mfma_f32_16x16x32_bf16 v[116:119], v[210:213], v[178:181], v[116:119]
	v_mfma_f32_16x16x32_bf16 v[112:115], v[218:221], v[178:181], v[112:115]
	v_mfma_f32_16x16x32_bf16 v[100:103], v[210:213], v[186:189], v[100:103]
	v_mfma_f32_16x16x32_bf16 v[96:99], v[218:221], v[186:189], v[96:99]
	v_mfma_f32_16x16x32_bf16 v[84:87], v[210:213], v[194:197], v[84:87]
	v_mfma_f32_16x16x32_bf16 v[80:83], v[218:221], v[194:197], v[80:83]
	v_mfma_f32_16x16x32_bf16 v[68:71], v[210:213], v[202:205], v[68:71]
	v_mfma_f32_16x16x32_bf16 v[64:67], v[218:221], v[202:205], v[64:67]
	v_mfma_f32_16x16x32_bf16 v[116:119], v[214:217], v[182:185], v[116:119]
	v_mfma_f32_16x16x32_bf16 v[112:115], v[222:225], v[182:185], v[112:115]
	v_mfma_f32_16x16x32_bf16 v[100:103], v[214:217], v[190:193], v[100:103]
	v_mfma_f32_16x16x32_bf16 v[96:99], v[222:225], v[190:193], v[96:99]
	v_mfma_f32_16x16x32_bf16 v[84:87], v[214:217], v[198:201], v[84:87]
	v_mfma_f32_16x16x32_bf16 v[80:83], v[222:225], v[198:201], v[80:83]
	v_mfma_f32_16x16x32_bf16 v[68:71], v[214:217], v[206:209], v[68:71]
	v_mfma_f32_16x16x32_bf16 v[64:67], v[222:225], v[206:209], v[64:67]
	s_setprio 0
	s_mov_b32 m0, s60
	v_lshl_add_u64 v[150:151], v[226:227], 0, s[20:21]
	s_barrier
	ds_read_b128 v[178:181], v156 offset:49152
	ds_read_b128 v[182:185], v156 offset:50176
	ds_read_b128 v[186:189], v156 offset:51200
	ds_read_b128 v[190:193], v156 offset:52224
	ds_read_b128 v[194:197], v156 offset:53248
	ds_read_b128 v[198:201], v156 offset:54272
	ds_read_b128 v[202:205], v156 offset:55296
	ds_read_b128 v[206:209], v156 offset:56320
	global_load_lds_dwordx4 v[150:151], off
	v_lshl_add_u64 v[150:151], v[228:229], 0, s[20:21]
	s_mov_b32 m0, s61
	s_nop 0
	global_load_lds_dwordx4 v[150:151], off
	s_barrier
; #define PG8_STAGE(bufoff, gbase, voff) do { _Pragma("unroll") for (int _i = 0; _i < 2; ++_i) \
;         __builtin_amdgcn_global_load_lds((const unsigned*)((const char*)(gbase) + (voff)[_i]), (LAS unsigned*)(lds + (bufoff) + ldsw + _i * 8192), 16, 0, 0); } while (0)
; #define PG8_MMA(ai, bj, At, Bt) do { __builtin_amdgcn_s_setprio(1); _Pragma("unroll") for (int m = 0; m < 4; ++m) _Pragma("unroll") for (int n = 0; n < 2; ++n) _Pragma("unroll") for (int k = 0; k < 2; ++k) \
;         acc[ai][bj][m][n] = __builtin_amdgcn_mfma_f32_16x16x32_bf16(Bt[n][k], At[m][k], acc[ai][bj][m][n], 0, 0, 0); __builtin_amdgcn_s_setprio(0); } while (0)
; #define PG8_WAIT_V(n) asm volatile("s_waitcnt vmcnt(" #n ")" ::: "memory")
; #define PG8_BAR __builtin_amdgcn_s_barrier()
;     ...
;             PG8_STAGE(PG8_SB(1, 1), b3 + hB, voffB);
;             PG8_WAIT_V(6); PG8_BAR; PG8_MMA(1, 1, At, B1); PG8_BAR;
; __device__ __forceinline__ float row_rstd(const float* ssq, int row) {
;     const f32x4* p = (const f32x4*)(ssq + (size_t)row * 16);
;     const f32x4 a = p[0], b = p[1], c = p[2], d = p[3];
;     const float s = ((a[0] + a[1]) + (a[2] + a[3])) + ((b[0] + b[1]) + (b[2] + b[3])) + ((c[0] + c[1]) + (c[2] + c[3])) + ((d[0] + d[1]) + (d[2] + d[3]));
;     return rsqrtf(s * (1.0f / 1024.0f) + 1e-6f);
;     __device__ __forceinline__ void operator()(const f32x4 (&acc)[2][2][4][2], const Unit& u, int wr, int wc, int fr, int fq) const {
;         const int row0 = u.pm * 256 + wr * 64 + fr, col0 = u.pn * 256 + wc * 32 + 8 * fq;
; #pragma unroll
;         for (int ai = 0; ai < 2; ++ai)
; #pragma unroll
;             for (int m = 0; m < 4; ++m) {
;                 const int row = row0 + ai * 128 + m * 16; const float rs = row_rstd(ssq, row);
;                 bf16_t* rowp = O + (size_t)row * ldc + col0;
	s_waitcnt lgkmcnt(0)
	s_setprio 1
	s_waitcnt lgkmcnt(0)
	v_mfma_f32_16x16x32_bf16 v[60:63], v[146:149], v[178:181], v[60:63]
	v_mfma_f32_16x16x32_bf16 v[56:59], v[170:173], v[178:181], v[56:59]
	v_mfma_f32_16x16x32_bf16 v[44:47], v[146:149], v[186:189], v[44:47]
	v_mfma_f32_16x16x32_bf16 v[40:43], v[170:173], v[186:189], v[40:43]
	v_mfma_f32_16x16x32_bf16 v[28:31], v[146:149], v[194:197], v[28:31]
	v_mfma_f32_16x16x32_bf16 v[24:27], v[170:173], v[194:197], v[24:27]
	v_mfma_f32_16x16x32_bf16 v[12:15], v[146:149], v[202:205], v[12:15]
	v_mfma_f32_16x16x32_bf16 v[8:11], v[170:173], v[202:205], v[8:11]
	v_mfma_f32_16x16x32_bf16 v[60:63], v[160:163], v[182:185], v[60:63]
	v_mfma_f32_16x16x32_bf16 v[56:59], v[174:177], v[182:185], v[56:59]
	v_mfma_f32_16x16x32_bf16 v[44:47], v[160:163], v[190:193], v[44:47]
	v_mfma_f32_16x16x32_bf16 v[40:43], v[174:177], v[190:193], v[40:43]
	v_mfma_f32_16x16x32_bf16 v[28:31], v[160:163], v[198:201], v[28:31]
	v_mfma_f32_16x16x32_bf16 v[24:27], v[174:177], v[198:201], v[24:27]
	v_mfma_f32_16x16x32_bf16 v[12:15], v[160:163], v[206:209], v[12:15]
	v_mfma_f32_16x16x32_bf16 v[8:11], v[174:177], v[206:209], v[8:11]
	s_setprio 0
	s_barrier
	s_add_u32 s36, s36, 0x40080
	s_addc_u32 s37, s37, 0
	s_add_i32 s38, s38, s55
	v_lshl_add_u64 v[146:147], s[36:37], 0, v[130:131]
	s_mov_b32 m0, s38
	s_nop 0
	global_load_lds_dwordx4 v[146:147], off
	v_lshl_add_u64 v[146:147], s[36:37], 0, v[134:135]
	s_add_i32 m0, s38, 0x2000
	s_nop 0
	global_load_lds_dwordx4 v[146:147], off
	s_waitcnt vmcnt(6)
	s_barrier
	s_setprio 1
	v_mfma_f32_16x16x32_bf16 v[52:55], v[210:213], v[178:181], v[52:55]
	v_mfma_f32_16x16x32_bf16 v[48:51], v[218:221], v[178:181], v[48:51]
	v_mfma_f32_16x16x32_bf16 v[36:39], v[210:213], v[186:189], v[36:39]
	v_mfma_f32_16x16x32_bf16 v[32:35], v[218:221], v[186:189], v[32:35]
	v_mfma_f32_16x16x32_bf16 v[20:23], v[210:213], v[194:197], v[20:23]
	v_mfma_f32_16x16x32_bf16 v[16:19], v[218:221], v[194:197], v[16:19]
	v_mfma_f32_16x16x32_bf16 v[4:7], v[210:213], v[202:205], v[4:7]
	v_mfma_f32_16x16x32_bf16 v[0:3], v[218:221], v[202:205], v[0:3]
	v_mfma_f32_16x16x32_bf16 v[52:55], v[214:217], v[182:185], v[52:55]
	v_mfma_f32_16x16x32_bf16 v[48:51], v[222:225], v[182:185], v[48:51]
	v_mfma_f32_16x16x32_bf16 v[36:39], v[214:217], v[190:193], v[36:39]
	v_mfma_f32_16x16x32_bf16 v[32:35], v[222:225], v[190:193], v[32:35]
	v_mfma_f32_16x16x32_bf16 v[20:23], v[214:217], v[198:201], v[20:23]
	v_mfma_f32_16x16x32_bf16 v[16:19], v[222:225], v[198:201], v[16:19]
	v_mfma_f32_16x16x32_bf16 v[4:7], v[214:217], v[206:209], v[4:7]
	v_mfma_f32_16x16x32_bf16 v[0:3], v[222:225], v[206:209], v[0:3]
	s_setprio 0
	s_add_i32 s42, s42, 2
	s_add_u32 s25, s25, 0x100
	s_addc_u32 s33, s33, 0
	s_add_u32 s34, s34, 0x100
	s_addc_u32 s35, s35, 0
	s_cmp_gt_u32 s42, 13
	s_barrier
	s_cbranch_scc0 .LBB0_1288
	v_lshl_add_u32 v150, s30, 8, v152
	v_ashrrev_i32_e32 v151, 31, v150
	v_lshlrev_b64 v[146:147], 6, v[150:151]
	v_lshl_add_u64 v[146:147], s[18:19], 0, v[146:147]
	v_subrev_u32_e32 v186, s18, v146
	v_add_u32_e32 v187, 0x0, v186
	global_load_dwordx4 v[188:191], v187, s[18:19]
	v_add_u32_e32 v187, 0x10, v186
	global_load_dwordx4 v[192:195], v187, s[18:19]
	v_add_u32_e32 v187, 0x20, v186
	global_load_dwordx4 v[196:199], v187, s[18:19]
	v_add_u32_e32 v187, 0x30, v186
	global_load_dwordx4 v[200:203], v187, s[18:19]
	v_add_u32_e32 v187, 0x400, v186
	global_load_dwordx4 v[204:207], v187, s[18:19]
	v_add_u32_e32 v187, 0x410, v186
	global_load_dwordx4 v[208:211], v187, s[18:19]
	v_add_u32_e32 v187, 0x420, v186
	global_load_dwordx4 v[212:215], v187, s[18:19]
	v_add_u32_e32 v187, 0x430, v186
	global_load_dwordx4 v[216:219], v187, s[18:19]
	v_add_u32_e32 v187, 0x800, v186
	global_load_dwordx4 v[220:223], v187, s[18:19]
	v_add_u32_e32 v187, 0x810, v186
	global_load_dwordx4 v[232:235], v187, s[18:19]
	v_add_u32_e32 v187, 0x820, v186
	global_load_dwordx4 v[236:239], v187, s[18:19]
	v_add_u32_e32 v187, 0x830, v186
	global_load_dwordx4 v[240:243], v187, s[18:19]
	v_lshl_or_b32 v148, s6, 8, v154
	v_mov_b64_e32 v[146:147], s[16:17]
	v_ashrrev_i32_e32 v149, 31, v148
	v_mad_i64_i32 v[164:165], s[6:7], v150, s66, v[146:147]
	v_or_b32_e32 v182, 16, v150
	v_lshlrev_b64 v[148:149], 1, v[148:149]
	v_ashrrev_i32_e32 v183, 31, v182
	s_mov_b32 s30, s24
	s_mov_b64 s[34:35], s[28:29]
	s_mov_b64 s[36:37], s[26:27]
	s_waitcnt vmcnt(8)
; __device__ __forceinline__ u32x4 pack8(const f32x4 v0, const f32x4 v1) { u32x4 w; w.x = pk2(v0[0], v0[1]); w.y = pk2(v0[2], v0[3]); w.z = pk2(v1[0], v1[1]); w.w = pk2(v1[2], v1[3]); return w; }
; __device__ __forceinline__ float row_rstd(const float* ssq, int row) {
;     const f32x4* p = (const f32x4*)(ssq + (size_t)row * 16);
;     const f32x4 a = p[0], b = p[1], c = p[2], d = p[3];
;     const float s = ((a[0] + a[1]) + (a[2] + a[3])) + ((b[0] + b[1]) + (b[2] + b[3])) + ((c[0] + c[1]) + (c[2] + c[3])) + ((d[0] + d[1]) + (d[2] + d[3]));
;     return rsqrtf(s * (1.0f / 1024.0f) + 1e-6f);
;     __device__ __forceinline__ void operator()(const f32x4 (&acc)[2][2][4][2], const Unit& u, int wr, int wc, int fr, int fq) const {
;         const int row0 = u.pm * 256 + wr * 64 + fr, col0 = u.pn * 256 + wc * 32 + 8 * fq;
; #pragma unroll
;         for (int ai = 0; ai < 2; ++ai)
; #pragma unroll
;             for (int m = 0; m < 4; ++m) {
;                 const int row = row0 + ai * 128 + m * 16; const float rs = row_rstd(ssq, row);
;                 bf16_t* rowp = O + (size_t)row * ldc + col0;
; #pragma unroll
;                 for (int bj = 0; bj < 2; ++bj) { f32x4 v0 = acc[ai][bj][m][0] * rs, v1 = acc[ai][bj][m][1] * rs;
;                     if (ACT == 1) {
; #pragma unroll
;                         for (int j = 0; j < 4; ++j) { const float a = fmaxf(v0[j], 0.f), b = fmaxf(v1[j], 0.f); v0[j] = a * a; v1[j] = b * b; } }
;                     *(u32x4*)(rowp + bj * 128) = pack8(v0, v1); }
	v_mov_b32_e32 v184, v189
	v_mov_b32_e32 v185, v190
	v_mov_b32_e32 v161, v191
	v_mov_b32_e32 v162, v193
	v_mov_b32_e32 v163, v194
	v_mov_b32_e32 v171, v195
	v_mov_b32_e32 v160, v188
	v_pk_add_f32 v[160:161], v[184:185], v[160:161]
	v_mov_b32_e32 v170, v192
	v_pk_add_f32 v[162:163], v[162:163], v[170:171]
	v_pk_add_f32 v[160:161], v[160:161], v[160:161] op_sel:[0,1] op_sel_hi:[1,0]
	v_pk_add_f32 v[162:163], v[162:163], v[162:163] op_sel:[0,1] op_sel_hi:[1,0]
	v_add_f32_e32 v172, v196, v197
	v_add_f32_e32 v174, v198, v199
	v_mov_b32_e32 v173, v202
	v_mov_b32_e32 v175, v203
	v_mov_b32_e32 v161, v200
	v_mov_b32_e32 v163, v201
	v_pk_add_f32 v[170:171], v[172:173], v[174:175]
	v_pk_add_f32 v[160:161], v[160:161], v[162:163]
	v_lshlrev_b64 v[162:163], 6, v[182:183]
	v_pk_add_f32 v[160:161], v[160:161], v[170:171]
	v_lshl_add_u64 v[162:163], s[18:19], 0, v[162:163]
	v_add_f32_e32 v151, v160, v161
	v_fmamk_f32 v151, v151, 0x3a800000, v158
	v_mul_f32_e32 v159, 0x4b800000, v151
	v_cmp_gt_f32_e32 vcc, s65, v151
	v_lshl_add_u64 v[160:161], v[164:165], 0, v[148:149]
	s_nop 0
	v_cndmask_b32_e32 v151, v151, v159, vcc
	v_rsq_f32_e32 v151, v151
	s_nop 0
	v_mul_f32_e32 v159, 0x45800000, v151
	v_cndmask_b32_e32 v164, v151, v159, vcc
	v_pk_mul_f32 v[126:127], v[126:127], v[164:165] op_sel_hi:[1,0]
	v_pk_mul_f32 v[124:125], v[124:125], v[164:165] op_sel_hi:[1,0]
	v_pk_mul_f32 v[122:123], v[122:123], v[164:165] op_sel_hi:[1,0]
	v_pk_mul_f32 v[120:121], v[120:121], v[164:165] op_sel_hi:[1,0]
	v_pk_mul_f32 v[118:119], v[118:119], v[164:165] op_sel_hi:[1,0]
	v_pk_mul_f32 v[116:117], v[116:117], v[164:165] op_sel_hi:[1,0]
	v_pk_mul_f32 v[170:171], v[114:115], v[164:165] op_sel_hi:[1,0]
	v_pk_mul_f32 v[164:165], v[112:113], v[164:165] op_sel_hi:[1,0]
	v_cvt_pk_bf16_f32 v112, v124, v125
	v_cvt_pk_bf16_f32 v113, v126, v127
	v_cvt_pk_bf16_f32 v114, v120, v121
	v_cvt_pk_bf16_f32 v115, v122, v123
	global_store_dwordx4 v[160:161], v[112:115], off
	s_nop 1
	v_cvt_pk_bf16_f32 v112, v116, v117
	v_cvt_pk_bf16_f32 v113, v118, v119
	v_cvt_pk_bf16_f32 v114, v164, v165
	v_cvt_pk_bf16_f32 v115, v170, v171
	global_store_dwordx4 v[160:161], v[112:115], off offset:256
	s_nop 0
	v_or_b32_e32 v160, 32, v150
	v_mad_i64_i32 v[162:163], s[6:7], v182, s66, v[146:147]
	v_ashrrev_i32_e32 v161, 31, v160
	v_add_u32_e32 v187, 0xc00, v186
	global_load_dwordx4 v[188:191], v187, s[18:19]
	v_add_u32_e32 v187, 0xc10, v186
	global_load_dwordx4 v[192:195], v187, s[18:19]
	v_add_u32_e32 v187, 0xc20, v186
	global_load_dwordx4 v[196:199], v187, s[18:19]
	v_add_u32_e32 v187, 0xc30, v186
	global_load_dwordx4 v[200:203], v187, s[18:19]
	s_waitcnt vmcnt(10)
	v_mov_b32_e32 v164, v205
	v_mov_b32_e32 v165, v206
	v_mov_b32_e32 v113, v207
	v_mov_b32_e32 v114, v209
	v_mov_b32_e32 v115, v210
	v_mov_b32_e32 v117, v211
	v_mov_b32_e32 v112, v204
	v_pk_add_f32 v[112:113], v[164:165], v[112:113]
	v_mov_b32_e32 v116, v208
	v_pk_add_f32 v[114:115], v[114:115], v[116:117]
	v_pk_add_f32 v[112:113], v[112:113], v[112:113] op_sel:[0,1] op_sel_hi:[1,0]
	v_pk_add_f32 v[114:115], v[114:115], v[114:115] op_sel:[0,1] op_sel_hi:[1,0]
	v_add_f32_e32 v118, v212, v213
	v_add_f32_e32 v120, v214, v215
	v_mov_b32_e32 v119, v218
	v_mov_b32_e32 v121, v219
	v_mov_b32_e32 v113, v216
	v_mov_b32_e32 v115, v217
	v_pk_add_f32 v[116:117], v[118:119], v[120:121]
	v_pk_add_f32 v[112:113], v[112:113], v[114:115]
	v_lshlrev_b64 v[114:115], 6, v[160:161]
	v_pk_add_f32 v[112:113], v[112:113], v[116:117]
	v_lshl_add_u64 v[114:115], s[18:19], 0, v[114:115]
	v_add_f32_e32 v112, v112, v113
	v_fmamk_f32 v112, v112, 0x3a800000, v158
	v_mul_f32_e32 v113, 0x4b800000, v112
	v_cmp_gt_f32_e32 vcc, s65, v112
	s_nop 1
	v_cndmask_b32_e32 v112, v112, v113, vcc
	v_rsq_f32_e32 v116, v112
	v_lshl_add_u64 v[112:113], v[162:163], 0, v[148:149]
	v_mul_f32_e32 v117, 0x45800000, v116
	v_cndmask_b32_e32 v116, v116, v117, vcc
	v_pk_mul_f32 v[110:111], v[110:111], v[116:117] op_sel_hi:[1,0]
	v_pk_mul_f32 v[108:109], v[108:109], v[116:117] op_sel_hi:[1,0]
	v_pk_mul_f32 v[106:107], v[106:107], v[116:117] op_sel_hi:[1,0]
	v_pk_mul_f32 v[104:105], v[104:105], v[116:117] op_sel_hi:[1,0]
	v_pk_mul_f32 v[102:103], v[102:103], v[116:117] op_sel_hi:[1,0]
	v_pk_mul_f32 v[100:101], v[100:101], v[116:117] op_sel_hi:[1,0]
	v_pk_mul_f32 v[118:119], v[98:99], v[116:117] op_sel_hi:[1,0]
	v_pk_mul_f32 v[116:117], v[96:97], v[116:117] op_sel_hi:[1,0]
	v_cvt_pk_bf16_f32 v96, v108, v109
	v_cvt_pk_bf16_f32 v97, v110, v111
	v_cvt_pk_bf16_f32 v98, v104, v105
	v_cvt_pk_bf16_f32 v99, v106, v107
	global_store_dwordx4 v[112:113], v[96:99], off
	s_nop 1
	v_cvt_pk_bf16_f32 v96, v100, v101
	v_cvt_pk_bf16_f32 v97, v102, v103
	v_cvt_pk_bf16_f32 v98, v116, v117
	v_cvt_pk_bf16_f32 v99, v118, v119
	global_store_dwordx4 v[112:113], v[96:99], off offset:256
	s_nop 0
	v_or_b32_e32 v112, 48, v150
	v_mad_i64_i32 v[114:115], s[6:7], v160, s66, v[146:147]
	v_ashrrev_i32_e32 v113, 31, v112
	v_add_u32_e32 v187, 0x2000, v186
	global_load_dwordx4 v[204:207], v187, s[18:19]
	v_add_u32_e32 v187, 0x2010, v186
	global_load_dwordx4 v[208:211], v187, s[18:19]
	v_add_u32_e32 v187, 0x2020, v186
	global_load_dwordx4 v[212:215], v187, s[18:19]
	v_add_u32_e32 v187, 0x2030, v186
	global_load_dwordx4 v[216:219], v187, s[18:19]
	s_waitcnt vmcnt(12)
; __device__ __forceinline__ u32x4 pack8(const f32x4 v0, const f32x4 v1) { u32x4 w; w.x = pk2(v0[0], v0[1]); w.y = pk2(v0[2], v0[3]); w.z = pk2(v1[0], v1[1]); w.w = pk2(v1[2], v1[3]); return w; }
; __device__ __forceinline__ float row_rstd(const float* ssq, int row) {
;     const f32x4* p = (const f32x4*)(ssq + (size_t)row * 16);
;     const f32x4 a = p[0], b = p[1], c = p[2], d = p[3];
;     const float s = ((a[0] + a[1]) + (a[2] + a[3])) + ((b[0] + b[1]) + (b[2] + b[3])) + ((c[0] + c[1]) + (c[2] + c[3])) + ((d[0] + d[1]) + (d[2] + d[3]));
;     return rsqrtf(s * (1.0f / 1024.0f) + 1e-6f);
;     __device__ __forceinline__ void operator()(const f32x4 (&acc)[2][2][4][2], const Unit& u, int wr, int wc, int fr, int fq) const {
;         const int row0 = u.pm * 256 + wr * 64 + fr, col0 = u.pn * 256 + wc * 32 + 8 * fq;
; #pragma unroll
;         for (int ai = 0; ai < 2; ++ai)
; #pragma unroll
;             for (int m = 0; m < 4; ++m) {
;                 const int row = row0 + ai * 128 + m * 16; const float rs = row_rstd(ssq, row);
;                 bf16_t* rowp = O + (size_t)row * ldc + col0;
; #pragma unroll
;                 for (int bj = 0; bj < 2; ++bj) { f32x4 v0 = acc[ai][bj][m][0] * rs, v1 = acc[ai][bj][m][1] * rs;
;                     if (ACT == 1) {
; #pragma unroll
;                         for (int j = 0; j < 4; ++j) { const float a = fmaxf(v0[j], 0.f), b = fmaxf(v1[j], 0.f); v0[j] = a * a; v1[j] = b * b; } }
;                     *(u32x4*)(rowp + bj * 128) = pack8(v0, v1); }
	v_mov_b32_e32 v116, v221
	v_mov_b32_e32 v117, v222
	v_mov_b32_e32 v97, v223
	v_mov_b32_e32 v98, v233
	v_mov_b32_e32 v99, v234
	v_mov_b32_e32 v101, v235
	v_mov_b32_e32 v96, v220
	v_pk_add_f32 v[96:97], v[116:117], v[96:97]
	v_mov_b32_e32 v100, v232
	v_pk_add_f32 v[98:99], v[98:99], v[100:101]
	v_pk_add_f32 v[96:97], v[96:97], v[96:97] op_sel:[0,1] op_sel_hi:[1,0]
	v_pk_add_f32 v[98:99], v[98:99], v[98:99] op_sel:[0,1] op_sel_hi:[1,0]
	v_add_f32_e32 v102, v236, v237
	v_add_f32_e32 v104, v238, v239
	v_mov_b32_e32 v103, v242
	v_mov_b32_e32 v105, v243
	v_mov_b32_e32 v97, v240
	v_mov_b32_e32 v99, v241
	v_pk_add_f32 v[100:101], v[102:103], v[104:105]
	v_pk_add_f32 v[96:97], v[96:97], v[98:99]
	v_lshlrev_b64 v[98:99], 6, v[112:113]
	v_pk_add_f32 v[96:97], v[96:97], v[100:101]
	v_lshl_add_u64 v[98:99], s[18:19], 0, v[98:99]
	v_add_f32_e32 v96, v96, v97
	v_fmamk_f32 v96, v96, 0x3a800000, v158
	v_mul_f32_e32 v97, 0x4b800000, v96
	v_cmp_gt_f32_e32 vcc, s65, v96
	s_nop 1
	v_cndmask_b32_e32 v96, v96, v97, vcc
	v_rsq_f32_e32 v100, v96
	v_lshl_add_u64 v[96:97], v[114:115], 0, v[148:149]
	v_mul_f32_e32 v101, 0x45800000, v100
	v_cndmask_b32_e32 v100, v100, v101, vcc
	v_pk_mul_f32 v[94:95], v[94:95], v[100:101] op_sel_hi:[1,0]
	v_pk_mul_f32 v[92:93], v[92:93], v[100:101] op_sel_hi:[1,0]
	v_pk_mul_f32 v[90:91], v[90:91], v[100:101] op_sel_hi:[1,0]
	v_pk_mul_f32 v[88:89], v[88:89], v[100:101] op_sel_hi:[1,0]
	v_pk_mul_f32 v[86:87], v[86:87], v[100:101] op_sel_hi:[1,0]
	v_pk_mul_f32 v[84:85], v[84:85], v[100:101] op_sel_hi:[1,0]
	v_pk_mul_f32 v[102:103], v[82:83], v[100:101] op_sel_hi:[1,0]
	v_pk_mul_f32 v[100:101], v[80:81], v[100:101] op_sel_hi:[1,0]
	v_cvt_pk_bf16_f32 v80, v92, v93
	v_cvt_pk_bf16_f32 v81, v94, v95
	v_cvt_pk_bf16_f32 v82, v88, v89
	v_cvt_pk_bf16_f32 v83, v90, v91
	global_store_dwordx4 v[96:97], v[80:83], off
	s_nop 1
	v_cvt_pk_bf16_f32 v80, v84, v85
	v_cvt_pk_bf16_f32 v81, v86, v87
	v_cvt_pk_bf16_f32 v82, v100, v101
	v_cvt_pk_bf16_f32 v83, v102, v103
	global_store_dwordx4 v[96:97], v[80:83], off offset:256
	s_nop 0
	v_add_u32_e32 v96, 0x80, v150
	v_mad_i64_i32 v[98:99], s[6:7], v112, s66, v[146:147]
	v_ashrrev_i32_e32 v97, 31, v96
	v_add_u32_e32 v187, 0x2400, v186
	global_load_dwordx4 v[220:223], v187, s[18:19]
	v_add_u32_e32 v187, 0x2410, v186
	global_load_dwordx4 v[232:235], v187, s[18:19]
	v_add_u32_e32 v187, 0x2420, v186
	global_load_dwordx4 v[236:239], v187, s[18:19]
	v_add_u32_e32 v187, 0x2430, v186
	global_load_dwordx4 v[240:243], v187, s[18:19]
	s_waitcnt vmcnt(12)
	v_mov_b32_e32 v100, v189
	v_mov_b32_e32 v101, v190
	v_mov_b32_e32 v81, v191
	v_mov_b32_e32 v82, v193
	v_mov_b32_e32 v83, v194
	v_mov_b32_e32 v85, v195
	v_mov_b32_e32 v80, v188
	v_pk_add_f32 v[80:81], v[100:101], v[80:81]
	v_mov_b32_e32 v84, v192
	v_pk_add_f32 v[82:83], v[82:83], v[84:85]
	v_pk_add_f32 v[80:81], v[80:81], v[80:81] op_sel:[0,1] op_sel_hi:[1,0]
	v_pk_add_f32 v[82:83], v[82:83], v[82:83] op_sel:[0,1] op_sel_hi:[1,0]
	v_add_f32_e32 v86, v196, v197
	v_add_f32_e32 v88, v198, v199
	v_mov_b32_e32 v87, v202
	v_mov_b32_e32 v89, v203
	v_mov_b32_e32 v81, v200
	v_mov_b32_e32 v83, v201
	v_pk_add_f32 v[84:85], v[86:87], v[88:89]
	v_pk_add_f32 v[80:81], v[80:81], v[82:83]
	v_lshlrev_b64 v[82:83], 6, v[96:97]
	v_pk_add_f32 v[80:81], v[80:81], v[84:85]
	v_lshl_add_u64 v[82:83], s[18:19], 0, v[82:83]
	v_add_f32_e32 v80, v80, v81
	v_fmamk_f32 v80, v80, 0x3a800000, v158
	v_mul_f32_e32 v81, 0x4b800000, v80
	v_cmp_gt_f32_e32 vcc, s65, v80
	s_nop 1
	v_cndmask_b32_e32 v80, v80, v81, vcc
	v_rsq_f32_e32 v84, v80
	v_lshl_add_u64 v[80:81], v[98:99], 0, v[148:149]
	v_mul_f32_e32 v85, 0x45800000, v84
	v_cndmask_b32_e32 v84, v84, v85, vcc
	v_pk_mul_f32 v[78:79], v[78:79], v[84:85] op_sel_hi:[1,0]
	v_pk_mul_f32 v[76:77], v[76:77], v[84:85] op_sel_hi:[1,0]
	v_pk_mul_f32 v[74:75], v[74:75], v[84:85] op_sel_hi:[1,0]
	v_pk_mul_f32 v[72:73], v[72:73], v[84:85] op_sel_hi:[1,0]
	v_pk_mul_f32 v[70:71], v[70:71], v[84:85] op_sel_hi:[1,0]
	v_pk_mul_f32 v[68:69], v[68:69], v[84:85] op_sel_hi:[1,0]
	v_pk_mul_f32 v[86:87], v[66:67], v[84:85] op_sel_hi:[1,0]
	v_pk_mul_f32 v[84:85], v[64:65], v[84:85] op_sel_hi:[1,0]
	v_cvt_pk_bf16_f32 v64, v76, v77
	v_cvt_pk_bf16_f32 v65, v78, v79
	v_cvt_pk_bf16_f32 v66, v72, v73
	v_cvt_pk_bf16_f32 v67, v74, v75
	global_store_dwordx4 v[80:81], v[64:67], off
	s_nop 1
	v_cvt_pk_bf16_f32 v64, v68, v69
	v_cvt_pk_bf16_f32 v65, v70, v71
	v_cvt_pk_bf16_f32 v66, v84, v85
	v_cvt_pk_bf16_f32 v67, v86, v87
	global_store_dwordx4 v[80:81], v[64:67], off offset:256
	s_nop 0
	v_add_u32_e32 v80, 0x90, v150
	v_mad_i64_i32 v[82:83], s[6:7], v96, s66, v[146:147]
	v_ashrrev_i32_e32 v81, 31, v80
	v_add_u32_e32 v187, 0x2800, v186
	global_load_dwordx4 v[188:191], v187, s[18:19]
	v_add_u32_e32 v187, 0x2810, v186
	global_load_dwordx4 v[192:195], v187, s[18:19]
	v_add_u32_e32 v187, 0x2820, v186
	global_load_dwordx4 v[196:199], v187, s[18:19]
	v_add_u32_e32 v187, 0x2830, v186
	global_load_dwordx4 v[200:203], v187, s[18:19]
	s_waitcnt vmcnt(12)
; __device__ __forceinline__ u32x4 pack8(const f32x4 v0, const f32x4 v1) { u32x4 w; w.x = pk2(v0[0], v0[1]); w.y = pk2(v0[2], v0[3]); w.z = pk2(v1[0], v1[1]); w.w = pk2(v1[2], v1[3]); return w; }
; __device__ __forceinline__ float row_rstd(const float* ssq, int row) {
;     const f32x4* p = (const f32x4*)(ssq + (size_t)row * 16);
;     const f32x4 a = p[0], b = p[1], c = p[2], d = p[3];
;     const float s = ((a[0] + a[1]) + (a[2] + a[3])) + ((b[0] + b[1]) + (b[2] + b[3])) + ((c[0] + c[1]) + (c[2] + c[3])) + ((d[0] + d[1]) + (d[2] + d[3]));
;     return rsqrtf(s * (1.0f / 1024.0f) + 1e-6f);
;     __device__ __forceinline__ void operator()(const f32x4 (&acc)[2][2][4][2], const Unit& u, int wr, int wc, int fr, int fq) const {
;         const int row0 = u.pm * 256 + wr * 64 + fr, col0 = u.pn * 256 + wc * 32 + 8 * fq;
; #pragma unroll
;         for (int ai = 0; ai < 2; ++ai)
; #pragma unroll
;             for (int m = 0; m < 4; ++m) {
;                 const int row = row0 + ai * 128 + m * 16; const float rs = row_rstd(ssq, row);
;                 bf16_t* rowp = O + (size_t)row * ldc + col0;
; #pragma unroll
;                 for (int bj = 0; bj < 2; ++bj) { f32x4 v0 = acc[ai][bj][m][0] * rs, v1 = acc[ai][bj][m][1] * rs;
;                     if (ACT == 1) {
; #pragma unroll
;                         for (int j = 0; j < 4; ++j) { const float a = fmaxf(v0[j], 0.f), b = fmaxf(v1[j], 0.f); v0[j] = a * a; v1[j] = b * b; } }
;                     *(u32x4*)(rowp + bj * 128) = pack8(v0, v1); }
	v_mov_b32_e32 v84, v205
	v_mov_b32_e32 v85, v206
	v_mov_b32_e32 v65, v207
	v_mov_b32_e32 v66, v209
	v_mov_b32_e32 v67, v210
	v_mov_b32_e32 v69, v211
	v_mov_b32_e32 v64, v204
	v_pk_add_f32 v[64:65], v[84:85], v[64:65]
	v_mov_b32_e32 v68, v208
	v_pk_add_f32 v[66:67], v[66:67], v[68:69]
	v_pk_add_f32 v[64:65], v[64:65], v[64:65] op_sel:[0,1] op_sel_hi:[1,0]
	v_pk_add_f32 v[66:67], v[66:67], v[66:67] op_sel:[0,1] op_sel_hi:[1,0]
	v_add_f32_e32 v70, v212, v213
	v_add_f32_e32 v72, v214, v215
	v_mov_b32_e32 v71, v218
	v_mov_b32_e32 v73, v219
	v_mov_b32_e32 v65, v216
	v_mov_b32_e32 v67, v217
	v_pk_add_f32 v[68:69], v[70:71], v[72:73]
	v_pk_add_f32 v[64:65], v[64:65], v[66:67]
	v_lshlrev_b64 v[66:67], 6, v[80:81]
	v_pk_add_f32 v[64:65], v[64:65], v[68:69]
	v_lshl_add_u64 v[66:67], s[18:19], 0, v[66:67]
	v_add_f32_e32 v64, v64, v65
	v_fmamk_f32 v64, v64, 0x3a800000, v158
	v_mul_f32_e32 v65, 0x4b800000, v64
	v_cmp_gt_f32_e32 vcc, s65, v64
	s_nop 1
	v_cndmask_b32_e32 v64, v64, v65, vcc
	v_rsq_f32_e32 v68, v64
	v_lshl_add_u64 v[64:65], v[82:83], 0, v[148:149]
	v_mul_f32_e32 v69, 0x45800000, v68
	v_cndmask_b32_e32 v68, v68, v69, vcc
	v_pk_mul_f32 v[62:63], v[62:63], v[68:69] op_sel_hi:[1,0]
	v_pk_mul_f32 v[60:61], v[60:61], v[68:69] op_sel_hi:[1,0]
	v_pk_mul_f32 v[58:59], v[58:59], v[68:69] op_sel_hi:[1,0]
	v_pk_mul_f32 v[56:57], v[56:57], v[68:69] op_sel_hi:[1,0]
	v_pk_mul_f32 v[54:55], v[54:55], v[68:69] op_sel_hi:[1,0]
	v_pk_mul_f32 v[52:53], v[52:53], v[68:69] op_sel_hi:[1,0]
	v_pk_mul_f32 v[70:71], v[50:51], v[68:69] op_sel_hi:[1,0]
	v_pk_mul_f32 v[68:69], v[48:49], v[68:69] op_sel_hi:[1,0]
	v_cvt_pk_bf16_f32 v48, v60, v61
	v_cvt_pk_bf16_f32 v49, v62, v63
	v_cvt_pk_bf16_f32 v50, v56, v57
	v_cvt_pk_bf16_f32 v51, v58, v59
	global_store_dwordx4 v[64:65], v[48:51], off
	s_nop 1
	v_cvt_pk_bf16_f32 v48, v52, v53
	v_cvt_pk_bf16_f32 v49, v54, v55
	v_cvt_pk_bf16_f32 v50, v68, v69
	v_cvt_pk_bf16_f32 v51, v70, v71
	global_store_dwordx4 v[64:65], v[48:51], off offset:256
	s_nop 0
	v_add_u32_e32 v64, 0xa0, v150
	v_mad_i64_i32 v[66:67], s[6:7], v80, s66, v[146:147]
	v_ashrrev_i32_e32 v65, 31, v64
	v_add_u32_e32 v187, 0x2c00, v186
	global_load_dwordx4 v[204:207], v187, s[18:19]
	v_add_u32_e32 v187, 0x2c10, v186
	global_load_dwordx4 v[208:211], v187, s[18:19]
	v_add_u32_e32 v187, 0x2c20, v186
	global_load_dwordx4 v[212:215], v187, s[18:19]
	v_add_u32_e32 v187, 0x2c30, v186
	global_load_dwordx4 v[216:219], v187, s[18:19]
	s_waitcnt vmcnt(12)
	v_mov_b32_e32 v68, v221
	v_mov_b32_e32 v69, v222
	v_mov_b32_e32 v49, v223
	v_mov_b32_e32 v50, v233
	v_mov_b32_e32 v51, v234
	v_mov_b32_e32 v53, v235
	v_mov_b32_e32 v48, v220
	v_pk_add_f32 v[48:49], v[68:69], v[48:49]
	v_mov_b32_e32 v52, v232
	v_pk_add_f32 v[50:51], v[50:51], v[52:53]
	v_pk_add_f32 v[48:49], v[48:49], v[48:49] op_sel:[0,1] op_sel_hi:[1,0]
	v_pk_add_f32 v[50:51], v[50:51], v[50:51] op_sel:[0,1] op_sel_hi:[1,0]
	v_add_f32_e32 v54, v236, v237
	v_add_f32_e32 v56, v238, v239
	v_mov_b32_e32 v55, v242
	v_mov_b32_e32 v57, v243
	v_mov_b32_e32 v49, v240
	v_mov_b32_e32 v51, v241
	v_pk_add_f32 v[52:53], v[54:55], v[56:57]
	v_pk_add_f32 v[48:49], v[48:49], v[50:51]
	v_lshlrev_b64 v[50:51], 6, v[64:65]
	v_pk_add_f32 v[48:49], v[48:49], v[52:53]
	v_lshl_add_u64 v[50:51], s[18:19], 0, v[50:51]
	v_add_f32_e32 v48, v48, v49
	v_fmamk_f32 v48, v48, 0x3a800000, v158
	v_mul_f32_e32 v49, 0x4b800000, v48
	v_cmp_gt_f32_e32 vcc, s65, v48
	s_nop 1
	v_cndmask_b32_e32 v48, v48, v49, vcc
	v_rsq_f32_e32 v52, v48
	v_lshl_add_u64 v[48:49], v[66:67], 0, v[148:149]
	v_mul_f32_e32 v53, 0x45800000, v52
	v_cndmask_b32_e32 v52, v52, v53, vcc
	v_pk_mul_f32 v[46:47], v[46:47], v[52:53] op_sel_hi:[1,0]
	v_pk_mul_f32 v[44:45], v[44:45], v[52:53] op_sel_hi:[1,0]
	v_pk_mul_f32 v[42:43], v[42:43], v[52:53] op_sel_hi:[1,0]
	v_pk_mul_f32 v[40:41], v[40:41], v[52:53] op_sel_hi:[1,0]
	v_pk_mul_f32 v[38:39], v[38:39], v[52:53] op_sel_hi:[1,0]
	v_pk_mul_f32 v[36:37], v[36:37], v[52:53] op_sel_hi:[1,0]
	v_pk_mul_f32 v[54:55], v[34:35], v[52:53] op_sel_hi:[1,0]
	v_pk_mul_f32 v[52:53], v[32:33], v[52:53] op_sel_hi:[1,0]
	v_cvt_pk_bf16_f32 v32, v44, v45
	v_cvt_pk_bf16_f32 v33, v46, v47
	v_cvt_pk_bf16_f32 v34, v40, v41
	v_cvt_pk_bf16_f32 v35, v42, v43
	global_store_dwordx4 v[48:49], v[32:35], off
	s_nop 1
	v_cvt_pk_bf16_f32 v32, v36, v37
	v_cvt_pk_bf16_f32 v33, v38, v39
	v_cvt_pk_bf16_f32 v34, v52, v53
	v_cvt_pk_bf16_f32 v35, v54, v55
	global_store_dwordx4 v[48:49], v[32:35], off offset:256
	s_nop 0
	v_add_u32_e32 v48, 0xb0, v150
	v_mad_i64_i32 v[50:51], s[6:7], v64, s66, v[146:147]
	v_ashrrev_i32_e32 v49, 31, v48
	s_mov_b32 s6, s22
	s_waitcnt vmcnt(8)
; #define PG8_WAIT_V(n) asm volatile("s_waitcnt vmcnt(" #n ")" ::: "memory")
; #define PG8_BAR __builtin_amdgcn_s_barrier()
; __device__ __forceinline__ u32x4 pack8(const f32x4 v0, const f32x4 v1) { u32x4 w; w.x = pk2(v0[0], v0[1]); w.y = pk2(v0[2], v0[3]); w.z = pk2(v1[0], v1[1]); w.w = pk2(v1[2], v1[3]); return w; }
;     ...
;         E(acc, cur, wr, wc, fr, fq);
;         if (!has_next) break;
; #pragma unroll
;         for (int a = 0; a < 2; ++a)
; #pragma unroll
;             for (int b = 0; b < 2; ++b)
; #pragma unroll
;                 for (int m = 0; m < 4; ++m)
; #pragma unroll
;                     for (int n = 0; n < 2; ++n) acc[a][b][m][n] = (f32x4){0.f, 0.f, 0.f, 0.f};
;         cur = nxt; cA = nA; cB = nB; ++ui;
;     }
;     PG8_WAIT_V(0);
;     if (wr == 0) PG8_BAR;
;     PG8_BAR;
; __device__ __forceinline__ float row_rstd(const float* ssq, int row) {
;     const f32x4* p = (const f32x4*)(ssq + (size_t)row * 16);
;     const f32x4 a = p[0], b = p[1], c = p[2], d = p[3];
;     const float s = ((a[0] + a[1]) + (a[2] + a[3])) + ((b[0] + b[1]) + (b[2] + b[3])) + ((c[0] + c[1]) + (c[2] + c[3])) + ((d[0] + d[1]) + (d[2] + d[3]));
;     return rsqrtf(s * (1.0f / 1024.0f) + 1e-6f);
;     __device__ __forceinline__ void operator()(const f32x4 (&acc)[2][2][4][2], const Unit& u, int wr, int wc, int fr, int fq) const {
;         const int row0 = u.pm * 256 + wr * 64 + fr, col0 = u.pn * 256 + wc * 32 + 8 * fq;
; #pragma unroll
;         for (int ai = 0; ai < 2; ++ai)
; #pragma unroll
;             for (int m = 0; m < 4; ++m) {
;                 const int row = row0 + ai * 128 + m * 16; const float rs = row_rstd(ssq, row);
;                 bf16_t* rowp = O + (size_t)row * ldc + col0;
; #pragma unroll
;                 for (int bj = 0; bj < 2; ++bj) { f32x4 v0 = acc[ai][bj][m][0] * rs, v1 = acc[ai][bj][m][1] * rs;
;                     if (ACT == 1) {
; #pragma unroll
;                         for (int j = 0; j < 4; ++j) { const float a = fmaxf(v0[j], 0.f), b = fmaxf(v1[j], 0.f); v0[j] = a * a; v1[j] = b * b; } }
;                     *(u32x4*)(rowp + bj * 128) = pack8(v0, v1); }
	v_mov_b32_e32 v52, v189
	v_mov_b32_e32 v53, v190
	v_mov_b32_e32 v33, v191
	v_mov_b32_e32 v34, v193
	v_mov_b32_e32 v35, v194
	v_mov_b32_e32 v37, v195
	v_mov_b32_e32 v32, v188
	v_pk_add_f32 v[32:33], v[52:53], v[32:33]
	v_mov_b32_e32 v36, v192
	v_pk_add_f32 v[34:35], v[34:35], v[36:37]
	v_pk_add_f32 v[32:33], v[32:33], v[32:33] op_sel:[0,1] op_sel_hi:[1,0]
	v_pk_add_f32 v[34:35], v[34:35], v[34:35] op_sel:[0,1] op_sel_hi:[1,0]
	v_add_f32_e32 v38, v196, v197
	v_add_f32_e32 v40, v198, v199
	v_mov_b32_e32 v39, v202
	v_mov_b32_e32 v41, v203
	v_mov_b32_e32 v33, v200
	v_mov_b32_e32 v35, v201
	v_pk_add_f32 v[36:37], v[38:39], v[40:41]
	v_pk_add_f32 v[32:33], v[32:33], v[34:35]
	v_lshlrev_b64 v[34:35], 6, v[48:49]
	v_pk_add_f32 v[32:33], v[32:33], v[36:37]
	v_lshl_add_u64 v[34:35], s[18:19], 0, v[34:35]
	v_add_f32_e32 v32, v32, v33
	v_fmamk_f32 v32, v32, 0x3a800000, v158
	v_mul_f32_e32 v33, 0x4b800000, v32
	v_cmp_gt_f32_e32 vcc, s65, v32
	s_nop 1
	v_cndmask_b32_e32 v32, v32, v33, vcc
	v_rsq_f32_e32 v36, v32
	v_lshl_add_u64 v[32:33], v[50:51], 0, v[148:149]
	v_mul_f32_e32 v37, 0x45800000, v36
	v_cndmask_b32_e32 v36, v36, v37, vcc
	v_pk_mul_f32 v[30:31], v[30:31], v[36:37] op_sel_hi:[1,0]
	v_pk_mul_f32 v[28:29], v[28:29], v[36:37] op_sel_hi:[1,0]
	v_pk_mul_f32 v[26:27], v[26:27], v[36:37] op_sel_hi:[1,0]
	v_pk_mul_f32 v[24:25], v[24:25], v[36:37] op_sel_hi:[1,0]
	v_pk_mul_f32 v[22:23], v[22:23], v[36:37] op_sel_hi:[1,0]
	v_pk_mul_f32 v[20:21], v[20:21], v[36:37] op_sel_hi:[1,0]
	v_pk_mul_f32 v[38:39], v[18:19], v[36:37] op_sel_hi:[1,0]
	v_pk_mul_f32 v[36:37], v[16:17], v[36:37] op_sel_hi:[1,0]
	v_cvt_pk_bf16_f32 v16, v28, v29
	v_cvt_pk_bf16_f32 v17, v30, v31
	v_cvt_pk_bf16_f32 v18, v24, v25
	v_cvt_pk_bf16_f32 v19, v26, v27
	global_store_dwordx4 v[32:33], v[16:19], off
	s_and_b64 vcc, exec, s[10:11]
	s_nop 0
	v_cvt_pk_bf16_f32 v16, v20, v21
	v_cvt_pk_bf16_f32 v17, v22, v23
	v_cvt_pk_bf16_f32 v18, v36, v37
	v_cvt_pk_bf16_f32 v19, v38, v39
	global_store_dwordx4 v[32:33], v[16:19], off offset:256
	s_nop 0
	s_waitcnt vmcnt(4)
	v_mov_b32_e32 v32, v205
	v_mov_b32_e32 v33, v206
	v_mov_b32_e32 v17, v207
	v_mov_b32_e32 v18, v209
	v_mov_b32_e32 v19, v210
	v_mov_b32_e32 v21, v211
	v_mov_b32_e32 v16, v204
	v_pk_add_f32 v[16:17], v[32:33], v[16:17]
	v_mov_b32_e32 v20, v208
	v_pk_add_f32 v[18:19], v[18:19], v[20:21]
	v_pk_add_f32 v[16:17], v[16:17], v[16:17] op_sel:[0,1] op_sel_hi:[1,0]
	v_pk_add_f32 v[18:19], v[18:19], v[18:19] op_sel:[0,1] op_sel_hi:[1,0]
	v_add_f32_e32 v22, v212, v213
	v_add_f32_e32 v24, v214, v215
	v_mov_b32_e32 v23, v218
	v_mov_b32_e32 v25, v219
	v_mov_b32_e32 v17, v216
	v_mov_b32_e32 v19, v217
	v_pk_add_f32 v[20:21], v[22:23], v[24:25]
	v_pk_add_f32 v[16:17], v[16:17], v[18:19]
	s_nop 0
	v_pk_add_f32 v[16:17], v[16:17], v[20:21]
	s_nop 0
	v_add_f32_e32 v16, v16, v17
	v_fmamk_f32 v16, v16, 0x3a800000, v158
	v_mul_f32_e32 v17, 0x4b800000, v16
	v_cmp_gt_f32_e64 s[10:11], s65, v16
	s_nop 1
	v_cndmask_b32_e64 v16, v16, v17, s[10:11]
	v_rsq_f32_e32 v18, v16
	v_mad_i64_i32 v[16:17], s[8:9], v48, s66, v[146:147]
	v_lshl_add_u64 v[16:17], v[16:17], 0, v[148:149]
	v_mul_f32_e32 v19, 0x45800000, v18
	v_cndmask_b32_e64 v18, v18, v19, s[10:11]
	v_pk_mul_f32 v[14:15], v[14:15], v[18:19] op_sel_hi:[1,0]
	v_pk_mul_f32 v[12:13], v[12:13], v[18:19] op_sel_hi:[1,0]
	v_pk_mul_f32 v[10:11], v[10:11], v[18:19] op_sel_hi:[1,0]
	v_pk_mul_f32 v[8:9], v[8:9], v[18:19] op_sel_hi:[1,0]
	v_pk_mul_f32 v[6:7], v[6:7], v[18:19] op_sel_hi:[1,0]
	v_pk_mul_f32 v[4:5], v[4:5], v[18:19] op_sel_hi:[1,0]
	v_pk_mul_f32 v[20:21], v[2:3], v[18:19] op_sel_hi:[1,0]
	v_pk_mul_f32 v[18:19], v[0:1], v[18:19] op_sel_hi:[1,0]
	v_cvt_pk_bf16_f32 v0, v12, v13
	v_cvt_pk_bf16_f32 v1, v14, v15
	v_cvt_pk_bf16_f32 v2, v8, v9
	v_cvt_pk_bf16_f32 v3, v10, v11
	global_store_dwordx4 v[16:17], v[0:3], off
	s_nop 1
	v_cvt_pk_bf16_f32 v0, v4, v5
	v_cvt_pk_bf16_f32 v1, v6, v7
	v_cvt_pk_bf16_f32 v2, v18, v19
	v_cvt_pk_bf16_f32 v3, v20, v21
	global_store_dwordx4 v[16:17], v[0:3], off offset:256
	s_cbranch_vccz .LBB0_1281
	s_waitcnt vmcnt(0)
	s_cmpk_gt_u32 s53, 0xff
	s_cbranch_scc1 .LBB0_1292
	s_barrier

; #define PG8_STAGE(bufoff, gbase, voff) do { _Pragma("unroll") for (int _i = 0; _i < 2; ++_i) \
;         __builtin_amdgcn_global_load_lds((const unsigned*)((const char*)(gbase) + (voff)[_i]), (LAS unsigned*)(lds + (bufoff) + ldsw + _i * 8192), 16, 0, 0); } while (0)
; #define PG8_LDA(dst, b, h) do { _Pragma("unroll") for (int m = 0; m < 4; ++m) _Pragma("unroll") for (int k = 0; k < 2; ++k) dst[m][k] = *(const LAS bf16x8*)(lds + PG8_SA(b, h) + aoff + m * 2048 + k * 1024); } while (0)
; #define PG8_LDB(dst, b, h) do { _Pragma("unroll") for (int n = 0; n < 2; ++n) _Pragma("unroll") for (int k = 0; k < 2; ++k) dst[n][k] = *(const LAS bf16x8*)(lds + PG8_SB(b, h) + boff + n * 2048 + k * 1024); } while (0)
; #define PG8_MMA(ai, bj, At, Bt) do { __builtin_amdgcn_s_setprio(1); _Pragma("unroll") for (int m = 0; m < 4; ++m) _Pragma("unroll") for (int n = 0; n < 2; ++n) _Pragma("unroll") for (int k = 0; k < 2; ++k) \
;         acc[ai][bj][m][n] = __builtin_amdgcn_mfma_f32_16x16x32_bf16(Bt[n][k], At[m][k], acc[ai][bj][m][n], 0, 0, 0); __builtin_amdgcn_s_setprio(0); } while (0)
; #define PG8_WAIT_V(n) asm volatile("s_waitcnt vmcnt(" #n ")" ::: "memory")
; #define PG8_WAIT_L(n) asm volatile("s_waitcnt lgkmcnt(" #n ")" ::: "memory")
; #define PG8_BAR __builtin_amdgcn_s_barrier()
; #define PG8_SCHED __builtin_amdgcn_sched_barrier(0)
;     ...
;             PG8_LDB(B0, 0, 0); PG8_SCHED; PG8_LDA(At, 0, 0); PG8_STAGE(PG8_SA(1, 1), a1 + hA, voffA);
;             PG8_WAIT_L(8); PG8_BAR; PG8_WAIT_L(0); PG8_MMA(0, 0, At, B0); PG8_BAR; PG8_SCHED;
;             PG8_LDB(B1, 0, 1); PG8_STAGE(PG8_SB(0, 0), b2, voffB);
;             PG8_BAR; PG8_WAIT_L(0); PG8_MMA(0, 1, At, B1); PG8_BAR;
;             PG8_LDA(At, 0, 1); PG8_STAGE(PG8_SA(0, 0), a2, voffA);
;             PG8_BAR; PG8_WAIT_L(0); PG8_MMA(1, 0, At, B0); PG8_BAR; PG8_SCHED;
;             PG8_STAGE(PG8_SB(0, 1), b2 + hB, voffB);
;             PG8_WAIT_V(6); PG8_BAR; PG8_MMA(1, 1, At, B1); PG8_BAR;
.LBB0_2099:
	ds_read_b128 v[156:159], v151
	ds_read_b128 v[160:163], v151 offset:1024
	ds_read_b128 v[170:173], v151 offset:2048
	ds_read_b128 v[174:177], v151 offset:3072
	s_add_u32 s38, s36, 0xfffc0080
	s_addc_u32 s39, s37, -1
	s_cmp_eq_u32 s71, 12
	s_cselect_b32 s41, s25, s39
	s_cselect_b32 s40, s44, s38
	s_cselect_b32 s39, s35, s70
	s_cselect_b32 s38, s45, s69
	v_lshl_add_u64 v[146:147], s[36:37], 0, v[138:139]
	s_add_i32 m0, s53, 0xc000
	ds_read_b128 v[178:181], v152
	ds_read_b128 v[182:185], v152 offset:1024
	ds_read_b128 v[186:189], v152 offset:2048
	ds_read_b128 v[190:193], v152 offset:3072
	ds_read_b128 v[194:197], v152 offset:4096
	ds_read_b128 v[198:201], v152 offset:5120
	ds_read_b128 v[202:205], v152 offset:6144
	ds_read_b128 v[206:209], v152 offset:7168
	global_load_lds_dwordx4 v[146:147], off
	v_lshl_add_u64 v[146:147], s[36:37], 0, v[136:137]
	s_add_i32 m0, s53, 0xe000
	s_nop 0
	global_load_lds_dwordx4 v[146:147], off
	s_waitcnt lgkmcnt(8)
	s_barrier
	s_waitcnt lgkmcnt(0)
	s_setprio 1
	s_waitcnt lgkmcnt(0)
	v_mfma_f32_16x16x32_bf16 v[124:127], v[156:159], v[178:181], v[124:127]
	v_mfma_f32_16x16x32_bf16 v[120:123], v[170:173], v[178:181], v[120:123]
	v_mfma_f32_16x16x32_bf16 v[108:111], v[156:159], v[186:189], v[108:111]
	v_mfma_f32_16x16x32_bf16 v[104:107], v[170:173], v[186:189], v[104:107]
	v_mfma_f32_16x16x32_bf16 v[92:95], v[156:159], v[194:197], v[92:95]
	v_mfma_f32_16x16x32_bf16 v[88:91], v[170:173], v[194:197], v[88:91]
	v_mfma_f32_16x16x32_bf16 v[76:79], v[156:159], v[202:205], v[76:79]
	v_mfma_f32_16x16x32_bf16 v[72:75], v[170:173], v[202:205], v[72:75]
	v_mfma_f32_16x16x32_bf16 v[124:127], v[160:163], v[182:185], v[124:127]
	v_mfma_f32_16x16x32_bf16 v[120:123], v[174:177], v[182:185], v[120:123]
	v_mfma_f32_16x16x32_bf16 v[108:111], v[160:163], v[190:193], v[108:111]
	v_mfma_f32_16x16x32_bf16 v[104:107], v[174:177], v[190:193], v[104:107]
	v_mfma_f32_16x16x32_bf16 v[92:95], v[160:163], v[198:201], v[92:95]
	v_mfma_f32_16x16x32_bf16 v[88:91], v[174:177], v[198:201], v[88:91]
	v_mfma_f32_16x16x32_bf16 v[76:79], v[160:163], v[206:209], v[76:79]
	v_mfma_f32_16x16x32_bf16 v[72:75], v[174:177], v[206:209], v[72:75]
	s_setprio 0
	s_barrier
	s_add_i32 s72, s61, s52
	v_lshl_add_u64 v[146:147], s[38:39], 0, v[130:131]
	s_mov_b32 m0, s72
	ds_read_b128 v[210:213], v153
	ds_read_b128 v[214:217], v153 offset:1024
	ds_read_b128 v[218:221], v153 offset:2048
	ds_read_b128 v[222:225], v153 offset:3072
	global_load_lds_dwordx4 v[146:147], off
	v_lshl_add_u64 v[164:165], s[38:39], 0, v[134:135]
	s_add_i32 m0, s72, 0x2000
	s_nop 0
	global_load_lds_dwordx4 v[164:165], off
	s_barrier
	s_waitcnt lgkmcnt(0)
	s_setprio 1
	s_waitcnt lgkmcnt(0)
	v_mfma_f32_16x16x32_bf16 v[116:119], v[210:213], v[178:181], v[116:119]
	v_mfma_f32_16x16x32_bf16 v[112:115], v[218:221], v[178:181], v[112:115]
	v_mfma_f32_16x16x32_bf16 v[100:103], v[210:213], v[186:189], v[100:103]
	v_mfma_f32_16x16x32_bf16 v[96:99], v[218:221], v[186:189], v[96:99]
	v_mfma_f32_16x16x32_bf16 v[84:87], v[210:213], v[194:197], v[84:87]
	v_mfma_f32_16x16x32_bf16 v[80:83], v[218:221], v[194:197], v[80:83]
	v_mfma_f32_16x16x32_bf16 v[68:71], v[210:213], v[202:205], v[68:71]
	v_mfma_f32_16x16x32_bf16 v[64:67], v[218:221], v[202:205], v[64:67]
	v_mfma_f32_16x16x32_bf16 v[116:119], v[214:217], v[182:185], v[116:119]
	v_mfma_f32_16x16x32_bf16 v[112:115], v[222:225], v[182:185], v[112:115]
	v_mfma_f32_16x16x32_bf16 v[100:103], v[214:217], v[190:193], v[100:103]
	v_mfma_f32_16x16x32_bf16 v[96:99], v[222:225], v[190:193], v[96:99]
	v_mfma_f32_16x16x32_bf16 v[84:87], v[214:217], v[198:201], v[84:87]
	v_mfma_f32_16x16x32_bf16 v[80:83], v[222:225], v[198:201], v[80:83]
	v_mfma_f32_16x16x32_bf16 v[68:71], v[214:217], v[206:209], v[68:71]
	v_mfma_f32_16x16x32_bf16 v[64:67], v[222:225], v[206:209], v[64:67]
	s_setprio 0
	s_mov_b32 m0, s53
	v_lshl_add_u64 v[226:227], s[40:41], 0, v[128:129]
	s_barrier
	ds_read_b128 v[178:181], v152 offset:16384
	ds_read_b128 v[182:185], v152 offset:17408
	ds_read_b128 v[186:189], v152 offset:18432
	ds_read_b128 v[190:193], v152 offset:19456
	ds_read_b128 v[194:197], v152 offset:20480
	ds_read_b128 v[198:201], v152 offset:21504
	ds_read_b128 v[202:205], v152 offset:22528
	ds_read_b128 v[206:209], v152 offset:23552
	global_load_lds_dwordx4 v[226:227], off
	v_lshl_add_u64 v[228:229], s[40:41], 0, v[132:133]
	s_mov_b32 m0, s54
	s_nop 0
	global_load_lds_dwordx4 v[228:229], off
	s_barrier
	s_waitcnt lgkmcnt(0)
	s_setprio 1
	s_waitcnt lgkmcnt(0)
	v_mfma_f32_16x16x32_bf16 v[60:63], v[156:159], v[178:181], v[60:63]
	v_mfma_f32_16x16x32_bf16 v[56:59], v[170:173], v[178:181], v[56:59]
	v_mfma_f32_16x16x32_bf16 v[44:47], v[156:159], v[186:189], v[44:47]
	v_mfma_f32_16x16x32_bf16 v[40:43], v[170:173], v[186:189], v[40:43]
	v_mfma_f32_16x16x32_bf16 v[28:31], v[156:159], v[194:197], v[28:31]
	v_mfma_f32_16x16x32_bf16 v[24:27], v[170:173], v[194:197], v[24:27]
	v_mfma_f32_16x16x32_bf16 v[12:15], v[156:159], v[202:205], v[12:15]
	v_mfma_f32_16x16x32_bf16 v[8:11], v[170:173], v[202:205], v[8:11]
	v_mfma_f32_16x16x32_bf16 v[60:63], v[160:163], v[182:185], v[60:63]
	v_mfma_f32_16x16x32_bf16 v[56:59], v[174:177], v[182:185], v[56:59]
	v_mfma_f32_16x16x32_bf16 v[44:47], v[160:163], v[190:193], v[44:47]
	v_mfma_f32_16x16x32_bf16 v[40:43], v[174:177], v[190:193], v[40:43]
	v_mfma_f32_16x16x32_bf16 v[28:31], v[160:163], v[198:201], v[28:31]
	v_mfma_f32_16x16x32_bf16 v[24:27], v[174:177], v[198:201], v[24:27]
	v_mfma_f32_16x16x32_bf16 v[12:15], v[160:163], v[206:209], v[12:15]
	v_mfma_f32_16x16x32_bf16 v[8:11], v[174:177], v[206:209], v[8:11]
	s_setprio 0
	s_barrier
; #define PG8_STAGE(bufoff, gbase, voff) do { _Pragma("unroll") for (int _i = 0; _i < 2; ++_i) \
;         __builtin_amdgcn_global_load_lds((const unsigned*)((const char*)(gbase) + (voff)[_i]), (LAS unsigned*)(lds + (bufoff) + ldsw + _i * 8192), 16, 0, 0); } while (0)
; #define PG8_LDA(dst, b, h) do { _Pragma("unroll") for (int m = 0; m < 4; ++m) _Pragma("unroll") for (int k = 0; k < 2; ++k) dst[m][k] = *(const LAS bf16x8*)(lds + PG8_SA(b, h) + aoff + m * 2048 + k * 1024); } while (0)
; #define PG8_LDB(dst, b, h) do { _Pragma("unroll") for (int n = 0; n < 2; ++n) _Pragma("unroll") for (int k = 0; k < 2; ++k) dst[n][k] = *(const LAS bf16x8*)(lds + PG8_SB(b, h) + boff + n * 2048 + k * 1024); } while (0)
; #define PG8_MMA(ai, bj, At, Bt) do { __builtin_amdgcn_s_setprio(1); _Pragma("unroll") for (int m = 0; m < 4; ++m) _Pragma("unroll") for (int n = 0; n < 2; ++n) _Pragma("unroll") for (int k = 0; k < 2; ++k) \
;         acc[ai][bj][m][n] = __builtin_amdgcn_mfma_f32_16x16x32_bf16(Bt[n][k], At[m][k], acc[ai][bj][m][n], 0, 0, 0); __builtin_amdgcn_s_setprio(0); } while (0)
; #define PG8_WAIT_V(n) asm volatile("s_waitcnt vmcnt(" #n ")" ::: "memory")
; #define PG8_WAIT_L(n) asm volatile("s_waitcnt lgkmcnt(" #n ")" ::: "memory")
; #define PG8_BAR __builtin_amdgcn_s_barrier()
; #define PG8_SCHED __builtin_amdgcn_sched_barrier(0)
;     ...
;             PG8_WAIT_V(6); PG8_BAR; PG8_MMA(1, 1, At, B1); PG8_BAR;
;             PG8_LDB(B0, 1, 0); PG8_SCHED; PG8_LDA(At, 1, 0); PG8_STAGE(PG8_SA(0, 1), a2 + hA, voffA);
;             PG8_WAIT_L(8); PG8_BAR; PG8_WAIT_L(0); PG8_MMA(0, 0, At, B0); PG8_BAR; PG8_SCHED;
;             PG8_LDB(B1, 1, 1); PG8_STAGE(PG8_SB(1, 0), b3, voffB);
;             PG8_BAR; PG8_WAIT_L(0); PG8_MMA(0, 1, At, B1); PG8_BAR;
;             PG8_LDA(At, 1, 1); PG8_STAGE(PG8_SA(1, 0), a3, voffA);
;             PG8_BAR; PG8_WAIT_L(0); PG8_MMA(1, 0, At, B0); PG8_BAR; PG8_SCHED;
	s_add_u32 s72, s38, 0x40000
	s_addc_u32 s73, s39, 0
	s_add_i32 s74, s62, s52
	v_lshl_add_u64 v[156:157], s[72:73], 0, v[130:131]
	s_mov_b32 m0, s74
	s_nop 0
	global_load_lds_dwordx4 v[156:157], off
	v_lshl_add_u64 v[156:157], s[72:73], 0, v[134:135]
	s_add_i32 m0, s74, 0x2000
	s_nop 0
	global_load_lds_dwordx4 v[156:157], off
	s_waitcnt vmcnt(6)
	s_barrier
	s_setprio 1
	v_mfma_f32_16x16x32_bf16 v[52:55], v[210:213], v[178:181], v[52:55]
	v_mfma_f32_16x16x32_bf16 v[48:51], v[218:221], v[178:181], v[48:51]
	v_mfma_f32_16x16x32_bf16 v[36:39], v[210:213], v[186:189], v[36:39]
	v_mfma_f32_16x16x32_bf16 v[32:35], v[218:221], v[186:189], v[32:35]
	v_mfma_f32_16x16x32_bf16 v[20:23], v[210:213], v[194:197], v[20:23]
	v_mfma_f32_16x16x32_bf16 v[16:19], v[218:221], v[194:197], v[16:19]
	v_mfma_f32_16x16x32_bf16 v[4:7], v[210:213], v[202:205], v[4:7]
	v_mfma_f32_16x16x32_bf16 v[0:3], v[218:221], v[202:205], v[0:3]
	v_mfma_f32_16x16x32_bf16 v[52:55], v[214:217], v[182:185], v[52:55]
	v_mfma_f32_16x16x32_bf16 v[48:51], v[222:225], v[182:185], v[48:51]
	v_mfma_f32_16x16x32_bf16 v[36:39], v[214:217], v[190:193], v[36:39]
	v_mfma_f32_16x16x32_bf16 v[32:35], v[222:225], v[190:193], v[32:35]
	v_mfma_f32_16x16x32_bf16 v[20:23], v[214:217], v[198:201], v[20:23]
	v_mfma_f32_16x16x32_bf16 v[16:19], v[222:225], v[198:201], v[16:19]
	v_mfma_f32_16x16x32_bf16 v[4:7], v[214:217], v[206:209], v[4:7]
	v_mfma_f32_16x16x32_bf16 v[0:3], v[222:225], v[206:209], v[0:3]
	s_setprio 0
	s_add_i32 s72, 0, 0x18000
	v_add_u32_e32 v155, s72, v149
	s_barrier
	ds_read_b128 v[156:159], v155
	ds_read_b128 v[160:163], v155 offset:1024
	ds_read_b128 v[170:173], v155 offset:2048
	ds_read_b128 v[174:177], v155 offset:3072
	s_add_u32 s40, s40, 0x40000
	s_addc_u32 s41, s41, 0
	s_mov_b32 m0, s55
	v_lshl_add_u64 v[210:211], s[40:41], 0, v[128:129]
	ds_read_b128 v[178:181], v152 offset:32768
	ds_read_b128 v[182:185], v152 offset:33792
	ds_read_b128 v[186:189], v152 offset:34816
	ds_read_b128 v[190:193], v152 offset:35840
	ds_read_b128 v[194:197], v152 offset:36864
	ds_read_b128 v[198:201], v152 offset:37888
	ds_read_b128 v[202:205], v152 offset:38912
	ds_read_b128 v[206:209], v152 offset:39936
	global_load_lds_dwordx4 v[210:211], off
	v_lshl_add_u64 v[210:211], s[40:41], 0, v[132:133]
	s_mov_b32 m0, s56
	s_nop 0
	global_load_lds_dwordx4 v[210:211], off
	s_waitcnt lgkmcnt(8)
	s_barrier
	s_waitcnt lgkmcnt(0)
	s_setprio 1
	s_waitcnt lgkmcnt(0)
	v_mfma_f32_16x16x32_bf16 v[124:127], v[156:159], v[178:181], v[124:127]
	v_mfma_f32_16x16x32_bf16 v[120:123], v[170:173], v[178:181], v[120:123]
	v_mfma_f32_16x16x32_bf16 v[108:111], v[156:159], v[186:189], v[108:111]
	v_mfma_f32_16x16x32_bf16 v[104:107], v[170:173], v[186:189], v[104:107]
	v_mfma_f32_16x16x32_bf16 v[92:95], v[156:159], v[194:197], v[92:95]
	v_mfma_f32_16x16x32_bf16 v[88:91], v[170:173], v[194:197], v[88:91]
	v_mfma_f32_16x16x32_bf16 v[76:79], v[156:159], v[202:205], v[76:79]
	v_mfma_f32_16x16x32_bf16 v[72:75], v[170:173], v[202:205], v[72:75]
	v_mfma_f32_16x16x32_bf16 v[124:127], v[160:163], v[182:185], v[124:127]
	v_mfma_f32_16x16x32_bf16 v[120:123], v[174:177], v[182:185], v[120:123]
	v_mfma_f32_16x16x32_bf16 v[108:111], v[160:163], v[190:193], v[108:111]
	v_mfma_f32_16x16x32_bf16 v[104:107], v[174:177], v[190:193], v[104:107]
	v_mfma_f32_16x16x32_bf16 v[92:95], v[160:163], v[198:201], v[92:95]
	v_mfma_f32_16x16x32_bf16 v[88:91], v[174:177], v[198:201], v[88:91]
	v_mfma_f32_16x16x32_bf16 v[76:79], v[160:163], v[206:209], v[76:79]
	v_mfma_f32_16x16x32_bf16 v[72:75], v[174:177], v[206:209], v[72:75]
	s_setprio 0
	s_barrier
	s_add_i32 s40, 0, 0x1c000
	s_add_i32 s41, s72, s52
	v_add_u32_e32 v155, s40, v149
	v_lshl_add_u64 v[146:147], v[146:147], 0, s[26:27]
	s_mov_b32 m0, s41
	ds_read_b128 v[210:213], v155
	ds_read_b128 v[214:217], v155 offset:1024
	ds_read_b128 v[218:221], v155 offset:2048
	ds_read_b128 v[222:225], v155 offset:3072
	global_load_lds_dwordx4 v[146:147], off
	v_lshl_add_u64 v[146:147], v[164:165], 0, s[26:27]
	s_add_i32 m0, s41, 0x2000
	s_nop 0
	global_load_lds_dwordx4 v[146:147], off
	s_barrier
	s_waitcnt lgkmcnt(0)
	s_setprio 1
	s_waitcnt lgkmcnt(0)
	v_mfma_f32_16x16x32_bf16 v[116:119], v[210:213], v[178:181], v[116:119]
	v_mfma_f32_16x16x32_bf16 v[112:115], v[218:221], v[178:181], v[112:115]
	v_mfma_f32_16x16x32_bf16 v[100:103], v[210:213], v[186:189], v[100:103]
	v_mfma_f32_16x16x32_bf16 v[96:99], v[218:221], v[186:189], v[96:99]
	v_mfma_f32_16x16x32_bf16 v[84:87], v[210:213], v[194:197], v[84:87]
	v_mfma_f32_16x16x32_bf16 v[80:83], v[218:221], v[194:197], v[80:83]
	v_mfma_f32_16x16x32_bf16 v[68:71], v[210:213], v[202:205], v[68:71]
	v_mfma_f32_16x16x32_bf16 v[64:67], v[218:221], v[202:205], v[64:67]
	v_mfma_f32_16x16x32_bf16 v[116:119], v[214:217], v[182:185], v[116:119]
	v_mfma_f32_16x16x32_bf16 v[112:115], v[222:225], v[182:185], v[112:115]
	v_mfma_f32_16x16x32_bf16 v[100:103], v[214:217], v[190:193], v[100:103]
	v_mfma_f32_16x16x32_bf16 v[96:99], v[222:225], v[190:193], v[96:99]
	v_mfma_f32_16x16x32_bf16 v[84:87], v[214:217], v[198:201], v[84:87]
	v_mfma_f32_16x16x32_bf16 v[80:83], v[222:225], v[198:201], v[80:83]
	v_mfma_f32_16x16x32_bf16 v[68:71], v[214:217], v[206:209], v[68:71]
	v_mfma_f32_16x16x32_bf16 v[64:67], v[222:225], v[206:209], v[64:67]
	s_setprio 0
	s_mov_b32 m0, s58
	v_lshl_add_u64 v[146:147], v[226:227], 0, s[26:27]
	s_barrier
	ds_read_b128 v[178:181], v152 offset:49152
	ds_read_b128 v[182:185], v152 offset:50176
	ds_read_b128 v[186:189], v152 offset:51200
	ds_read_b128 v[190:193], v152 offset:52224
	ds_read_b128 v[194:197], v152 offset:53248
	ds_read_b128 v[198:201], v152 offset:54272
	ds_read_b128 v[202:205], v152 offset:55296
	ds_read_b128 v[206:209], v152 offset:56320
	global_load_lds_dwordx4 v[146:147], off
	v_lshl_add_u64 v[146:147], v[228:229], 0, s[26:27]
	s_mov_b32 m0, s59
	s_nop 0
	global_load_lds_dwordx4 v[146:147], off
	s_barrier
; #define PG8_STAGE(bufoff, gbase, voff) do { _Pragma("unroll") for (int _i = 0; _i < 2; ++_i) \
;         __builtin_amdgcn_global_load_lds((const unsigned*)((const char*)(gbase) + (voff)[_i]), (LAS unsigned*)(lds + (bufoff) + ldsw + _i * 8192), 16, 0, 0); } while (0)
; #define PG8_LDA(dst, b, h) do { _Pragma("unroll") for (int m = 0; m < 4; ++m) _Pragma("unroll") for (int k = 0; k < 2; ++k) dst[m][k] = *(const LAS bf16x8*)(lds + PG8_SA(b, h) + aoff + m * 2048 + k * 1024); } while (0)
; #define PG8_LDB(dst, b, h) do { _Pragma("unroll") for (int n = 0; n < 2; ++n) _Pragma("unroll") for (int k = 0; k < 2; ++k) dst[n][k] = *(const LAS bf16x8*)(lds + PG8_SB(b, h) + boff + n * 2048 + k * 1024); } while (0)
; #define PG8_MMA(ai, bj, At, Bt) do { __builtin_amdgcn_s_setprio(1); _Pragma("unroll") for (int m = 0; m < 4; ++m) _Pragma("unroll") for (int n = 0; n < 2; ++n) _Pragma("unroll") for (int k = 0; k < 2; ++k) \
;         acc[ai][bj][m][n] = __builtin_amdgcn_mfma_f32_16x16x32_bf16(Bt[n][k], At[m][k], acc[ai][bj][m][n], 0, 0, 0); __builtin_amdgcn_s_setprio(0); } while (0)
; #define PG8_WAIT_V(n) asm volatile("s_waitcnt vmcnt(" #n ")" ::: "memory")
; #define PG8_WAIT_L(n) asm volatile("s_waitcnt lgkmcnt(" #n ")" ::: "memory")
; #define PG8_BAR __builtin_amdgcn_s_barrier()
; #define PG8_SCHED __builtin_amdgcn_sched_barrier(0)
;     ...
;             PG8_WAIT_L(8); PG8_BAR; PG8_WAIT_L(0); PG8_MMA(0, 0, At, B0); PG8_BAR; PG8_SCHED;
;             PG8_LDB(B1, 1, 1); PG8_STAGE(PG8_SB(1, 0), b3, voffB);
;             PG8_BAR; PG8_WAIT_L(0); PG8_MMA(0, 1, At, B1); PG8_BAR;
;             PG8_LDA(At, 1, 1); PG8_STAGE(PG8_SA(1, 0), a3, voffA);
;             PG8_BAR; PG8_WAIT_L(0); PG8_MMA(1, 0, At, B0); PG8_BAR; PG8_SCHED;
;             PG8_STAGE(PG8_SB(1, 1), b3 + hB, voffB);
;             PG8_WAIT_V(6); PG8_BAR; PG8_MMA(1, 1, At, B1); PG8_BAR;
; __device__ __forceinline__ float row_rstd(const float* ssq, int row) {
;     const f32x4* p = (const f32x4*)(ssq + (size_t)row * 16);
;     const f32x4 a = p[0], b = p[1], c = p[2], d = p[3];
;     const float s = ((a[0] + a[1]) + (a[2] + a[3])) + ((b[0] + b[1]) + (b[2] + b[3])) + ((c[0] + c[1]) + (c[2] + c[3])) + ((d[0] + d[1]) + (d[2] + d[3]));
;     return rsqrtf(s * (1.0f / 1024.0f) + 1e-6f);
	s_waitcnt lgkmcnt(0)
	s_setprio 1
	s_waitcnt lgkmcnt(0)
	v_mfma_f32_16x16x32_bf16 v[60:63], v[156:159], v[178:181], v[60:63]
	v_mfma_f32_16x16x32_bf16 v[56:59], v[170:173], v[178:181], v[56:59]
	v_mfma_f32_16x16x32_bf16 v[44:47], v[156:159], v[186:189], v[44:47]
	v_mfma_f32_16x16x32_bf16 v[40:43], v[170:173], v[186:189], v[40:43]
	v_mfma_f32_16x16x32_bf16 v[28:31], v[156:159], v[194:197], v[28:31]
	v_mfma_f32_16x16x32_bf16 v[24:27], v[170:173], v[194:197], v[24:27]
	v_mfma_f32_16x16x32_bf16 v[12:15], v[156:159], v[202:205], v[12:15]
	v_mfma_f32_16x16x32_bf16 v[8:11], v[170:173], v[202:205], v[8:11]
	v_mfma_f32_16x16x32_bf16 v[60:63], v[160:163], v[182:185], v[60:63]
	v_mfma_f32_16x16x32_bf16 v[56:59], v[174:177], v[182:185], v[56:59]
	v_mfma_f32_16x16x32_bf16 v[44:47], v[160:163], v[190:193], v[44:47]
	v_mfma_f32_16x16x32_bf16 v[40:43], v[174:177], v[190:193], v[40:43]
	v_mfma_f32_16x16x32_bf16 v[28:31], v[160:163], v[198:201], v[28:31]
	v_mfma_f32_16x16x32_bf16 v[24:27], v[174:177], v[198:201], v[24:27]
	v_mfma_f32_16x16x32_bf16 v[12:15], v[160:163], v[206:209], v[12:15]
	v_mfma_f32_16x16x32_bf16 v[8:11], v[174:177], v[206:209], v[8:11]
	s_setprio 0
	s_barrier
	s_add_u32 s38, s38, 0x40080
	s_addc_u32 s39, s39, 0
	s_add_i32 s40, s40, s52
	v_lshl_add_u64 v[146:147], s[38:39], 0, v[130:131]
	s_mov_b32 m0, s40
	s_nop 0
	global_load_lds_dwordx4 v[146:147], off
	v_lshl_add_u64 v[146:147], s[38:39], 0, v[134:135]
	s_add_i32 m0, s40, 0x2000
	s_nop 0
	global_load_lds_dwordx4 v[146:147], off
	s_waitcnt vmcnt(6)
	s_barrier
	s_setprio 1
	v_mfma_f32_16x16x32_bf16 v[52:55], v[210:213], v[178:181], v[52:55]
	v_mfma_f32_16x16x32_bf16 v[48:51], v[218:221], v[178:181], v[48:51]
	v_mfma_f32_16x16x32_bf16 v[36:39], v[210:213], v[186:189], v[36:39]
	v_mfma_f32_16x16x32_bf16 v[32:35], v[218:221], v[186:189], v[32:35]
	v_mfma_f32_16x16x32_bf16 v[20:23], v[210:213], v[194:197], v[20:23]
	v_mfma_f32_16x16x32_bf16 v[16:19], v[218:221], v[194:197], v[16:19]
	v_mfma_f32_16x16x32_bf16 v[4:7], v[210:213], v[202:205], v[4:7]
	v_mfma_f32_16x16x32_bf16 v[0:3], v[218:221], v[202:205], v[0:3]
	v_mfma_f32_16x16x32_bf16 v[52:55], v[214:217], v[182:185], v[52:55]
	v_mfma_f32_16x16x32_bf16 v[48:51], v[222:225], v[182:185], v[48:51]
	v_mfma_f32_16x16x32_bf16 v[36:39], v[214:217], v[190:193], v[36:39]
	v_mfma_f32_16x16x32_bf16 v[32:35], v[222:225], v[190:193], v[32:35]
	v_mfma_f32_16x16x32_bf16 v[20:23], v[214:217], v[198:201], v[20:23]
	v_mfma_f32_16x16x32_bf16 v[16:19], v[222:225], v[198:201], v[16:19]
	v_mfma_f32_16x16x32_bf16 v[4:7], v[214:217], v[206:209], v[4:7]
	v_mfma_f32_16x16x32_bf16 v[0:3], v[222:225], v[206:209], v[0:3]
	s_setprio 0
	s_add_i32 s71, s71, 2
	s_add_u32 s69, s69, 0x100
	s_addc_u32 s70, s70, 0
	s_add_u32 s36, s36, 0x100
	s_addc_u32 s37, s37, 0
	s_cmp_gt_u32 s71, 13
	s_barrier
	s_cbranch_scc0 .LBB0_2099
	v_lshl_add_u32 v146, s68, 8, v148
	v_ashrrev_i32_e32 v147, 31, v146
	v_lshlrev_b64 v[156:157], 6, v[146:147]
	v_lshl_add_u64 v[164:165], s[22:23], 0, v[156:157]
	v_subrev_u32_e32 v180, s22, v164
	v_add_u32_e32 v181, 0x0, v180
	global_load_dwordx4 v[182:185], v181, s[22:23]
	v_add_u32_e32 v181, 0x10, v180
	global_load_dwordx4 v[186:189], v181, s[22:23]
	v_add_u32_e32 v181, 0x20, v180
	global_load_dwordx4 v[190:193], v181, s[22:23]
	v_add_u32_e32 v181, 0x30, v180
	global_load_dwordx4 v[194:197], v181, s[22:23]
	v_add_u32_e32 v181, 0x400, v180
	global_load_dwordx4 v[198:201], v181, s[22:23]
	v_add_u32_e32 v181, 0x410, v180
	global_load_dwordx4 v[202:205], v181, s[22:23]
	v_add_u32_e32 v181, 0x420, v180
	global_load_dwordx4 v[206:209], v181, s[22:23]
	v_add_u32_e32 v181, 0x430, v180
	global_load_dwordx4 v[210:213], v181, s[22:23]
	v_add_u32_e32 v181, 0x800, v180
	global_load_dwordx4 v[214:217], v181, s[22:23]
	v_add_u32_e32 v181, 0x810, v180
	global_load_dwordx4 v[218:221], v181, s[22:23]
	v_add_u32_e32 v181, 0x820, v180
	global_load_dwordx4 v[222:225], v181, s[22:23]
	v_add_u32_e32 v181, 0x830, v180
	global_load_dwordx4 v[232:235], v181, s[22:23]
	v_add_u32_e32 v181, 0xc00, v180
	global_load_dwordx4 v[236:239], v181, s[22:23]
	v_add_u32_e32 v181, 0xc10, v180
	global_load_dwordx4 v[240:243], v181, s[22:23]
	v_add_u32_e32 v181, 0xc20, v180
	global_load_dwordx4 v[244:247], v181, s[22:23]
	v_add_u32_e32 v181, 0xc30, v180
	global_load_dwordx4 v[248:251], v181, s[22:23]
	v_or_b32_e32 v164, 16, v146
	v_lshl_or_b32 v147, s33, 9, v150
	v_ashrrev_i32_e32 v165, 31, v164
	v_lshl_add_u32 v155, v146, 13, v147
	s_waitcnt vmcnt(12)
; __device__ __forceinline__ u32x4 pack8(const f32x4 v0, const f32x4 v1) { u32x4 w; w.x = pk2(v0[0], v0[1]); w.y = pk2(v0[2], v0[3]); w.z = pk2(v1[0], v1[1]); w.w = pk2(v1[2], v1[3]); return w; }
; __device__ __forceinline__ float row_rstd(const float* ssq, int row) {
;     const f32x4* p = (const f32x4*)(ssq + (size_t)row * 16);
;     const f32x4 a = p[0], b = p[1], c = p[2], d = p[3];
;     const float s = ((a[0] + a[1]) + (a[2] + a[3])) + ((b[0] + b[1]) + (b[2] + b[3])) + ((c[0] + c[1]) + (c[2] + c[3])) + ((d[0] + d[1]) + (d[2] + d[3]));
;     return rsqrtf(s * (1.0f / 1024.0f) + 1e-6f);
;     __device__ __forceinline__ void operator()(const f32x4 (&acc)[2][2][4][2], const Unit& u, int wr, int wc, int fr, int fq) const {
;     ...
;             for (int m = 0; m < 4; ++m) {
;                 const int row = row0 + ai * 128 + m * 16; const float rs = row_rstd(ssq, row);
; #pragma unroll
;                 for (int bj = 0; bj < 2; ++bj) { f32x4 v0 = acc[ai][bj][m][0] * rs, v1 = acc[ai][bj][m][1] * rs;
; #pragma unroll
;                     for (int j = 0; j < 4; ++j) { const float a = fmaxf(v0[j], 0.f), b = fmaxf(v1[j], 0.f); v0[j] = a * a; v1[j] = b * b; }
;                     __builtin_amdgcn_raw_buffer_store_b128(pack8(v0, v1), rsrc, (unsigned)(((size_t)row * DFF + col0 + bj * 128) * 2), 0, 16  ); }
	v_mov_b32_e32 v178, v183
	v_mov_b32_e32 v179, v184
	v_mov_b32_e32 v157, v185
	v_mov_b32_e32 v158, v187
	v_mov_b32_e32 v159, v188
	v_mov_b32_e32 v161, v189
	v_mov_b32_e32 v156, v182
	v_pk_add_f32 v[156:157], v[178:179], v[156:157]
	v_mov_b32_e32 v160, v186
	v_pk_add_f32 v[158:159], v[158:159], v[160:161]
	v_pk_add_f32 v[156:157], v[156:157], v[156:157] op_sel:[0,1] op_sel_hi:[1,0]
	v_pk_add_f32 v[158:159], v[158:159], v[158:159] op_sel:[0,1] op_sel_hi:[1,0]
	v_add_f32_e32 v162, v190, v191
	v_add_f32_e32 v170, v192, v193
	v_mov_b32_e32 v163, v196
	v_mov_b32_e32 v171, v197
	v_mov_b32_e32 v157, v194
	v_mov_b32_e32 v159, v195
	v_pk_add_f32 v[160:161], v[162:163], v[170:171]
	v_pk_add_f32 v[156:157], v[156:157], v[158:159]
	s_nop 0
	v_pk_add_f32 v[156:157], v[156:157], v[160:161]
	s_nop 0
	v_add_f32_e32 v156, v156, v157
	v_fmamk_f32 v156, v156, 0x3a800000, v154
	v_mul_f32_e32 v157, 0x4b800000, v156
	v_cmp_gt_f32_e32 vcc, s63, v156
	s_nop 1
	v_cndmask_b32_e32 v156, v156, v157, vcc
	v_rsq_f32_e32 v158, v156
	v_lshlrev_b64 v[156:157], 6, v[164:165]
	v_lshl_add_u64 v[156:157], s[22:23], 0, v[156:157]
	v_mul_f32_e32 v159, 0x45800000, v158
	v_cndmask_b32_e32 v158, v158, v159, vcc
	v_pk_mul_f32 v[126:127], v[126:127], v[158:159] op_sel_hi:[1,0]
	v_pk_mul_f32 v[124:125], v[124:125], v[158:159] op_sel_hi:[1,0]
	v_pk_mul_f32 v[122:123], v[122:123], v[158:159] op_sel_hi:[1,0]
	v_pk_mul_f32 v[120:121], v[120:121], v[158:159] op_sel_hi:[1,0]
	v_pk_mul_f32 v[114:115], v[114:115], v[158:159] op_sel_hi:[1,0]
	v_pk_mul_f32 v[112:113], v[112:113], v[158:159] op_sel_hi:[1,0]
	v_pk_mul_f32 v[118:119], v[118:119], v[158:159] op_sel_hi:[1,0]
	v_pk_mul_f32 v[116:117], v[116:117], v[158:159] op_sel_hi:[1,0]
	v_max_f32_e32 v124, 0, v124
	v_max_f32_e32 v120, 0, v120
	v_max_f32_e32 v125, 0, v125
	v_max_f32_e32 v121, 0, v121
	v_max_f32_e32 v126, 0, v126
	v_max_f32_e32 v122, 0, v122
	v_max_f32_e32 v127, 0, v127
	v_max_f32_e32 v123, 0, v123
	v_max_f32_e32 v112, 0, v112
	v_max_f32_e32 v113, 0, v113
	v_max_f32_e32 v114, 0, v114
	v_max_f32_e32 v115, 0, v115
	v_max_f32_e32 v116, 0, v116
	v_max_f32_e32 v117, 0, v117
	v_max_f32_e32 v118, 0, v118
	v_max_f32_e32 v119, 0, v119
	v_mul_f32_e32 v124, v124, v124
	v_mul_f32_e32 v120, v120, v120
	v_mul_f32_e32 v125, v125, v125
	v_mul_f32_e32 v121, v121, v121
	v_mul_f32_e32 v126, v126, v126
	v_mul_f32_e32 v122, v122, v122
	v_mul_f32_e32 v127, v127, v127
	v_mul_f32_e32 v123, v123, v123
	v_mul_f32_e32 v158, v112, v112
	v_mul_f32_e32 v159, v113, v113
	v_mul_f32_e32 v160, v114, v114
	v_mul_f32_e32 v161, v115, v115
	v_cvt_pk_bf16_f32 v112, v124, v125
	v_cvt_pk_bf16_f32 v113, v126, v127
	v_cvt_pk_bf16_f32 v114, v120, v121
	v_cvt_pk_bf16_f32 v115, v122, v123
	v_mul_f32_e32 v116, v116, v116
	v_mul_f32_e32 v117, v117, v117
	v_mul_f32_e32 v118, v118, v118
	v_mul_f32_e32 v119, v119, v119
	buffer_store_dwordx4 v[112:115], v155, s[12:15], 0 offen sc1
	s_nop 1
	v_cvt_pk_bf16_f32 v112, v116, v117
	v_cvt_pk_bf16_f32 v113, v118, v119
	v_cvt_pk_bf16_f32 v114, v158, v159
	v_cvt_pk_bf16_f32 v115, v160, v161
	buffer_store_dwordx4 v[112:115], v155, s[12:15], 0 offen offset:256 sc1
	s_nop 0
	v_or_b32_e32 v156, 32, v146
	v_ashrrev_i32_e32 v157, 31, v156
	v_lshl_add_u32 v155, v164, 13, v147
	v_add_u32_e32 v181, 0x2000, v180
	global_load_dwordx4 v[182:185], v181, s[22:23]
	v_add_u32_e32 v181, 0x2010, v180
	global_load_dwordx4 v[186:189], v181, s[22:23]
	v_add_u32_e32 v181, 0x2020, v180
	global_load_dwordx4 v[190:193], v181, s[22:23]
	v_add_u32_e32 v181, 0x2030, v180
	global_load_dwordx4 v[194:197], v181, s[22:23]
	s_waitcnt vmcnt(14)
	v_mov_b32_e32 v158, v199
	v_mov_b32_e32 v159, v200
	v_mov_b32_e32 v113, v201
	v_mov_b32_e32 v114, v203
	v_mov_b32_e32 v115, v204
	v_mov_b32_e32 v117, v205
	v_mov_b32_e32 v112, v198
	v_pk_add_f32 v[112:113], v[158:159], v[112:113]
	v_mov_b32_e32 v116, v202
	v_pk_add_f32 v[114:115], v[114:115], v[116:117]
	v_pk_add_f32 v[112:113], v[112:113], v[112:113] op_sel:[0,1] op_sel_hi:[1,0]
	v_pk_add_f32 v[114:115], v[114:115], v[114:115] op_sel:[0,1] op_sel_hi:[1,0]
	v_add_f32_e32 v118, v206, v207
	v_add_f32_e32 v120, v208, v209
	v_mov_b32_e32 v119, v212
	v_mov_b32_e32 v121, v213
	v_mov_b32_e32 v113, v210
	v_mov_b32_e32 v115, v211
	v_pk_add_f32 v[116:117], v[118:119], v[120:121]
	v_pk_add_f32 v[112:113], v[112:113], v[114:115]
	s_nop 0
	v_pk_add_f32 v[112:113], v[112:113], v[116:117]
	s_nop 0
	v_add_f32_e32 v112, v112, v113
	v_fmamk_f32 v112, v112, 0x3a800000, v154
	v_mul_f32_e32 v113, 0x4b800000, v112
	v_cmp_gt_f32_e32 vcc, s63, v112
	s_nop 1
	v_cndmask_b32_e32 v112, v112, v113, vcc
	v_rsq_f32_e32 v114, v112
	v_lshlrev_b64 v[112:113], 6, v[156:157]
	v_lshl_add_u64 v[112:113], s[22:23], 0, v[112:113]
	v_mul_f32_e32 v115, 0x45800000, v114
	v_cndmask_b32_e32 v114, v114, v115, vcc
	v_pk_mul_f32 v[110:111], v[110:111], v[114:115] op_sel_hi:[1,0]
	v_pk_mul_f32 v[108:109], v[108:109], v[114:115] op_sel_hi:[1,0]
	v_pk_mul_f32 v[106:107], v[106:107], v[114:115] op_sel_hi:[1,0]
	v_pk_mul_f32 v[104:105], v[104:105], v[114:115] op_sel_hi:[1,0]
	v_pk_mul_f32 v[98:99], v[98:99], v[114:115] op_sel_hi:[1,0]
	v_pk_mul_f32 v[96:97], v[96:97], v[114:115] op_sel_hi:[1,0]
	v_pk_mul_f32 v[102:103], v[102:103], v[114:115] op_sel_hi:[1,0]
	v_pk_mul_f32 v[100:101], v[100:101], v[114:115] op_sel_hi:[1,0]
	v_max_f32_e32 v108, 0, v108
	v_max_f32_e32 v104, 0, v104
	v_max_f32_e32 v109, 0, v109
	v_max_f32_e32 v105, 0, v105
	v_max_f32_e32 v110, 0, v110
	v_max_f32_e32 v106, 0, v106
	v_max_f32_e32 v111, 0, v111
	v_max_f32_e32 v107, 0, v107
	v_max_f32_e32 v96, 0, v96
	v_max_f32_e32 v97, 0, v97
	v_max_f32_e32 v98, 0, v98
	v_max_f32_e32 v99, 0, v99
	v_max_f32_e32 v100, 0, v100
; __device__ __forceinline__ u32x4 pack8(const f32x4 v0, const f32x4 v1) { u32x4 w; w.x = pk2(v0[0], v0[1]); w.y = pk2(v0[2], v0[3]); w.z = pk2(v1[0], v1[1]); w.w = pk2(v1[2], v1[3]); return w; }
; __device__ __forceinline__ float row_rstd(const float* ssq, int row) {
;     const f32x4* p = (const f32x4*)(ssq + (size_t)row * 16);
;     const f32x4 a = p[0], b = p[1], c = p[2], d = p[3];
;     const float s = ((a[0] + a[1]) + (a[2] + a[3])) + ((b[0] + b[1]) + (b[2] + b[3])) + ((c[0] + c[1]) + (c[2] + c[3])) + ((d[0] + d[1]) + (d[2] + d[3]));
;     return rsqrtf(s * (1.0f / 1024.0f) + 1e-6f);
;     __device__ __forceinline__ void operator()(const f32x4 (&acc)[2][2][4][2], const Unit& u, int wr, int wc, int fr, int fq) const {
;     ...
;             for (int m = 0; m < 4; ++m) {
;                 const int row = row0 + ai * 128 + m * 16; const float rs = row_rstd(ssq, row);
; #pragma unroll
;                 for (int bj = 0; bj < 2; ++bj) { f32x4 v0 = acc[ai][bj][m][0] * rs, v1 = acc[ai][bj][m][1] * rs;
; #pragma unroll
;                     for (int j = 0; j < 4; ++j) { const float a = fmaxf(v0[j], 0.f), b = fmaxf(v1[j], 0.f); v0[j] = a * a; v1[j] = b * b; }
;                     __builtin_amdgcn_raw_buffer_store_b128(pack8(v0, v1), rsrc, (unsigned)(((size_t)row * DFF + col0 + bj * 128) * 2), 0, 16  ); }
	v_max_f32_e32 v101, 0, v101
	v_max_f32_e32 v102, 0, v102
	v_max_f32_e32 v103, 0, v103
	v_mul_f32_e32 v108, v108, v108
	v_mul_f32_e32 v104, v104, v104
	v_mul_f32_e32 v109, v109, v109
	v_mul_f32_e32 v105, v105, v105
	v_mul_f32_e32 v110, v110, v110
	v_mul_f32_e32 v106, v106, v106
	v_mul_f32_e32 v111, v111, v111
	v_mul_f32_e32 v107, v107, v107
	v_mul_f32_e32 v114, v96, v96
	v_mul_f32_e32 v115, v97, v97
	v_mul_f32_e32 v116, v98, v98
	v_mul_f32_e32 v117, v99, v99
	v_cvt_pk_bf16_f32 v96, v108, v109
	v_cvt_pk_bf16_f32 v97, v110, v111
	v_cvt_pk_bf16_f32 v98, v104, v105
	v_cvt_pk_bf16_f32 v99, v106, v107
	v_mul_f32_e32 v100, v100, v100
	v_mul_f32_e32 v101, v101, v101
	v_mul_f32_e32 v102, v102, v102
	v_mul_f32_e32 v103, v103, v103
	buffer_store_dwordx4 v[96:99], v155, s[12:15], 0 offen sc1
	s_nop 1
	v_cvt_pk_bf16_f32 v96, v100, v101
	v_cvt_pk_bf16_f32 v97, v102, v103
	v_cvt_pk_bf16_f32 v98, v114, v115
	v_cvt_pk_bf16_f32 v99, v116, v117
	buffer_store_dwordx4 v[96:99], v155, s[12:15], 0 offen offset:256 sc1
	s_nop 0
	v_or_b32_e32 v112, 48, v146
	v_ashrrev_i32_e32 v113, 31, v112
	v_lshl_add_u32 v116, v156, 13, v147
	v_add_u32_e32 v181, 0x2400, v180
	global_load_dwordx4 v[198:201], v181, s[22:23]
	v_add_u32_e32 v181, 0x2410, v180
	global_load_dwordx4 v[202:205], v181, s[22:23]
	v_add_u32_e32 v181, 0x2420, v180
	global_load_dwordx4 v[206:209], v181, s[22:23]
	v_add_u32_e32 v181, 0x2430, v180
	global_load_dwordx4 v[210:213], v181, s[22:23]
	s_waitcnt vmcnt(16)
	v_mov_b32_e32 v114, v215
	v_mov_b32_e32 v115, v216
	v_mov_b32_e32 v97, v217
	v_mov_b32_e32 v98, v219
	v_mov_b32_e32 v99, v220
	v_mov_b32_e32 v101, v221
	v_mov_b32_e32 v96, v214
	v_pk_add_f32 v[96:97], v[114:115], v[96:97]
	v_mov_b32_e32 v100, v218
	v_pk_add_f32 v[98:99], v[98:99], v[100:101]
	v_pk_add_f32 v[96:97], v[96:97], v[96:97] op_sel:[0,1] op_sel_hi:[1,0]
	v_pk_add_f32 v[98:99], v[98:99], v[98:99] op_sel:[0,1] op_sel_hi:[1,0]
	v_add_f32_e32 v102, v222, v223
	v_add_f32_e32 v104, v224, v225
	v_mov_b32_e32 v103, v234
	v_mov_b32_e32 v105, v235
	v_mov_b32_e32 v97, v232
	v_mov_b32_e32 v99, v233
	v_pk_add_f32 v[100:101], v[102:103], v[104:105]
	v_pk_add_f32 v[96:97], v[96:97], v[98:99]
	s_nop 0
	v_pk_add_f32 v[96:97], v[96:97], v[100:101]
	s_nop 0
	v_add_f32_e32 v96, v96, v97
	v_fmamk_f32 v96, v96, 0x3a800000, v154
	v_mul_f32_e32 v97, 0x4b800000, v96
	v_cmp_gt_f32_e32 vcc, s63, v96
	s_nop 1
	v_cndmask_b32_e32 v96, v96, v97, vcc
	v_rsq_f32_e32 v98, v96
	v_lshlrev_b64 v[96:97], 6, v[112:113]
	v_lshl_add_u64 v[96:97], s[22:23], 0, v[96:97]
	v_mul_f32_e32 v99, 0x45800000, v98
	v_cndmask_b32_e32 v98, v98, v99, vcc
	v_pk_mul_f32 v[94:95], v[94:95], v[98:99] op_sel_hi:[1,0]
	v_pk_mul_f32 v[92:93], v[92:93], v[98:99] op_sel_hi:[1,0]
	v_pk_mul_f32 v[90:91], v[90:91], v[98:99] op_sel_hi:[1,0]
	v_pk_mul_f32 v[88:89], v[88:89], v[98:99] op_sel_hi:[1,0]
	v_pk_mul_f32 v[82:83], v[82:83], v[98:99] op_sel_hi:[1,0]
	v_pk_mul_f32 v[80:81], v[80:81], v[98:99] op_sel_hi:[1,0]
	v_pk_mul_f32 v[86:87], v[86:87], v[98:99] op_sel_hi:[1,0]
	v_pk_mul_f32 v[84:85], v[84:85], v[98:99] op_sel_hi:[1,0]
	v_max_f32_e32 v92, 0, v92
	v_max_f32_e32 v88, 0, v88
	v_max_f32_e32 v93, 0, v93
	v_max_f32_e32 v89, 0, v89
	v_max_f32_e32 v94, 0, v94
	v_max_f32_e32 v90, 0, v90
	v_max_f32_e32 v95, 0, v95
	v_max_f32_e32 v91, 0, v91
	v_max_f32_e32 v80, 0, v80
	v_max_f32_e32 v81, 0, v81
	v_max_f32_e32 v82, 0, v82
	v_max_f32_e32 v83, 0, v83
	v_max_f32_e32 v84, 0, v84
	v_max_f32_e32 v85, 0, v85
	v_max_f32_e32 v86, 0, v86
	v_max_f32_e32 v87, 0, v87
	v_mul_f32_e32 v92, v92, v92
	v_mul_f32_e32 v88, v88, v88
	v_mul_f32_e32 v93, v93, v93
	v_mul_f32_e32 v89, v89, v89
	v_mul_f32_e32 v94, v94, v94
	v_mul_f32_e32 v90, v90, v90
	v_mul_f32_e32 v95, v95, v95
	v_mul_f32_e32 v91, v91, v91
	v_mul_f32_e32 v98, v80, v80
	v_mul_f32_e32 v99, v81, v81
	v_mul_f32_e32 v100, v82, v82
	v_mul_f32_e32 v101, v83, v83
	v_cvt_pk_bf16_f32 v80, v92, v93
	v_cvt_pk_bf16_f32 v81, v94, v95
	v_cvt_pk_bf16_f32 v82, v88, v89
	v_cvt_pk_bf16_f32 v83, v90, v91
	v_mul_f32_e32 v84, v84, v84
	v_mul_f32_e32 v85, v85, v85
	v_mul_f32_e32 v86, v86, v86
	v_mul_f32_e32 v87, v87, v87
	buffer_store_dwordx4 v[80:83], v116, s[12:15], 0 offen sc1
	s_nop 1
	v_cvt_pk_bf16_f32 v80, v84, v85
	v_cvt_pk_bf16_f32 v81, v86, v87
	v_cvt_pk_bf16_f32 v82, v98, v99
	v_cvt_pk_bf16_f32 v83, v100, v101
	buffer_store_dwordx4 v[80:83], v116, s[12:15], 0 offen offset:256 sc1
	s_nop 0
	v_add_u32_e32 v96, 0x80, v146
	v_ashrrev_i32_e32 v97, 31, v96
	v_lshl_add_u32 v100, v112, 13, v147
	v_add_u32_e32 v181, 0x2800, v180
	global_load_dwordx4 v[214:217], v181, s[22:23]
	v_add_u32_e32 v181, 0x2810, v180
	global_load_dwordx4 v[218:221], v181, s[22:23]
	v_add_u32_e32 v181, 0x2820, v180
	global_load_dwordx4 v[222:225], v181, s[22:23]
	v_add_u32_e32 v181, 0x2830, v180
	global_load_dwordx4 v[232:235], v181, s[22:23]
	s_waitcnt vmcnt(18)
; __device__ __forceinline__ u32x4 pack8(const f32x4 v0, const f32x4 v1) { u32x4 w; w.x = pk2(v0[0], v0[1]); w.y = pk2(v0[2], v0[3]); w.z = pk2(v1[0], v1[1]); w.w = pk2(v1[2], v1[3]); return w; }
; __device__ __forceinline__ float row_rstd(const float* ssq, int row) {
;     const f32x4* p = (const f32x4*)(ssq + (size_t)row * 16);
;     const f32x4 a = p[0], b = p[1], c = p[2], d = p[3];
;     const float s = ((a[0] + a[1]) + (a[2] + a[3])) + ((b[0] + b[1]) + (b[2] + b[3])) + ((c[0] + c[1]) + (c[2] + c[3])) + ((d[0] + d[1]) + (d[2] + d[3]));
;     return rsqrtf(s * (1.0f / 1024.0f) + 1e-6f);
;     __device__ __forceinline__ void operator()(const f32x4 (&acc)[2][2][4][2], const Unit& u, int wr, int wc, int fr, int fq) const {
;     ...
;             for (int m = 0; m < 4; ++m) {
;                 const int row = row0 + ai * 128 + m * 16; const float rs = row_rstd(ssq, row);
; #pragma unroll
;                 for (int bj = 0; bj < 2; ++bj) { f32x4 v0 = acc[ai][bj][m][0] * rs, v1 = acc[ai][bj][m][1] * rs;
; #pragma unroll
;                     for (int j = 0; j < 4; ++j) { const float a = fmaxf(v0[j], 0.f), b = fmaxf(v1[j], 0.f); v0[j] = a * a; v1[j] = b * b; }
;                     __builtin_amdgcn_raw_buffer_store_b128(pack8(v0, v1), rsrc, (unsigned)(((size_t)row * DFF + col0 + bj * 128) * 2), 0, 16  ); }
	v_mov_b32_e32 v98, v237
	v_mov_b32_e32 v99, v238
	v_mov_b32_e32 v81, v239
	v_mov_b32_e32 v82, v241
	v_mov_b32_e32 v83, v242
	v_mov_b32_e32 v85, v243
	v_mov_b32_e32 v80, v236
	v_pk_add_f32 v[80:81], v[98:99], v[80:81]
	v_mov_b32_e32 v84, v240
	v_pk_add_f32 v[82:83], v[82:83], v[84:85]
	v_pk_add_f32 v[80:81], v[80:81], v[80:81] op_sel:[0,1] op_sel_hi:[1,0]
	v_pk_add_f32 v[82:83], v[82:83], v[82:83] op_sel:[0,1] op_sel_hi:[1,0]
	v_add_f32_e32 v86, v244, v245
	v_add_f32_e32 v88, v246, v247
	v_mov_b32_e32 v87, v250
	v_mov_b32_e32 v89, v251
	v_mov_b32_e32 v81, v248
	v_mov_b32_e32 v83, v249
	v_pk_add_f32 v[84:85], v[86:87], v[88:89]
	v_pk_add_f32 v[80:81], v[80:81], v[82:83]
	s_nop 0
	v_pk_add_f32 v[80:81], v[80:81], v[84:85]
	s_nop 0
	v_add_f32_e32 v80, v80, v81
	v_fmamk_f32 v80, v80, 0x3a800000, v154
	v_mul_f32_e32 v81, 0x4b800000, v80
	v_cmp_gt_f32_e32 vcc, s63, v80
	s_nop 1
	v_cndmask_b32_e32 v80, v80, v81, vcc
	v_rsq_f32_e32 v82, v80
	v_lshlrev_b64 v[80:81], 6, v[96:97]
	v_lshl_add_u64 v[80:81], s[22:23], 0, v[80:81]
	v_mul_f32_e32 v83, 0x45800000, v82
	v_cndmask_b32_e32 v82, v82, v83, vcc
	v_pk_mul_f32 v[78:79], v[78:79], v[82:83] op_sel_hi:[1,0]
	v_pk_mul_f32 v[76:77], v[76:77], v[82:83] op_sel_hi:[1,0]
	v_pk_mul_f32 v[74:75], v[74:75], v[82:83] op_sel_hi:[1,0]
	v_pk_mul_f32 v[72:73], v[72:73], v[82:83] op_sel_hi:[1,0]
	v_pk_mul_f32 v[66:67], v[66:67], v[82:83] op_sel_hi:[1,0]
	v_pk_mul_f32 v[64:65], v[64:65], v[82:83] op_sel_hi:[1,0]
	v_pk_mul_f32 v[70:71], v[70:71], v[82:83] op_sel_hi:[1,0]
	v_pk_mul_f32 v[68:69], v[68:69], v[82:83] op_sel_hi:[1,0]
	v_max_f32_e32 v76, 0, v76
	v_max_f32_e32 v72, 0, v72
	v_max_f32_e32 v77, 0, v77
	v_max_f32_e32 v73, 0, v73
	v_max_f32_e32 v78, 0, v78
	v_max_f32_e32 v74, 0, v74
	v_max_f32_e32 v79, 0, v79
	v_max_f32_e32 v75, 0, v75
	v_max_f32_e32 v64, 0, v64
	v_max_f32_e32 v65, 0, v65
	v_max_f32_e32 v66, 0, v66
	v_max_f32_e32 v67, 0, v67
	v_max_f32_e32 v68, 0, v68
	v_max_f32_e32 v69, 0, v69
	v_max_f32_e32 v70, 0, v70
	v_max_f32_e32 v71, 0, v71
	v_mul_f32_e32 v76, v76, v76
	v_mul_f32_e32 v72, v72, v72
	v_mul_f32_e32 v77, v77, v77
	v_mul_f32_e32 v73, v73, v73
	v_mul_f32_e32 v78, v78, v78
	v_mul_f32_e32 v74, v74, v74
	v_mul_f32_e32 v79, v79, v79
	v_mul_f32_e32 v75, v75, v75
	v_mul_f32_e32 v82, v64, v64
	v_mul_f32_e32 v83, v65, v65
	v_mul_f32_e32 v84, v66, v66
	v_mul_f32_e32 v85, v67, v67
	v_cvt_pk_bf16_f32 v64, v76, v77
	v_cvt_pk_bf16_f32 v65, v78, v79
	v_cvt_pk_bf16_f32 v66, v72, v73
	v_cvt_pk_bf16_f32 v67, v74, v75
	v_mul_f32_e32 v68, v68, v68
	v_mul_f32_e32 v69, v69, v69
	v_mul_f32_e32 v70, v70, v70
	v_mul_f32_e32 v71, v71, v71
	buffer_store_dwordx4 v[64:67], v100, s[12:15], 0 offen sc1
	s_nop 1
	v_cvt_pk_bf16_f32 v64, v68, v69
	v_cvt_pk_bf16_f32 v65, v70, v71
	v_cvt_pk_bf16_f32 v66, v82, v83
	v_cvt_pk_bf16_f32 v67, v84, v85
	buffer_store_dwordx4 v[64:67], v100, s[12:15], 0 offen offset:256 sc1
	s_nop 0
	v_add_u32_e32 v80, 0x90, v146
	v_ashrrev_i32_e32 v81, 31, v80
	v_lshl_add_u32 v84, v96, 13, v147
	v_add_u32_e32 v181, 0x2c00, v180
	global_load_dwordx4 v[236:239], v181, s[22:23]
	v_add_u32_e32 v181, 0x2c10, v180
	global_load_dwordx4 v[240:243], v181, s[22:23]
	v_add_u32_e32 v181, 0x2c20, v180
	global_load_dwordx4 v[244:247], v181, s[22:23]
	v_add_u32_e32 v181, 0x2c30, v180
	global_load_dwordx4 v[248:251], v181, s[22:23]
	s_waitcnt vmcnt(18)
	v_mov_b32_e32 v82, v183
	v_mov_b32_e32 v83, v184
	v_mov_b32_e32 v65, v185
	v_mov_b32_e32 v66, v187
	v_mov_b32_e32 v67, v188
	v_mov_b32_e32 v69, v189
	v_mov_b32_e32 v64, v182
	v_pk_add_f32 v[64:65], v[82:83], v[64:65]
	v_mov_b32_e32 v68, v186
	v_pk_add_f32 v[66:67], v[66:67], v[68:69]
	v_pk_add_f32 v[64:65], v[64:65], v[64:65] op_sel:[0,1] op_sel_hi:[1,0]
	v_pk_add_f32 v[66:67], v[66:67], v[66:67] op_sel:[0,1] op_sel_hi:[1,0]
	v_add_f32_e32 v70, v190, v191
	v_add_f32_e32 v72, v192, v193
	v_mov_b32_e32 v71, v196
	v_mov_b32_e32 v73, v197
	v_mov_b32_e32 v65, v194
	v_mov_b32_e32 v67, v195
	v_pk_add_f32 v[68:69], v[70:71], v[72:73]
	v_pk_add_f32 v[64:65], v[64:65], v[66:67]
	s_nop 0
	v_pk_add_f32 v[64:65], v[64:65], v[68:69]
	s_nop 0
	v_add_f32_e32 v64, v64, v65
	v_fmamk_f32 v64, v64, 0x3a800000, v154
	v_mul_f32_e32 v65, 0x4b800000, v64
	v_cmp_gt_f32_e32 vcc, s63, v64
	s_nop 1
	v_cndmask_b32_e32 v64, v64, v65, vcc
	v_rsq_f32_e32 v66, v64
	v_lshlrev_b64 v[64:65], 6, v[80:81]
	v_lshl_add_u64 v[64:65], s[22:23], 0, v[64:65]
	v_mul_f32_e32 v67, 0x45800000, v66
	v_cndmask_b32_e32 v66, v66, v67, vcc
	v_pk_mul_f32 v[62:63], v[62:63], v[66:67] op_sel_hi:[1,0]
	v_pk_mul_f32 v[60:61], v[60:61], v[66:67] op_sel_hi:[1,0]
	v_pk_mul_f32 v[58:59], v[58:59], v[66:67] op_sel_hi:[1,0]
	v_pk_mul_f32 v[56:57], v[56:57], v[66:67] op_sel_hi:[1,0]
	v_pk_mul_f32 v[50:51], v[50:51], v[66:67] op_sel_hi:[1,0]
	v_pk_mul_f32 v[48:49], v[48:49], v[66:67] op_sel_hi:[1,0]
	v_pk_mul_f32 v[54:55], v[54:55], v[66:67] op_sel_hi:[1,0]
	v_pk_mul_f32 v[52:53], v[52:53], v[66:67] op_sel_hi:[1,0]
	v_max_f32_e32 v60, 0, v60
	v_max_f32_e32 v56, 0, v56
	v_max_f32_e32 v61, 0, v61
	v_max_f32_e32 v57, 0, v57
	v_max_f32_e32 v62, 0, v62
	v_max_f32_e32 v58, 0, v58
	v_max_f32_e32 v63, 0, v63
	v_max_f32_e32 v59, 0, v59
	v_max_f32_e32 v48, 0, v48
	v_max_f32_e32 v49, 0, v49
	v_max_f32_e32 v50, 0, v50
	v_max_f32_e32 v51, 0, v51
	v_max_f32_e32 v52, 0, v52
	v_max_f32_e32 v53, 0, v53
	v_max_f32_e32 v54, 0, v54
	v_max_f32_e32 v55, 0, v55
	v_mul_f32_e32 v60, v60, v60
	v_mul_f32_e32 v56, v56, v56
	v_mul_f32_e32 v61, v61, v61
	v_mul_f32_e32 v57, v57, v57
	v_mul_f32_e32 v62, v62, v62
	v_mul_f32_e32 v58, v58, v58
	v_mul_f32_e32 v63, v63, v63
	v_mul_f32_e32 v59, v59, v59
	v_mul_f32_e32 v66, v48, v48
	v_mul_f32_e32 v67, v49, v49
	v_mul_f32_e32 v68, v50, v50
	v_mul_f32_e32 v69, v51, v51
	v_cvt_pk_bf16_f32 v48, v60, v61
	v_cvt_pk_bf16_f32 v49, v62, v63
	v_cvt_pk_bf16_f32 v50, v56, v57
	v_cvt_pk_bf16_f32 v51, v58, v59
	v_mul_f32_e32 v52, v52, v52
	v_mul_f32_e32 v53, v53, v53
	v_mul_f32_e32 v54, v54, v54
	v_mul_f32_e32 v55, v55, v55
	buffer_store_dwordx4 v[48:51], v84, s[12:15], 0 offen sc1
	s_nop 1
	v_cvt_pk_bf16_f32 v48, v52, v53
	v_cvt_pk_bf16_f32 v49, v54, v55
	v_cvt_pk_bf16_f32 v50, v66, v67
	v_cvt_pk_bf16_f32 v51, v68, v69
	buffer_store_dwordx4 v[48:51], v84, s[12:15], 0 offen offset:256 sc1
	s_nop 0
	v_add_u32_e32 v64, 0xa0, v146
	v_ashrrev_i32_e32 v65, 31, v64
	v_lshl_add_u32 v68, v80, 13, v147
	s_waitcnt vmcnt(14)
; __device__ __forceinline__ u32x4 pack8(const f32x4 v0, const f32x4 v1) { u32x4 w; w.x = pk2(v0[0], v0[1]); w.y = pk2(v0[2], v0[3]); w.z = pk2(v1[0], v1[1]); w.w = pk2(v1[2], v1[3]); return w; }
; __device__ __forceinline__ float row_rstd(const float* ssq, int row) {
;     const f32x4* p = (const f32x4*)(ssq + (size_t)row * 16);
;     const f32x4 a = p[0], b = p[1], c = p[2], d = p[3];
;     const float s = ((a[0] + a[1]) + (a[2] + a[3])) + ((b[0] + b[1]) + (b[2] + b[3])) + ((c[0] + c[1]) + (c[2] + c[3])) + ((d[0] + d[1]) + (d[2] + d[3]));
;     return rsqrtf(s * (1.0f / 1024.0f) + 1e-6f);
;     __device__ __forceinline__ void operator()(const f32x4 (&acc)[2][2][4][2], const Unit& u, int wr, int wc, int fr, int fq) const {
;     ...
;             for (int m = 0; m < 4; ++m) {
;                 const int row = row0 + ai * 128 + m * 16; const float rs = row_rstd(ssq, row);
; #pragma unroll
;                 for (int bj = 0; bj < 2; ++bj) { f32x4 v0 = acc[ai][bj][m][0] * rs, v1 = acc[ai][bj][m][1] * rs;
; #pragma unroll
;                     for (int j = 0; j < 4; ++j) { const float a = fmaxf(v0[j], 0.f), b = fmaxf(v1[j], 0.f); v0[j] = a * a; v1[j] = b * b; }
;                     __builtin_amdgcn_raw_buffer_store_b128(pack8(v0, v1), rsrc, (unsigned)(((size_t)row * DFF + col0 + bj * 128) * 2), 0, 16  ); }
	v_mov_b32_e32 v66, v199
	v_mov_b32_e32 v67, v200
	v_mov_b32_e32 v49, v201
	v_mov_b32_e32 v50, v203
	v_mov_b32_e32 v51, v204
	v_mov_b32_e32 v53, v205
	v_mov_b32_e32 v48, v198
	v_pk_add_f32 v[48:49], v[66:67], v[48:49]
	v_mov_b32_e32 v52, v202
	v_pk_add_f32 v[50:51], v[50:51], v[52:53]
	v_pk_add_f32 v[48:49], v[48:49], v[48:49] op_sel:[0,1] op_sel_hi:[1,0]
	v_pk_add_f32 v[50:51], v[50:51], v[50:51] op_sel:[0,1] op_sel_hi:[1,0]
	v_add_f32_e32 v54, v206, v207
	v_add_f32_e32 v56, v208, v209
	v_mov_b32_e32 v55, v212
	v_mov_b32_e32 v57, v213
	v_mov_b32_e32 v49, v210
	v_mov_b32_e32 v51, v211
	v_pk_add_f32 v[52:53], v[54:55], v[56:57]
	v_pk_add_f32 v[48:49], v[48:49], v[50:51]
	s_nop 0
	v_pk_add_f32 v[48:49], v[48:49], v[52:53]
	s_nop 0
	v_add_f32_e32 v48, v48, v49
	v_fmamk_f32 v48, v48, 0x3a800000, v154
	v_mul_f32_e32 v49, 0x4b800000, v48
	v_cmp_gt_f32_e32 vcc, s63, v48
	s_nop 1
	v_cndmask_b32_e32 v48, v48, v49, vcc
	v_rsq_f32_e32 v50, v48
	v_lshlrev_b64 v[48:49], 6, v[64:65]
	v_lshl_add_u64 v[48:49], s[22:23], 0, v[48:49]
	v_mul_f32_e32 v51, 0x45800000, v50
	v_cndmask_b32_e32 v50, v50, v51, vcc
	v_pk_mul_f32 v[46:47], v[46:47], v[50:51] op_sel_hi:[1,0]
	v_pk_mul_f32 v[44:45], v[44:45], v[50:51] op_sel_hi:[1,0]
	v_pk_mul_f32 v[42:43], v[42:43], v[50:51] op_sel_hi:[1,0]
	v_pk_mul_f32 v[40:41], v[40:41], v[50:51] op_sel_hi:[1,0]
	v_pk_mul_f32 v[34:35], v[34:35], v[50:51] op_sel_hi:[1,0]
	v_pk_mul_f32 v[32:33], v[32:33], v[50:51] op_sel_hi:[1,0]
	v_pk_mul_f32 v[38:39], v[38:39], v[50:51] op_sel_hi:[1,0]
	v_pk_mul_f32 v[36:37], v[36:37], v[50:51] op_sel_hi:[1,0]
	v_max_f32_e32 v44, 0, v44
	v_max_f32_e32 v40, 0, v40
	v_max_f32_e32 v45, 0, v45
	v_max_f32_e32 v41, 0, v41
	v_max_f32_e32 v46, 0, v46
	v_max_f32_e32 v42, 0, v42
	v_max_f32_e32 v47, 0, v47
	v_max_f32_e32 v43, 0, v43
	v_max_f32_e32 v32, 0, v32
	v_max_f32_e32 v33, 0, v33
	v_max_f32_e32 v34, 0, v34
	v_max_f32_e32 v35, 0, v35
	v_max_f32_e32 v36, 0, v36
	v_max_f32_e32 v37, 0, v37
	v_max_f32_e32 v38, 0, v38
	v_max_f32_e32 v39, 0, v39
	v_mul_f32_e32 v44, v44, v44
	v_mul_f32_e32 v40, v40, v40
	v_mul_f32_e32 v45, v45, v45
	v_mul_f32_e32 v41, v41, v41
	v_mul_f32_e32 v46, v46, v46
	v_mul_f32_e32 v42, v42, v42
	v_mul_f32_e32 v47, v47, v47
	v_mul_f32_e32 v43, v43, v43
	v_mul_f32_e32 v50, v32, v32
	v_mul_f32_e32 v51, v33, v33
	v_mul_f32_e32 v52, v34, v34
	v_mul_f32_e32 v53, v35, v35
	v_cvt_pk_bf16_f32 v32, v44, v45
	v_cvt_pk_bf16_f32 v33, v46, v47
	v_cvt_pk_bf16_f32 v34, v40, v41
	v_cvt_pk_bf16_f32 v35, v42, v43
	v_mul_f32_e32 v36, v36, v36
	v_mul_f32_e32 v37, v37, v37
	v_mul_f32_e32 v38, v38, v38
	v_mul_f32_e32 v39, v39, v39
	buffer_store_dwordx4 v[32:35], v68, s[12:15], 0 offen sc1
	s_nop 1
	v_cvt_pk_bf16_f32 v32, v36, v37
	v_cvt_pk_bf16_f32 v33, v38, v39
	v_cvt_pk_bf16_f32 v34, v50, v51
	v_cvt_pk_bf16_f32 v35, v52, v53
	buffer_store_dwordx4 v[32:35], v68, s[12:15], 0 offen offset:256 sc1
	s_nop 0
	v_add_u32_e32 v48, 0xb0, v146
	v_ashrrev_i32_e32 v49, 31, v48
	v_lshl_add_u32 v52, v64, 13, v147
	s_waitcnt vmcnt(10)
	v_mov_b32_e32 v50, v215
	v_mov_b32_e32 v51, v216
	v_mov_b32_e32 v33, v217
	v_mov_b32_e32 v34, v219
	v_mov_b32_e32 v35, v220
	v_mov_b32_e32 v37, v221
	v_mov_b32_e32 v32, v214
	v_pk_add_f32 v[32:33], v[50:51], v[32:33]
	v_mov_b32_e32 v36, v218
	v_pk_add_f32 v[34:35], v[34:35], v[36:37]
	v_pk_add_f32 v[32:33], v[32:33], v[32:33] op_sel:[0,1] op_sel_hi:[1,0]
	v_pk_add_f32 v[34:35], v[34:35], v[34:35] op_sel:[0,1] op_sel_hi:[1,0]
	v_add_f32_e32 v38, v222, v223
	v_add_f32_e32 v40, v224, v225
	v_mov_b32_e32 v39, v234
	v_mov_b32_e32 v41, v235
	v_mov_b32_e32 v33, v232
	v_mov_b32_e32 v35, v233
	v_pk_add_f32 v[36:37], v[38:39], v[40:41]
	v_pk_add_f32 v[32:33], v[32:33], v[34:35]
	s_nop 0
	v_pk_add_f32 v[32:33], v[32:33], v[36:37]
	s_nop 0
	v_add_f32_e32 v32, v32, v33
	v_fmamk_f32 v32, v32, 0x3a800000, v154
	v_mul_f32_e32 v33, 0x4b800000, v32
	v_cmp_gt_f32_e32 vcc, s63, v32
	s_nop 1
	v_cndmask_b32_e32 v32, v32, v33, vcc
	v_rsq_f32_e32 v34, v32
	v_lshlrev_b64 v[32:33], 6, v[48:49]
	v_lshl_add_u64 v[32:33], s[22:23], 0, v[32:33]
	v_mul_f32_e32 v35, 0x45800000, v34
	v_cndmask_b32_e32 v34, v34, v35, vcc
	v_pk_mul_f32 v[30:31], v[30:31], v[34:35] op_sel_hi:[1,0]
	v_pk_mul_f32 v[28:29], v[28:29], v[34:35] op_sel_hi:[1,0]
	v_pk_mul_f32 v[26:27], v[26:27], v[34:35] op_sel_hi:[1,0]
	v_pk_mul_f32 v[24:25], v[24:25], v[34:35] op_sel_hi:[1,0]
	v_pk_mul_f32 v[18:19], v[18:19], v[34:35] op_sel_hi:[1,0]
	v_pk_mul_f32 v[16:17], v[16:17], v[34:35] op_sel_hi:[1,0]
	v_pk_mul_f32 v[22:23], v[22:23], v[34:35] op_sel_hi:[1,0]
	v_pk_mul_f32 v[20:21], v[20:21], v[34:35] op_sel_hi:[1,0]
	v_max_f32_e32 v28, 0, v28
	v_max_f32_e32 v24, 0, v24
	v_max_f32_e32 v29, 0, v29
	v_max_f32_e32 v25, 0, v25
	v_max_f32_e32 v30, 0, v30
	v_max_f32_e32 v26, 0, v26
	v_max_f32_e32 v31, 0, v31
	v_max_f32_e32 v27, 0, v27
	v_max_f32_e32 v16, 0, v16
	v_max_f32_e32 v17, 0, v17
	v_max_f32_e32 v18, 0, v18
	v_max_f32_e32 v19, 0, v19
	v_max_f32_e32 v20, 0, v20
	v_max_f32_e32 v21, 0, v21
	v_max_f32_e32 v22, 0, v22
	v_max_f32_e32 v23, 0, v23
	v_mul_f32_e32 v28, v28, v28
	v_mul_f32_e32 v24, v24, v24
	v_mul_f32_e32 v29, v29, v29
	v_mul_f32_e32 v25, v25, v25
	v_mul_f32_e32 v30, v30, v30
	v_mul_f32_e32 v26, v26, v26
	v_mul_f32_e32 v31, v31, v31
	v_mul_f32_e32 v27, v27, v27
	v_mul_f32_e32 v34, v16, v16
	v_mul_f32_e32 v35, v17, v17
	v_mul_f32_e32 v36, v18, v18
	v_mul_f32_e32 v37, v19, v19
	v_cvt_pk_bf16_f32 v16, v28, v29
	v_cvt_pk_bf16_f32 v17, v30, v31
	v_cvt_pk_bf16_f32 v18, v24, v25
	v_cvt_pk_bf16_f32 v19, v26, v27
	v_mul_f32_e32 v20, v20, v20
	v_mul_f32_e32 v21, v21, v21
	v_mul_f32_e32 v22, v22, v22
	v_mul_f32_e32 v23, v23, v23
	buffer_store_dwordx4 v[16:19], v52, s[12:15], 0 offen sc1
	s_nop 1
	v_cvt_pk_bf16_f32 v16, v20, v21
	v_cvt_pk_bf16_f32 v17, v22, v23
	v_cvt_pk_bf16_f32 v18, v34, v35
	v_cvt_pk_bf16_f32 v19, v36, v37
	buffer_store_dwordx4 v[16:19], v52, s[12:15], 0 offen offset:256 sc1
	s_nop 0
	s_waitcnt vmcnt(6)
; __device__ __forceinline__ u32x4 pack8(const f32x4 v0, const f32x4 v1) { u32x4 w; w.x = pk2(v0[0], v0[1]); w.y = pk2(v0[2], v0[3]); w.z = pk2(v1[0], v1[1]); w.w = pk2(v1[2], v1[3]); return w; }
; __device__ __forceinline__ float row_rstd(const float* ssq, int row) {
;     const f32x4* p = (const f32x4*)(ssq + (size_t)row * 16);
;     const f32x4 a = p[0], b = p[1], c = p[2], d = p[3];
;     const float s = ((a[0] + a[1]) + (a[2] + a[3])) + ((b[0] + b[1]) + (b[2] + b[3])) + ((c[0] + c[1]) + (c[2] + c[3])) + ((d[0] + d[1]) + (d[2] + d[3]));
;     return rsqrtf(s * (1.0f / 1024.0f) + 1e-6f);
;     __device__ __forceinline__ void operator()(const f32x4 (&acc)[2][2][4][2], const Unit& u, int wr, int wc, int fr, int fq) const {
;     ...
;             for (int m = 0; m < 4; ++m) {
;                 const int row = row0 + ai * 128 + m * 16; const float rs = row_rstd(ssq, row);
; #pragma unroll
;                 for (int bj = 0; bj < 2; ++bj) { f32x4 v0 = acc[ai][bj][m][0] * rs, v1 = acc[ai][bj][m][1] * rs;
; #pragma unroll
;                     for (int j = 0; j < 4; ++j) { const float a = fmaxf(v0[j], 0.f), b = fmaxf(v1[j], 0.f); v0[j] = a * a; v1[j] = b * b; }
;                     __builtin_amdgcn_raw_buffer_store_b128(pack8(v0, v1), rsrc, (unsigned)(((size_t)row * DFF + col0 + bj * 128) * 2), 0, 16  ); }
;             }
;         asm volatile("s_waitcnt vmcnt(0)" ::: "memory");
;         if (fr == 0 && fq == 0) (void)__hip_atomic_fetch_add(ready + 64 * (pm_off + u.pm), 1u, __ATOMIC_RELAXED, __HIP_MEMORY_SCOPE_AGENT);
	v_mov_b32_e32 v32, v237
	v_mov_b32_e32 v33, v238
	v_mov_b32_e32 v17, v239
	v_mov_b32_e32 v18, v241
	v_mov_b32_e32 v19, v242
	v_mov_b32_e32 v21, v243
	v_mov_b32_e32 v16, v236
	v_pk_add_f32 v[16:17], v[32:33], v[16:17]
	v_mov_b32_e32 v20, v240
	v_pk_add_f32 v[18:19], v[18:19], v[20:21]
	v_pk_add_f32 v[16:17], v[16:17], v[16:17] op_sel:[0,1] op_sel_hi:[1,0]
	v_pk_add_f32 v[18:19], v[18:19], v[18:19] op_sel:[0,1] op_sel_hi:[1,0]
	v_add_f32_e32 v22, v244, v245
	v_add_f32_e32 v24, v246, v247
	v_mov_b32_e32 v23, v250
	v_mov_b32_e32 v25, v251
	v_mov_b32_e32 v17, v248
	v_mov_b32_e32 v19, v249
	v_pk_add_f32 v[20:21], v[22:23], v[24:25]
	v_pk_add_f32 v[16:17], v[16:17], v[18:19]
	s_nop 0
	v_pk_add_f32 v[16:17], v[16:17], v[20:21]
	s_nop 0
	v_add_f32_e32 v16, v16, v17
	v_fmamk_f32 v16, v16, 0x3a800000, v154
	v_mul_f32_e32 v17, 0x4b800000, v16
	v_cmp_gt_f32_e32 vcc, s63, v16
	s_nop 1
	v_cndmask_b32_e32 v16, v16, v17, vcc
	v_rsq_f32_e32 v16, v16
	v_lshl_add_u32 v17, v48, 13, v147
	v_mul_f32_e32 v18, 0x45800000, v16
	v_cndmask_b32_e32 v16, v16, v18, vcc
	v_pk_mul_f32 v[14:15], v[14:15], v[16:17] op_sel_hi:[1,0]
	v_pk_mul_f32 v[12:13], v[12:13], v[16:17] op_sel_hi:[1,0]
	v_pk_mul_f32 v[10:11], v[10:11], v[16:17] op_sel_hi:[1,0]
	v_pk_mul_f32 v[8:9], v[8:9], v[16:17] op_sel_hi:[1,0]
	v_pk_mul_f32 v[2:3], v[2:3], v[16:17] op_sel_hi:[1,0]
	v_pk_mul_f32 v[0:1], v[0:1], v[16:17] op_sel_hi:[1,0]
	v_pk_mul_f32 v[6:7], v[6:7], v[16:17] op_sel_hi:[1,0]
	v_pk_mul_f32 v[4:5], v[4:5], v[16:17] op_sel_hi:[1,0]
	v_max_f32_e32 v12, 0, v12
	v_max_f32_e32 v8, 0, v8
	v_max_f32_e32 v13, 0, v13
	v_max_f32_e32 v9, 0, v9
	v_max_f32_e32 v14, 0, v14
	v_max_f32_e32 v10, 0, v10
	v_max_f32_e32 v15, 0, v15
	v_max_f32_e32 v11, 0, v11
	v_max_f32_e32 v0, 0, v0
	v_max_f32_e32 v1, 0, v1
	v_max_f32_e32 v2, 0, v2
	v_max_f32_e32 v3, 0, v3
	v_max_f32_e32 v4, 0, v4
	v_max_f32_e32 v5, 0, v5
	v_max_f32_e32 v6, 0, v6
	v_max_f32_e32 v7, 0, v7
	v_mul_f32_e32 v12, v12, v12
	v_mul_f32_e32 v8, v8, v8
	v_mul_f32_e32 v13, v13, v13
	v_mul_f32_e32 v9, v9, v9
	v_mul_f32_e32 v14, v14, v14
	v_mul_f32_e32 v10, v10, v10
	v_mul_f32_e32 v15, v15, v15
	v_mul_f32_e32 v11, v11, v11
	v_mul_f32_e32 v16, v0, v0
	v_mul_f32_e32 v18, v1, v1
	v_mul_f32_e32 v19, v2, v2
	v_mul_f32_e32 v20, v3, v3
	v_cvt_pk_bf16_f32 v0, v12, v13
	v_cvt_pk_bf16_f32 v1, v14, v15
	v_cvt_pk_bf16_f32 v2, v8, v9
	v_cvt_pk_bf16_f32 v3, v10, v11
	v_mul_f32_e32 v4, v4, v4
	v_mul_f32_e32 v5, v5, v5
	v_mul_f32_e32 v6, v6, v6
	v_mul_f32_e32 v7, v7, v7
	buffer_store_dwordx4 v[0:3], v17, s[12:15], 0 offen sc1
	s_nop 1
	v_cvt_pk_bf16_f32 v0, v4, v5
	v_cvt_pk_bf16_f32 v1, v6, v7
	v_cvt_pk_bf16_f32 v2, v16, v18
	v_cvt_pk_bf16_f32 v3, v19, v20
	buffer_store_dwordx4 v[0:3], v17, s[12:15], 0 offen offset:256 sc1
	s_waitcnt vmcnt(0)
	s_and_saveexec_b64 s[36:37], s[6:7]
	s_cbranch_execz .LBB0_2091
	s_mov_b64 s[38:39], exec
	v_mbcnt_lo_u32_b32 v0, s38, 0
	v_mbcnt_hi_u32_b32 v0, s39, v0
	v_cmp_eq_u32_e32 vcc, 0, v0
	s_and_b64 s[40:41], exec, vcc
	s_mov_b64 exec, s[40:41]
	s_cbranch_execz .LBB0_2091
	s_lshl_b32 s40, s68, 6
	s_ashr_i32 s41, s40, 31
	s_lshl_b64 s[40:41], s[40:41], 2
	s_add_u32 s40, s66, s40
	s_addc_u32 s41, s67, s41
	s_bcnt1_i32_b64 s25, s[38:39]
	v_mov_b32_e32 v0, s25
	global_atomic_add v131, v0, s[40:41]
	s_branch .LBB0_2091

; #define PG8_STAGE(bufoff, gbase, voff) do { _Pragma("unroll") for (int _i = 0; _i < 2; ++_i) \
;         __builtin_amdgcn_global_load_lds((const unsigned*)((const char*)(gbase) + (voff)[_i]), (LAS unsigned*)(lds + (bufoff) + ldsw + _i * 8192), 16, 0, 0); } while (0)
; #define PG8_LDA(dst, b, h) do { _Pragma("unroll") for (int m = 0; m < 4; ++m) _Pragma("unroll") for (int k = 0; k < 2; ++k) dst[m][k] = *(const LAS bf16x8*)(lds + PG8_SA(b, h) + aoff + m * 2048 + k * 1024); } while (0)
; #define PG8_LDB(dst, b, h) do { _Pragma("unroll") for (int n = 0; n < 2; ++n) _Pragma("unroll") for (int k = 0; k < 2; ++k) dst[n][k] = *(const LAS bf16x8*)(lds + PG8_SB(b, h) + boff + n * 2048 + k * 1024); } while (0)
; #define PG8_MMA(ai, bj, At, Bt) do { __builtin_amdgcn_s_setprio(1); _Pragma("unroll") for (int m = 0; m < 4; ++m) _Pragma("unroll") for (int n = 0; n < 2; ++n) _Pragma("unroll") for (int k = 0; k < 2; ++k) \
;         acc[ai][bj][m][n] = __builtin_amdgcn_mfma_f32_16x16x32_bf16(Bt[n][k], At[m][k], acc[ai][bj][m][n], 0, 0, 0); __builtin_amdgcn_s_setprio(0); } while (0)
; #define PG8_WAIT_V(n) asm volatile("s_waitcnt vmcnt(" #n ")" ::: "memory")
; #define PG8_WAIT_L(n) asm volatile("s_waitcnt lgkmcnt(" #n ")" ::: "memory")
; #define PG8_BAR __builtin_amdgcn_s_barrier()
; #define PG8_SCHED __builtin_amdgcn_sched_barrier(0)
;     ...
;         for (int t = 0; t < nt; t += 2) {
;             const bool last = (t == nt - 2);
;             const char* a1 = cA + (size_t)(t + 1) * kstep;
;             const char* a2 = last ? nA : cA + (size_t)(t + 2) * kstep; const char* b2 = last ? nB : cB + (size_t)(t + 2) * kstep;
;             const char* a3 = a2 + kstep; const char* b3 = b2 + kstep;
;             if (last && has_next) PG8_A_READY(nxt);
;             PG8_LDB(B0, 0, 0); PG8_SCHED; PG8_LDA(At, 0, 0); PG8_STAGE(PG8_SA(1, 1), a1 + hA, voffA);
;             PG8_WAIT_L(8); PG8_BAR; PG8_WAIT_L(0); PG8_MMA(0, 0, At, B0); PG8_BAR; PG8_SCHED;
;             PG8_LDB(B1, 0, 1); PG8_STAGE(PG8_SB(0, 0), b2, voffB);
;             PG8_BAR; PG8_WAIT_L(0); PG8_MMA(0, 1, At, B1); PG8_BAR;
;             PG8_LDA(At, 0, 1); PG8_STAGE(PG8_SA(0, 0), a2, voffA);
;             PG8_BAR; PG8_WAIT_L(0); PG8_MMA(1, 0, At, B0); PG8_BAR; PG8_SCHED;
;             PG8_STAGE(PG8_SB(0, 1), b2 + hB, voffB);
;             PG8_WAIT_V(6); PG8_BAR; PG8_MMA(1, 1, At, B1); PG8_BAR;
.LBB0_2122:
	ds_read_b128 v[150:153], v143
	ds_read_b128 v[154:157], v143 offset:1024
	ds_read_b128 v[158:161], v143 offset:2048
	ds_read_b128 v[162:165], v143 offset:3072
	s_add_u32 s36, s34, 0xfffc0080
	s_addc_u32 s37, s35, -1
	s_cmp_eq_u32 s71, 12
	s_cselect_b32 s39, s21, s37
	s_cselect_b32 s38, s44, s36
	s_cselect_b32 s37, s29, s70
	s_cselect_b32 s36, s45, s69
	v_lshl_add_u64 v[202:203], s[34:35], 0, v[138:139]
	s_add_i32 m0, s53, 0xc000
	ds_read_b128 v[170:173], v146
	ds_read_b128 v[174:177], v146 offset:1024
	ds_read_b128 v[178:181], v146 offset:2048
	ds_read_b128 v[182:185], v146 offset:3072
	ds_read_b128 v[186:189], v146 offset:4096
	ds_read_b128 v[190:193], v146 offset:5120
	ds_read_b128 v[194:197], v146 offset:6144
	ds_read_b128 v[198:201], v146 offset:7168
	global_load_lds_dwordx4 v[202:203], off
	v_lshl_add_u64 v[202:203], s[34:35], 0, v[136:137]
	s_add_i32 m0, s53, 0xe000
	s_nop 0
	global_load_lds_dwordx4 v[202:203], off
	s_waitcnt lgkmcnt(8)
	s_barrier
	s_waitcnt lgkmcnt(0)
	s_setprio 1
	s_waitcnt lgkmcnt(0)
	v_mfma_f32_16x16x32_bf16 v[124:127], v[150:153], v[170:173], v[124:127]
	v_mfma_f32_16x16x32_bf16 v[120:123], v[158:161], v[170:173], v[120:123]
	v_mfma_f32_16x16x32_bf16 v[108:111], v[150:153], v[178:181], v[108:111]
	v_mfma_f32_16x16x32_bf16 v[104:107], v[158:161], v[178:181], v[104:107]
	v_mfma_f32_16x16x32_bf16 v[92:95], v[150:153], v[186:189], v[92:95]
	v_mfma_f32_16x16x32_bf16 v[88:91], v[158:161], v[186:189], v[88:91]
	v_mfma_f32_16x16x32_bf16 v[76:79], v[150:153], v[194:197], v[76:79]
	v_mfma_f32_16x16x32_bf16 v[72:75], v[158:161], v[194:197], v[72:75]
	v_mfma_f32_16x16x32_bf16 v[124:127], v[154:157], v[174:177], v[124:127]
	v_mfma_f32_16x16x32_bf16 v[120:123], v[162:165], v[174:177], v[120:123]
	v_mfma_f32_16x16x32_bf16 v[108:111], v[154:157], v[182:185], v[108:111]
	v_mfma_f32_16x16x32_bf16 v[104:107], v[162:165], v[182:185], v[104:107]
	v_mfma_f32_16x16x32_bf16 v[92:95], v[154:157], v[190:193], v[92:95]
	v_mfma_f32_16x16x32_bf16 v[88:91], v[162:165], v[190:193], v[88:91]
	v_mfma_f32_16x16x32_bf16 v[76:79], v[154:157], v[198:201], v[76:79]
	v_mfma_f32_16x16x32_bf16 v[72:75], v[162:165], v[198:201], v[72:75]
	s_setprio 0
	s_barrier
	s_add_i32 s72, s61, s52
	v_lshl_add_u64 v[218:219], s[36:37], 0, v[130:131]
	s_mov_b32 m0, s72
	ds_read_b128 v[202:205], v147
	ds_read_b128 v[206:209], v147 offset:1024
	ds_read_b128 v[210:213], v147 offset:2048
	ds_read_b128 v[214:217], v147 offset:3072
	global_load_lds_dwordx4 v[218:219], off
	v_lshl_add_u64 v[220:221], s[36:37], 0, v[134:135]
	s_add_i32 m0, s72, 0x2000
	s_nop 0
	global_load_lds_dwordx4 v[220:221], off
	s_barrier
	s_waitcnt lgkmcnt(0)
	s_setprio 1
	s_waitcnt lgkmcnt(0)
	v_mfma_f32_16x16x32_bf16 v[116:119], v[202:205], v[170:173], v[116:119]
	v_mfma_f32_16x16x32_bf16 v[112:115], v[210:213], v[170:173], v[112:115]
	v_mfma_f32_16x16x32_bf16 v[100:103], v[202:205], v[178:181], v[100:103]
	v_mfma_f32_16x16x32_bf16 v[96:99], v[210:213], v[178:181], v[96:99]
	v_mfma_f32_16x16x32_bf16 v[84:87], v[202:205], v[186:189], v[84:87]
	v_mfma_f32_16x16x32_bf16 v[80:83], v[210:213], v[186:189], v[80:83]
	v_mfma_f32_16x16x32_bf16 v[68:71], v[202:205], v[194:197], v[68:71]
	v_mfma_f32_16x16x32_bf16 v[64:67], v[210:213], v[194:197], v[64:67]
	v_mfma_f32_16x16x32_bf16 v[116:119], v[206:209], v[174:177], v[116:119]
	v_mfma_f32_16x16x32_bf16 v[112:115], v[214:217], v[174:177], v[112:115]
	v_mfma_f32_16x16x32_bf16 v[100:103], v[206:209], v[182:185], v[100:103]
	v_mfma_f32_16x16x32_bf16 v[96:99], v[214:217], v[182:185], v[96:99]
	v_mfma_f32_16x16x32_bf16 v[84:87], v[206:209], v[190:193], v[84:87]
	v_mfma_f32_16x16x32_bf16 v[80:83], v[214:217], v[190:193], v[80:83]
	v_mfma_f32_16x16x32_bf16 v[68:71], v[206:209], v[198:201], v[68:71]
	v_mfma_f32_16x16x32_bf16 v[64:67], v[214:217], v[198:201], v[64:67]
	s_setprio 0
	s_mov_b32 m0, s53
	v_lshl_add_u64 v[222:223], s[38:39], 0, v[128:129]
	s_barrier
	ds_read_b128 v[170:173], v146 offset:16384
	ds_read_b128 v[174:177], v146 offset:17408
	ds_read_b128 v[178:181], v146 offset:18432
	ds_read_b128 v[182:185], v146 offset:19456
	ds_read_b128 v[186:189], v146 offset:20480
	ds_read_b128 v[190:193], v146 offset:21504
	ds_read_b128 v[194:197], v146 offset:22528
	ds_read_b128 v[198:201], v146 offset:23552
	global_load_lds_dwordx4 v[222:223], off
	v_lshl_add_u64 v[224:225], s[38:39], 0, v[132:133]
	s_mov_b32 m0, s54
	s_nop 0
	global_load_lds_dwordx4 v[224:225], off
	s_barrier
	s_waitcnt lgkmcnt(0)
	s_setprio 1
	s_waitcnt lgkmcnt(0)
	v_mfma_f32_16x16x32_bf16 v[60:63], v[150:153], v[170:173], v[60:63]
	v_mfma_f32_16x16x32_bf16 v[56:59], v[158:161], v[170:173], v[56:59]
	v_mfma_f32_16x16x32_bf16 v[44:47], v[150:153], v[178:181], v[44:47]
	v_mfma_f32_16x16x32_bf16 v[40:43], v[158:161], v[178:181], v[40:43]
	v_mfma_f32_16x16x32_bf16 v[28:31], v[150:153], v[186:189], v[28:31]
	v_mfma_f32_16x16x32_bf16 v[24:27], v[158:161], v[186:189], v[24:27]
	v_mfma_f32_16x16x32_bf16 v[12:15], v[150:153], v[194:197], v[12:15]
	v_mfma_f32_16x16x32_bf16 v[8:11], v[158:161], v[194:197], v[8:11]
	v_mfma_f32_16x16x32_bf16 v[60:63], v[154:157], v[174:177], v[60:63]
	v_mfma_f32_16x16x32_bf16 v[56:59], v[162:165], v[174:177], v[56:59]
	v_mfma_f32_16x16x32_bf16 v[44:47], v[154:157], v[182:185], v[44:47]
	v_mfma_f32_16x16x32_bf16 v[40:43], v[162:165], v[182:185], v[40:43]
	v_mfma_f32_16x16x32_bf16 v[28:31], v[154:157], v[190:193], v[28:31]
	v_mfma_f32_16x16x32_bf16 v[24:27], v[162:165], v[190:193], v[24:27]
	v_mfma_f32_16x16x32_bf16 v[12:15], v[154:157], v[198:201], v[12:15]
	v_mfma_f32_16x16x32_bf16 v[8:11], v[162:165], v[198:201], v[8:11]
	s_setprio 0
	s_barrier
; #define PG8_STAGE(bufoff, gbase, voff) do { _Pragma("unroll") for (int _i = 0; _i < 2; ++_i) \
;         __builtin_amdgcn_global_load_lds((const unsigned*)((const char*)(gbase) + (voff)[_i]), (LAS unsigned*)(lds + (bufoff) + ldsw + _i * 8192), 16, 0, 0); } while (0)
; #define PG8_LDA(dst, b, h) do { _Pragma("unroll") for (int m = 0; m < 4; ++m) _Pragma("unroll") for (int k = 0; k < 2; ++k) dst[m][k] = *(const LAS bf16x8*)(lds + PG8_SA(b, h) + aoff + m * 2048 + k * 1024); } while (0)
; #define PG8_LDB(dst, b, h) do { _Pragma("unroll") for (int n = 0; n < 2; ++n) _Pragma("unroll") for (int k = 0; k < 2; ++k) dst[n][k] = *(const LAS bf16x8*)(lds + PG8_SB(b, h) + boff + n * 2048 + k * 1024); } while (0)
; #define PG8_MMA(ai, bj, At, Bt) do { __builtin_amdgcn_s_setprio(1); _Pragma("unroll") for (int m = 0; m < 4; ++m) _Pragma("unroll") for (int n = 0; n < 2; ++n) _Pragma("unroll") for (int k = 0; k < 2; ++k) \
;         acc[ai][bj][m][n] = __builtin_amdgcn_mfma_f32_16x16x32_bf16(Bt[n][k], At[m][k], acc[ai][bj][m][n], 0, 0, 0); __builtin_amdgcn_s_setprio(0); } while (0)
; #define PG8_WAIT_V(n) asm volatile("s_waitcnt vmcnt(" #n ")" ::: "memory")
; #define PG8_WAIT_L(n) asm volatile("s_waitcnt lgkmcnt(" #n ")" ::: "memory")
; #define PG8_BAR __builtin_amdgcn_s_barrier()
; #define PG8_SCHED __builtin_amdgcn_sched_barrier(0)
;     ...
;             PG8_WAIT_V(6); PG8_BAR; PG8_MMA(1, 1, At, B1); PG8_BAR;
;             PG8_LDB(B0, 1, 0); PG8_SCHED; PG8_LDA(At, 1, 0); PG8_STAGE(PG8_SA(0, 1), a2 + hA, voffA);
;             PG8_WAIT_L(8); PG8_BAR; PG8_WAIT_L(0); PG8_MMA(0, 0, At, B0); PG8_BAR; PG8_SCHED;
;             PG8_LDB(B1, 1, 1); PG8_STAGE(PG8_SB(1, 0), b3, voffB);
;             PG8_BAR; PG8_WAIT_L(0); PG8_MMA(0, 1, At, B1); PG8_BAR;
;             PG8_LDA(At, 1, 1); PG8_STAGE(PG8_SA(1, 0), a3, voffA);
;             PG8_BAR; PG8_WAIT_L(0); PG8_MMA(1, 0, At, B0); PG8_BAR; PG8_SCHED;
	s_add_u32 s72, s36, 0x40000
	s_addc_u32 s73, s37, 0
	s_add_i32 s74, s62, s52
	v_lshl_add_u64 v[150:151], s[72:73], 0, v[130:131]
	s_mov_b32 m0, s74
	s_nop 0
	global_load_lds_dwordx4 v[150:151], off
	v_lshl_add_u64 v[150:151], s[72:73], 0, v[134:135]
	s_add_i32 m0, s74, 0x2000
	s_nop 0
	global_load_lds_dwordx4 v[150:151], off
	s_waitcnt vmcnt(6)
	s_barrier
	s_setprio 1
	v_mfma_f32_16x16x32_bf16 v[52:55], v[202:205], v[170:173], v[52:55]
	v_mfma_f32_16x16x32_bf16 v[48:51], v[210:213], v[170:173], v[48:51]
	v_mfma_f32_16x16x32_bf16 v[36:39], v[202:205], v[178:181], v[36:39]
	v_mfma_f32_16x16x32_bf16 v[32:35], v[210:213], v[178:181], v[32:35]
	v_mfma_f32_16x16x32_bf16 v[20:23], v[202:205], v[186:189], v[20:23]
	v_mfma_f32_16x16x32_bf16 v[16:19], v[210:213], v[186:189], v[16:19]
	v_mfma_f32_16x16x32_bf16 v[4:7], v[202:205], v[194:197], v[4:7]
	v_mfma_f32_16x16x32_bf16 v[0:3], v[210:213], v[194:197], v[0:3]
	v_mfma_f32_16x16x32_bf16 v[52:55], v[206:209], v[174:177], v[52:55]
	v_mfma_f32_16x16x32_bf16 v[48:51], v[214:217], v[174:177], v[48:51]
	v_mfma_f32_16x16x32_bf16 v[36:39], v[206:209], v[182:185], v[36:39]
	v_mfma_f32_16x16x32_bf16 v[32:35], v[214:217], v[182:185], v[32:35]
	v_mfma_f32_16x16x32_bf16 v[20:23], v[206:209], v[190:193], v[20:23]
	v_mfma_f32_16x16x32_bf16 v[16:19], v[214:217], v[190:193], v[16:19]
	v_mfma_f32_16x16x32_bf16 v[4:7], v[206:209], v[198:201], v[4:7]
	v_mfma_f32_16x16x32_bf16 v[0:3], v[214:217], v[198:201], v[0:3]
	s_setprio 0
	s_add_i32 s72, 0, 0x18000
	v_add_u32_e32 v149, s72, v141
	s_barrier
	ds_read_b128 v[150:153], v149
	ds_read_b128 v[154:157], v149 offset:1024
	ds_read_b128 v[158:161], v149 offset:2048
	ds_read_b128 v[162:165], v149 offset:3072
	s_add_u32 s38, s38, 0x40000
	s_addc_u32 s39, s39, 0
	s_mov_b32 m0, s55
	v_lshl_add_u64 v[202:203], s[38:39], 0, v[128:129]
	ds_read_b128 v[170:173], v146 offset:32768
	ds_read_b128 v[174:177], v146 offset:33792
	ds_read_b128 v[178:181], v146 offset:34816
	ds_read_b128 v[182:185], v146 offset:35840
	ds_read_b128 v[186:189], v146 offset:36864
	ds_read_b128 v[190:193], v146 offset:37888
	ds_read_b128 v[194:197], v146 offset:38912
	ds_read_b128 v[198:201], v146 offset:39936
	global_load_lds_dwordx4 v[202:203], off
	v_lshl_add_u64 v[202:203], s[38:39], 0, v[132:133]
	s_mov_b32 m0, s56
	s_nop 0
	global_load_lds_dwordx4 v[202:203], off
	s_waitcnt lgkmcnt(8)
	s_barrier
	s_waitcnt lgkmcnt(0)
	s_setprio 1
	s_waitcnt lgkmcnt(0)
	v_mfma_f32_16x16x32_bf16 v[124:127], v[150:153], v[170:173], v[124:127]
	v_mfma_f32_16x16x32_bf16 v[120:123], v[158:161], v[170:173], v[120:123]
	v_mfma_f32_16x16x32_bf16 v[108:111], v[150:153], v[178:181], v[108:111]
	v_mfma_f32_16x16x32_bf16 v[104:107], v[158:161], v[178:181], v[104:107]
	v_mfma_f32_16x16x32_bf16 v[92:95], v[150:153], v[186:189], v[92:95]
	v_mfma_f32_16x16x32_bf16 v[88:91], v[158:161], v[186:189], v[88:91]
	v_mfma_f32_16x16x32_bf16 v[76:79], v[150:153], v[194:197], v[76:79]
	v_mfma_f32_16x16x32_bf16 v[72:75], v[158:161], v[194:197], v[72:75]
	v_mfma_f32_16x16x32_bf16 v[124:127], v[154:157], v[174:177], v[124:127]
	v_mfma_f32_16x16x32_bf16 v[120:123], v[162:165], v[174:177], v[120:123]
	v_mfma_f32_16x16x32_bf16 v[108:111], v[154:157], v[182:185], v[108:111]
	v_mfma_f32_16x16x32_bf16 v[104:107], v[162:165], v[182:185], v[104:107]
	v_mfma_f32_16x16x32_bf16 v[92:95], v[154:157], v[190:193], v[92:95]
	v_mfma_f32_16x16x32_bf16 v[88:91], v[162:165], v[190:193], v[88:91]
	v_mfma_f32_16x16x32_bf16 v[76:79], v[154:157], v[198:201], v[76:79]
	v_mfma_f32_16x16x32_bf16 v[72:75], v[162:165], v[198:201], v[72:75]
	s_setprio 0
	s_barrier
	s_add_i32 s38, 0, 0x1c000
	s_add_i32 s39, s72, s52
	v_add_u32_e32 v149, s38, v141
	v_lshl_add_u64 v[218:219], v[218:219], 0, s[22:23]
	s_mov_b32 m0, s39
	ds_read_b128 v[202:205], v149
	ds_read_b128 v[206:209], v149 offset:1024
	ds_read_b128 v[210:213], v149 offset:2048
	ds_read_b128 v[214:217], v149 offset:3072
	global_load_lds_dwordx4 v[218:219], off
	v_lshl_add_u64 v[218:219], v[220:221], 0, s[22:23]
	s_add_i32 m0, s39, 0x2000
	s_nop 0
	global_load_lds_dwordx4 v[218:219], off
	s_barrier
	s_waitcnt lgkmcnt(0)
	s_setprio 1
	s_waitcnt lgkmcnt(0)
	v_mfma_f32_16x16x32_bf16 v[116:119], v[202:205], v[170:173], v[116:119]
	v_mfma_f32_16x16x32_bf16 v[112:115], v[210:213], v[170:173], v[112:115]
	v_mfma_f32_16x16x32_bf16 v[100:103], v[202:205], v[178:181], v[100:103]
	v_mfma_f32_16x16x32_bf16 v[96:99], v[210:213], v[178:181], v[96:99]
	v_mfma_f32_16x16x32_bf16 v[84:87], v[202:205], v[186:189], v[84:87]
	v_mfma_f32_16x16x32_bf16 v[80:83], v[210:213], v[186:189], v[80:83]
	v_mfma_f32_16x16x32_bf16 v[68:71], v[202:205], v[194:197], v[68:71]
	v_mfma_f32_16x16x32_bf16 v[64:67], v[210:213], v[194:197], v[64:67]
	v_mfma_f32_16x16x32_bf16 v[116:119], v[206:209], v[174:177], v[116:119]
	v_mfma_f32_16x16x32_bf16 v[112:115], v[214:217], v[174:177], v[112:115]
	v_mfma_f32_16x16x32_bf16 v[100:103], v[206:209], v[182:185], v[100:103]
	v_mfma_f32_16x16x32_bf16 v[96:99], v[214:217], v[182:185], v[96:99]
	v_mfma_f32_16x16x32_bf16 v[84:87], v[206:209], v[190:193], v[84:87]
	v_mfma_f32_16x16x32_bf16 v[80:83], v[214:217], v[190:193], v[80:83]
	v_mfma_f32_16x16x32_bf16 v[68:71], v[206:209], v[198:201], v[68:71]
	v_mfma_f32_16x16x32_bf16 v[64:67], v[214:217], v[198:201], v[64:67]
	s_setprio 0
	s_mov_b32 m0, s58
	v_lshl_add_u64 v[218:219], v[222:223], 0, s[22:23]
	s_barrier
	ds_read_b128 v[170:173], v146 offset:49152
	ds_read_b128 v[174:177], v146 offset:50176
	ds_read_b128 v[178:181], v146 offset:51200
	ds_read_b128 v[182:185], v146 offset:52224
	ds_read_b128 v[186:189], v146 offset:53248
	ds_read_b128 v[190:193], v146 offset:54272
	ds_read_b128 v[194:197], v146 offset:55296
	ds_read_b128 v[198:201], v146 offset:56320
	global_load_lds_dwordx4 v[218:219], off
	v_lshl_add_u64 v[218:219], v[224:225], 0, s[22:23]
	s_mov_b32 m0, s59
	s_nop 0
	global_load_lds_dwordx4 v[218:219], off
	s_barrier
; #define PG8_STAGE(bufoff, gbase, voff) do { _Pragma("unroll") for (int _i = 0; _i < 2; ++_i) \
;         __builtin_amdgcn_global_load_lds((const unsigned*)((const char*)(gbase) + (voff)[_i]), (LAS unsigned*)(lds + (bufoff) + ldsw + _i * 8192), 16, 0, 0); } while (0)
; #define PG8_LDA(dst, b, h) do { _Pragma("unroll") for (int m = 0; m < 4; ++m) _Pragma("unroll") for (int k = 0; k < 2; ++k) dst[m][k] = *(const LAS bf16x8*)(lds + PG8_SA(b, h) + aoff + m * 2048 + k * 1024); } while (0)
; #define PG8_LDB(dst, b, h) do { _Pragma("unroll") for (int n = 0; n < 2; ++n) _Pragma("unroll") for (int k = 0; k < 2; ++k) dst[n][k] = *(const LAS bf16x8*)(lds + PG8_SB(b, h) + boff + n * 2048 + k * 1024); } while (0)
; #define PG8_MMA(ai, bj, At, Bt) do { __builtin_amdgcn_s_setprio(1); _Pragma("unroll") for (int m = 0; m < 4; ++m) _Pragma("unroll") for (int n = 0; n < 2; ++n) _Pragma("unroll") for (int k = 0; k < 2; ++k) \
;         acc[ai][bj][m][n] = __builtin_amdgcn_mfma_f32_16x16x32_bf16(Bt[n][k], At[m][k], acc[ai][bj][m][n], 0, 0, 0); __builtin_amdgcn_s_setprio(0); } while (0)
; #define PG8_WAIT_V(n) asm volatile("s_waitcnt vmcnt(" #n ")" ::: "memory")
; #define PG8_WAIT_L(n) asm volatile("s_waitcnt lgkmcnt(" #n ")" ::: "memory")
; #define PG8_BAR __builtin_amdgcn_s_barrier()
;     ...
;             PG8_WAIT_L(8); PG8_BAR; PG8_WAIT_L(0); PG8_MMA(0, 0, At, B0); PG8_BAR; PG8_SCHED;
;             PG8_LDB(B1, 1, 1); PG8_STAGE(PG8_SB(1, 0), b3, voffB);
;             PG8_BAR; PG8_WAIT_L(0); PG8_MMA(0, 1, At, B1); PG8_BAR;
;             PG8_LDA(At, 1, 1); PG8_STAGE(PG8_SA(1, 0), a3, voffA);
;             PG8_BAR; PG8_WAIT_L(0); PG8_MMA(1, 0, At, B0); PG8_BAR; PG8_SCHED;
;             PG8_STAGE(PG8_SB(1, 1), b3 + hB, voffB);
;             PG8_WAIT_V(6); PG8_BAR; PG8_MMA(1, 1, At, B1); PG8_BAR;
;     __device__ __forceinline__ void operator()(const f32x4 (&acc)[2][2][4][2], const Unit& u, int wr, int wc, int fr, int fq) const {
;         const __amdgpu_buffer_rsrc_t rsrc = __builtin_amdgcn_make_buffer_rsrc((void*)O, 0, T_ALL * DFF * 2, 0x00020000);
;         const int row0 = row_off + u.pm * 256 + wr * 64 + fr, col0 = u.pn * 256 + wc * 32 + 8 * fq;
; #pragma unroll
;         for (int ai = 0; ai < 2; ++ai)
; #pragma unroll
;             for (int m = 0; m < 4; ++m) {
;                 const int row = row0 + ai * 128 + m * 16; const float rs = row_rstd(ssq, row);
	s_waitcnt lgkmcnt(0)
	s_setprio 1
	s_waitcnt lgkmcnt(0)
	v_mfma_f32_16x16x32_bf16 v[60:63], v[150:153], v[170:173], v[60:63]
	v_mfma_f32_16x16x32_bf16 v[56:59], v[158:161], v[170:173], v[56:59]
	v_mfma_f32_16x16x32_bf16 v[44:47], v[150:153], v[178:181], v[44:47]
	v_mfma_f32_16x16x32_bf16 v[40:43], v[158:161], v[178:181], v[40:43]
	v_mfma_f32_16x16x32_bf16 v[28:31], v[150:153], v[186:189], v[28:31]
	v_mfma_f32_16x16x32_bf16 v[24:27], v[158:161], v[186:189], v[24:27]
	v_mfma_f32_16x16x32_bf16 v[12:15], v[150:153], v[194:197], v[12:15]
	v_mfma_f32_16x16x32_bf16 v[8:11], v[158:161], v[194:197], v[8:11]
	v_mfma_f32_16x16x32_bf16 v[60:63], v[154:157], v[174:177], v[60:63]
	v_mfma_f32_16x16x32_bf16 v[56:59], v[162:165], v[174:177], v[56:59]
	v_mfma_f32_16x16x32_bf16 v[44:47], v[154:157], v[182:185], v[44:47]
	v_mfma_f32_16x16x32_bf16 v[40:43], v[162:165], v[182:185], v[40:43]
	v_mfma_f32_16x16x32_bf16 v[28:31], v[154:157], v[190:193], v[28:31]
	v_mfma_f32_16x16x32_bf16 v[24:27], v[162:165], v[190:193], v[24:27]
	v_mfma_f32_16x16x32_bf16 v[12:15], v[154:157], v[198:201], v[12:15]
	v_mfma_f32_16x16x32_bf16 v[8:11], v[162:165], v[198:201], v[8:11]
	s_setprio 0
	s_barrier
	s_add_u32 s36, s36, 0x40080
	s_addc_u32 s37, s37, 0
	s_add_i32 s38, s38, s52
	v_lshl_add_u64 v[150:151], s[36:37], 0, v[130:131]
	s_mov_b32 m0, s38
	s_nop 0
	global_load_lds_dwordx4 v[150:151], off
	v_lshl_add_u64 v[150:151], s[36:37], 0, v[134:135]
	s_add_i32 m0, s38, 0x2000
	s_nop 0
	global_load_lds_dwordx4 v[150:151], off
	s_waitcnt vmcnt(6)
	s_barrier
	s_setprio 1
	v_mfma_f32_16x16x32_bf16 v[52:55], v[202:205], v[170:173], v[52:55]
	v_mfma_f32_16x16x32_bf16 v[48:51], v[210:213], v[170:173], v[48:51]
	v_mfma_f32_16x16x32_bf16 v[36:39], v[202:205], v[178:181], v[36:39]
	v_mfma_f32_16x16x32_bf16 v[32:35], v[210:213], v[178:181], v[32:35]
	v_mfma_f32_16x16x32_bf16 v[20:23], v[202:205], v[186:189], v[20:23]
	v_mfma_f32_16x16x32_bf16 v[16:19], v[210:213], v[186:189], v[16:19]
	v_mfma_f32_16x16x32_bf16 v[4:7], v[202:205], v[194:197], v[4:7]
	v_mfma_f32_16x16x32_bf16 v[0:3], v[210:213], v[194:197], v[0:3]
	v_mfma_f32_16x16x32_bf16 v[52:55], v[206:209], v[174:177], v[52:55]
	v_mfma_f32_16x16x32_bf16 v[48:51], v[214:217], v[174:177], v[48:51]
	v_mfma_f32_16x16x32_bf16 v[36:39], v[206:209], v[182:185], v[36:39]
	v_mfma_f32_16x16x32_bf16 v[32:35], v[214:217], v[182:185], v[32:35]
	v_mfma_f32_16x16x32_bf16 v[20:23], v[206:209], v[190:193], v[20:23]
	v_mfma_f32_16x16x32_bf16 v[16:19], v[214:217], v[190:193], v[16:19]
	v_mfma_f32_16x16x32_bf16 v[4:7], v[206:209], v[198:201], v[4:7]
	v_mfma_f32_16x16x32_bf16 v[0:3], v[214:217], v[198:201], v[0:3]
	s_setprio 0
	s_add_i32 s71, s71, 2
	s_add_u32 s69, s69, 0x100
	s_addc_u32 s70, s70, 0
	s_add_u32 s34, s34, 0x100
	s_addc_u32 s35, s35, 0
	s_cmp_gt_u32 s71, 13
	s_barrier
	s_cbranch_scc0 .LBB0_2122
	v_lshl_add_u32 v150, s68, 8, v140
	v_add_u32_e32 v164, 0x4000, v150
	v_ashrrev_i32_e32 v165, 31, v164
	v_lshlrev_b64 v[152:153], 6, v[164:165]
	v_lshl_add_u64 v[170:171], s[14:15], 0, v[152:153]
	v_subrev_u32_e32 v176, s14, v170
	v_add_u32_e32 v177, 0x0, v176
	global_load_dwordx4 v[178:181], v177, s[14:15]
	v_add_u32_e32 v177, 0x10, v176
	global_load_dwordx4 v[182:185], v177, s[14:15]
	v_add_u32_e32 v177, 0x20, v176
	global_load_dwordx4 v[186:189], v177, s[14:15]
	v_add_u32_e32 v177, 0x30, v176
	global_load_dwordx4 v[190:193], v177, s[14:15]
	v_add_u32_e32 v177, 0x400, v176
	global_load_dwordx4 v[194:197], v177, s[14:15]
	v_add_u32_e32 v177, 0x410, v176
	global_load_dwordx4 v[198:201], v177, s[14:15]
	v_add_u32_e32 v177, 0x420, v176
	global_load_dwordx4 v[202:205], v177, s[14:15]
	v_add_u32_e32 v177, 0x430, v176
	global_load_dwordx4 v[206:209], v177, s[14:15]
	v_add_u32_e32 v177, 0x800, v176
	global_load_dwordx4 v[210:213], v177, s[14:15]
	v_add_u32_e32 v177, 0x810, v176
	global_load_dwordx4 v[214:217], v177, s[14:15]
	v_add_u32_e32 v177, 0x820, v176
	global_load_dwordx4 v[232:235], v177, s[14:15]
	v_add_u32_e32 v177, 0x830, v176
	global_load_dwordx4 v[236:239], v177, s[14:15]
	v_add_u32_e32 v177, 0xc00, v176
	global_load_dwordx4 v[240:243], v177, s[14:15]
	v_add_u32_e32 v177, 0xc10, v176
	global_load_dwordx4 v[244:247], v177, s[14:15]
	v_add_u32_e32 v177, 0xc20, v176
	global_load_dwordx4 v[248:251], v177, s[14:15]
	v_add_u32_e32 v177, 0xc30, v176
	global_load_dwordx4 v[252:255], v177, s[14:15]
	s_nop 0
	v_lshl_or_b32 v149, s33, 9, v142
	v_lshl_add_u32 v151, v164, 13, v149
	v_add_u32_e32 v174, 0x4010, v150
	v_ashrrev_i32_e32 v175, 31, v174
	s_waitcnt vmcnt(12)
; __device__ __forceinline__ u32x4 pack8(const f32x4 v0, const f32x4 v1) { u32x4 w; w.x = pk2(v0[0], v0[1]); w.y = pk2(v0[2], v0[3]); w.z = pk2(v1[0], v1[1]); w.w = pk2(v1[2], v1[3]); return w; }
; __device__ __forceinline__ float row_rstd(const float* ssq, int row) {
;     const f32x4* p = (const f32x4*)(ssq + (size_t)row * 16);
;     const f32x4 a = p[0], b = p[1], c = p[2], d = p[3];
;     const float s = ((a[0] + a[1]) + (a[2] + a[3])) + ((b[0] + b[1]) + (b[2] + b[3])) + ((c[0] + c[1]) + (c[2] + c[3])) + ((d[0] + d[1]) + (d[2] + d[3]));
;     return rsqrtf(s * (1.0f / 1024.0f) + 1e-6f);
;     __device__ __forceinline__ void operator()(const f32x4 (&acc)[2][2][4][2], const Unit& u, int wr, int wc, int fr, int fq) const {
;     ...
;             for (int m = 0; m < 4; ++m) {
;                 const int row = row0 + ai * 128 + m * 16; const float rs = row_rstd(ssq, row);
; #pragma unroll
;                 for (int bj = 0; bj < 2; ++bj) { f32x4 v0 = acc[ai][bj][m][0] * rs, v1 = acc[ai][bj][m][1] * rs;
; #pragma unroll
;                     for (int j = 0; j < 4; ++j) { const float a = fmaxf(v0[j], 0.f), b = fmaxf(v1[j], 0.f); v0[j] = a * a; v1[j] = b * b; }
;                     __builtin_amdgcn_raw_buffer_store_b128(pack8(v0, v1), rsrc, (unsigned)(((size_t)row * DFF + col0 + bj * 128) * 2), 0, 16  ); }
	v_mov_b32_e32 v164, v179
	v_mov_b32_e32 v165, v180
	v_mov_b32_e32 v153, v181
	v_mov_b32_e32 v154, v183
	v_mov_b32_e32 v155, v184
	v_mov_b32_e32 v157, v185
	v_mov_b32_e32 v152, v178
	v_pk_add_f32 v[152:153], v[164:165], v[152:153]
	v_mov_b32_e32 v156, v182
	v_pk_add_f32 v[154:155], v[154:155], v[156:157]
	v_pk_add_f32 v[152:153], v[152:153], v[152:153] op_sel:[0,1] op_sel_hi:[1,0]
	v_pk_add_f32 v[154:155], v[154:155], v[154:155] op_sel:[0,1] op_sel_hi:[1,0]
	v_add_f32_e32 v158, v186, v187
	v_add_f32_e32 v160, v188, v189
	v_mov_b32_e32 v159, v192
	v_mov_b32_e32 v161, v193
	v_mov_b32_e32 v153, v190
	v_mov_b32_e32 v155, v191
	v_pk_add_f32 v[156:157], v[158:159], v[160:161]
	v_pk_add_f32 v[152:153], v[152:153], v[154:155]
	s_nop 0
	v_pk_add_f32 v[152:153], v[152:153], v[156:157]
	s_nop 0
	v_add_f32_e32 v152, v152, v153
	v_fmamk_f32 v152, v152, 0x3a800000, v148
	v_mul_f32_e32 v153, 0x4b800000, v152
	v_cmp_gt_f32_e32 vcc, s63, v152
	s_nop 1
	v_cndmask_b32_e32 v152, v152, v153, vcc
	v_rsq_f32_e32 v154, v152
	v_lshlrev_b64 v[152:153], 6, v[174:175]
	v_lshl_add_u64 v[152:153], s[14:15], 0, v[152:153]
	v_mul_f32_e32 v155, 0x45800000, v154
	v_cndmask_b32_e32 v154, v154, v155, vcc
	v_pk_mul_f32 v[126:127], v[126:127], v[154:155] op_sel_hi:[1,0]
	v_pk_mul_f32 v[124:125], v[124:125], v[154:155] op_sel_hi:[1,0]
	v_pk_mul_f32 v[122:123], v[122:123], v[154:155] op_sel_hi:[1,0]
	v_pk_mul_f32 v[120:121], v[120:121], v[154:155] op_sel_hi:[1,0]
	v_pk_mul_f32 v[114:115], v[114:115], v[154:155] op_sel_hi:[1,0]
	v_pk_mul_f32 v[112:113], v[112:113], v[154:155] op_sel_hi:[1,0]
	v_pk_mul_f32 v[118:119], v[118:119], v[154:155] op_sel_hi:[1,0]
	v_pk_mul_f32 v[116:117], v[116:117], v[154:155] op_sel_hi:[1,0]
	v_max_f32_e32 v124, 0, v124
	v_max_f32_e32 v120, 0, v120
	v_max_f32_e32 v125, 0, v125
	v_max_f32_e32 v121, 0, v121
	v_max_f32_e32 v126, 0, v126
	v_max_f32_e32 v122, 0, v122
	v_max_f32_e32 v127, 0, v127
	v_max_f32_e32 v123, 0, v123
	v_max_f32_e32 v112, 0, v112
	v_max_f32_e32 v113, 0, v113
	v_max_f32_e32 v114, 0, v114
	v_max_f32_e32 v115, 0, v115
	v_max_f32_e32 v116, 0, v116
	v_max_f32_e32 v117, 0, v117
	v_max_f32_e32 v118, 0, v118
	v_max_f32_e32 v119, 0, v119
	v_mul_f32_e32 v124, v124, v124
	v_mul_f32_e32 v120, v120, v120
	v_mul_f32_e32 v125, v125, v125
	v_mul_f32_e32 v121, v121, v121
	v_mul_f32_e32 v126, v126, v126
	v_mul_f32_e32 v122, v122, v122
	v_mul_f32_e32 v127, v127, v127
	v_mul_f32_e32 v123, v123, v123
	v_mul_f32_e32 v154, v112, v112
	v_mul_f32_e32 v155, v113, v113
	v_mul_f32_e32 v156, v114, v114
	v_mul_f32_e32 v157, v115, v115
	v_cvt_pk_bf16_f32 v112, v124, v125
	v_cvt_pk_bf16_f32 v113, v126, v127
	v_cvt_pk_bf16_f32 v114, v120, v121
	v_cvt_pk_bf16_f32 v115, v122, v123
	v_mul_f32_e32 v116, v116, v116
	v_mul_f32_e32 v117, v117, v117
	v_mul_f32_e32 v118, v118, v118
	v_mul_f32_e32 v119, v119, v119
	buffer_store_dwordx4 v[112:115], v151, s[8:11], 0 offen sc1
	s_nop 1
	v_cvt_pk_bf16_f32 v112, v116, v117
	v_cvt_pk_bf16_f32 v113, v118, v119
	v_cvt_pk_bf16_f32 v114, v154, v155
	v_cvt_pk_bf16_f32 v115, v156, v157
	buffer_store_dwordx4 v[112:115], v151, s[8:11], 0 offen offset:256 sc1
	s_nop 0
	v_add_u32_e32 v152, 0x4020, v150
	v_ashrrev_i32_e32 v153, 31, v152
	v_lshl_add_u32 v151, v174, 13, v149
	v_add_u32_e32 v177, 0x2000, v176
	global_load_dwordx4 v[178:181], v177, s[14:15]
	v_add_u32_e32 v177, 0x2010, v176
	global_load_dwordx4 v[182:185], v177, s[14:15]
	v_add_u32_e32 v177, 0x2020, v176
	global_load_dwordx4 v[186:189], v177, s[14:15]
	v_add_u32_e32 v177, 0x2030, v176
	global_load_dwordx4 v[190:193], v177, s[14:15]
	s_waitcnt vmcnt(14)
	v_mov_b32_e32 v154, v195
	v_mov_b32_e32 v155, v196
	v_mov_b32_e32 v113, v197
	v_mov_b32_e32 v114, v199
	v_mov_b32_e32 v115, v200
	v_mov_b32_e32 v117, v201
	v_mov_b32_e32 v112, v194
	v_pk_add_f32 v[112:113], v[154:155], v[112:113]
	v_mov_b32_e32 v116, v198
	v_pk_add_f32 v[114:115], v[114:115], v[116:117]
	v_pk_add_f32 v[112:113], v[112:113], v[112:113] op_sel:[0,1] op_sel_hi:[1,0]
	v_pk_add_f32 v[114:115], v[114:115], v[114:115] op_sel:[0,1] op_sel_hi:[1,0]
	v_add_f32_e32 v118, v202, v203
	v_add_f32_e32 v120, v204, v205
	v_mov_b32_e32 v119, v208
	v_mov_b32_e32 v121, v209
	v_mov_b32_e32 v113, v206
	v_mov_b32_e32 v115, v207
	v_pk_add_f32 v[116:117], v[118:119], v[120:121]
	v_pk_add_f32 v[112:113], v[112:113], v[114:115]
	s_nop 0
	v_pk_add_f32 v[112:113], v[112:113], v[116:117]
	s_nop 0
	v_add_f32_e32 v112, v112, v113
	v_fmamk_f32 v112, v112, 0x3a800000, v148
	v_mul_f32_e32 v113, 0x4b800000, v112
	v_cmp_gt_f32_e32 vcc, s63, v112
	s_nop 1
	v_cndmask_b32_e32 v112, v112, v113, vcc
	v_rsq_f32_e32 v114, v112
	v_lshlrev_b64 v[112:113], 6, v[152:153]
	v_lshl_add_u64 v[112:113], s[14:15], 0, v[112:113]
	v_mul_f32_e32 v115, 0x45800000, v114
	v_cndmask_b32_e32 v114, v114, v115, vcc
	v_pk_mul_f32 v[110:111], v[110:111], v[114:115] op_sel_hi:[1,0]
	v_pk_mul_f32 v[108:109], v[108:109], v[114:115] op_sel_hi:[1,0]
	v_pk_mul_f32 v[106:107], v[106:107], v[114:115] op_sel_hi:[1,0]
	v_pk_mul_f32 v[104:105], v[104:105], v[114:115] op_sel_hi:[1,0]
	v_pk_mul_f32 v[98:99], v[98:99], v[114:115] op_sel_hi:[1,0]
	v_pk_mul_f32 v[96:97], v[96:97], v[114:115] op_sel_hi:[1,0]
	v_pk_mul_f32 v[102:103], v[102:103], v[114:115] op_sel_hi:[1,0]
	v_pk_mul_f32 v[100:101], v[100:101], v[114:115] op_sel_hi:[1,0]
	v_max_f32_e32 v108, 0, v108
	v_max_f32_e32 v104, 0, v104
	v_max_f32_e32 v109, 0, v109
	v_max_f32_e32 v105, 0, v105
	v_max_f32_e32 v110, 0, v110
	v_max_f32_e32 v106, 0, v106
	v_max_f32_e32 v111, 0, v111
	v_max_f32_e32 v107, 0, v107
	v_max_f32_e32 v96, 0, v96
	v_max_f32_e32 v97, 0, v97
	v_max_f32_e32 v98, 0, v98
	v_max_f32_e32 v99, 0, v99
	v_max_f32_e32 v100, 0, v100
; __device__ __forceinline__ u32x4 pack8(const f32x4 v0, const f32x4 v1) { u32x4 w; w.x = pk2(v0[0], v0[1]); w.y = pk2(v0[2], v0[3]); w.z = pk2(v1[0], v1[1]); w.w = pk2(v1[2], v1[3]); return w; }
; __device__ __forceinline__ float row_rstd(const float* ssq, int row) {
;     const f32x4* p = (const f32x4*)(ssq + (size_t)row * 16);
;     const f32x4 a = p[0], b = p[1], c = p[2], d = p[3];
;     const float s = ((a[0] + a[1]) + (a[2] + a[3])) + ((b[0] + b[1]) + (b[2] + b[3])) + ((c[0] + c[1]) + (c[2] + c[3])) + ((d[0] + d[1]) + (d[2] + d[3]));
;     return rsqrtf(s * (1.0f / 1024.0f) + 1e-6f);
;     __device__ __forceinline__ void operator()(const f32x4 (&acc)[2][2][4][2], const Unit& u, int wr, int wc, int fr, int fq) const {
;     ...
;             for (int m = 0; m < 4; ++m) {
;                 const int row = row0 + ai * 128 + m * 16; const float rs = row_rstd(ssq, row);
; #pragma unroll
;                 for (int bj = 0; bj < 2; ++bj) { f32x4 v0 = acc[ai][bj][m][0] * rs, v1 = acc[ai][bj][m][1] * rs;
; #pragma unroll
;                     for (int j = 0; j < 4; ++j) { const float a = fmaxf(v0[j], 0.f), b = fmaxf(v1[j], 0.f); v0[j] = a * a; v1[j] = b * b; }
;                     __builtin_amdgcn_raw_buffer_store_b128(pack8(v0, v1), rsrc, (unsigned)(((size_t)row * DFF + col0 + bj * 128) * 2), 0, 16  ); }
	v_max_f32_e32 v101, 0, v101
	v_max_f32_e32 v102, 0, v102
	v_max_f32_e32 v103, 0, v103
	v_mul_f32_e32 v108, v108, v108
	v_mul_f32_e32 v104, v104, v104
	v_mul_f32_e32 v109, v109, v109
	v_mul_f32_e32 v105, v105, v105
	v_mul_f32_e32 v110, v110, v110
	v_mul_f32_e32 v106, v106, v106
	v_mul_f32_e32 v111, v111, v111
	v_mul_f32_e32 v107, v107, v107
	v_mul_f32_e32 v114, v96, v96
	v_mul_f32_e32 v115, v97, v97
	v_mul_f32_e32 v116, v98, v98
	v_mul_f32_e32 v117, v99, v99
	v_cvt_pk_bf16_f32 v96, v108, v109
	v_cvt_pk_bf16_f32 v97, v110, v111
	v_cvt_pk_bf16_f32 v98, v104, v105
	v_cvt_pk_bf16_f32 v99, v106, v107
	v_mul_f32_e32 v100, v100, v100
	v_mul_f32_e32 v101, v101, v101
	v_mul_f32_e32 v102, v102, v102
	v_mul_f32_e32 v103, v103, v103
	buffer_store_dwordx4 v[96:99], v151, s[8:11], 0 offen sc1
	s_nop 1
	v_cvt_pk_bf16_f32 v96, v100, v101
	v_cvt_pk_bf16_f32 v97, v102, v103
	v_cvt_pk_bf16_f32 v98, v114, v115
	v_cvt_pk_bf16_f32 v99, v116, v117
	buffer_store_dwordx4 v[96:99], v151, s[8:11], 0 offen offset:256 sc1
	s_nop 0
	v_add_u32_e32 v112, 0x4030, v150
	v_ashrrev_i32_e32 v113, 31, v112
	v_lshl_add_u32 v116, v152, 13, v149
	v_add_u32_e32 v177, 0x2400, v176
	global_load_dwordx4 v[194:197], v177, s[14:15]
	v_add_u32_e32 v177, 0x2410, v176
	global_load_dwordx4 v[198:201], v177, s[14:15]
	v_add_u32_e32 v177, 0x2420, v176
	global_load_dwordx4 v[202:205], v177, s[14:15]
	v_add_u32_e32 v177, 0x2430, v176
	global_load_dwordx4 v[206:209], v177, s[14:15]
	s_waitcnt vmcnt(16)
	v_mov_b32_e32 v114, v211
	v_mov_b32_e32 v115, v212
	v_mov_b32_e32 v97, v213
	v_mov_b32_e32 v98, v215
	v_mov_b32_e32 v99, v216
	v_mov_b32_e32 v101, v217
	v_mov_b32_e32 v96, v210
	v_pk_add_f32 v[96:97], v[114:115], v[96:97]
	v_mov_b32_e32 v100, v214
	v_pk_add_f32 v[98:99], v[98:99], v[100:101]
	v_pk_add_f32 v[96:97], v[96:97], v[96:97] op_sel:[0,1] op_sel_hi:[1,0]
	v_pk_add_f32 v[98:99], v[98:99], v[98:99] op_sel:[0,1] op_sel_hi:[1,0]
	v_add_f32_e32 v102, v232, v233
	v_add_f32_e32 v104, v234, v235
	v_mov_b32_e32 v103, v238
	v_mov_b32_e32 v105, v239
	v_mov_b32_e32 v97, v236
	v_mov_b32_e32 v99, v237
	v_pk_add_f32 v[100:101], v[102:103], v[104:105]
	v_pk_add_f32 v[96:97], v[96:97], v[98:99]
	s_nop 0
	v_pk_add_f32 v[96:97], v[96:97], v[100:101]
	s_nop 0
	v_add_f32_e32 v96, v96, v97
	v_fmamk_f32 v96, v96, 0x3a800000, v148
	v_mul_f32_e32 v97, 0x4b800000, v96
	v_cmp_gt_f32_e32 vcc, s63, v96
	s_nop 1
	v_cndmask_b32_e32 v96, v96, v97, vcc
	v_rsq_f32_e32 v98, v96
	v_lshlrev_b64 v[96:97], 6, v[112:113]
	v_lshl_add_u64 v[96:97], s[14:15], 0, v[96:97]
	v_mul_f32_e32 v99, 0x45800000, v98
	v_cndmask_b32_e32 v98, v98, v99, vcc
	v_pk_mul_f32 v[94:95], v[94:95], v[98:99] op_sel_hi:[1,0]
	v_pk_mul_f32 v[92:93], v[92:93], v[98:99] op_sel_hi:[1,0]
	v_pk_mul_f32 v[90:91], v[90:91], v[98:99] op_sel_hi:[1,0]
	v_pk_mul_f32 v[88:89], v[88:89], v[98:99] op_sel_hi:[1,0]
	v_pk_mul_f32 v[82:83], v[82:83], v[98:99] op_sel_hi:[1,0]
	v_pk_mul_f32 v[80:81], v[80:81], v[98:99] op_sel_hi:[1,0]
	v_pk_mul_f32 v[86:87], v[86:87], v[98:99] op_sel_hi:[1,0]
	v_pk_mul_f32 v[84:85], v[84:85], v[98:99] op_sel_hi:[1,0]
	v_max_f32_e32 v92, 0, v92
	v_max_f32_e32 v88, 0, v88
	v_max_f32_e32 v93, 0, v93
	v_max_f32_e32 v89, 0, v89
	v_max_f32_e32 v94, 0, v94
	v_max_f32_e32 v90, 0, v90
	v_max_f32_e32 v95, 0, v95
	v_max_f32_e32 v91, 0, v91
	v_max_f32_e32 v80, 0, v80
	v_max_f32_e32 v81, 0, v81
	v_max_f32_e32 v82, 0, v82
	v_max_f32_e32 v83, 0, v83
	v_max_f32_e32 v84, 0, v84
	v_max_f32_e32 v85, 0, v85
	v_max_f32_e32 v86, 0, v86
	v_max_f32_e32 v87, 0, v87
	v_mul_f32_e32 v92, v92, v92
	v_mul_f32_e32 v88, v88, v88
	v_mul_f32_e32 v93, v93, v93
	v_mul_f32_e32 v89, v89, v89
	v_mul_f32_e32 v94, v94, v94
	v_mul_f32_e32 v90, v90, v90
	v_mul_f32_e32 v95, v95, v95
	v_mul_f32_e32 v91, v91, v91
	v_mul_f32_e32 v98, v80, v80
	v_mul_f32_e32 v99, v81, v81
	v_mul_f32_e32 v100, v82, v82
	v_mul_f32_e32 v101, v83, v83
	v_cvt_pk_bf16_f32 v80, v92, v93
	v_cvt_pk_bf16_f32 v81, v94, v95
	v_cvt_pk_bf16_f32 v82, v88, v89
	v_cvt_pk_bf16_f32 v83, v90, v91
	v_mul_f32_e32 v84, v84, v84
	v_mul_f32_e32 v85, v85, v85
	v_mul_f32_e32 v86, v86, v86
	v_mul_f32_e32 v87, v87, v87
	buffer_store_dwordx4 v[80:83], v116, s[8:11], 0 offen sc1
	s_nop 1
	v_cvt_pk_bf16_f32 v80, v84, v85
	v_cvt_pk_bf16_f32 v81, v86, v87
	v_cvt_pk_bf16_f32 v82, v98, v99
	v_cvt_pk_bf16_f32 v83, v100, v101
	buffer_store_dwordx4 v[80:83], v116, s[8:11], 0 offen offset:256 sc1
	s_nop 0
	v_add_u32_e32 v96, 0x4080, v150
	v_ashrrev_i32_e32 v97, 31, v96
	v_lshl_add_u32 v100, v112, 13, v149
	v_add_u32_e32 v177, 0x2800, v176
	global_load_dwordx4 v[210:213], v177, s[14:15]
	v_add_u32_e32 v177, 0x2810, v176
	global_load_dwordx4 v[214:217], v177, s[14:15]
	v_add_u32_e32 v177, 0x2820, v176
	global_load_dwordx4 v[232:235], v177, s[14:15]
	v_add_u32_e32 v177, 0x2830, v176
	global_load_dwordx4 v[236:239], v177, s[14:15]
	s_waitcnt vmcnt(18)
; __device__ __forceinline__ u32x4 pack8(const f32x4 v0, const f32x4 v1) { u32x4 w; w.x = pk2(v0[0], v0[1]); w.y = pk2(v0[2], v0[3]); w.z = pk2(v1[0], v1[1]); w.w = pk2(v1[2], v1[3]); return w; }
; __device__ __forceinline__ float row_rstd(const float* ssq, int row) {
;     const f32x4* p = (const f32x4*)(ssq + (size_t)row * 16);
;     const f32x4 a = p[0], b = p[1], c = p[2], d = p[3];
;     const float s = ((a[0] + a[1]) + (a[2] + a[3])) + ((b[0] + b[1]) + (b[2] + b[3])) + ((c[0] + c[1]) + (c[2] + c[3])) + ((d[0] + d[1]) + (d[2] + d[3]));
;     return rsqrtf(s * (1.0f / 1024.0f) + 1e-6f);
;     __device__ __forceinline__ void operator()(const f32x4 (&acc)[2][2][4][2], const Unit& u, int wr, int wc, int fr, int fq) const {
;     ...
;             for (int m = 0; m < 4; ++m) {
;                 const int row = row0 + ai * 128 + m * 16; const float rs = row_rstd(ssq, row);
; #pragma unroll
;                 for (int bj = 0; bj < 2; ++bj) { f32x4 v0 = acc[ai][bj][m][0] * rs, v1 = acc[ai][bj][m][1] * rs;
; #pragma unroll
;                     for (int j = 0; j < 4; ++j) { const float a = fmaxf(v0[j], 0.f), b = fmaxf(v1[j], 0.f); v0[j] = a * a; v1[j] = b * b; }
;                     __builtin_amdgcn_raw_buffer_store_b128(pack8(v0, v1), rsrc, (unsigned)(((size_t)row * DFF + col0 + bj * 128) * 2), 0, 16  ); }
	v_mov_b32_e32 v98, v241
	v_mov_b32_e32 v99, v242
	v_mov_b32_e32 v81, v243
	v_mov_b32_e32 v82, v245
	v_mov_b32_e32 v83, v246
	v_mov_b32_e32 v85, v247
	v_mov_b32_e32 v80, v240
	v_pk_add_f32 v[80:81], v[98:99], v[80:81]
	v_mov_b32_e32 v84, v244
	v_pk_add_f32 v[82:83], v[82:83], v[84:85]
	v_pk_add_f32 v[80:81], v[80:81], v[80:81] op_sel:[0,1] op_sel_hi:[1,0]
	v_pk_add_f32 v[82:83], v[82:83], v[82:83] op_sel:[0,1] op_sel_hi:[1,0]
	v_add_f32_e32 v86, v248, v249
	v_add_f32_e32 v88, v250, v251
	v_mov_b32_e32 v87, v254
	v_mov_b32_e32 v89, v255
	v_mov_b32_e32 v81, v252
	v_mov_b32_e32 v83, v253
	v_pk_add_f32 v[84:85], v[86:87], v[88:89]
	v_pk_add_f32 v[80:81], v[80:81], v[82:83]
	s_nop 0
	v_pk_add_f32 v[80:81], v[80:81], v[84:85]
	s_nop 0
	v_add_f32_e32 v80, v80, v81
	v_fmamk_f32 v80, v80, 0x3a800000, v148
	v_mul_f32_e32 v81, 0x4b800000, v80
	v_cmp_gt_f32_e32 vcc, s63, v80
	s_nop 1
	v_cndmask_b32_e32 v80, v80, v81, vcc
	v_rsq_f32_e32 v82, v80
	v_lshlrev_b64 v[80:81], 6, v[96:97]
	v_lshl_add_u64 v[80:81], s[14:15], 0, v[80:81]
	v_mul_f32_e32 v83, 0x45800000, v82
	v_cndmask_b32_e32 v82, v82, v83, vcc
	v_pk_mul_f32 v[78:79], v[78:79], v[82:83] op_sel_hi:[1,0]
	v_pk_mul_f32 v[76:77], v[76:77], v[82:83] op_sel_hi:[1,0]
	v_pk_mul_f32 v[74:75], v[74:75], v[82:83] op_sel_hi:[1,0]
	v_pk_mul_f32 v[72:73], v[72:73], v[82:83] op_sel_hi:[1,0]
	v_pk_mul_f32 v[66:67], v[66:67], v[82:83] op_sel_hi:[1,0]
	v_pk_mul_f32 v[64:65], v[64:65], v[82:83] op_sel_hi:[1,0]
	v_pk_mul_f32 v[70:71], v[70:71], v[82:83] op_sel_hi:[1,0]
	v_pk_mul_f32 v[68:69], v[68:69], v[82:83] op_sel_hi:[1,0]
	v_max_f32_e32 v76, 0, v76
	v_max_f32_e32 v72, 0, v72
	v_max_f32_e32 v77, 0, v77
	v_max_f32_e32 v73, 0, v73
	v_max_f32_e32 v78, 0, v78
	v_max_f32_e32 v74, 0, v74
	v_max_f32_e32 v79, 0, v79
	v_max_f32_e32 v75, 0, v75
	v_max_f32_e32 v64, 0, v64
	v_max_f32_e32 v65, 0, v65
	v_max_f32_e32 v66, 0, v66
	v_max_f32_e32 v67, 0, v67
	v_max_f32_e32 v68, 0, v68
	v_max_f32_e32 v69, 0, v69
	v_max_f32_e32 v70, 0, v70
	v_max_f32_e32 v71, 0, v71
	v_mul_f32_e32 v76, v76, v76
	v_mul_f32_e32 v72, v72, v72
	v_mul_f32_e32 v77, v77, v77
	v_mul_f32_e32 v73, v73, v73
	v_mul_f32_e32 v78, v78, v78
	v_mul_f32_e32 v74, v74, v74
	v_mul_f32_e32 v79, v79, v79
	v_mul_f32_e32 v75, v75, v75
	v_mul_f32_e32 v82, v64, v64
	v_mul_f32_e32 v83, v65, v65
	v_mul_f32_e32 v84, v66, v66
	v_mul_f32_e32 v85, v67, v67
	v_cvt_pk_bf16_f32 v64, v76, v77
	v_cvt_pk_bf16_f32 v65, v78, v79
	v_cvt_pk_bf16_f32 v66, v72, v73
	v_cvt_pk_bf16_f32 v67, v74, v75
	v_mul_f32_e32 v68, v68, v68
	v_mul_f32_e32 v69, v69, v69
	v_mul_f32_e32 v70, v70, v70
	v_mul_f32_e32 v71, v71, v71
	buffer_store_dwordx4 v[64:67], v100, s[8:11], 0 offen sc1
	s_nop 1
	v_cvt_pk_bf16_f32 v64, v68, v69
	v_cvt_pk_bf16_f32 v65, v70, v71
	v_cvt_pk_bf16_f32 v66, v82, v83
	v_cvt_pk_bf16_f32 v67, v84, v85
	buffer_store_dwordx4 v[64:67], v100, s[8:11], 0 offen offset:256 sc1
	s_nop 0
	v_add_u32_e32 v80, 0x4090, v150
	v_ashrrev_i32_e32 v81, 31, v80
	v_lshl_add_u32 v84, v96, 13, v149
	v_add_u32_e32 v177, 0x2c00, v176
	global_load_dwordx4 v[240:243], v177, s[14:15]
	v_add_u32_e32 v177, 0x2c10, v176
	global_load_dwordx4 v[244:247], v177, s[14:15]
	v_add_u32_e32 v177, 0x2c20, v176
	global_load_dwordx4 v[248:251], v177, s[14:15]
	v_add_u32_e32 v177, 0x2c30, v176
	global_load_dwordx4 v[252:255], v177, s[14:15]
	s_waitcnt vmcnt(18)
	v_mov_b32_e32 v82, v179
	v_mov_b32_e32 v83, v180
	v_mov_b32_e32 v65, v181
	v_mov_b32_e32 v66, v183
	v_mov_b32_e32 v67, v184
	v_mov_b32_e32 v69, v185
	v_mov_b32_e32 v64, v178
	v_pk_add_f32 v[64:65], v[82:83], v[64:65]
	v_mov_b32_e32 v68, v182
	v_pk_add_f32 v[66:67], v[66:67], v[68:69]
	v_pk_add_f32 v[64:65], v[64:65], v[64:65] op_sel:[0,1] op_sel_hi:[1,0]
	v_pk_add_f32 v[66:67], v[66:67], v[66:67] op_sel:[0,1] op_sel_hi:[1,0]
	v_add_f32_e32 v70, v186, v187
	v_add_f32_e32 v72, v188, v189
	v_mov_b32_e32 v71, v192
	v_mov_b32_e32 v73, v193
	v_mov_b32_e32 v65, v190
	v_mov_b32_e32 v67, v191
	v_pk_add_f32 v[68:69], v[70:71], v[72:73]
	v_pk_add_f32 v[64:65], v[64:65], v[66:67]
	s_nop 0
	v_pk_add_f32 v[64:65], v[64:65], v[68:69]
	s_nop 0
	v_add_f32_e32 v64, v64, v65
	v_fmamk_f32 v64, v64, 0x3a800000, v148
	v_mul_f32_e32 v65, 0x4b800000, v64
	v_cmp_gt_f32_e32 vcc, s63, v64
	s_nop 1
	v_cndmask_b32_e32 v64, v64, v65, vcc
	v_rsq_f32_e32 v66, v64
	v_lshlrev_b64 v[64:65], 6, v[80:81]
	v_lshl_add_u64 v[64:65], s[14:15], 0, v[64:65]
	v_mul_f32_e32 v67, 0x45800000, v66
	v_cndmask_b32_e32 v66, v66, v67, vcc
	v_pk_mul_f32 v[62:63], v[62:63], v[66:67] op_sel_hi:[1,0]
	v_pk_mul_f32 v[60:61], v[60:61], v[66:67] op_sel_hi:[1,0]
	v_pk_mul_f32 v[58:59], v[58:59], v[66:67] op_sel_hi:[1,0]
	v_pk_mul_f32 v[56:57], v[56:57], v[66:67] op_sel_hi:[1,0]
	v_pk_mul_f32 v[50:51], v[50:51], v[66:67] op_sel_hi:[1,0]
	v_pk_mul_f32 v[48:49], v[48:49], v[66:67] op_sel_hi:[1,0]
	v_pk_mul_f32 v[54:55], v[54:55], v[66:67] op_sel_hi:[1,0]
	v_pk_mul_f32 v[52:53], v[52:53], v[66:67] op_sel_hi:[1,0]
	v_max_f32_e32 v60, 0, v60
	v_max_f32_e32 v56, 0, v56
	v_max_f32_e32 v61, 0, v61
	v_max_f32_e32 v57, 0, v57
	v_max_f32_e32 v62, 0, v62
	v_max_f32_e32 v58, 0, v58
	v_max_f32_e32 v63, 0, v63
	v_max_f32_e32 v59, 0, v59
	v_max_f32_e32 v48, 0, v48
	v_max_f32_e32 v49, 0, v49
	v_max_f32_e32 v50, 0, v50
	v_max_f32_e32 v51, 0, v51
	v_max_f32_e32 v52, 0, v52
	v_max_f32_e32 v53, 0, v53
	v_max_f32_e32 v54, 0, v54
	v_max_f32_e32 v55, 0, v55
	v_mul_f32_e32 v60, v60, v60
	v_mul_f32_e32 v56, v56, v56
	v_mul_f32_e32 v61, v61, v61
	v_mul_f32_e32 v57, v57, v57
	v_mul_f32_e32 v62, v62, v62
	v_mul_f32_e32 v58, v58, v58
	v_mul_f32_e32 v63, v63, v63
	v_mul_f32_e32 v59, v59, v59
	v_mul_f32_e32 v66, v48, v48
	v_mul_f32_e32 v67, v49, v49
	v_mul_f32_e32 v68, v50, v50
	v_mul_f32_e32 v69, v51, v51
	v_cvt_pk_bf16_f32 v48, v60, v61
	v_cvt_pk_bf16_f32 v49, v62, v63
	v_cvt_pk_bf16_f32 v50, v56, v57
	v_cvt_pk_bf16_f32 v51, v58, v59
	v_mul_f32_e32 v52, v52, v52
	v_mul_f32_e32 v53, v53, v53
	v_mul_f32_e32 v54, v54, v54
	v_mul_f32_e32 v55, v55, v55
	buffer_store_dwordx4 v[48:51], v84, s[8:11], 0 offen sc1
	s_nop 1
	v_cvt_pk_bf16_f32 v48, v52, v53
	v_cvt_pk_bf16_f32 v49, v54, v55
	v_cvt_pk_bf16_f32 v50, v66, v67
	v_cvt_pk_bf16_f32 v51, v68, v69
	buffer_store_dwordx4 v[48:51], v84, s[8:11], 0 offen offset:256 sc1
	s_nop 0
	v_add_u32_e32 v64, 0x40a0, v150
	v_ashrrev_i32_e32 v65, 31, v64
	v_lshl_add_u32 v68, v80, 13, v149
	s_waitcnt vmcnt(14)
; __device__ __forceinline__ u32x4 pack8(const f32x4 v0, const f32x4 v1) { u32x4 w; w.x = pk2(v0[0], v0[1]); w.y = pk2(v0[2], v0[3]); w.z = pk2(v1[0], v1[1]); w.w = pk2(v1[2], v1[3]); return w; }
; __device__ __forceinline__ float row_rstd(const float* ssq, int row) {
;     const f32x4* p = (const f32x4*)(ssq + (size_t)row * 16);
;     const f32x4 a = p[0], b = p[1], c = p[2], d = p[3];
;     const float s = ((a[0] + a[1]) + (a[2] + a[3])) + ((b[0] + b[1]) + (b[2] + b[3])) + ((c[0] + c[1]) + (c[2] + c[3])) + ((d[0] + d[1]) + (d[2] + d[3]));
;     return rsqrtf(s * (1.0f / 1024.0f) + 1e-6f);
;     __device__ __forceinline__ void operator()(const f32x4 (&acc)[2][2][4][2], const Unit& u, int wr, int wc, int fr, int fq) const {
;     ...
;             for (int m = 0; m < 4; ++m) {
;                 const int row = row0 + ai * 128 + m * 16; const float rs = row_rstd(ssq, row);
; #pragma unroll
;                 for (int bj = 0; bj < 2; ++bj) { f32x4 v0 = acc[ai][bj][m][0] * rs, v1 = acc[ai][bj][m][1] * rs;
; #pragma unroll
;                     for (int j = 0; j < 4; ++j) { const float a = fmaxf(v0[j], 0.f), b = fmaxf(v1[j], 0.f); v0[j] = a * a; v1[j] = b * b; }
;                     __builtin_amdgcn_raw_buffer_store_b128(pack8(v0, v1), rsrc, (unsigned)(((size_t)row * DFF + col0 + bj * 128) * 2), 0, 16  ); }
	v_mov_b32_e32 v66, v195
	v_mov_b32_e32 v67, v196
	v_mov_b32_e32 v49, v197
	v_mov_b32_e32 v50, v199
	v_mov_b32_e32 v51, v200
	v_mov_b32_e32 v53, v201
	v_mov_b32_e32 v48, v194
	v_pk_add_f32 v[48:49], v[66:67], v[48:49]
	v_mov_b32_e32 v52, v198
	v_pk_add_f32 v[50:51], v[50:51], v[52:53]
	v_pk_add_f32 v[48:49], v[48:49], v[48:49] op_sel:[0,1] op_sel_hi:[1,0]
	v_pk_add_f32 v[50:51], v[50:51], v[50:51] op_sel:[0,1] op_sel_hi:[1,0]
	v_add_f32_e32 v54, v202, v203
	v_add_f32_e32 v56, v204, v205
	v_mov_b32_e32 v55, v208
	v_mov_b32_e32 v57, v209
	v_mov_b32_e32 v49, v206
	v_mov_b32_e32 v51, v207
	v_pk_add_f32 v[52:53], v[54:55], v[56:57]
	v_pk_add_f32 v[48:49], v[48:49], v[50:51]
	s_nop 0
	v_pk_add_f32 v[48:49], v[48:49], v[52:53]
	s_nop 0
	v_add_f32_e32 v48, v48, v49
	v_fmamk_f32 v48, v48, 0x3a800000, v148
	v_mul_f32_e32 v49, 0x4b800000, v48
	v_cmp_gt_f32_e32 vcc, s63, v48
	s_nop 1
	v_cndmask_b32_e32 v48, v48, v49, vcc
	v_rsq_f32_e32 v50, v48
	v_lshlrev_b64 v[48:49], 6, v[64:65]
	v_lshl_add_u64 v[48:49], s[14:15], 0, v[48:49]
	v_mul_f32_e32 v51, 0x45800000, v50
	v_cndmask_b32_e32 v50, v50, v51, vcc
	v_pk_mul_f32 v[46:47], v[46:47], v[50:51] op_sel_hi:[1,0]
	v_pk_mul_f32 v[44:45], v[44:45], v[50:51] op_sel_hi:[1,0]
	v_pk_mul_f32 v[42:43], v[42:43], v[50:51] op_sel_hi:[1,0]
	v_pk_mul_f32 v[40:41], v[40:41], v[50:51] op_sel_hi:[1,0]
	v_pk_mul_f32 v[34:35], v[34:35], v[50:51] op_sel_hi:[1,0]
	v_pk_mul_f32 v[32:33], v[32:33], v[50:51] op_sel_hi:[1,0]
	v_pk_mul_f32 v[38:39], v[38:39], v[50:51] op_sel_hi:[1,0]
	v_pk_mul_f32 v[36:37], v[36:37], v[50:51] op_sel_hi:[1,0]
	v_max_f32_e32 v44, 0, v44
	v_max_f32_e32 v40, 0, v40
	v_max_f32_e32 v45, 0, v45
	v_max_f32_e32 v41, 0, v41
	v_max_f32_e32 v46, 0, v46
	v_max_f32_e32 v42, 0, v42
	v_max_f32_e32 v47, 0, v47
	v_max_f32_e32 v43, 0, v43
	v_max_f32_e32 v32, 0, v32
	v_max_f32_e32 v33, 0, v33
	v_max_f32_e32 v34, 0, v34
	v_max_f32_e32 v35, 0, v35
	v_max_f32_e32 v36, 0, v36
	v_max_f32_e32 v37, 0, v37
	v_max_f32_e32 v38, 0, v38
	v_max_f32_e32 v39, 0, v39
	v_mul_f32_e32 v44, v44, v44
	v_mul_f32_e32 v40, v40, v40
	v_mul_f32_e32 v45, v45, v45
	v_mul_f32_e32 v41, v41, v41
	v_mul_f32_e32 v46, v46, v46
	v_mul_f32_e32 v42, v42, v42
	v_mul_f32_e32 v47, v47, v47
	v_mul_f32_e32 v43, v43, v43
	v_mul_f32_e32 v50, v32, v32
	v_mul_f32_e32 v51, v33, v33
	v_mul_f32_e32 v52, v34, v34
	v_mul_f32_e32 v53, v35, v35
	v_cvt_pk_bf16_f32 v32, v44, v45
	v_cvt_pk_bf16_f32 v33, v46, v47
	v_cvt_pk_bf16_f32 v34, v40, v41
	v_cvt_pk_bf16_f32 v35, v42, v43
	v_mul_f32_e32 v36, v36, v36
	v_mul_f32_e32 v37, v37, v37
	v_mul_f32_e32 v38, v38, v38
	v_mul_f32_e32 v39, v39, v39
	buffer_store_dwordx4 v[32:35], v68, s[8:11], 0 offen sc1
	s_nop 1
	v_cvt_pk_bf16_f32 v32, v36, v37
	v_cvt_pk_bf16_f32 v33, v38, v39
	v_cvt_pk_bf16_f32 v34, v50, v51
	v_cvt_pk_bf16_f32 v35, v52, v53
	buffer_store_dwordx4 v[32:35], v68, s[8:11], 0 offen offset:256 sc1
	s_nop 0
	v_add_u32_e32 v48, 0x40b0, v150
	v_ashrrev_i32_e32 v49, 31, v48
	v_lshl_add_u32 v52, v64, 13, v149
	s_waitcnt vmcnt(10)
	v_mov_b32_e32 v50, v211
	v_mov_b32_e32 v51, v212
	v_mov_b32_e32 v33, v213
	v_mov_b32_e32 v34, v215
	v_mov_b32_e32 v35, v216
	v_mov_b32_e32 v37, v217
	v_mov_b32_e32 v32, v210
	v_pk_add_f32 v[32:33], v[50:51], v[32:33]
	v_mov_b32_e32 v36, v214
	v_pk_add_f32 v[34:35], v[34:35], v[36:37]
	v_pk_add_f32 v[32:33], v[32:33], v[32:33] op_sel:[0,1] op_sel_hi:[1,0]
	v_pk_add_f32 v[34:35], v[34:35], v[34:35] op_sel:[0,1] op_sel_hi:[1,0]
	v_add_f32_e32 v38, v232, v233
	v_add_f32_e32 v40, v234, v235
	v_mov_b32_e32 v39, v238
	v_mov_b32_e32 v41, v239
	v_mov_b32_e32 v33, v236
	v_mov_b32_e32 v35, v237
	v_pk_add_f32 v[36:37], v[38:39], v[40:41]
	v_pk_add_f32 v[32:33], v[32:33], v[34:35]
	s_nop 0
	v_pk_add_f32 v[32:33], v[32:33], v[36:37]
	s_nop 0
	v_add_f32_e32 v32, v32, v33
	v_fmamk_f32 v32, v32, 0x3a800000, v148
	v_mul_f32_e32 v33, 0x4b800000, v32
	v_cmp_gt_f32_e32 vcc, s63, v32
	s_nop 1
	v_cndmask_b32_e32 v32, v32, v33, vcc
	v_rsq_f32_e32 v34, v32
	v_lshlrev_b64 v[32:33], 6, v[48:49]
	v_lshl_add_u64 v[32:33], s[14:15], 0, v[32:33]
	v_mul_f32_e32 v35, 0x45800000, v34
	v_cndmask_b32_e32 v34, v34, v35, vcc
	v_pk_mul_f32 v[30:31], v[30:31], v[34:35] op_sel_hi:[1,0]
	v_pk_mul_f32 v[28:29], v[28:29], v[34:35] op_sel_hi:[1,0]
	v_pk_mul_f32 v[26:27], v[26:27], v[34:35] op_sel_hi:[1,0]
	v_pk_mul_f32 v[24:25], v[24:25], v[34:35] op_sel_hi:[1,0]
	v_pk_mul_f32 v[18:19], v[18:19], v[34:35] op_sel_hi:[1,0]
	v_pk_mul_f32 v[16:17], v[16:17], v[34:35] op_sel_hi:[1,0]
	v_pk_mul_f32 v[22:23], v[22:23], v[34:35] op_sel_hi:[1,0]
	v_pk_mul_f32 v[20:21], v[20:21], v[34:35] op_sel_hi:[1,0]
	v_max_f32_e32 v28, 0, v28
	v_max_f32_e32 v24, 0, v24
	v_max_f32_e32 v29, 0, v29
	v_max_f32_e32 v25, 0, v25
	v_max_f32_e32 v30, 0, v30
	v_max_f32_e32 v26, 0, v26
	v_max_f32_e32 v31, 0, v31
	v_max_f32_e32 v27, 0, v27
	v_max_f32_e32 v16, 0, v16
	v_max_f32_e32 v17, 0, v17
	v_max_f32_e32 v18, 0, v18
	v_max_f32_e32 v19, 0, v19
	v_max_f32_e32 v20, 0, v20
	v_max_f32_e32 v21, 0, v21
	v_max_f32_e32 v22, 0, v22
	v_max_f32_e32 v23, 0, v23
	v_mul_f32_e32 v28, v28, v28
	v_mul_f32_e32 v24, v24, v24
	v_mul_f32_e32 v29, v29, v29
	v_mul_f32_e32 v25, v25, v25
	v_mul_f32_e32 v30, v30, v30
	v_mul_f32_e32 v26, v26, v26
	v_mul_f32_e32 v31, v31, v31
	v_mul_f32_e32 v27, v27, v27
	v_mul_f32_e32 v34, v16, v16
	v_mul_f32_e32 v35, v17, v17
	v_mul_f32_e32 v36, v18, v18
	v_mul_f32_e32 v37, v19, v19
	v_cvt_pk_bf16_f32 v16, v28, v29
	v_cvt_pk_bf16_f32 v17, v30, v31
	v_cvt_pk_bf16_f32 v18, v24, v25
	v_cvt_pk_bf16_f32 v19, v26, v27
	v_mul_f32_e32 v20, v20, v20
	v_mul_f32_e32 v21, v21, v21
	v_mul_f32_e32 v22, v22, v22
	v_mul_f32_e32 v23, v23, v23
	buffer_store_dwordx4 v[16:19], v52, s[8:11], 0 offen sc1
	s_nop 1
	v_cvt_pk_bf16_f32 v16, v20, v21
	v_cvt_pk_bf16_f32 v17, v22, v23
	v_cvt_pk_bf16_f32 v18, v34, v35
	v_cvt_pk_bf16_f32 v19, v36, v37
	buffer_store_dwordx4 v[16:19], v52, s[8:11], 0 offen offset:256 sc1
	s_nop 0
	s_waitcnt vmcnt(6)
; __device__ __forceinline__ u32x4 pack8(const f32x4 v0, const f32x4 v1) { u32x4 w; w.x = pk2(v0[0], v0[1]); w.y = pk2(v0[2], v0[3]); w.z = pk2(v1[0], v1[1]); w.w = pk2(v1[2], v1[3]); return w; }
; __device__ __forceinline__ float row_rstd(const float* ssq, int row) {
;     const f32x4* p = (const f32x4*)(ssq + (size_t)row * 16);
;     const f32x4 a = p[0], b = p[1], c = p[2], d = p[3];
;     const float s = ((a[0] + a[1]) + (a[2] + a[3])) + ((b[0] + b[1]) + (b[2] + b[3])) + ((c[0] + c[1]) + (c[2] + c[3])) + ((d[0] + d[1]) + (d[2] + d[3]));
;     return rsqrtf(s * (1.0f / 1024.0f) + 1e-6f);
;     __device__ __forceinline__ void operator()(const f32x4 (&acc)[2][2][4][2], const Unit& u, int wr, int wc, int fr, int fq) const {
;     ...
;             for (int m = 0; m < 4; ++m) {
;                 const int row = row0 + ai * 128 + m * 16; const float rs = row_rstd(ssq, row);
; #pragma unroll
;                 for (int bj = 0; bj < 2; ++bj) { f32x4 v0 = acc[ai][bj][m][0] * rs, v1 = acc[ai][bj][m][1] * rs;
; #pragma unroll
;                     for (int j = 0; j < 4; ++j) { const float a = fmaxf(v0[j], 0.f), b = fmaxf(v1[j], 0.f); v0[j] = a * a; v1[j] = b * b; }
;                     __builtin_amdgcn_raw_buffer_store_b128(pack8(v0, v1), rsrc, (unsigned)(((size_t)row * DFF + col0 + bj * 128) * 2), 0, 16  ); }
;             }
;         asm volatile("s_waitcnt vmcnt(0)" ::: "memory");
;         if (fr == 0 && fq == 0) (void)__hip_atomic_fetch_add(ready + 64 * (pm_off + u.pm), 1u, __ATOMIC_RELAXED, __HIP_MEMORY_SCOPE_AGENT);
	v_mov_b32_e32 v32, v241
	v_mov_b32_e32 v33, v242
	v_mov_b32_e32 v17, v243
	v_mov_b32_e32 v18, v245
	v_mov_b32_e32 v19, v246
	v_mov_b32_e32 v21, v247
	v_mov_b32_e32 v16, v240
	v_pk_add_f32 v[16:17], v[32:33], v[16:17]
	v_mov_b32_e32 v20, v244
	v_pk_add_f32 v[18:19], v[18:19], v[20:21]
	v_pk_add_f32 v[16:17], v[16:17], v[16:17] op_sel:[0,1] op_sel_hi:[1,0]
	v_pk_add_f32 v[18:19], v[18:19], v[18:19] op_sel:[0,1] op_sel_hi:[1,0]
	v_add_f32_e32 v22, v248, v249
	v_add_f32_e32 v24, v250, v251
	v_mov_b32_e32 v23, v254
	v_mov_b32_e32 v25, v255
	v_mov_b32_e32 v17, v252
	v_mov_b32_e32 v19, v253
	v_pk_add_f32 v[20:21], v[22:23], v[24:25]
	v_pk_add_f32 v[16:17], v[16:17], v[18:19]
	s_nop 0
	v_pk_add_f32 v[16:17], v[16:17], v[20:21]
	s_nop 0
	v_add_f32_e32 v16, v16, v17
	v_fmamk_f32 v16, v16, 0x3a800000, v148
	v_mul_f32_e32 v17, 0x4b800000, v16
	v_cmp_gt_f32_e32 vcc, s63, v16
	s_nop 1
	v_cndmask_b32_e32 v16, v16, v17, vcc
	v_rsq_f32_e32 v16, v16
	v_lshl_add_u32 v17, v48, 13, v149
	v_mul_f32_e32 v18, 0x45800000, v16
	v_cndmask_b32_e32 v16, v16, v18, vcc
	v_pk_mul_f32 v[14:15], v[14:15], v[16:17] op_sel_hi:[1,0]
	v_pk_mul_f32 v[12:13], v[12:13], v[16:17] op_sel_hi:[1,0]
	v_pk_mul_f32 v[10:11], v[10:11], v[16:17] op_sel_hi:[1,0]
	v_pk_mul_f32 v[8:9], v[8:9], v[16:17] op_sel_hi:[1,0]
	v_pk_mul_f32 v[2:3], v[2:3], v[16:17] op_sel_hi:[1,0]
	v_pk_mul_f32 v[0:1], v[0:1], v[16:17] op_sel_hi:[1,0]
	v_pk_mul_f32 v[6:7], v[6:7], v[16:17] op_sel_hi:[1,0]
	v_pk_mul_f32 v[4:5], v[4:5], v[16:17] op_sel_hi:[1,0]
	v_max_f32_e32 v12, 0, v12
	v_max_f32_e32 v8, 0, v8
	v_max_f32_e32 v13, 0, v13
	v_max_f32_e32 v9, 0, v9
	v_max_f32_e32 v14, 0, v14
	v_max_f32_e32 v10, 0, v10
	v_max_f32_e32 v15, 0, v15
	v_max_f32_e32 v11, 0, v11
	v_max_f32_e32 v0, 0, v0
	v_max_f32_e32 v1, 0, v1
	v_max_f32_e32 v2, 0, v2
	v_max_f32_e32 v3, 0, v3
	v_max_f32_e32 v4, 0, v4
	v_max_f32_e32 v5, 0, v5
	v_max_f32_e32 v6, 0, v6
	v_max_f32_e32 v7, 0, v7
	v_mul_f32_e32 v12, v12, v12
	v_mul_f32_e32 v8, v8, v8
	v_mul_f32_e32 v13, v13, v13
	v_mul_f32_e32 v9, v9, v9
	v_mul_f32_e32 v14, v14, v14
	v_mul_f32_e32 v10, v10, v10
	v_mul_f32_e32 v15, v15, v15
	v_mul_f32_e32 v11, v11, v11
	v_mul_f32_e32 v16, v0, v0
	v_mul_f32_e32 v18, v1, v1
	v_mul_f32_e32 v19, v2, v2
	v_mul_f32_e32 v20, v3, v3
	v_cvt_pk_bf16_f32 v0, v12, v13
	v_cvt_pk_bf16_f32 v1, v14, v15
	v_cvt_pk_bf16_f32 v2, v8, v9
	v_cvt_pk_bf16_f32 v3, v10, v11
	v_mul_f32_e32 v4, v4, v4
	v_mul_f32_e32 v5, v5, v5
	v_mul_f32_e32 v6, v6, v6
	v_mul_f32_e32 v7, v7, v7
	buffer_store_dwordx4 v[0:3], v17, s[8:11], 0 offen sc1
	s_nop 1
	v_cvt_pk_bf16_f32 v0, v4, v5
	v_cvt_pk_bf16_f32 v1, v6, v7
	v_cvt_pk_bf16_f32 v2, v16, v18
	v_cvt_pk_bf16_f32 v3, v19, v20
	buffer_store_dwordx4 v[0:3], v17, s[8:11], 0 offen offset:256 sc1
	s_waitcnt vmcnt(0)
	s_and_saveexec_b64 s[34:35], s[6:7]
	s_cbranch_execz .LBB0_2114
	s_mov_b64 s[36:37], exec
	v_mbcnt_lo_u32_b32 v0, s36, 0
	v_mbcnt_hi_u32_b32 v0, s37, v0
	v_cmp_eq_u32_e32 vcc, 0, v0
	s_and_b64 s[38:39], exec, vcc
	s_mov_b64 exec, s[38:39]
	s_cbranch_execz .LBB0_2114
	s_lshl_b32 s21, s68, 6
	s_add_i32 s38, s21, 0x1000
	s_ashr_i32 s39, s38, 31
	s_lshl_b64 s[38:39], s[38:39], 2
	s_add_u32 s38, s66, s38
	s_addc_u32 s39, s67, s39
	s_bcnt1_i32_b64 s21, s[36:37]
	v_mov_b32_e32 v0, s21
	global_atomic_add v131, v0, s[38:39]
	s_branch .LBB0_2114
